# v18 plus 168 XNACK-replay s_nop 0 between back-to-back loads removed
# speedup vs baseline: 1.0018x; 1.0018x over previous
; __device__ __forceinline__ unsigned cvtpk(float lo, float hi) { unsigned r; asm volatile("v_cvt_pk_bf16_f32 %0, %1, %2" : "=v"(r) : "v"(lo), "v"(hi)); return r; }
; #define P1_SRC(m) ((m) < NLAT ? PIN(I_X) + (size_t)(m) * DM : PIN(I_CTX) + (size_t)((m) - NLAT) * DM)
; __device__ __forceinline__ float ssq16(const f32x4 (&v)[4]) {
;     float s = 0.f;
; #pragma unroll
;     for (int j = 0; j < 4; ++j) s += (v[j].x * v[j].x + v[j].y * v[j].y) + (v[j].z * v[j].z + v[j].w * v[j].w);
;     return wave_sum(s);
; }
; __device__ __forceinline__ void prenorm_store(const f32x4 (&v)[4], float rinv, const float* g, const float* shift, const float* scale, bf16_t* orow, int lane) {
; #pragma unroll
;     for (int j = 0; j < 4; ++j) { const int q = lane + 64 * j; const f32x4 gg = ((const f32x4*)g)[q], sh = ((const f32x4*)shift)[q], sc = ((const f32x4*)scale)[q];
;         const f32x4 h = (v[j] * rinv * gg) * (sc + 1.0f) + sh; u32x2 w; w.x = cvtpk(h.x, h.y); w.y = cvtpk(h.z, h.w); ((u32x2*)orow)[q] = w; }
; }
; __global__ void __launch_bounds__(512, 2) fwd_megakernel(Params p) {
;     ...
;     if (NGW == 2048) {
;     for (int m0 = gw; m0 < MTOT; m0 += 4 * NGW) { f32x4 vb[4][4]; const float* mod = MOD_ROW(0, m0);
; #pragma unroll
;         for (int i = 0; i < 4; ++i) { const int mi = m0 + i * NGW; load16(P1_SRC(mi < MTOT ? mi : m0), lane, vb[i]); }
;         f32x4 gv[4], sh[4], sc[4];
; #pragma unroll
;         for (int j = 0; j < 4; ++j) { gv[j] = ((const f32x4*)PIN(I_GPREMIX))[lane + 64 * j]; sh[j] = ((const f32x4*)mod)[lane + 64 * j]; sc[j] = ((const f32x4*)(mod + 1024))[lane + 64 * j] + 1.0f; }
; #pragma unroll
;         for (int i = 0; i < 4; ++i) { const int mi = m0 + i * NGW; if (mi < MTOT) { const float rinv = rsqrtf(ssq16(vb[i]) * (1.f / DM) + EPSN); bf16_t* orow = BA + (size_t)mi * DM;
; #pragma unroll
;             for (int j = 0; j < 4; ++j) { const f32x4 h = (vb[i][j] * rinv * gv[j]) * sc[j] + sh[j]; u32x2 w; w.x = cvtpk(h.x, h.y); w.y = cvtpk(h.z, h.w); ((u32x2*)orow)[lane + 64 * j] = w; } } } }
;     } else
;     for (int m0 = gw; m0 < MTOT; m0 += 4 * NGW) { f32x4 vb[4][4];
; #pragma unroll
;         for (int i = 0; i < 4; ++i) { const int mi = m0 + i * NGW; load16(P1_SRC(mi < MTOT ? mi : m0), lane, vb[i]); }
; #pragma unroll
;         for (int i = 0; i < 4; ++i) { const int mi = m0 + i * NGW; if (mi < MTOT) P1_ROW(mi, vb[i]); } } }
.LBB0_90:
	s_load_dwordx2 s[4:5], s[10:11], 0x30
	s_lshl_b64 s[26:27], s[26:27], 2
	s_add_u32 s26, s42, s26
	s_addc_u32 s27, s43, s27
	s_add_u32 s28, s26, 0x1000
	s_waitcnt lgkmcnt(0)
	global_load_dwordx4 v[16:19], v65, s[4:5]
	s_addc_u32 s29, s27, 0
	global_load_dwordx4 v[20:23], v65, s[28:29]
	global_load_dwordx4 v[24:27], v65, s[26:27]
	v_pk_mul_f32 v[28:29], v[14:15], v[14:15]
	v_pk_mul_f32 v[30:31], v[12:13], v[12:13]
	v_pk_mul_f32 v[32:33], v[10:11], v[10:11]
	v_pk_mul_f32 v[34:35], v[8:9], v[8:9]
	v_pk_mov_b32 v[40:41], v[30:31], v[28:29] op_sel:[1,0]
	v_mov_b32_e32 v31, v29
	v_pk_mov_b32 v[28:29], v[34:35], v[32:33] op_sel:[1,0]
	v_mov_b32_e32 v35, v33
	v_mul_f32_e32 v39, v0, v0
	v_mul_f32_e32 v36, v5, v5
	v_mul_f32_e32 v38, v7, v7
	v_pk_add_f32 v[30:31], v[40:41], v[30:31]
	v_pk_add_f32 v[28:29], v[28:29], v[34:35]
	v_mul_f32_e32 v42, v1, v1
	v_mul_f32_e32 v43, v2, v2
	v_mul_f32_e32 v44, v3, v3
	v_pk_fma_f32 v[32:33], v[4:5], v[4:5], v[36:37] op_sel_hi:[1,1,0]
	v_pk_fma_f32 v[36:37], v[6:7], v[6:7], v[38:39] op_sel_hi:[1,1,0]
	v_pk_add_f32 v[30:31], v[30:31], v[30:31] op_sel:[0,1] op_sel_hi:[1,0]
	v_pk_add_f32 v[28:29], v[28:29], v[28:29] op_sel:[0,1] op_sel_hi:[1,0]
	v_mov_b32_e32 v33, v43
	v_mov_b32_e32 v37, v44
	v_mov_b32_e32 v31, v39
	v_mov_b32_e32 v29, v42
	v_pk_add_f32 v[32:33], v[32:33], v[36:37]
	v_pk_add_f32 v[28:29], v[30:31], v[28:29]
	v_mov_b32_e32 v45, 0
	v_pk_add_f32 v[28:29], v[28:29], v[32:33]
	v_mov_b32_e32 v46, 0
	v_add_f32_e32 v28, v28, v29
	s_ashr_i32 s25, s24, 31
	s_lshl_b64 s[24:25], s[24:25], 11
	v_add_f32_dpp v28, v28, v28 quad_perm:[1,0,3,2] row_mask:0xf bank_mask:0xf bound_ctrl:1
	s_nop 1
	v_add_f32_dpp v28, v28, v28 quad_perm:[2,3,0,1] row_mask:0xf bank_mask:0xf bound_ctrl:1
	s_nop 1
	v_add_f32_dpp v28, v28, v28 row_half_mirror row_mask:0xf bank_mask:0xf bound_ctrl:1
	s_nop 1
	v_add_f32_dpp v28, v28, v28 row_mirror row_mask:0xf bank_mask:0xf bound_ctrl:1
	s_nop 1
	v_mov_b32_dpp v45, v28 row_bcast:15 row_mask:0xa bank_mask:0xf
	v_add_f32_e32 v28, v28, v45
	s_nop 1
	v_mov_b32_dpp v46, v28 row_bcast:31 row_mask:0xc bank_mask:0xf
	v_add_f32_e32 v28, v28, v46
	s_nop 0
	v_readlane_b32 s9, v28, 63
	s_nop 1
	v_cvt_i32_f32_e32 v28, s9
	v_cvt_f32_i32_e32 v28, v28
	v_fmamk_f32 v28, v28, 0x3a800000, v72
	v_mul_f32_e32 v29, 0x4b800000, v28
	v_cmp_gt_f32_e32 vcc, s47, v28
	s_nop 1
	v_cndmask_b32_e32 v28, v28, v29, vcc
	v_rsq_f32_e32 v30, v28
	v_lshl_add_u64 v[28:29], v[70:71], 0, s[24:25]
	v_mul_f32_e32 v31, 0x45800000, v30
	v_cndmask_b32_e32 v30, v30, v31, vcc
	v_pk_mul_f32 v[14:15], v[14:15], v[30:31] op_sel_hi:[1,0]
	v_pk_mul_f32 v[12:13], v[12:13], v[30:31] op_sel_hi:[1,0]
	v_pk_mul_f32 v[10:11], v[10:11], v[30:31] op_sel_hi:[1,0]
	s_waitcnt vmcnt(2)
	v_pk_mul_f32 v[12:13], v[16:17], v[12:13]
	v_pk_mul_f32 v[14:15], v[18:19], v[14:15]
	s_waitcnt vmcnt(1)
	v_pk_add_f32 v[18:19], v[20:21], 1.0 op_sel_hi:[1,0]
	v_pk_add_f32 v[16:17], v[22:23], 1.0 op_sel_hi:[1,0]
	s_waitcnt vmcnt(0)
	v_pk_fma_f32 v[12:13], v[18:19], v[12:13], v[24:25]
	v_pk_fma_f32 v[14:15], v[16:17], v[14:15], v[26:27]
	v_cvt_pk_bf16_f32 v12, v12, v13
	v_pk_mul_f32 v[8:9], v[8:9], v[30:31] op_sel_hi:[1,0]
	v_cvt_pk_bf16_f32 v13, v14, v15
	global_store_dwordx2 v[28:29], v[12:13], off
	global_load_dwordx4 v[12:15], v65, s[4:5] offset:1024
	global_load_dwordx4 v[16:19], v73, s[28:29]
	global_load_dwordx4 v[20:23], v65, s[26:27] offset:1024
	v_pk_mul_f32 v[6:7], v[6:7], v[30:31] op_sel_hi:[1,0]
	v_pk_mul_f32 v[4:5], v[4:5], v[30:31] op_sel_hi:[1,0]
	v_pk_mul_f32 v[2:3], v[2:3], v[30:31] op_sel_hi:[1,0]
	v_pk_mul_f32 v[0:1], v[0:1], v[30:31] op_sel_hi:[1,0]
	s_waitcnt vmcnt(2)
	v_pk_mul_f32 v[8:9], v[12:13], v[8:9]
	v_pk_mul_f32 v[10:11], v[14:15], v[10:11]
	s_waitcnt vmcnt(1)
	v_pk_add_f32 v[14:15], v[16:17], 1.0 op_sel_hi:[1,0]
	v_pk_add_f32 v[12:13], v[18:19], 1.0 op_sel_hi:[1,0]
	s_waitcnt vmcnt(0)
	v_pk_fma_f32 v[8:9], v[14:15], v[8:9], v[20:21]
	v_pk_fma_f32 v[10:11], v[12:13], v[10:11], v[22:23]
	v_cvt_pk_bf16_f32 v8, v8, v9
	s_nop 0
	v_cvt_pk_bf16_f32 v9, v10, v11
	global_store_dwordx2 v[28:29], v[8:9], off offset:512
	global_load_dwordx4 v[8:11], v65, s[4:5] offset:2048
	global_load_dwordx4 v[12:15], v74, s[28:29]
	global_load_dwordx4 v[16:19], v65, s[26:27] offset:2048
	s_waitcnt vmcnt(2)
	v_pk_mul_f32 v[4:5], v[4:5], v[8:9]
	v_pk_mul_f32 v[6:7], v[6:7], v[10:11]
	s_waitcnt vmcnt(1)
	v_pk_add_f32 v[10:11], v[12:13], 1.0 op_sel_hi:[1,0]
	v_pk_add_f32 v[8:9], v[14:15], 1.0 op_sel_hi:[1,0]
	s_waitcnt vmcnt(0)
	v_pk_fma_f32 v[4:5], v[4:5], v[10:11], v[16:17]
	v_pk_fma_f32 v[6:7], v[6:7], v[8:9], v[18:19]
	v_cvt_pk_bf16_f32 v4, v4, v5
	s_nop 0
	v_cvt_pk_bf16_f32 v5, v6, v7
	global_store_dwordx2 v[28:29], v[4:5], off offset:1024
	global_load_dwordx4 v[4:7], v65, s[4:5] offset:3072
	global_load_dwordx4 v[8:11], v75, s[28:29]
	global_load_dwordx4 v[12:15], v65, s[26:27] offset:3072
	s_waitcnt vmcnt(2)
	v_pk_mul_f32 v[0:1], v[0:1], v[4:5]
	v_pk_mul_f32 v[2:3], v[2:3], v[6:7]
	s_waitcnt vmcnt(1)
	v_pk_add_f32 v[6:7], v[8:9], 1.0 op_sel_hi:[1,0]
	v_pk_add_f32 v[4:5], v[10:11], 1.0 op_sel_hi:[1,0]
	s_waitcnt vmcnt(0)
	v_pk_fma_f32 v[0:1], v[0:1], v[6:7], v[12:13]
	v_pk_fma_f32 v[2:3], v[2:3], v[4:5], v[14:15]
	v_cvt_pk_bf16_f32 v0, v0, v1
	s_nop 0
	v_cvt_pk_bf16_f32 v1, v2, v3
	global_store_dwordx2 v[28:29], v[0:1], off offset:1536

; __device__ __forceinline__ unsigned cvtpk(float lo, float hi) { unsigned r; asm volatile("v_cvt_pk_bf16_f32 %0, %1, %2" : "=v"(r) : "v"(lo), "v"(hi)); return r; }
; #define P1_SRC(m) ((m) < NLAT ? PIN(I_X) + (size_t)(m) * DM : PIN(I_CTX) + (size_t)((m) - NLAT) * DM)
; __device__ __forceinline__ float ssq16(const f32x4 (&v)[4]) {
;     float s = 0.f;
; #pragma unroll
;     for (int j = 0; j < 4; ++j) s += (v[j].x * v[j].x + v[j].y * v[j].y) + (v[j].z * v[j].z + v[j].w * v[j].w);
;     return wave_sum(s);
; }
; __device__ __forceinline__ void prenorm_store(const f32x4 (&v)[4], float rinv, const float* g, const float* shift, const float* scale, bf16_t* orow, int lane) {
; #pragma unroll
;     for (int j = 0; j < 4; ++j) { const int q = lane + 64 * j; const f32x4 gg = ((const f32x4*)g)[q], sh = ((const f32x4*)shift)[q], sc = ((const f32x4*)scale)[q];
;         const f32x4 h = (v[j] * rinv * gg) * (sc + 1.0f) + sh; u32x2 w; w.x = cvtpk(h.x, h.y); w.y = cvtpk(h.z, h.w); ((u32x2*)orow)[q] = w; }
; }
; __global__ void __launch_bounds__(512, 2) fwd_megakernel(Params p) {
;     ...
;     if (NGW == 2048) {
;     for (int m0 = gw; m0 < MTOT; m0 += 4 * NGW) { f32x4 vb[4][4]; const float* mod = MOD_ROW(0, m0);
; #pragma unroll
;         for (int i = 0; i < 4; ++i) { const int mi = m0 + i * NGW; load16(P1_SRC(mi < MTOT ? mi : m0), lane, vb[i]); }
;         f32x4 gv[4], sh[4], sc[4];
; #pragma unroll
;         for (int j = 0; j < 4; ++j) { gv[j] = ((const f32x4*)PIN(I_GPREMIX))[lane + 64 * j]; sh[j] = ((const f32x4*)mod)[lane + 64 * j]; sc[j] = ((const f32x4*)(mod + 1024))[lane + 64 * j] + 1.0f; }
; #pragma unroll
;         for (int i = 0; i < 4; ++i) { const int mi = m0 + i * NGW; if (mi < MTOT) { const float rinv = rsqrtf(ssq16(vb[i]) * (1.f / DM) + EPSN); bf16_t* orow = BA + (size_t)mi * DM;
; #pragma unroll
;             for (int j = 0; j < 4; ++j) { const f32x4 h = (vb[i][j] * rinv * gv[j]) * sc[j] + sh[j]; u32x2 w; w.x = cvtpk(h.x, h.y); w.y = cvtpk(h.z, h.w); ((u32x2*)orow)[lane + 64 * j] = w; } } } }
;     } else
;     for (int m0 = gw; m0 < MTOT; m0 += 4 * NGW) { f32x4 vb[4][4];
; #pragma unroll
;         for (int i = 0; i < 4; ++i) { const int mi = m0 + i * NGW; load16(P1_SRC(mi < MTOT ? mi : m0), lane, vb[i]); }
; #pragma unroll
;         for (int i = 0; i < 4; ++i) { const int mi = m0 + i * NGW; if (mi < MTOT) P1_ROW(mi, vb[i]); } } }
.LBB0_94:
	s_lshl_b64 s[4:5], s[4:5], 2
	s_add_u32 s38, s42, s4
	s_addc_u32 s39, s43, s5
	s_add_u32 s40, s38, 0x1000
	global_load_dwordx4 v[76:79], v[68:69], off
	s_addc_u32 s41, s39, 0
	global_load_dwordx4 v[80:83], v65, s[40:41]
	global_load_dwordx4 v[84:87], v65, s[38:39]
	s_waitcnt vmcnt(18)
	v_pk_mul_f32 v[88:89], v[62:63], v[62:63]
	v_pk_mul_f32 v[90:91], v[60:61], v[60:61]
	s_waitcnt vmcnt(17)
	v_pk_mul_f32 v[92:93], v[58:59], v[58:59]
	v_pk_mul_f32 v[94:95], v[56:57], v[56:57]
	v_pk_mov_b32 v[102:103], v[90:91], v[88:89] op_sel:[1,0]
	v_mov_b32_e32 v91, v89
	v_pk_mov_b32 v[88:89], v[94:95], v[92:93] op_sel:[1,0]
	v_mov_b32_e32 v95, v93
	s_waitcnt vmcnt(15)
	v_mul_f32_e32 v99, v48, v48
	v_mul_f32_e32 v96, v53, v53
	v_mul_f32_e32 v98, v55, v55
	v_pk_add_f32 v[90:91], v[102:103], v[90:91]
	v_pk_add_f32 v[88:89], v[88:89], v[94:95]
	v_mul_f32_e32 v101, v49, v49
	v_mul_f32_e32 v104, v50, v50
	v_mul_f32_e32 v105, v51, v51
	v_pk_fma_f32 v[92:93], v[52:53], v[52:53], v[96:97] op_sel_hi:[1,1,0]
	v_pk_fma_f32 v[96:97], v[54:55], v[54:55], v[98:99] op_sel_hi:[1,1,0]
	v_pk_add_f32 v[90:91], v[90:91], v[90:91] op_sel:[0,1] op_sel_hi:[1,0]
	v_pk_add_f32 v[88:89], v[88:89], v[88:89] op_sel:[0,1] op_sel_hi:[1,0]
	v_mov_b32_e32 v93, v104
	v_mov_b32_e32 v97, v105
	v_mov_b32_e32 v91, v99
	v_mov_b32_e32 v89, v101
	v_pk_add_f32 v[92:93], v[92:93], v[96:97]
	v_pk_add_f32 v[88:89], v[90:91], v[88:89]
	v_mov_b32_e32 v106, 0
	v_pk_add_f32 v[88:89], v[88:89], v[92:93]
	v_mov_b32_e32 v107, 0
	v_add_f32_e32 v88, v88, v89
	s_nop 1
	v_add_f32_dpp v88, v88, v88 quad_perm:[1,0,3,2] row_mask:0xf bank_mask:0xf bound_ctrl:1
	s_nop 1
	v_add_f32_dpp v88, v88, v88 quad_perm:[2,3,0,1] row_mask:0xf bank_mask:0xf bound_ctrl:1
	s_nop 1
	v_add_f32_dpp v88, v88, v88 row_half_mirror row_mask:0xf bank_mask:0xf bound_ctrl:1
	s_nop 1
	v_add_f32_dpp v88, v88, v88 row_mirror row_mask:0xf bank_mask:0xf bound_ctrl:1
	s_nop 1
	v_mov_b32_dpp v106, v88 row_bcast:15 row_mask:0xa bank_mask:0xf
	v_add_f32_e32 v88, v88, v106
	s_nop 1
	v_mov_b32_dpp v107, v88 row_bcast:31 row_mask:0xc bank_mask:0xf
	v_add_f32_e32 v88, v88, v107
	s_nop 0
	v_readlane_b32 s4, v88, 63
	s_nop 1
	v_cvt_i32_f32_e32 v88, s4
	v_cvt_f32_i32_e32 v90, v88
	v_lshl_add_u64 v[88:89], s[16:17], 0, v[66:67]
	v_add_co_u32_e64 v88, s[4:5], s48, v88
	v_fmamk_f32 v90, v90, 0x3a800000, v72
	v_mul_f32_e32 v91, 0x4b800000, v90
	v_cmp_gt_f32_e32 vcc, s47, v90
	v_addc_co_u32_e64 v89, s[4:5], 0, v89, s[4:5]
	s_nop 0
	v_cndmask_b32_e32 v90, v90, v91, vcc
	v_rsq_f32_e32 v90, v90
	s_nop 0
	v_mul_f32_e32 v91, 0x45800000, v90
	v_cndmask_b32_e32 v90, v90, v91, vcc
	v_pk_mul_f32 v[62:63], v[62:63], v[90:91] op_sel_hi:[1,0]
	v_pk_mul_f32 v[60:61], v[60:61], v[90:91] op_sel_hi:[1,0]
	v_pk_mul_f32 v[58:59], v[58:59], v[90:91] op_sel_hi:[1,0]
	s_waitcnt vmcnt(2)
	v_pk_mul_f32 v[60:61], v[76:77], v[60:61]
	v_pk_mul_f32 v[62:63], v[78:79], v[62:63]
	s_waitcnt vmcnt(1)
	v_pk_add_f32 v[78:79], v[80:81], 1.0 op_sel_hi:[1,0]
	v_pk_add_f32 v[76:77], v[82:83], 1.0 op_sel_hi:[1,0]
	s_waitcnt vmcnt(0)
	v_pk_fma_f32 v[60:61], v[78:79], v[60:61], v[84:85]
	v_pk_fma_f32 v[62:63], v[76:77], v[62:63], v[86:87]
	v_cvt_pk_bf16_f32 v60, v60, v61
	v_pk_mul_f32 v[56:57], v[56:57], v[90:91] op_sel_hi:[1,0]
	v_cvt_pk_bf16_f32 v61, v62, v63
	global_store_dwordx2 v[88:89], v[60:61], off
	global_load_dwordx4 v[60:63], v[68:69], off offset:1024
	global_load_dwordx4 v[76:79], v73, s[40:41]
	global_load_dwordx4 v[80:83], v65, s[38:39] offset:1024
	v_pk_mul_f32 v[54:55], v[54:55], v[90:91] op_sel_hi:[1,0]
	v_pk_mul_f32 v[52:53], v[52:53], v[90:91] op_sel_hi:[1,0]
	v_pk_mul_f32 v[50:51], v[50:51], v[90:91] op_sel_hi:[1,0]
	v_pk_mul_f32 v[48:49], v[48:49], v[90:91] op_sel_hi:[1,0]
	s_andn2_b64 vcc, exec, s[36:37]
	s_waitcnt vmcnt(2)
	v_pk_mul_f32 v[56:57], v[60:61], v[56:57]
	v_pk_mul_f32 v[58:59], v[62:63], v[58:59]
	s_waitcnt vmcnt(1)
	v_pk_add_f32 v[62:63], v[76:77], 1.0 op_sel_hi:[1,0]
	v_pk_add_f32 v[60:61], v[78:79], 1.0 op_sel_hi:[1,0]
	s_waitcnt vmcnt(0)
	v_pk_fma_f32 v[56:57], v[62:63], v[56:57], v[80:81]
	v_pk_fma_f32 v[58:59], v[60:61], v[58:59], v[82:83]
	v_cvt_pk_bf16_f32 v56, v56, v57
	s_nop 0
	v_cvt_pk_bf16_f32 v57, v58, v59
	global_store_dwordx2 v[88:89], v[56:57], off offset:512
	global_load_dwordx4 v[56:59], v[68:69], off offset:2048
	global_load_dwordx4 v[60:63], v74, s[40:41]
	global_load_dwordx4 v[76:79], v65, s[38:39] offset:2048
	s_waitcnt vmcnt(2)
	v_pk_mul_f32 v[52:53], v[52:53], v[56:57]
	v_pk_mul_f32 v[54:55], v[54:55], v[58:59]
	s_waitcnt vmcnt(1)
	v_pk_add_f32 v[58:59], v[60:61], 1.0 op_sel_hi:[1,0]
	v_pk_add_f32 v[56:57], v[62:63], 1.0 op_sel_hi:[1,0]
	s_waitcnt vmcnt(0)
	v_pk_fma_f32 v[52:53], v[52:53], v[58:59], v[76:77]
	v_pk_fma_f32 v[54:55], v[54:55], v[56:57], v[78:79]
	v_cvt_pk_bf16_f32 v52, v52, v53
	s_nop 0
	v_cvt_pk_bf16_f32 v53, v54, v55
	global_store_dwordx2 v[88:89], v[52:53], off offset:1024
	global_load_dwordx4 v[52:55], v[68:69], off offset:3072
	global_load_dwordx4 v[56:59], v75, s[40:41]
	global_load_dwordx4 v[60:63], v65, s[38:39] offset:3072
	s_waitcnt vmcnt(2)
	v_pk_mul_f32 v[48:49], v[48:49], v[52:53]
	v_pk_mul_f32 v[50:51], v[50:51], v[54:55]
	s_waitcnt vmcnt(1)
	v_pk_add_f32 v[54:55], v[56:57], 1.0 op_sel_hi:[1,0]
	v_pk_add_f32 v[52:53], v[58:59], 1.0 op_sel_hi:[1,0]
	s_waitcnt vmcnt(0)
	v_pk_fma_f32 v[48:49], v[48:49], v[54:55], v[60:61]
	v_pk_fma_f32 v[50:51], v[50:51], v[52:53], v[62:63]
	v_cvt_pk_bf16_f32 v48, v48, v49
	s_nop 0
	v_cvt_pk_bf16_f32 v49, v50, v51
	global_store_dwordx2 v[88:89], v[48:49], off offset:1536
	s_cbranch_vccnz .LBB0_99
	s_cmpk_gt_i32 s9, 0x7fff
	s_mov_b64 s[4:5], 0x6000
	s_cbranch_scc1 .LBB0_97
	s_ashr_i32 s4, s9, 31
	s_lshr_b32 s4, s4, 19
	s_add_i32 s9, s9, s4
	s_ashr_i32 s4, s9, 13
	s_mulk_i32 s4, 0x1800
	s_ashr_i32 s5, s4, 31
; __device__ __forceinline__ unsigned cvtpk(float lo, float hi) { unsigned r; asm volatile("v_cvt_pk_bf16_f32 %0, %1, %2" : "=v"(r) : "v"(lo), "v"(hi)); return r; }
; #define P1_SRC(m) ((m) < NLAT ? PIN(I_X) + (size_t)(m) * DM : PIN(I_CTX) + (size_t)((m) - NLAT) * DM)
; __device__ __forceinline__ float ssq16(const f32x4 (&v)[4]) {
;     float s = 0.f;
; #pragma unroll
;     for (int j = 0; j < 4; ++j) s += (v[j].x * v[j].x + v[j].y * v[j].y) + (v[j].z * v[j].z + v[j].w * v[j].w);
;     return wave_sum(s);
; }
; __device__ __forceinline__ void prenorm_store(const f32x4 (&v)[4], float rinv, const float* g, const float* shift, const float* scale, bf16_t* orow, int lane) {
; #pragma unroll
;     for (int j = 0; j < 4; ++j) { const int q = lane + 64 * j; const f32x4 gg = ((const f32x4*)g)[q], sh = ((const f32x4*)shift)[q], sc = ((const f32x4*)scale)[q];
;         const f32x4 h = (v[j] * rinv * gg) * (sc + 1.0f) + sh; u32x2 w; w.x = cvtpk(h.x, h.y); w.y = cvtpk(h.z, h.w); ((u32x2*)orow)[q] = w; }
; }
; __global__ void __launch_bounds__(512, 2) fwd_megakernel(Params p) {
;     ...
;     if (NGW == 2048) {
;     for (int m0 = gw; m0 < MTOT; m0 += 4 * NGW) { f32x4 vb[4][4]; const float* mod = MOD_ROW(0, m0);
; #pragma unroll
;         for (int i = 0; i < 4; ++i) { const int mi = m0 + i * NGW; load16(P1_SRC(mi < MTOT ? mi : m0), lane, vb[i]); }
;         f32x4 gv[4], sh[4], sc[4];
; #pragma unroll
;         for (int j = 0; j < 4; ++j) { gv[j] = ((const f32x4*)PIN(I_GPREMIX))[lane + 64 * j]; sh[j] = ((const f32x4*)mod)[lane + 64 * j]; sc[j] = ((const f32x4*)(mod + 1024))[lane + 64 * j] + 1.0f; }
; #pragma unroll
;         for (int i = 0; i < 4; ++i) { const int mi = m0 + i * NGW; if (mi < MTOT) { const float rinv = rsqrtf(ssq16(vb[i]) * (1.f / DM) + EPSN); bf16_t* orow = BA + (size_t)mi * DM;
; #pragma unroll
;             for (int j = 0; j < 4; ++j) { const f32x4 h = (vb[i][j] * rinv * gv[j]) * sc[j] + sh[j]; u32x2 w; w.x = cvtpk(h.x, h.y); w.y = cvtpk(h.z, h.w); ((u32x2*)orow)[lane + 64 * j] = w; } } } }
;     } else
;     for (int m0 = gw; m0 < MTOT; m0 += 4 * NGW) { f32x4 vb[4][4];
; #pragma unroll
;         for (int i = 0; i < 4; ++i) { const int mi = m0 + i * NGW; load16(P1_SRC(mi < MTOT ? mi : m0), lane, vb[i]); }
; #pragma unroll
;         for (int i = 0; i < 4; ++i) { const int mi = m0 + i * NGW; if (mi < MTOT) P1_ROW(mi, vb[i]); } } }
.LBB0_97:
	s_load_dwordx2 s[36:37], s[10:11], 0x30
	s_lshl_b64 s[4:5], s[4:5], 2
	s_add_u32 s38, s42, s4
	s_addc_u32 s39, s43, s5
	s_add_u32 s40, s38, 0x1000
	s_waitcnt lgkmcnt(0)
	global_load_dwordx4 v[48:51], v65, s[36:37]
	s_addc_u32 s41, s39, 0
	global_load_dwordx4 v[52:55], v65, s[40:41]
	global_load_dwordx4 v[56:59], v65, s[38:39]
	v_pk_mul_f32 v[60:61], v[46:47], v[46:47]
	v_pk_mul_f32 v[62:63], v[44:45], v[44:45]
	v_pk_mul_f32 v[76:77], v[42:43], v[42:43]
	v_pk_mul_f32 v[78:79], v[40:41], v[40:41]
	v_pk_mov_b32 v[84:85], v[62:63], v[60:61] op_sel:[1,0]
	v_mov_b32_e32 v63, v61
	v_pk_mov_b32 v[60:61], v[78:79], v[76:77] op_sel:[1,0]
	v_mov_b32_e32 v79, v77
	v_mul_f32_e32 v83, v32, v32
	v_mul_f32_e32 v80, v37, v37
	v_mul_f32_e32 v82, v39, v39
	v_pk_add_f32 v[62:63], v[84:85], v[62:63]
	v_pk_add_f32 v[60:61], v[60:61], v[78:79]
	v_mul_f32_e32 v86, v33, v33
	v_mul_f32_e32 v87, v34, v34
	v_mul_f32_e32 v88, v35, v35
	v_pk_fma_f32 v[76:77], v[36:37], v[36:37], v[80:81] op_sel_hi:[1,1,0]
	v_pk_fma_f32 v[80:81], v[38:39], v[38:39], v[82:83] op_sel_hi:[1,1,0]
	v_pk_add_f32 v[62:63], v[62:63], v[62:63] op_sel:[0,1] op_sel_hi:[1,0]
	v_pk_add_f32 v[60:61], v[60:61], v[60:61] op_sel:[0,1] op_sel_hi:[1,0]
	v_mov_b32_e32 v77, v87
	v_mov_b32_e32 v81, v88
	v_mov_b32_e32 v63, v83
	v_mov_b32_e32 v61, v86
	v_pk_add_f32 v[76:77], v[76:77], v[80:81]
	v_pk_add_f32 v[60:61], v[62:63], v[60:61]
	v_mov_b32_e32 v89, 0
	v_pk_add_f32 v[60:61], v[60:61], v[76:77]
	v_mov_b32_e32 v90, 0
	v_add_f32_e32 v60, v60, v61
	s_nop 1
	v_add_f32_dpp v60, v60, v60 quad_perm:[1,0,3,2] row_mask:0xf bank_mask:0xf bound_ctrl:1
	s_nop 1
	v_add_f32_dpp v60, v60, v60 quad_perm:[2,3,0,1] row_mask:0xf bank_mask:0xf bound_ctrl:1
	s_nop 1
	v_add_f32_dpp v60, v60, v60 row_half_mirror row_mask:0xf bank_mask:0xf bound_ctrl:1
	s_nop 1
	v_add_f32_dpp v60, v60, v60 row_mirror row_mask:0xf bank_mask:0xf bound_ctrl:1
	s_nop 1
	v_mov_b32_dpp v89, v60 row_bcast:15 row_mask:0xa bank_mask:0xf
	v_add_f32_e32 v60, v60, v89
	s_nop 1
	v_mov_b32_dpp v90, v60 row_bcast:31 row_mask:0xc bank_mask:0xf
	v_add_f32_e32 v60, v60, v90
	s_nop 0
	v_readlane_b32 s4, v60, 63
	s_nop 1
	v_cvt_i32_f32_e32 v60, s4
	v_cvt_f32_i32_e32 v62, v60
	v_lshl_add_u64 v[60:61], s[20:21], 0, v[66:67]
	v_add_co_u32_e64 v60, s[4:5], s48, v60
	v_fmamk_f32 v62, v62, 0x3a800000, v72
	v_mul_f32_e32 v63, 0x4b800000, v62
	v_cmp_gt_f32_e32 vcc, s47, v62
	v_addc_co_u32_e64 v61, s[4:5], 0, v61, s[4:5]
	s_nop 0
	v_cndmask_b32_e32 v62, v62, v63, vcc
	v_rsq_f32_e32 v62, v62
	s_nop 0
	v_mul_f32_e32 v63, 0x45800000, v62
	v_cndmask_b32_e32 v62, v62, v63, vcc
	v_pk_mul_f32 v[46:47], v[46:47], v[62:63] op_sel_hi:[1,0]
	v_pk_mul_f32 v[44:45], v[44:45], v[62:63] op_sel_hi:[1,0]
	v_pk_mul_f32 v[42:43], v[42:43], v[62:63] op_sel_hi:[1,0]
	s_waitcnt vmcnt(2)
	v_pk_mul_f32 v[44:45], v[48:49], v[44:45]
	v_pk_mul_f32 v[46:47], v[50:51], v[46:47]
	s_waitcnt vmcnt(1)
	v_pk_add_f32 v[50:51], v[52:53], 1.0 op_sel_hi:[1,0]
	v_pk_add_f32 v[48:49], v[54:55], 1.0 op_sel_hi:[1,0]
	s_waitcnt vmcnt(0)
	v_pk_fma_f32 v[44:45], v[50:51], v[44:45], v[56:57]
	v_pk_fma_f32 v[46:47], v[48:49], v[46:47], v[58:59]
	v_cvt_pk_bf16_f32 v44, v44, v45
	v_pk_mul_f32 v[40:41], v[40:41], v[62:63] op_sel_hi:[1,0]
	v_cvt_pk_bf16_f32 v45, v46, v47
	global_store_dwordx2 v[60:61], v[44:45], off
	global_load_dwordx4 v[44:47], v65, s[36:37] offset:1024
	global_load_dwordx4 v[48:51], v73, s[40:41]
	global_load_dwordx4 v[52:55], v65, s[38:39] offset:1024
	v_pk_mul_f32 v[38:39], v[38:39], v[62:63] op_sel_hi:[1,0]
	v_pk_mul_f32 v[36:37], v[36:37], v[62:63] op_sel_hi:[1,0]
	v_pk_mul_f32 v[34:35], v[34:35], v[62:63] op_sel_hi:[1,0]
	v_pk_mul_f32 v[32:33], v[32:33], v[62:63] op_sel_hi:[1,0]
	s_waitcnt vmcnt(2)
	v_pk_mul_f32 v[40:41], v[44:45], v[40:41]
	v_pk_mul_f32 v[42:43], v[46:47], v[42:43]
	s_waitcnt vmcnt(1)
	v_pk_add_f32 v[46:47], v[48:49], 1.0 op_sel_hi:[1,0]
	v_pk_add_f32 v[44:45], v[50:51], 1.0 op_sel_hi:[1,0]
	s_waitcnt vmcnt(0)
	v_pk_fma_f32 v[40:41], v[46:47], v[40:41], v[52:53]
	v_pk_fma_f32 v[42:43], v[44:45], v[42:43], v[54:55]
	v_cvt_pk_bf16_f32 v40, v40, v41
	s_nop 0
	v_cvt_pk_bf16_f32 v41, v42, v43
	global_store_dwordx2 v[60:61], v[40:41], off offset:512
	global_load_dwordx4 v[40:43], v65, s[36:37] offset:2048
	global_load_dwordx4 v[44:47], v74, s[40:41]
	global_load_dwordx4 v[48:51], v65, s[38:39] offset:2048
	s_waitcnt vmcnt(2)
	v_pk_mul_f32 v[36:37], v[36:37], v[40:41]
	v_pk_mul_f32 v[38:39], v[38:39], v[42:43]
	s_waitcnt vmcnt(1)
	v_pk_add_f32 v[42:43], v[44:45], 1.0 op_sel_hi:[1,0]
	v_pk_add_f32 v[40:41], v[46:47], 1.0 op_sel_hi:[1,0]
	s_waitcnt vmcnt(0)
	v_pk_fma_f32 v[36:37], v[36:37], v[42:43], v[48:49]
	v_pk_fma_f32 v[38:39], v[38:39], v[40:41], v[50:51]
	v_cvt_pk_bf16_f32 v36, v36, v37
	s_nop 0
	v_cvt_pk_bf16_f32 v37, v38, v39
	global_store_dwordx2 v[60:61], v[36:37], off offset:1024
	global_load_dwordx4 v[36:39], v65, s[36:37] offset:3072
	global_load_dwordx4 v[40:43], v75, s[40:41]
	global_load_dwordx4 v[44:47], v65, s[38:39] offset:3072
	s_waitcnt vmcnt(2)
	v_pk_mul_f32 v[32:33], v[32:33], v[36:37]
	v_pk_mul_f32 v[34:35], v[34:35], v[38:39]
	s_waitcnt vmcnt(1)
	v_pk_add_f32 v[38:39], v[40:41], 1.0 op_sel_hi:[1,0]
	v_pk_add_f32 v[36:37], v[42:43], 1.0 op_sel_hi:[1,0]
	s_waitcnt vmcnt(0)
	v_pk_fma_f32 v[32:33], v[32:33], v[38:39], v[44:45]
	v_pk_fma_f32 v[34:35], v[34:35], v[36:37], v[46:47]
	v_cvt_pk_bf16_f32 v32, v32, v33
	s_nop 0
	v_cvt_pk_bf16_f32 v33, v34, v35
	global_store_dwordx2 v[60:61], v[32:33], off offset:1536
	s_andn2_b64 vcc, exec, s[34:35]
	s_cbranch_vccz .LBB0_100

; __device__ __forceinline__ unsigned cvtpk(float lo, float hi) { unsigned r; asm volatile("v_cvt_pk_bf16_f32 %0, %1, %2" : "=v"(r) : "v"(lo), "v"(hi)); return r; }
; #define P1_SRC(m) ((m) < NLAT ? PIN(I_X) + (size_t)(m) * DM : PIN(I_CTX) + (size_t)((m) - NLAT) * DM)
; __device__ __forceinline__ float ssq16(const f32x4 (&v)[4]) {
;     float s = 0.f;
; #pragma unroll
;     for (int j = 0; j < 4; ++j) s += (v[j].x * v[j].x + v[j].y * v[j].y) + (v[j].z * v[j].z + v[j].w * v[j].w);
;     return wave_sum(s);
; }
; __device__ __forceinline__ void prenorm_store(const f32x4 (&v)[4], float rinv, const float* g, const float* shift, const float* scale, bf16_t* orow, int lane) {
; #pragma unroll
;     for (int j = 0; j < 4; ++j) { const int q = lane + 64 * j; const f32x4 gg = ((const f32x4*)g)[q], sh = ((const f32x4*)shift)[q], sc = ((const f32x4*)scale)[q];
;         const f32x4 h = (v[j] * rinv * gg) * (sc + 1.0f) + sh; u32x2 w; w.x = cvtpk(h.x, h.y); w.y = cvtpk(h.z, h.w); ((u32x2*)orow)[q] = w; }
; }
; __global__ void __launch_bounds__(512, 2) fwd_megakernel(Params p) {
;     ...
;     if (NGW == 2048) {
;     for (int m0 = gw; m0 < MTOT; m0 += 4 * NGW) { f32x4 vb[4][4]; const float* mod = MOD_ROW(0, m0);
; #pragma unroll
;         for (int i = 0; i < 4; ++i) { const int mi = m0 + i * NGW; load16(P1_SRC(mi < MTOT ? mi : m0), lane, vb[i]); }
;         f32x4 gv[4], sh[4], sc[4];
; #pragma unroll
;         for (int j = 0; j < 4; ++j) { gv[j] = ((const f32x4*)PIN(I_GPREMIX))[lane + 64 * j]; sh[j] = ((const f32x4*)mod)[lane + 64 * j]; sc[j] = ((const f32x4*)(mod + 1024))[lane + 64 * j] + 1.0f; }
; #pragma unroll
;         for (int i = 0; i < 4; ++i) { const int mi = m0 + i * NGW; if (mi < MTOT) { const float rinv = rsqrtf(ssq16(vb[i]) * (1.f / DM) + EPSN); bf16_t* orow = BA + (size_t)mi * DM;
; #pragma unroll
;             for (int j = 0; j < 4; ++j) { const f32x4 h = (vb[i][j] * rinv * gv[j]) * sc[j] + sh[j]; u32x2 w; w.x = cvtpk(h.x, h.y); w.y = cvtpk(h.z, h.w); ((u32x2*)orow)[lane + 64 * j] = w; } } } }
;     } else
;     for (int m0 = gw; m0 < MTOT; m0 += 4 * NGW) { f32x4 vb[4][4];
; #pragma unroll
;         for (int i = 0; i < 4; ++i) { const int mi = m0 + i * NGW; load16(P1_SRC(mi < MTOT ? mi : m0), lane, vb[i]); }
; #pragma unroll
;         for (int i = 0; i < 4; ++i) { const int mi = m0 + i * NGW; if (mi < MTOT) P1_ROW(mi, vb[i]); } } }
.LBB0_102:
	s_load_dwordx2 s[4:5], s[10:11], 0x30
	s_lshl_b64 s[34:35], s[34:35], 2
	s_add_u32 s34, s42, s34
	s_addc_u32 s35, s43, s35
	s_add_u32 s36, s34, 0x1000
	s_waitcnt lgkmcnt(0)
	global_load_dwordx4 v[32:35], v65, s[4:5]
	s_addc_u32 s37, s35, 0
	global_load_dwordx4 v[36:39], v65, s[36:37]
	global_load_dwordx4 v[40:43], v65, s[34:35]
	v_pk_mul_f32 v[44:45], v[30:31], v[30:31]
	v_pk_mul_f32 v[46:47], v[28:29], v[28:29]
	v_pk_mul_f32 v[48:49], v[26:27], v[26:27]
	v_pk_mul_f32 v[50:51], v[24:25], v[24:25]
	v_pk_mov_b32 v[56:57], v[46:47], v[44:45] op_sel:[1,0]
	v_mov_b32_e32 v47, v45
	v_pk_mov_b32 v[44:45], v[50:51], v[48:49] op_sel:[1,0]
	v_mov_b32_e32 v51, v49
	v_mul_f32_e32 v55, v16, v16
	v_mul_f32_e32 v52, v21, v21
	v_mul_f32_e32 v54, v23, v23
	v_pk_add_f32 v[46:47], v[56:57], v[46:47]
	v_pk_add_f32 v[44:45], v[44:45], v[50:51]
	v_mul_f32_e32 v58, v17, v17
	v_mul_f32_e32 v59, v18, v18
	v_mul_f32_e32 v60, v19, v19
	v_pk_fma_f32 v[48:49], v[20:21], v[20:21], v[52:53] op_sel_hi:[1,1,0]
	v_pk_fma_f32 v[52:53], v[22:23], v[22:23], v[54:55] op_sel_hi:[1,1,0]
	v_pk_add_f32 v[46:47], v[46:47], v[46:47] op_sel:[0,1] op_sel_hi:[1,0]
	v_pk_add_f32 v[44:45], v[44:45], v[44:45] op_sel:[0,1] op_sel_hi:[1,0]
	v_mov_b32_e32 v49, v59
	v_mov_b32_e32 v53, v60
	v_mov_b32_e32 v47, v55
	v_mov_b32_e32 v45, v58
	v_pk_add_f32 v[48:49], v[48:49], v[52:53]
	v_pk_add_f32 v[44:45], v[46:47], v[44:45]
	v_mov_b32_e32 v61, 0
	v_pk_add_f32 v[44:45], v[44:45], v[48:49]
	v_mov_b32_e32 v62, 0
	v_add_f32_e32 v44, v44, v45
	s_ashr_i32 s29, s28, 31
	s_lshl_b64 s[28:29], s[28:29], 11
	v_add_f32_dpp v44, v44, v44 quad_perm:[1,0,3,2] row_mask:0xf bank_mask:0xf bound_ctrl:1
	s_nop 1
	v_add_f32_dpp v44, v44, v44 quad_perm:[2,3,0,1] row_mask:0xf bank_mask:0xf bound_ctrl:1
	s_nop 1
	v_add_f32_dpp v44, v44, v44 row_half_mirror row_mask:0xf bank_mask:0xf bound_ctrl:1
	s_nop 1
	v_add_f32_dpp v44, v44, v44 row_mirror row_mask:0xf bank_mask:0xf bound_ctrl:1
	s_nop 1
	v_mov_b32_dpp v61, v44 row_bcast:15 row_mask:0xa bank_mask:0xf
	v_add_f32_e32 v44, v44, v61
	s_nop 1
	v_mov_b32_dpp v62, v44 row_bcast:31 row_mask:0xc bank_mask:0xf
	v_add_f32_e32 v44, v44, v62
	s_nop 0
	v_readlane_b32 s9, v44, 63
	s_nop 1
	v_cvt_i32_f32_e32 v44, s9
	v_cvt_f32_i32_e32 v44, v44
	v_fmamk_f32 v44, v44, 0x3a800000, v72
	v_mul_f32_e32 v45, 0x4b800000, v44
	v_cmp_gt_f32_e32 vcc, s47, v44
	s_nop 1
	v_cndmask_b32_e32 v44, v44, v45, vcc
	v_rsq_f32_e32 v46, v44
	v_lshl_add_u64 v[44:45], v[70:71], 0, s[28:29]
	v_mul_f32_e32 v47, 0x45800000, v46
	v_cndmask_b32_e32 v46, v46, v47, vcc
	v_pk_mul_f32 v[30:31], v[30:31], v[46:47] op_sel_hi:[1,0]
	v_pk_mul_f32 v[28:29], v[28:29], v[46:47] op_sel_hi:[1,0]
	v_pk_mul_f32 v[26:27], v[26:27], v[46:47] op_sel_hi:[1,0]
	s_waitcnt vmcnt(2)
	v_pk_mul_f32 v[28:29], v[32:33], v[28:29]
	v_pk_mul_f32 v[30:31], v[34:35], v[30:31]
	s_waitcnt vmcnt(1)
	v_pk_add_f32 v[34:35], v[36:37], 1.0 op_sel_hi:[1,0]
	v_pk_add_f32 v[32:33], v[38:39], 1.0 op_sel_hi:[1,0]
	s_waitcnt vmcnt(0)
	v_pk_fma_f32 v[28:29], v[34:35], v[28:29], v[40:41]
	v_pk_fma_f32 v[30:31], v[32:33], v[30:31], v[42:43]
	v_cvt_pk_bf16_f32 v28, v28, v29
	v_pk_mul_f32 v[24:25], v[24:25], v[46:47] op_sel_hi:[1,0]
	v_cvt_pk_bf16_f32 v29, v30, v31
	global_store_dwordx2 v[44:45], v[28:29], off
	global_load_dwordx4 v[28:31], v65, s[4:5] offset:1024
	global_load_dwordx4 v[32:35], v73, s[36:37]
	global_load_dwordx4 v[36:39], v65, s[34:35] offset:1024
	v_pk_mul_f32 v[22:23], v[22:23], v[46:47] op_sel_hi:[1,0]
	v_pk_mul_f32 v[20:21], v[20:21], v[46:47] op_sel_hi:[1,0]
	v_pk_mul_f32 v[18:19], v[18:19], v[46:47] op_sel_hi:[1,0]
	v_pk_mul_f32 v[16:17], v[16:17], v[46:47] op_sel_hi:[1,0]
	s_waitcnt vmcnt(2)
	v_pk_mul_f32 v[24:25], v[28:29], v[24:25]
	v_pk_mul_f32 v[26:27], v[30:31], v[26:27]
	s_waitcnt vmcnt(1)
	v_pk_add_f32 v[30:31], v[32:33], 1.0 op_sel_hi:[1,0]
	v_pk_add_f32 v[28:29], v[34:35], 1.0 op_sel_hi:[1,0]
	s_waitcnt vmcnt(0)
	v_pk_fma_f32 v[24:25], v[30:31], v[24:25], v[36:37]
	v_pk_fma_f32 v[26:27], v[28:29], v[26:27], v[38:39]
	v_cvt_pk_bf16_f32 v24, v24, v25
	s_nop 0
	v_cvt_pk_bf16_f32 v25, v26, v27
	global_store_dwordx2 v[44:45], v[24:25], off offset:512
	global_load_dwordx4 v[24:27], v65, s[4:5] offset:2048
	global_load_dwordx4 v[28:31], v74, s[36:37]
	global_load_dwordx4 v[32:35], v65, s[34:35] offset:2048
	s_waitcnt vmcnt(2)
	v_pk_mul_f32 v[20:21], v[20:21], v[24:25]
	v_pk_mul_f32 v[22:23], v[22:23], v[26:27]
	s_waitcnt vmcnt(1)
	v_pk_add_f32 v[26:27], v[28:29], 1.0 op_sel_hi:[1,0]
	v_pk_add_f32 v[24:25], v[30:31], 1.0 op_sel_hi:[1,0]
	s_waitcnt vmcnt(0)
	v_pk_fma_f32 v[20:21], v[20:21], v[26:27], v[32:33]
	v_pk_fma_f32 v[22:23], v[22:23], v[24:25], v[34:35]
	v_cvt_pk_bf16_f32 v20, v20, v21
	s_nop 0
	v_cvt_pk_bf16_f32 v21, v22, v23
	global_store_dwordx2 v[44:45], v[20:21], off offset:1024
	global_load_dwordx4 v[20:23], v65, s[4:5] offset:3072
	global_load_dwordx4 v[24:27], v75, s[36:37]
	global_load_dwordx4 v[28:31], v65, s[34:35] offset:3072
	s_waitcnt vmcnt(2)
	v_pk_mul_f32 v[16:17], v[16:17], v[20:21]
	v_pk_mul_f32 v[18:19], v[18:19], v[22:23]
	s_waitcnt vmcnt(1)
	v_pk_add_f32 v[22:23], v[24:25], 1.0 op_sel_hi:[1,0]
	v_pk_add_f32 v[20:21], v[26:27], 1.0 op_sel_hi:[1,0]
	s_waitcnt vmcnt(0)
	v_pk_fma_f32 v[16:17], v[16:17], v[22:23], v[28:29]
	v_pk_fma_f32 v[18:19], v[18:19], v[20:21], v[30:31]
	v_cvt_pk_bf16_f32 v16, v16, v17
	s_nop 0
	v_cvt_pk_bf16_f32 v17, v18, v19
	global_store_dwordx2 v[44:45], v[16:17], off offset:1536
	s_andn2_b64 vcc, exec, s[26:27]
	s_cbranch_vccnz .LBB0_91

; #define LAS __attribute__((address_space(3)))
; __device__ __forceinline__ float bflo(unsigned w) { return __uint_as_float(w << 16); }
; __device__ __forceinline__ float bfhi(unsigned w) { return __uint_as_float(w & 0xffff0000u); }
; __device__ __forceinline__ float sigmoidf_(float x) { return __builtin_amdgcn_rcpf(1.f + __expf(-x)); }
; __global__ void __launch_bounds__(512, 2) fwd_megakernel(Params p) {
;     ...
;                 if (!dead) { u32x4 ua[6], ug[6];
; #pragma unroll
;                   for (int i = 0; i < 6; ++i) { const int it = tid + 512 * i, rr = it >> 5, c8 = it & 31, t = t0 - 15 + rr; const bool ok = it < urows && t >= 0 && t < seq_len;
;                       const bf16_t* zr = BZ + (size_t)(seq_base + (ok ? t : t0)) * ZW; ua[i] = *(const u32x4*)(zr + 416 + 8 * c8); ug[i] = *(const u32x4*)(zr + 672 + 8 * c8); if (!ok) ua[i] = (u32x4){0u, 0u, 0u, 0u}; }
; #pragma unroll
;                   for (int i = 0; i < 6; ++i) { const int it = tid + 512 * i, rr = it >> 5, c8 = it & 31; const u32x4 a = ua[i], gg = ug[i];
;                       if (it < urows) {
;                         const f32x4 u0 = {bflo(a.x) * sigmoidf_(bflo(gg.x)), bfhi(a.x) * sigmoidf_(bfhi(gg.x)), bflo(a.y) * sigmoidf_(bflo(gg.y)), bfhi(a.y) * sigmoidf_(bfhi(gg.y))};
;                         const f32x4 u1 = {bflo(a.z) * sigmoidf_(bflo(gg.z)), bfhi(a.z) * sigmoidf_(bfhi(gg.z)), bflo(a.w) * sigmoidf_(bflo(gg.w)), bfhi(a.w) * sigmoidf_(bfhi(gg.w))};
;                         *(LAS f32x4*)(U + rr * 256 + 8 * c8) = u0; *(LAS f32x4*)(U + rr * 256 + 8 * c8 + 4) = u1; } } }
.LBB0_261:
	v_readlane_b32 s4, v255, 16
	v_readlane_b32 s5, v255, 17
	s_and_b64 s[94:95], s[4:5], s[2:3]
	s_and_b64 vcc, exec, s[94:95]
	s_cbranch_vccnz .LBB0_275
	v_add_u32_e32 v55, 0x200, v105
	s_lshl_b32 s2, s24, 5
	s_add_i32 s25, s63, -15
	v_ashrrev_i32_e32 v0, 5, v55
	s_or_b32 s22, s2, 0x3c0
	v_add_u32_e32 v0, s25, v0
	v_cmp_gt_i32_e64 s[18:19], s22, v55
	v_cmp_gt_u32_e32 vcc, s36, v0
	s_waitcnt vmcnt(1)
	v_mov_b32_e32 v6, s63
	s_and_b64 s[16:17], s[18:19], vcc
	v_lshlrev_b32_e32 v56, 3, v105
	v_cndmask_b32_e64 v0, v6, v0, s[16:17]
	v_and_b32_e32 v42, 0xf8, v56
	v_add_u32_e32 v0, s62, v0
	s_waitcnt vmcnt(0)
	v_mov_b64_e32 v[2:3], s[82:83]
	v_mad_i64_i32 v[4:5], s[2:3], v0, s66, v[2:3]
	v_lshlrev_b32_e32 v0, 1, v42
	v_lshl_add_u64 v[4:5], v[4:5], 0, v[0:1]
	v_add_u32_e32 v54, 0x400, v105
	global_load_dwordx4 v[38:41], v[4:5], off offset:832
	global_load_dwordx4 v[34:37], v[4:5], off offset:1344
	v_ashrrev_i32_e32 v4, 5, v54
	v_add_u32_e32 v4, s25, v4
	v_cmp_gt_i32_e64 s[14:15], s22, v54
	v_cmp_gt_u32_e32 vcc, s36, v4
	s_and_b64 s[12:13], s[14:15], vcc
	v_cndmask_b32_e64 v4, v6, v4, s[12:13]
	v_add_u32_e32 v4, s62, v4
	v_mad_i64_i32 v[4:5], s[2:3], v4, s66, v[2:3]
	v_lshl_add_u64 v[4:5], v[4:5], 0, v[0:1]
	v_add_u32_e32 v53, 0x600, v105
	global_load_dwordx4 v[30:33], v[4:5], off offset:832
	global_load_dwordx4 v[26:29], v[4:5], off offset:1344
	v_ashrrev_i32_e32 v4, 5, v53
	v_add_u32_e32 v4, s25, v4
	v_cmp_gt_i32_e64 s[10:11], s22, v53
	v_cmp_gt_u32_e32 vcc, s36, v4
	s_and_b64 s[8:9], s[10:11], vcc
	v_cndmask_b32_e64 v4, v6, v4, s[8:9]
	v_add_u32_e32 v4, s62, v4
	v_mad_i64_i32 v[4:5], s[2:3], v4, s66, v[2:3]
	v_lshl_add_u64 v[4:5], v[4:5], 0, v[0:1]
	v_add_u32_e32 v52, 0x800, v105
	global_load_dwordx4 v[22:25], v[4:5], off offset:832
	global_load_dwordx4 v[18:21], v[4:5], off offset:1344
	v_ashrrev_i32_e32 v4, 5, v52
	v_add_u32_e32 v4, s25, v4
	v_cmp_gt_i32_e64 s[6:7], s22, v52
	v_cmp_gt_u32_e32 vcc, s36, v4
	s_and_b64 s[4:5], s[6:7], vcc
	v_cndmask_b32_e64 v4, v6, v4, s[4:5]
	v_add_u32_e32 v4, s62, v4
	v_mad_i64_i32 v[4:5], s[2:3], v4, s66, v[2:3]
	v_lshl_add_u64 v[4:5], v[4:5], 0, v[0:1]
	v_add_u32_e32 v50, 0xa00, v105
	global_load_dwordx4 v[14:17], v[4:5], off offset:832
	global_load_dwordx4 v[10:13], v[4:5], off offset:1344
	v_ashrrev_i32_e32 v4, 5, v50
	v_add_u32_e32 v4, s25, v4
	v_cmp_gt_i32_e64 s[2:3], s22, v50
	v_cmp_gt_u32_e32 vcc, s36, v4
	s_and_b64 vcc, s[2:3], vcc
	v_lshl_add_u32 v51, v42, 2, 0
	v_cndmask_b32_e32 v4, v6, v4, vcc
	v_add_u32_e32 v4, s62, v4
	v_mad_i64_i32 v[2:3], s[20:21], v4, s66, v[2:3]
	v_lshl_add_u64 v[2:3], v[2:3], 0, v[0:1]
	global_load_dwordx4 v[6:9], v[2:3], off offset:832
	global_load_dwordx4 v[2:5], v[2:3], off offset:1344
	v_cmp_gt_i32_e64 s[20:21], s22, v105
	s_and_saveexec_b64 s[22:23], s[20:21]
	s_cbranch_execz .LBB0_268
	v_ashrrev_i32_e32 v42, 5, v105
	v_add_u32_e32 v42, s25, v42
	v_cmp_gt_u32_e64 s[20:21], s36, v42
	v_mov_b32_e32 v43, s63
	s_nop 0
	v_cndmask_b32_e64 v42, v43, v42, s[20:21]
	v_add_u32_e32 v44, s62, v42
	v_mov_b64_e32 v[42:43], s[82:83]
	v_mad_i64_i32 v[42:43], s[26:27], v44, s66, v[42:43]
	v_lshl_add_u64 v[46:47], v[42:43], 0, v[0:1]
	global_load_dwordx4 v[42:45], v[46:47], off offset:832
	s_waitcnt vmcnt(0)
	v_cndmask_b32_e64 v0, 0, v45, s[20:21]
	global_load_dwordx4 v[46:49], v[46:47], off offset:1344
	v_cndmask_b32_e64 v58, 0, v43, s[20:21]
	v_cndmask_b32_e64 v45, 0, v42, s[20:21]
	v_cndmask_b32_e64 v57, 0, v44, s[20:21]
	v_lshlrev_b32_e32 v44, 16, v45
	v_and_b32_e32 v45, 0xffff0000, v45
	v_and_b32_e32 v59, 0xffff0000, v57
	s_waitcnt vmcnt(0)
	v_lshlrev_b32_e32 v42, 16, v46
	v_and_b32_e32 v43, 0xffff0000, v46
	v_mul_f32_e32 v42, 0xbfb8aa3b, v42
	v_mul_f32_e32 v43, 0xbfb8aa3b, v43
	v_exp_f32_e32 v42, v42
	v_exp_f32_e32 v43, v43
	v_lshlrev_b32_e32 v46, 16, v58
	v_add_f32_e32 v42, 1.0, v42
	v_add_f32_e32 v43, 1.0, v43
	v_rcp_f32_e32 v42, v42
	v_rcp_f32_e32 v43, v43
	s_nop 0
	v_pk_mul_f32 v[42:43], v[42:43], v[44:45]
	v_lshlrev_b32_e32 v44, 16, v47
	v_and_b32_e32 v45, 0xffff0000, v47
	v_mul_f32_e32 v44, 0xbfb8aa3b, v44
	v_mul_f32_e32 v45, 0xbfb8aa3b, v45
	v_exp_f32_e32 v44, v44
	v_exp_f32_e32 v45, v45
	v_and_b32_e32 v47, 0xffff0000, v58
	v_lshlrev_b32_e32 v58, 16, v57
	v_add_f32_e32 v44, 1.0, v44
	v_add_f32_e32 v45, 1.0, v45
	v_rcp_f32_e32 v44, v44
	v_rcp_f32_e32 v45, v45
	s_nop 0
	v_pk_mul_f32 v[44:45], v[44:45], v[46:47]
	v_lshlrev_b32_e32 v46, 16, v48
	v_and_b32_e32 v47, 0xffff0000, v48
	v_mul_f32_e32 v46, 0xbfb8aa3b, v46
	v_mul_f32_e32 v47, 0xbfb8aa3b, v47
	v_exp_f32_e32 v46, v46
	v_exp_f32_e32 v47, v47
	v_lshlrev_b32_e32 v48, 16, v49
	v_and_b32_e32 v49, 0xffff0000, v49
	v_mul_f32_e32 v48, 0xbfb8aa3b, v48
	v_mul_f32_e32 v49, 0xbfb8aa3b, v49
	v_exp_f32_e32 v48, v48
	v_exp_f32_e32 v49, v49
	v_add_f32_e32 v46, 1.0, v46
	v_add_f32_e32 v47, 1.0, v47
	v_rcp_f32_e32 v46, v46
	v_rcp_f32_e32 v47, v47
	v_add_f32_e32 v48, 1.0, v48
	v_add_f32_e32 v49, 1.0, v49
	v_rcp_f32_e32 v48, v48
	v_rcp_f32_e32 v49, v49
	v_pk_mul_f32 v[46:47], v[46:47], v[58:59]
	v_lshlrev_b32_e32 v58, 16, v0
	v_and_b32_e32 v59, 0xffff0000, v0
	v_and_b32_e32 v0, 0x3fffff00, v56
	v_lshl_add_u32 v0, v0, 2, v51
	v_pk_mul_f32 v[48:49], v[48:49], v[58:59]
	ds_write_b128 v0, v[42:45]
	ds_write_b128 v0, v[46:49] offset:16
	s_or_b64 exec, exec, s[22:23]
	s_and_saveexec_b64 s[20:21], s[18:19]
	s_cbranch_execnz .LBB0_269

; __global__ void __launch_bounds__(512, 2) fwd_megakernel(Params p) {
;     ...
;                 if (wact) { const int tw = t0 + wave * 8; const size_t mw = (size_t)seq_base + tw; const bf16_t* zw = BZ + mw * ZW;
;                   u32x2 zq[8], bgt[8], cgt[10], hht[10]; unsigned kvv[8]; unsigned short krv[8];
; #pragma unroll
;                   for (int k8 = 0; k8 < 8; ++k8) { const bf16_t* zr = zw + (size_t)k8 * ZW; zq[k8] = *(const u32x2*)(zr + 4 * lane); kvv[k8] = *(const unsigned*)(zr + 256 + 2 * lane); krv[k8] = zr[384 + (lane & 31)];
;                       bgt[k8] = *(const u32x2*)(zr + 928 + 4 * lane); }
; #pragma unroll
;                   for (int j = 0; j < 10; ++j) { const int tt = tw - 1 + j; const bool ok = tt >= 0 && tt < seq_len; const bf16_t* z2 = BZ + (size_t)(seq_base + (ok ? tt : tw)) * ZW;
;                       cgt[j] = *(const u32x2*)(z2 + 1184 + 4 * lane); hht[j] = *(const u32x2*)(z2 + 1440 + 4 * lane); if (!ok) { cgt[j] = (u32x2){0u, 0u}; } }
;                   const f32x4 gqv = ((const f32x4*)gq)[lane]; const float gk0 = gkv[2 * lane], gk1 = gkv[2 * lane + 1]; const f32x4 gsc = ((const f32x4*)(gbr + 768))[lane];
;                   const f32x4 sw0 = ((const f32x4*)sw)[lane], sw1 = ((const f32x4*)(sw + 256))[lane], sw2 = ((const f32x4*)(sw + 512))[lane];
.LBB0_275:
	v_readlane_b32 s2, v255, 10
	s_cmp_ge_u32 s2, s24
	s_cselect_b64 s[28:29], -1, 0
	s_and_b64 vcc, exec, s[28:29]
	s_cbranch_vccnz .LBB0_309
	v_readlane_b32 s2, v255, 10
	s_add_i32 s37, s63, s2
	s_ashr_i32 s2, s62, 31
	s_add_u32 s48, s62, s37
	s_addc_u32 s49, s2, 0
	s_mul_i32 s2, s49, 0xe00
	s_mul_hi_u32 s3, s48, 0xe00
	s_add_i32 s3, s3, s2
	s_mul_i32 s2, s48, 0xe00
	v_and_b32_e32 v117, 63, v105
	s_add_u32 s10, s82, s2
	s_addc_u32 s11, s83, s3
	v_lshlrev_b32_e32 v0, 2, v117
	v_and_b32_e32 v119, 31, v105
	s_waitcnt vmcnt(0)
	v_lshl_add_u64 v[4:5], s[10:11], 0, v[0:1]
	s_movk_i32 s2, 0x1000
	v_lshlrev_b32_e32 v46, 1, v119
	v_mov_b32_e32 v47, v1
	v_add_co_u32_e32 v8, vcc, s2, v4
	v_lshl_add_u64 v[6:7], s[10:11], 0, v[46:47]
	s_nop 0
	v_addc_co_u32_e32 v9, vcc, 0, v5, vcc
	v_lshlrev_b32_e32 v32, 3, v117
	v_mov_b32_e32 v33, v1
	v_add_co_u32_e32 v6, vcc, s2, v6
	v_lshl_add_u64 v[2:3], s[10:11], 0, v[32:33]
	s_nop 0
	v_addc_co_u32_e32 v7, vcc, 0, v7, vcc
	global_load_dwordx2 v[100:101], v32, s[10:11]
	global_load_dword v118, v0, s[10:11] offset:512
	global_load_dwordx2 v[86:87], v32, s[10:11] offset:1856
	global_load_dwordx2 v[80:81], v32, s[10:11] offset:3584
	global_load_dword v116, v[8:9], off
	global_load_ushort v115, v[6:7], off offset:256
	v_add_co_u32_e32 v6, vcc, s2, v2
	s_add_u32 s2, s10, 0x1c00
	s_nop 0
	v_addc_co_u32_e32 v7, vcc, 0, v3, vcc
	s_addc_u32 s3, s11, 0
	s_movk_i32 s4, 0x2000
	global_load_dwordx2 v[78:79], v[6:7], off offset:1344
	global_load_dwordx2 v[72:73], v32, s[2:3]
	global_load_dword v114, v[8:9], off offset:3584
	global_load_ushort v113, v46, s[2:3] offset:768
	v_add_co_u32_e32 v6, vcc, s4, v2
	s_add_u32 s2, s10, 0x2a00
	s_nop 0
	v_addc_co_u32_e32 v7, vcc, 0, v3, vcc
	s_addc_u32 s3, s11, 0
	global_load_dwordx2 v[70:71], v[6:7], off offset:832
	global_load_dwordx2 v[66:67], v32, s[2:3]
	v_add_co_u32_e32 v6, vcc, s4, v4
	s_movk_i32 s4, 0x3000
	s_nop 0
	v_addc_co_u32_e32 v7, vcc, 0, v5, vcc
	global_load_dword v112, v[6:7], off offset:3072
	global_load_ushort v111, v46, s[2:3] offset:768
	v_add_co_u32_e32 v6, vcc, s4, v2
	s_add_u32 s2, s10, 0x3800
	s_nop 0
	v_addc_co_u32_e32 v7, vcc, 0, v3, vcc
	v_add_co_u32_e32 v8, vcc, s4, v4
	s_addc_u32 s3, s11, 0
	s_nop 0
	v_addc_co_u32_e32 v9, vcc, 0, v5, vcc
	s_movk_i32 s4, 0x4000
	global_load_dwordx2 v[62:63], v[6:7], off offset:320
	global_load_dwordx2 v[58:59], v32, s[2:3]
	global_load_dword v110, v[8:9], off offset:2560
	global_load_ushort v109, v46, s[2:3] offset:768
	global_load_dwordx2 v[54:55], v[6:7], off offset:3904
	s_add_u32 s2, s10, 0x4600
	v_add_co_u32_e32 v6, vcc, s4, v4
	s_addc_u32 s3, s11, 0
	s_nop 0
	v_addc_co_u32_e32 v7, vcc, 0, v5, vcc
	global_load_dwordx2 v[52:53], v32, s[2:3]
	global_load_dword v108, v[6:7], off offset:2048
	global_load_ushort v107, v46, s[2:3] offset:768
	v_add_co_u32_e32 v6, vcc, s4, v2
	s_add_u32 s2, s10, 0x5400
	s_nop 0
	v_addc_co_u32_e32 v7, vcc, 0, v3, vcc
	s_addc_u32 s3, s11, 0
	s_movk_i32 s4, 0x5000
	global_load_dwordx2 v[44:45], v[6:7], off offset:3392
	global_load_dwordx2 v[42:43], v32, s[2:3]
	v_add_co_u32_e32 v6, vcc, s4, v4
	v_and_b32_e32 v120, 8, v105
	s_nop 0
	v_addc_co_u32_e32 v7, vcc, 0, v5, vcc
	global_load_dword v106, v[6:7], off offset:1536
	global_load_ushort v104, v46, s[2:3] offset:768
	v_add_co_u32_e32 v6, vcc, s4, v2
	s_movk_i32 s4, 0x6000
	s_nop 0
	v_addc_co_u32_e32 v7, vcc, 0, v3, vcc
	v_add_co_u32_e32 v4, vcc, s4, v4
	s_add_u32 s2, s10, 0x6200
	s_nop 0
	v_addc_co_u32_e32 v5, vcc, 0, v5, vcc
	s_addc_u32 s3, s11, 0
	v_add_co_u32_e32 v2, vcc, s4, v2
	s_add_i32 s4, s37, -1
	s_cmp_lt_u32 s4, s36
	s_cselect_b64 s[24:25], -1, 0
	global_load_dwordx2 v[28:29], v[6:7], off offset:2880
	global_load_dwordx2 v[24:25], v32, s[2:3]
	global_load_dword v103, v[4:5], off offset:1024
	global_load_ushort v102, v46, s[2:3] offset:768
	s_and_b64 s[2:3], s[24:25], exec
	s_cselect_b32 s2, s4, s37
	s_add_i32 s2, s2, s62
	s_mul_hi_i32 s3, s2, 0xe00
	s_mulk_i32 s2, 0xe00
	s_add_u32 s2, s82, s2
	v_addc_co_u32_e32 v3, vcc, 0, v3, vcc
	s_addc_u32 s3, s83, s3
	global_load_dwordx2 v[22:23], v[2:3], off offset:2368
	global_load_dwordx2 v[94:95], v32, s[2:3] offset:2368
	global_load_dwordx2 v[92:93], v32, s[2:3] offset:2880
	s_add_i32 s2, s37, s62
	s_mul_hi_i32 s3, s2, 0xe00
	s_mulk_i32 s2, 0xe00
	s_add_u32 s2, s82, s2
	s_addc_u32 s3, s83, s3
	s_or_b32 s4, s37, 1
	s_cmp_lt_u32 s4, s36
	s_cselect_b64 s[26:27], -1, 0
	global_load_dwordx2 v[96:97], v32, s[2:3] offset:2368
	global_load_dwordx2 v[88:89], v32, s[2:3] offset:2880
	s_and_b64 s[2:3], s[26:27], exec
	s_cselect_b32 s2, s4, s37
	s_add_i32 s2, s2, s62
	s_mul_hi_i32 s3, s2, 0xe00
	s_mulk_i32 s2, 0xe00
	s_add_u32 s2, s82, s2
	s_addc_u32 s3, s83, s3
	s_or_b32 s4, s37, 2
	s_cmp_lt_u32 s4, s36
	s_cselect_b64 s[22:23], -1, 0
	global_load_dwordx2 v[98:99], v32, s[2:3] offset:2368
	global_load_dwordx2 v[90:91], v32, s[2:3] offset:2880
	s_and_b64 s[2:3], s[22:23], exec
	s_cselect_b32 s2, s4, s37
	s_add_i32 s2, s2, s62
	s_mul_hi_i32 s3, s2, 0xe00
	s_mulk_i32 s2, 0xe00
	s_add_u32 s2, s82, s2
	s_addc_u32 s3, s83, s3
	s_or_b32 s4, s37, 3
	s_cmp_lt_u32 s4, s36
	s_cselect_b64 s[20:21], -1, 0
	global_load_dwordx2 v[84:85], v32, s[2:3] offset:2368
	global_load_dwordx2 v[82:83], v32, s[2:3] offset:2880
	s_and_b64 s[2:3], s[20:21], exec
	s_cselect_b32 s2, s4, s37
	s_add_i32 s2, s2, s62
	s_mul_hi_i32 s3, s2, 0xe00
	s_mulk_i32 s2, 0xe00
	s_add_u32 s2, s82, s2
	s_addc_u32 s3, s83, s3
	s_or_b32 s4, s37, 4
	s_cmp_lt_u32 s4, s36
	s_cselect_b64 s[18:19], -1, 0
	global_load_dwordx2 v[76:77], v32, s[2:3] offset:2368
	global_load_dwordx2 v[74:75], v32, s[2:3] offset:2880
	s_and_b64 s[2:3], s[18:19], exec
; __device__ __forceinline__ unsigned cvtpk(float lo, float hi) { unsigned r; asm volatile("v_cvt_pk_bf16_f32 %0, %1, %2" : "=v"(r) : "v"(lo), "v"(hi)); return r; }
; __device__ __forceinline__ float bflo(unsigned w) { return __uint_as_float(w << 16); }
; __device__ __forceinline__ float bfhi(unsigned w) { return __uint_as_float(w & 0xffff0000u); }
; __device__ __forceinline__ float bf2f(unsigned short h) { return __uint_as_float((unsigned)h << 16); }
; __global__ void __launch_bounds__(512, 2) fwd_megakernel(Params p) {
;     ...
;                   const f32x4 gqv = ((const f32x4*)gq)[lane]; const float gk0 = gkv[2 * lane], gk1 = gkv[2 * lane + 1]; const f32x4 gsc = ((const f32x4*)(gbr + 768))[lane];
;                   const f32x4 sw0 = ((const f32x4*)sw)[lane], sw1 = ((const f32x4*)(sw + 256))[lane], sw2 = ((const f32x4*)(sw + 512))[lane];
;                   f32x4 pr[10];
; #pragma unroll
;                   for (int j = 0; j < 10; ++j) pr[j] = (f32x4){bflo(cgt[j].x) * bflo(hht[j].x), bfhi(cgt[j].x) * bfhi(hht[j].x), bflo(cgt[j].y) * bflo(hht[j].y), bfhi(cgt[j].y) * bfhi(hht[j].y)};
; #pragma unroll
;                   for (int k8 = 0; k8 < 8; ++k8) { const int t = tw + k8; const size_t m = mw + k8;
;                     { const u32x2 w = zq[k8]; const f32x4 v = {bflo(w.x), bfhi(w.x), bflo(w.y), bfhi(w.y)};
;                       const float ri = rsqrtf(wave_sum((v.x * v.x + v.y * v.y) + (v.z * v.z + v.w * v.w)) * (1.f / 256.f) + EPSN); const f32x4 o = v * ri * gqv;
;                       u32x2 ow; ow.x = cvtpk(o.x, o.y); ow.y = cvtpk(o.z, o.w); *(u32x2*)(BQN + m * 256 + 4 * lane) = ow; }
;                     { const unsigned w = kvv[k8]; const float v0 = bflo(w), v1 = bfhi(w);
;                       const float ri = rsqrtf(wave_sum(v0 * v0 + v1 * v1) * (1.f / 128.f) + EPSN); *(unsigned*)(BKVN + m * 128 + 2 * lane) = cvtpk(v0 * ri * gk0, v1 * ri * gk1); }
;                     { const int e = lane & 31; const float v = bf2f(krv[k8]); const float prn = swz_xor<8>(v); float o = v;
;                       if (is_lat) { const int a = e >> 4, i = e & 15; const float pos = (float)(a == 0 ? (t >> 6) : (t & 63)); const float ang = pos * rope_inv(i & 7), c = __cosf(ang), s = __sinf(ang);
;                           o = (i < 8) ? (v * c - prn * s) : (v * c + prn * s); }
;                       if (lane < 32) BKR[m * 32 + e] = f2bf(o); }
	s_cselect_b32 s2, s4, s37
	s_add_i32 s2, s2, s62
	s_mul_hi_i32 s3, s2, 0xe00
	s_mulk_i32 s2, 0xe00
	s_add_u32 s2, s82, s2
	s_addc_u32 s3, s83, s3
	s_or_b32 s4, s37, 5
	s_cmp_lt_u32 s4, s36
	s_cselect_b64 s[16:17], -1, 0
	global_load_dwordx2 v[68:69], v32, s[2:3] offset:2368
	global_load_dwordx2 v[64:65], v32, s[2:3] offset:2880
	s_and_b64 s[2:3], s[16:17], exec
	s_cselect_b32 s2, s4, s37
	s_add_i32 s2, s2, s62
	s_mul_hi_i32 s3, s2, 0xe00
	s_mulk_i32 s2, 0xe00
	s_add_u32 s2, s82, s2
	s_addc_u32 s3, s83, s3
	s_or_b32 s4, s37, 6
	s_cmp_lt_u32 s4, s36
	s_cselect_b64 s[14:15], -1, 0
	global_load_dwordx2 v[60:61], v32, s[2:3] offset:2368
	global_load_dwordx2 v[56:57], v32, s[2:3] offset:2880
	s_and_b64 s[2:3], s[14:15], exec
	s_cselect_b32 s2, s4, s37
	s_add_i32 s2, s2, s62
	s_mul_hi_i32 s3, s2, 0xe00
	s_mulk_i32 s2, 0xe00
	s_add_u32 s2, s82, s2
	s_addc_u32 s3, s83, s3
	s_or_b32 s4, s37, 7
	s_cmp_lt_u32 s4, s36
	s_cselect_b64 s[8:9], -1, 0
	global_load_dwordx2 v[50:51], v32, s[2:3] offset:2368
	global_load_dwordx2 v[48:49], v32, s[2:3] offset:2880
	s_and_b64 s[2:3], s[8:9], exec
	s_cselect_b32 s2, s4, s37
	s_add_i32 s2, s2, s62
	s_mul_hi_i32 s3, s2, 0xe00
	s_mulk_i32 s2, 0xe00
	s_add_u32 s2, s82, s2
	s_addc_u32 s3, s83, s3
	s_add_i32 s6, s37, 8
	s_cmp_lt_u32 s6, s36
	global_load_dwordx2 v[40:41], v32, s[2:3] offset:2368
	global_load_dwordx2 v[38:39], v32, s[2:3] offset:2880
	s_cselect_b64 s[2:3], -1, 0
	s_and_b64 s[4:5], s[2:3], exec
	s_cselect_b32 s4, s6, s37
	s_add_i32 s4, s4, s62
	s_mul_hi_i32 s5, s4, 0xe00
	s_mulk_i32 s4, 0xe00
	s_add_u32 s4, s82, s4
	v_and_b32_e32 v105, 7, v105
	s_addc_u32 s5, s83, s5
	v_cvt_f32_ubyte0_e32 v105, v105
	global_load_dwordx2 v[30:31], v32, s[4:5] offset:2368
	global_load_dwordx2 v[26:27], v32, s[4:5] offset:2880
	v_cmp_gt_u32_e64 s[4:5], 16, v119
	v_mul_f32_e32 v119, 0xbfd49a78, v105
	s_mov_b32 s6, 0xc2fc0000
	v_cmp_gt_f32_e32 vcc, s6, v119
	v_mov_b32_e32 v119, 0x42800000
	v_lshlrev_b32_e32 v6, 4, v117
	v_cndmask_b32_e32 v119, 0, v119, vcc
	v_fmac_f32_e32 v119, 0xbfd49a78, v105
	v_exp_f32_e32 v105, v119
	v_cmp_eq_u32_e64 s[6:7], 0, v120
	s_waitcnt vmcnt(50)
	v_lshlrev_b32_e32 v121, 16, v101
	v_lshlrev_b32_e32 v120, 16, v100
	v_and_b32_e32 v101, 0xffff0000, v101
	v_and_b32_e32 v100, 0xffff0000, v100
	global_load_dwordx4 v[18:21], v6, s[74:75]
	global_load_dwordx2 v[34:35], v32, s[86:87]
	global_load_dwordx4 v[2:5], v6, s[56:57] offset:3072
	global_load_dwordx4 v[10:13], v6, s[80:81]
	global_load_dwordx4 v[14:17], v6, s[80:81] offset:1024
	global_load_dwordx4 v[6:9], v6, s[80:81] offset:2048
	v_not_b32_e32 v119, 63
	v_pk_mul_f32 v[122:123], v[100:101], v[100:101]
	v_cndmask_b32_e32 v119, 0, v119, vcc
	v_pk_fma_f32 v[122:123], v[120:121], v[120:121], v[122:123]
	v_ldexp_f32 v105, v105, v119
	v_add_f32_e32 v119, v122, v123
	v_mov_b32_e32 v122, v1
	v_mov_b32_e32 v124, v120
	v_add_f32_dpp v119, v119, v119 quad_perm:[1,0,3,2] row_mask:0xf bank_mask:0xf bound_ctrl:1
	v_mov_b32_e32 v125, v100
	v_mov_b32_e32 v100, v121
	v_add_f32_dpp v119, v119, v119 quad_perm:[2,3,0,1] row_mask:0xf bank_mask:0xf bound_ctrl:1
	v_lshl_add_u64 v[36:37], s[84:85], 0, v[32:33]
	v_lshl_add_u64 v[32:33], s[88:89], 0, v[0:1]
	v_add_f32_dpp v119, v119, v119 row_half_mirror row_mask:0xf bank_mask:0xf bound_ctrl:1
	s_lshr_b32 s76, s37, 6
	s_and_b32 s77, s37, 56
	v_add_f32_dpp v119, v119, v119 row_mirror row_mask:0xf bank_mask:0xf bound_ctrl:1
	s_nop 1
	v_mov_b32_dpp v122, v119 row_bcast:15 row_mask:0xa bank_mask:0xf
	v_add_f32_e32 v119, v119, v122
	v_mov_b32_e32 v122, v1
	s_nop 1
	v_mov_b32_dpp v122, v119 row_bcast:31 row_mask:0xc bank_mask:0xf
	v_add_f32_e32 v119, v119, v122
	s_nop 0
	v_readlane_b32 s12, v119, 63
	s_nop 1
	v_cvt_i32_f32_e32 v119, s12
	v_cvt_f32_i32_e32 v119, v119
	v_fmamk_f32 v119, v119, 0x3b800000, v211
	v_cmp_gt_f32_e32 vcc, s68, v119
	v_mul_f32_e32 v122, 0x4b800000, v119
	s_nop 0
	v_cndmask_b32_e32 v119, v119, v122, vcc
	v_rsq_f32_e32 v119, v119
	s_nop 0
	v_mul_f32_e32 v122, 0x45800000, v119
	v_cndmask_b32_e32 v122, v119, v122, vcc
	v_pk_mul_f32 v[124:125], v[122:123], v[124:125] op_sel_hi:[0,1]
	v_pk_mul_f32 v[100:101], v[122:123], v[100:101] op_sel_hi:[0,1]
	global_load_ushort v122, v46, s[10:11] offset:768
	s_lshl_b64 s[10:11], s[48:49], 9
	s_waitcnt vmcnt(6)
	v_pk_mul_f32 v[100:101], v[20:21], v[100:101]
	v_pk_mul_f32 v[120:121], v[18:19], v[124:125]
	s_nop 0
	v_cvt_pk_bf16_f32 v120, v120, v121
	v_cvt_pk_bf16_f32 v121, v100, v101
	v_lshl_add_u64 v[100:101], v[36:37], 0, s[10:11]
	global_store_dwordx2 v[100:101], v[120:121], off
	v_lshlrev_b32_e32 v100, 16, v118
	v_and_b32_e32 v101, 0xffff0000, v118
	v_pk_mul_f32 v[118:119], v[100:101], v[100:101]
	s_nop 0
	v_add_f32_e32 v118, v118, v119
	v_mov_b32_e32 v119, v1
	s_nop 0
	v_add_f32_dpp v118, v118, v118 quad_perm:[1,0,3,2] row_mask:0xf bank_mask:0xf bound_ctrl:1
	s_nop 1
	v_add_f32_dpp v118, v118, v118 quad_perm:[2,3,0,1] row_mask:0xf bank_mask:0xf bound_ctrl:1
	s_nop 1
	v_add_f32_dpp v118, v118, v118 row_half_mirror row_mask:0xf bank_mask:0xf bound_ctrl:1
	s_nop 1
	v_add_f32_dpp v118, v118, v118 row_mirror row_mask:0xf bank_mask:0xf bound_ctrl:1
	s_nop 1
	v_mov_b32_dpp v119, v118 row_bcast:15 row_mask:0xa bank_mask:0xf
	v_add_f32_e32 v118, v118, v119
	v_mov_b32_e32 v119, v1
	s_nop 1
	v_mov_b32_dpp v119, v118 row_bcast:31 row_mask:0xc bank_mask:0xf
	v_add_f32_e32 v118, v118, v119
	s_nop 0
	v_readlane_b32 s10, v118, 63
	s_nop 1
	v_cvt_i32_f32_e32 v118, s10
	s_lshl_b64 s[10:11], s[48:49], 8
	v_cvt_f32_i32_e32 v118, v118
	v_fmamk_f32 v118, v118, 0x3c000000, v211
	v_cmp_gt_f32_e32 vcc, s68, v118
	v_mul_f32_e32 v119, 0x4b800000, v118
	s_nop 0
	v_cndmask_b32_e32 v118, v118, v119, vcc
	v_rsq_f32_e32 v118, v118
	s_nop 0
	v_mul_f32_e32 v119, 0x45800000, v118
	v_cndmask_b32_e32 v118, v118, v119, vcc
	v_mul_f32_e32 v100, v118, v100
	v_mul_f32_e32 v101, v118, v101
	s_waitcnt vmcnt(6)
	v_mul_f32_e32 v100, v34, v100
	v_mul_f32_e32 v101, v35, v101
	v_cvt_pk_bf16_f32 v118, v100, v101
	v_lshl_add_u64 v[100:101], v[32:33], 0, s[10:11]
	global_store_dword v[100:101], v118, off
	s_waitcnt vmcnt(2)
	v_lshlrev_b32_e32 v100, 16, v122
	ds_swizzle_b32 v101, v100 offset:swizzle(SWAP,8)
	v_cndmask_b32_e64 v118, 0, 1, s[0:1]
	v_cmp_ne_u32_e64 s[10:11], 1, v118
	s_andn2_b64 vcc, exec, s[0:1]
	s_cbranch_vccnz .LBB0_278
	v_mov_b32_e32 v118, s77
	v_mov_b32_e32 v119, s76
	v_cndmask_b32_e64 v118, v118, v119, s[4:5]
	v_cvt_f32_u32_e32 v118, v118
	v_mul_f32_e32 v118, v105, v118
	v_mul_f32_e32 v118, 0.15915494, v118
	v_sin_f32_e32 v119, v118
	v_cos_f32_e32 v118, v118
	s_waitcnt lgkmcnt(0)
	v_mul_f32_e32 v101, v119, v101
	v_cndmask_b32_e64 v101, v101, -v101, s[6:7]
	v_fmac_f32_e32 v101, v118, v100
	v_mov_b32_e32 v100, v101

; #define LAS __attribute__((address_space(3)))
; __device__ __forceinline__ unsigned cvtpk(float lo, float hi) { unsigned r; asm volatile("v_cvt_pk_bf16_f32 %0, %1, %2" : "=v"(r) : "v"(lo), "v"(hi)); return r; }
; __device__ __forceinline__ float bflo(unsigned w) { return __uint_as_float(w << 16); }
; __device__ __forceinline__ float bfhi(unsigned w) { return __uint_as_float(w & 0xffff0000u); }
; __device__ __forceinline__ int lane_id() { return (int)__builtin_amdgcn_mbcnt_hi(~0u, __builtin_amdgcn_mbcnt_lo(~0u, 0u)); }
; __device__ __forceinline__ void attn_unit(const bf16_t* __restrict__ Qb, bool rope_q, int tq0, const bf16_t* __restrict__ KVh, const bf16_t* __restrict__ KR,
;                                           int ctx_row0, int lat_row0, int NT, bf16_t* __restrict__ Ob, LAS unsigned char* lds, int wave_s) {
;   int tid = wave_s * 64 + lane_id(); asm volatile("" : "+v"(tid));
;   const int wid = tid >> 6, lane = tid & 63, r32 = lane & 31, hi = lane >> 5;
;   LAS float* al_l = (LAS float*)(lds + OFF_WS) + wid * 64;
;   float mref = 0.f, l_reg = 0.f; f32x16 o[2] = {}; f32x16 negm = {}; asm volatile("" : "+v"(negm)); bf16x8 qr[6];
;   { const bf16_t* Qw = Qb + (long)(wid * QBLK + r32) * 768;
; #pragma unroll
;     for (int d0 = 0; d0 < 4; ++d0) { const u32x4 w = *(const u32x4*)(Qw + d0 * 16 + hi * 8);
;       u32x4 s = {cvtpk(bflo(w.x) * C2, bfhi(w.x) * C2), cvtpk(bflo(w.y) * C2, bfhi(w.y) * C2), cvtpk(bflo(w.z) * C2, bfhi(w.z) * C2), cvtpk(bflo(w.w) * C2, bfhi(w.w) * C2)};
;       qr[d0] = __builtin_bit_cast(bf16x8, s); }
; __global__ void __launch_bounds__(512, 2) fwd_megakernel(Params p) {
;     ...
;                 else { const int uc = u - 1024, b = uc >> 3, h = uc & 7; const int q0 = NLAT + b * CTXL;
;                     att::attn_unit(BQ + (size_t)q0 * 768 + h * 96, false, 0, BKV + h * 128, BKR, q0, 0, 4, BA + (size_t)q0 * DM + h * 64, lds, wave); }
.LBB0_458:
	s_and_b32 s21, s12, 7
	s_lshl_b32 s22, s12, 5
	s_cmpk_gt_i32 s12, 0x3ff
	s_mov_b64 s[0:1], -1
	s_mul_i32 s9, s21, 0xc0
	s_cbranch_scc0 .LBB0_465
	s_and_b32 s70, s22, 0x7fffff00
	s_mul_i32 s1, s70, 0x600
	s_mul_hi_u32 s0, s70, 0x600
	s_add_u32 s1, s15, s1
	s_addc_u32 s2, s16, s0
	s_add_u32 s0, s1, s9
	v_mov_b32_e32 v22, v206
	v_mov_b32_e32 v2, v1
	v_mov_b32_e32 v3, v1
	v_mov_b32_e32 v4, v1
	v_mov_b32_e32 v5, v1
	v_mov_b32_e32 v6, v1
	v_mov_b32_e32 v7, v1
	v_mov_b32_e32 v8, v1
	v_mov_b32_e32 v9, v1
	v_mov_b32_e32 v10, v1
	v_mov_b32_e32 v11, v1
	v_mov_b32_e32 v12, v1
	v_mov_b32_e32 v13, v1
	v_mov_b32_e32 v14, v1
	v_mov_b32_e32 v15, v1
	s_addc_u32 s1, s2, 0
	v_mov_b32_e32 v0, v1
	v_mov_b64_e32 v[16:17], v[14:15]
	s_waitcnt vmcnt(34)
	v_ashrrev_i32_e32 v121, 1, v22
	s_movk_i32 s2, 0xffe0
	v_bfe_u32 v134, v22, 5, 1
	v_mov_b64_e32 v[14:15], v[12:13]
	v_mov_b64_e32 v[12:13], v[10:11]
	v_mov_b64_e32 v[10:11], v[8:9]
	v_mov_b64_e32 v[8:9], v[6:7]
	v_mov_b64_e32 v[6:7], v[4:5]
	v_mov_b64_e32 v[4:5], v[2:3]
	v_mov_b64_e32 v[2:3], v[0:1]
	v_bfi_b32 v0, s2, v121, v22
	v_mov_b64_e32 v[18:19], s[0:1]
	v_mad_i64_i32 v[18:19], s[0:1], v0, s67, v[18:19]
	v_lshlrev_b32_e32 v130, 4, v134
	v_mov_b32_e32 v131, v1
	v_lshl_add_u64 v[20:21], v[18:19], 0, v[130:131]
	global_load_dwordx4 v[24:27], v[20:21], off
	s_mov_b32 s0, s71
	s_mov_b32 s1, s52
	s_mov_b32 s53, s71
	v_and_b32_e32 v120, 63, v22
	v_cmp_gt_u32_e64 s[2:3], 32, v120
	v_ashrrev_i32_e32 v78, 4, v22
	s_waitcnt vmcnt(0)
	v_lshlrev_b32_e32 v0, 16, v24
	v_and_b32_e32 v23, 0xffff0000, v24
	v_mul_f32_e32 v0, 0x3e16c740, v0
	v_mul_f32_e32 v23, 0x3e16c740, v23
	v_cvt_pk_bf16_f32 v82, v0, v23
	v_lshlrev_b32_e32 v0, 16, v25
	v_and_b32_e32 v23, 0xffff0000, v25
	v_mul_f32_e32 v0, 0x3e16c740, v0
	v_mul_f32_e32 v23, 0x3e16c740, v23
	v_cvt_pk_bf16_f32 v83, v0, v23
	v_lshlrev_b32_e32 v0, 16, v26
	v_and_b32_e32 v23, 0xffff0000, v26
	v_mul_f32_e32 v0, 0x3e16c740, v0
	v_mul_f32_e32 v23, 0x3e16c740, v23
	v_cvt_pk_bf16_f32 v84, v0, v23
	v_lshlrev_b32_e32 v0, 16, v27
	v_and_b32_e32 v23, 0xffff0000, v27
	v_mul_f32_e32 v0, 0x3e16c740, v0
	v_mul_f32_e32 v23, 0x3e16c740, v23
	v_cvt_pk_bf16_f32 v85, v0, v23
	global_load_dwordx4 v[24:27], v[20:21], off offset:32
	s_waitcnt vmcnt(0)
	v_lshlrev_b32_e32 v0, 16, v24
	v_and_b32_e32 v23, 0xffff0000, v24
	v_mul_f32_e32 v0, 0x3e16c740, v0
	v_mul_f32_e32 v23, 0x3e16c740, v23
	v_cvt_pk_bf16_f32 v86, v0, v23
	v_lshlrev_b32_e32 v0, 16, v25
	v_and_b32_e32 v23, 0xffff0000, v25
	v_mul_f32_e32 v0, 0x3e16c740, v0
	v_mul_f32_e32 v23, 0x3e16c740, v23
	v_cvt_pk_bf16_f32 v87, v0, v23
	v_lshlrev_b32_e32 v0, 16, v26
	v_and_b32_e32 v23, 0xffff0000, v26
	v_mul_f32_e32 v0, 0x3e16c740, v0
	v_mul_f32_e32 v23, 0x3e16c740, v23
	v_cvt_pk_bf16_f32 v88, v0, v23
	v_lshlrev_b32_e32 v0, 16, v27
	v_and_b32_e32 v23, 0xffff0000, v27
	v_mul_f32_e32 v0, 0x3e16c740, v0
	v_mul_f32_e32 v23, 0x3e16c740, v23
	v_cvt_pk_bf16_f32 v89, v0, v23
	global_load_dwordx4 v[24:27], v[20:21], off offset:64
	s_waitcnt vmcnt(0)
	v_lshlrev_b32_e32 v0, 16, v24
	v_and_b32_e32 v23, 0xffff0000, v24
	v_mul_f32_e32 v0, 0x3e16c740, v0
	v_mul_f32_e32 v23, 0x3e16c740, v23
	v_cvt_pk_bf16_f32 v90, v0, v23
	v_lshlrev_b32_e32 v0, 16, v25
	v_and_b32_e32 v23, 0xffff0000, v25
	v_mul_f32_e32 v0, 0x3e16c740, v0
	v_mul_f32_e32 v23, 0x3e16c740, v23
	v_cvt_pk_bf16_f32 v91, v0, v23
	v_lshlrev_b32_e32 v0, 16, v26
	v_and_b32_e32 v23, 0xffff0000, v26
	v_mul_f32_e32 v0, 0x3e16c740, v0
	v_mul_f32_e32 v23, 0x3e16c740, v23
	v_cvt_pk_bf16_f32 v92, v0, v23
	v_lshlrev_b32_e32 v0, 16, v27
	v_and_b32_e32 v23, 0xffff0000, v27
	v_mul_f32_e32 v0, 0x3e16c740, v0
	v_mul_f32_e32 v23, 0x3e16c740, v23
	v_cvt_pk_bf16_f32 v93, v0, v23
	global_load_dwordx4 v[24:27], v[20:21], off offset:96
	s_waitcnt vmcnt(0)
	v_lshlrev_b32_e32 v0, 16, v24
	v_and_b32_e32 v20, 0xffff0000, v24
	v_mul_f32_e32 v0, 0x3e16c740, v0
	v_mul_f32_e32 v20, 0x3e16c740, v20
	v_cvt_pk_bf16_f32 v94, v0, v20
	v_lshlrev_b32_e32 v0, 16, v25
	v_and_b32_e32 v20, 0xffff0000, v25
	v_mul_f32_e32 v0, 0x3e16c740, v0
	v_mul_f32_e32 v20, 0x3e16c740, v20
	v_cvt_pk_bf16_f32 v95, v0, v20
	v_lshlrev_b32_e32 v0, 16, v26
	v_and_b32_e32 v20, 0xffff0000, v26
	v_mul_f32_e32 v0, 0x3e16c740, v0
	v_mul_f32_e32 v20, 0x3e16c740, v20
	v_cvt_pk_bf16_f32 v96, v0, v20
	v_lshlrev_b32_e32 v0, 16, v27
	v_and_b32_e32 v20, 0xffff0000, v27
	v_mul_f32_e32 v0, 0x3e16c740, v0
	v_mul_f32_e32 v20, 0x3e16c740, v20
	v_cvt_pk_bf16_f32 v97, v0, v20
	global_load_dwordx4 v[24:27], v[18:19], off offset:128
	global_load_dwordx4 v[28:31], v[18:19], off offset:144
	s_waitcnt vmcnt(1)
	v_lshlrev_b32_e32 v20, 16, v24
	s_waitcnt vmcnt(0)
; __device__ __forceinline__ unsigned cvtpk(float lo, float hi) { unsigned r; asm volatile("v_cvt_pk_bf16_f32 %0, %1, %2" : "=v"(r) : "v"(lo), "v"(hi)); return r; }
; __device__ __forceinline__ float bflo(unsigned w) { return __uint_as_float(w << 16); }
; __device__ __forceinline__ float bfhi(unsigned w) { return __uint_as_float(w & 0xffff0000u); }
; __device__ __forceinline__ float rope_inv(int i) { return exp2f(-1.6609640474436813f * (float)i); }
; __device__ __forceinline__ int v_st(int k, int c) { const int kk = (k & ~0xC) | ((k & 4) << 1) | ((k & 8) >> 1); return ((kk >> 3) * 4 + (c >> 5)) * 512 + ((kk & 7) * 32 + (c & 31)) * 2; }
; __device__ __forceinline__ void attn_unit(const bf16_t* __restrict__ Qb, bool rope_q, int tq0, const bf16_t* __restrict__ KVh, const bf16_t* __restrict__ KR,
;                                           int ctx_row0, int lat_row0, int NT, bf16_t* __restrict__ Ob, LAS unsigned char* lds, int wave_s) {
;     ...
;       const u32x4 lo = *(const u32x4*)(Qw + 64 + a * 16), hh = *(const u32x4*)(Qw + 64 + a * 16 + 8);
;       const float pos = (float)(a == 0 ? (t >> 6) : (t & 63)); float ov[8];
; #pragma unroll
;       for (int i = 0; i < 8; ++i) { const float ang = rope_q ? pos * rope_inv(i) : 0.f, c = __cosf(ang) * C2, s = __sinf(ang) * C2;
;         const float l = (i & 1) ? bfhi(lo[i >> 1]) : bflo(lo[i >> 1]), h = (i & 1) ? bfhi(hh[i >> 1]) : bflo(hh[i >> 1]);
;         ov[i] = hi ? (h * c + l * s) : (l * c - h * s); }
;       u32x4 w = {cvtpk(ov[0], ov[1]), cvtpk(ov[2], ov[3]), cvtpk(ov[4], ov[5]), cvtpk(ov[6], ov[7])}; qr[4 + a] = __builtin_bit_cast(bf16x8, w);
;     }
;   }
;   const int sr = tid >> 4, sc = (tid & 15) * 8, rr = (tid & 255) >> 2, rc = (tid & 3) * 8;
;   const int st0 = (sc < 64) ? OFF_K + KSWZ(sr, sc * 2) : OFF_V + v_st(sr, sc - 64);
;   const int st1 = (sc < 64) ? OFF_K + KSWZ(32 + sr, sc * 2) : OFF_V + v_st(32 + sr, sc - 64);
	v_lshlrev_b32_e32 v21, 16, v28
	v_pk_mul_f32 v[32:33], v[20:21], s[0:1]
	v_pk_mul_f32 v[20:21], v[20:21], s[52:53]
	v_add_f32_e32 v0, v32, v33
	v_sub_f32_e32 v20, v20, v21
	v_cndmask_b32_e64 v0, v0, v20, s[2:3]
	v_and_b32_e32 v21, 0xffff0000, v28
	v_and_b32_e32 v20, 0xffff0000, v24
	v_pk_mul_f32 v[32:33], v[20:21], s[0:1]
	v_pk_mul_f32 v[20:21], v[20:21], s[52:53]
	v_add_f32_e32 v23, v32, v33
	v_sub_f32_e32 v20, v20, v21
	v_cndmask_b32_e64 v23, v23, v20, s[2:3]
	v_lshlrev_b32_e32 v21, 16, v29
	v_lshlrev_b32_e32 v20, 16, v25
	v_pk_mul_f32 v[32:33], v[20:21], s[0:1]
	v_pk_mul_f32 v[20:21], v[20:21], s[52:53]
	v_add_f32_e32 v24, v32, v33
	v_sub_f32_e32 v20, v20, v21
	v_cndmask_b32_e64 v28, v24, v20, s[2:3]
	v_and_b32_e32 v21, 0xffff0000, v29
	v_and_b32_e32 v20, 0xffff0000, v25
	v_pk_mul_f32 v[24:25], v[20:21], s[0:1]
	v_pk_mul_f32 v[20:21], v[20:21], s[52:53]
	v_add_f32_e32 v24, v24, v25
	v_sub_f32_e32 v20, v20, v21
	v_cndmask_b32_e64 v29, v24, v20, s[2:3]
	v_lshlrev_b32_e32 v21, 16, v30
	v_lshlrev_b32_e32 v20, 16, v26
	v_pk_mul_f32 v[24:25], v[20:21], s[0:1]
	v_pk_mul_f32 v[20:21], v[20:21], s[52:53]
	v_add_f32_e32 v24, v24, v25
	v_sub_f32_e32 v20, v20, v21
	v_cndmask_b32_e64 v32, v24, v20, s[2:3]
	v_and_b32_e32 v21, 0xffff0000, v30
	v_and_b32_e32 v20, 0xffff0000, v26
	v_pk_mul_f32 v[24:25], v[20:21], s[0:1]
	v_pk_mul_f32 v[20:21], v[20:21], s[52:53]
	v_add_f32_e32 v24, v24, v25
	v_sub_f32_e32 v20, v20, v21
	v_cndmask_b32_e64 v26, v24, v20, s[2:3]
	v_lshlrev_b32_e32 v21, 16, v31
	v_lshlrev_b32_e32 v20, 16, v27
	v_pk_mul_f32 v[24:25], v[20:21], s[0:1]
	v_pk_mul_f32 v[20:21], v[20:21], s[52:53]
	v_add_f32_e32 v24, v24, v25
	v_sub_f32_e32 v20, v20, v21
	v_cndmask_b32_e64 v30, v24, v20, s[2:3]
	v_and_b32_e32 v21, 0xffff0000, v31
	v_and_b32_e32 v20, 0xffff0000, v27
	v_pk_mul_f32 v[24:25], v[20:21], s[0:1]
	v_pk_mul_f32 v[20:21], v[20:21], s[52:53]
	v_add_f32_e32 v24, v24, v25
	v_sub_f32_e32 v20, v20, v21
	v_cndmask_b32_e64 v20, v24, v20, s[2:3]
	v_cvt_pk_bf16_f32 v98, v0, v23
	v_cvt_pk_bf16_f32 v99, v28, v29
	v_cvt_pk_bf16_f32 v100, v32, v26
	v_cvt_pk_bf16_f32 v101, v30, v20
	global_load_dwordx4 v[24:27], v[18:19], off offset:160
	global_load_dwordx4 v[18:21], v[18:19], off offset:176
	s_waitcnt vmcnt(1)
	v_lshlrev_b32_e32 v28, 16, v24
	s_waitcnt vmcnt(0)
	v_lshlrev_b32_e32 v29, 16, v18
	v_pk_mul_f32 v[30:31], v[28:29], s[0:1]
	v_pk_mul_f32 v[28:29], v[28:29], s[52:53]
	v_add_f32_e32 v0, v30, v31
	v_sub_f32_e32 v23, v28, v29
	v_and_b32_e32 v29, 0xffff0000, v18
	v_and_b32_e32 v28, 0xffff0000, v24
	v_pk_mul_f32 v[30:31], v[28:29], s[0:1]
	v_pk_mul_f32 v[28:29], v[28:29], s[52:53]
	v_cndmask_b32_e64 v0, v0, v23, s[2:3]
	v_sub_f32_e32 v23, v28, v29
	v_lshlrev_b32_e32 v29, 16, v19
	v_lshlrev_b32_e32 v28, 16, v25
	v_add_f32_e32 v18, v30, v31
	v_pk_mul_f32 v[30:31], v[28:29], s[0:1]
	v_pk_mul_f32 v[28:29], v[28:29], s[52:53]
	v_cndmask_b32_e64 v23, v18, v23, s[2:3]
	v_add_f32_e32 v18, v30, v31
	v_sub_f32_e32 v24, v28, v29
	v_cndmask_b32_e64 v28, v18, v24, s[2:3]
	v_and_b32_e32 v19, 0xffff0000, v19
	v_and_b32_e32 v18, 0xffff0000, v25
	v_pk_mul_f32 v[24:25], v[18:19], s[0:1]
	v_pk_mul_f32 v[18:19], v[18:19], s[52:53]
	v_add_f32_e32 v24, v24, v25
	v_sub_f32_e32 v18, v18, v19
	v_cndmask_b32_e64 v29, v24, v18, s[2:3]
	v_lshlrev_b32_e32 v19, 16, v20
	v_lshlrev_b32_e32 v18, 16, v26
	v_pk_mul_f32 v[24:25], v[18:19], s[0:1]
	v_pk_mul_f32 v[18:19], v[18:19], s[52:53]
	v_add_f32_e32 v24, v24, v25
	v_sub_f32_e32 v18, v18, v19
	v_cndmask_b32_e64 v30, v24, v18, s[2:3]
	v_and_b32_e32 v19, 0xffff0000, v20
	v_and_b32_e32 v18, 0xffff0000, v26
	v_pk_mul_f32 v[24:25], v[18:19], s[0:1]
	v_pk_mul_f32 v[18:19], v[18:19], s[52:53]
	v_add_f32_e32 v20, v24, v25
	v_sub_f32_e32 v18, v18, v19
	v_cndmask_b32_e64 v26, v20, v18, s[2:3]
	v_lshlrev_b32_e32 v19, 16, v21
	v_lshlrev_b32_e32 v18, 16, v27
	v_pk_mul_f32 v[24:25], v[18:19], s[0:1]
	v_pk_mul_f32 v[18:19], v[18:19], s[52:53]
	v_add_f32_e32 v20, v24, v25
	v_sub_f32_e32 v18, v18, v19
	v_cndmask_b32_e64 v24, v20, v18, s[2:3]
	v_and_b32_e32 v19, 0xffff0000, v21
	v_and_b32_e32 v18, 0xffff0000, v27
	v_pk_mul_f32 v[20:21], v[18:19], s[0:1]
	v_pk_mul_f32 v[18:19], v[18:19], s[52:53]
	v_add_f32_e32 v20, v20, v21
	v_sub_f32_e32 v18, v18, v19
	v_cndmask_b32_e64 v18, v20, v18, s[2:3]
	v_cvt_pk_bf16_f32 v102, v0, v23
	v_cvt_pk_bf16_f32 v103, v28, v29
	v_cvt_pk_bf16_f32 v104, v30, v26
	v_cvt_pk_bf16_f32 v105, v24, v18
	v_lshlrev_b32_e32 v18, 3, v22
	v_and_b32_e32 v0, 0x78, v18
	v_subrev_u32_e32 v21, 64, v0
	v_lshrrev_b32_e32 v20, 1, v78
	v_bfe_u32 v23, v22, 4, 2
	v_cmp_lt_u32_e32 vcc, 63, v0
	v_lshrrev_b32_e32 v19, 5, v21
	v_and_or_b32 v20, v20, 4, v23
	v_lshlrev_b32_e32 v21, 1, v21
	s_and_saveexec_b64 s[0:1], vcc
	s_xor_b64 s[0:1], exec, s[0:1]
	v_and_b32_e32 v23, 0xfffff0, v78
	v_lshlrev_b32_e32 v24, 1, v78
	v_and_or_b32 v23, v24, 8, v23
	v_lshrrev_b32_e32 v23, 1, v23
	v_and_b32_e32 v24, 48, v21
	v_add_u32_e32 v23, v23, v19
	v_lshl_or_b32 v24, v20, 6, v24
	v_lshl_or_b32 v146, v23, 9, v24
	s_or_saveexec_b64 s[0:1], s[0:1]
	v_lshlrev_b32_e32 v23, 8, v78
	v_lshlrev_b32_e32 v0, 1, v0
	v_and_b32_e32 v24, 0xf0, v22
	v_bitop3_b32 v23, v23, v0, v24 bitop3:0xf6
	s_xor_b64 exec, exec, s[0:1]
	v_add_u32_e32 v146, 0xc000, v23
	s_or_b64 exec, exec, s[0:1]
	s_and_saveexec_b64 s[0:1], vcc
	s_xor_b64 s[0:1], exec, s[0:1]
	s_cbranch_execz .LBB0_466
	v_add_u32_e32 v23, 32, v78
	v_and_b32_e32 v24, 0xfffff0, v23
	v_lshlrev_b32_e32 v23, 1, v23
	v_and_or_b32 v23, v23, 8, v24
	v_lshrrev_b32_e32 v23, 1, v23
	v_and_b32_e32 v21, 48, v21
	v_add_u32_e32 v19, v23, v19
	v_lshl_or_b32 v20, v20, 6, v21
	v_lshl_or_b32 v147, v19, 9, v20
	s_andn2_saveexec_b64 s[0:1], s[0:1]
	s_cbranch_execnz .LBB0_467
	s_branch .LBB0_468

; #define PHASE_IDS() int tid = wave * 64 + lane_id(); asm volatile("" : "+v"(tid)); int G = gridDim.x, blk = blockIdx.x; asm volatile("" : "+s"(G), "+s"(blk)); const int NGW = G * 8; const int lane = tid & 63; const int gw = blk * 8 + wave; (void)lane; (void)gw; (void)NGW; \
;     KP pp = (KP)__builtin_amdgcn_kernarg_segment_ptr(); asm volatile("" : "+s"(pp)); unsigned char* ws = pp->ws; (void)ws;
; __global__ void __launch_bounds__(512, 2) fwd_megakernel(Params p) {
;     ...
;         { PHASE_IDS(); const float* gbr = PIN(I_GBR) + l * 1024; const f32x4 g0 = ((const f32x4*)gbr)[2 * lane], g1 = ((const f32x4*)gbr)[2 * lane + 1];
;           for (int m0 = gw; m0 < Mact; m0 += 8 * NGW) { u32x4 w[8];
; #pragma unroll
;               for (int i = 0; i < 8; ++i) { const int m = m0 + i * NGW; w[i] = ((const u32x4*)(BA + (size_t)(m < Mact ? m : m0) * DM))[lane]; }
.LBB0_604:
	s_or_b64 exec, exec, s[0:1]
	v_readlane_b32 s0, v255, 16
	v_readlane_b32 s1, v255, 17
	s_and_b64 s[0:1], s[0:1], exec
	s_mov_b32 s0, 0x8400
	s_cselect_b32 s53, 0x8000, s0
	v_mov_b32_e32 v0, v206
	v_readlane_b32 s1, v255, 0
	s_mov_b32 s0, s92
	s_waitcnt lgkmcnt(0)
	s_barrier
	s_lshl_b32 s0, s0, 3
	v_readlane_b32 s2, v255, 3
	s_add_i32 s0, s0, s2
	v_readlane_b32 s2, v255, 1
	v_readlane_b32 s3, v255, 2
	s_cmp_ge_i32 s0, s53
	s_cbranch_scc1 .LBB0_621
	s_load_dwordx2 s[4:5], s[2:3], 0xa0
	v_readlane_b32 s6, v255, 28
	v_readlane_b32 s7, v255, 29
	s_lshl_b32 s28, s1, 3
	s_lshl_b64 s[6:7], s[6:7], 2
	v_and_b32_e32 v0, 63, v0
	s_waitcnt lgkmcnt(0)
	s_add_u32 s4, s4, s6
	v_lshlrev_b32_e32 v6, 5, v0
	s_addc_u32 s5, s5, s7
	global_load_dwordx4 v[2:5], v6, s[4:5]
	global_load_dwordx4 v[6:9], v6, s[4:5] offset:16
	s_load_dwordx2 s[2:3], s[2:3], 0xc8
	v_lshlrev_b32_e32 v0, 4, v0
	s_lshl_b32 s29, s1, 6
	s_lshl_b32 s34, s1, 4
	s_mul_i32 s35, s1, 24
	s_waitcnt lgkmcnt(0)
	v_lshl_add_u64 v[10:11], s[2:3], 0, v[0:1]
	s_mov_b64 s[2:3], 0x3000000
	v_lshl_add_u64 v[38:39], v[10:11], 0, s[2:3]
	s_lshl_b32 s36, s1, 5
	s_mul_i32 s37, s1, 40
	s_mul_i32 s46, s1, 48
	s_mul_i32 s47, s1, 56
	s_branch .LBB0_607

; #define LOADY(m, y, ns) do { if ((m) >= NLAT) load16part<ns>(WSP(float, WS_PART), (m) - NLAT, lane, y); else load16bf(BY + (size_t)(m) * DM, lane, y); } while (0)
; #define R3_SRC(m) ((l == 0) ? ((m) < NLAT ? PIN(I_X) + (size_t)(m) * DM : PIN(I_CTX) + (size_t)((m) - NLAT) * DM) : (const float*)XS_ROW(m))
; __global__ void __launch_bounds__(512, 2) fwd_megakernel(Params p) {
;     ...
;         for (int m0 = gw; m0 < Mact; m0 += 4 * NGW) { f32x4 yb[4][4], xb[4][4];
; #pragma unroll
;             for (int i = 0; i < 4; ++i) { const int mi = m0 + i * NGW, mc = mi < Mact ? mi : m0; LOADY(mc, yb[i], 4); load16(R3_SRC(mc), lane, xb[i]); }
; #pragma unroll
;             for (int i = 0; i < 4; ++i) { const int mi = m0 + i * NGW; if (mi < Mact) R3_ROW(mi, yb[i], xb[i]); } } }
.LBB0_771:
	v_pk_mul_f32 v[34:35], v[32:33], v[32:33]
	v_pk_mul_f32 v[36:37], v[30:31], v[30:31]
	v_mul_f32_e32 v0, v2, v2
	v_pk_mov_b32 v[38:39], v[36:37], v[34:35] op_sel:[1,0]
	v_mov_b32_e32 v37, v35
	v_pk_add_f32 v[34:35], v[38:39], v[36:37]
	v_pk_mul_f32 v[36:37], v[12:13], v[12:13]
	v_pk_mul_f32 v[38:39], v[10:11], v[10:11]
	v_pk_add_f32 v[34:35], v[34:35], v[34:35] op_sel:[0,1] op_sel_hi:[1,0]
	v_pk_mov_b32 v[40:41], v[38:39], v[36:37] op_sel:[1,0]
	v_mov_b32_e32 v39, v37
	v_pk_add_f32 v[36:37], v[40:41], v[38:39]
	v_mul_f32_e32 v38, v3, v3
	v_pk_add_f32 v[36:37], v[36:37], v[36:37] op_sel:[0,1] op_sel_hi:[1,0]
	v_mov_b32_e32 v35, v0
	v_mov_b32_e32 v37, v38
	v_mul_f32_e32 v0, v7, v7
	v_mul_f32_e32 v39, v4, v4
	v_pk_add_f32 v[34:35], v[34:35], v[36:37]
	v_pk_fma_f32 v[36:37], v[6:7], v[6:7], v[0:1] op_sel_hi:[1,1,0]
	v_mul_f32_e32 v0, v9, v9
	v_mul_f32_e32 v40, v5, v5
	v_mov_b32_e32 v37, v39
	v_pk_fma_f32 v[38:39], v[8:9], v[8:9], v[0:1] op_sel_hi:[1,1,0]
	s_ashr_i32 s4, s8, 31
	v_mov_b32_e32 v39, v40
	v_pk_add_f32 v[36:37], v[36:37], v[38:39]
	s_lshr_b32 s4, s4, 19
	v_pk_add_f32 v[34:35], v[34:35], v[36:37]
	s_add_i32 s4, s8, s4
	v_add_f32_e32 v0, v34, v35
	v_mov_b32_e32 v34, v1
	s_ashr_i32 s13, s4, 13
	v_add_f32_dpp v0, v0, v0 quad_perm:[1,0,3,2] row_mask:0xf bank_mask:0xf bound_ctrl:1
	s_and_b64 s[4:5], exec, s[6:7]
	s_cselect_b32 s4, s13, 4
	v_add_f32_dpp v0, v0, v0 quad_perm:[2,3,0,1] row_mask:0xf bank_mask:0xf bound_ctrl:1
	s_add_i32 s4, s4, s92
	s_mulk_i32 s4, 0x1800
	v_add_f32_dpp v0, v0, v0 row_half_mirror row_mask:0xf bank_mask:0xf bound_ctrl:1
	s_ashr_i32 s5, s4, 31
	s_lshl_b64 s[4:5], s[4:5], 2
	v_add_f32_dpp v0, v0, v0 row_mirror row_mask:0xf bank_mask:0xf bound_ctrl:1
	s_add_u32 s4, s62, s4
	s_addc_u32 s5, s63, s5
	v_mov_b32_dpp v34, v0 row_bcast:15 row_mask:0xa bank_mask:0xf
	v_add_f32_e32 v0, v0, v34
	v_mov_b32_e32 v34, v1
	s_nop 1
	v_mov_b32_dpp v34, v0 row_bcast:31 row_mask:0xc bank_mask:0xf
	v_add_f32_e32 v0, v0, v34
	s_nop 0
	v_readlane_b32 s6, v0, 63
	s_nop 1
	v_cvt_i32_f32_e32 v0, s6
	s_add_u32 s6, s4, 0x2000
	s_addc_u32 s7, s5, 0
	v_cvt_f32_i32_e32 v0, v0
	v_fmamk_f32 v0, v0, 0x3a800000, v211
	v_cmp_gt_f32_e32 vcc, s68, v0
	v_mul_f32_e32 v34, 0x4b800000, v0
	s_nop 0
	v_cndmask_b32_e32 v0, v0, v34, vcc
	v_rsq_f32_e32 v0, v0
	s_nop 0
	v_mul_f32_e32 v34, 0x45800000, v0
	v_cndmask_b32_e32 v0, v0, v34, vcc
	v_pk_mul_f32 v[38:39], v[0:1], v[32:33] op_sel_hi:[0,1]
	v_pk_mul_f32 v[40:41], v[0:1], v[30:31] op_sel_hi:[0,1]
	global_load_dwordx4 v[30:33], v[136:137], off
	global_load_dwordx4 v[34:37], v131, s[6:7]
	s_waitcnt vmcnt(1)
	v_pk_mul_f32 v[30:31], v[40:41], v[30:31]
	v_pk_mul_f32 v[32:33], v[38:39], v[32:33]
	s_waitcnt vmcnt(0)
	v_pk_fma_f32 v[26:27], v[34:35], v[30:31], v[26:27]
	v_pk_fma_f32 v[28:29], v[36:37], v[32:33], v[28:29]
	global_store_dwordx4 v131, v[26:29], s[0:1] nt
	v_pk_mul_f32 v[34:35], v[0:1], v[10:11] op_sel_hi:[0,1]
	v_pk_mul_f32 v[36:37], v[0:1], v[12:13] op_sel_hi:[0,1]
	global_load_dwordx4 v[10:13], v[136:137], off offset:1024
	global_load_dwordx4 v[30:33], v144, s[6:7]
	s_waitcnt vmcnt(1)
	v_pk_mul_f32 v[12:13], v[36:37], v[12:13]
	v_pk_mul_f32 v[10:11], v[34:35], v[10:11]
	s_waitcnt vmcnt(0)
	v_pk_fma_f32 v[12:13], v[32:33], v[12:13], v[24:25]
	v_pk_fma_f32 v[10:11], v[30:31], v[10:11], v[22:23]
	global_store_dwordx4 v131, v[10:13], s[0:1] offset:1024 nt
	v_pk_mul_f32 v[30:31], v[0:1], v[6:7] op_sel_hi:[0,1]
	v_pk_mul_f32 v[32:33], v[0:1], v[8:9] op_sel_hi:[0,1]
	global_load_dwordx4 v[6:9], v[136:137], off offset:2048
	global_load_dwordx4 v[22:25], v145, s[6:7]
	s_waitcnt vmcnt(1)
	v_pk_mul_f32 v[8:9], v[32:33], v[8:9]
	v_pk_mul_f32 v[6:7], v[30:31], v[6:7]
	s_waitcnt vmcnt(0)
	v_pk_fma_f32 v[8:9], v[24:25], v[8:9], v[20:21]
	v_pk_fma_f32 v[6:7], v[22:23], v[6:7], v[18:19]
	global_store_dwordx4 v131, v[6:9], s[0:1] offset:2048 nt
	v_pk_mul_f32 v[22:23], v[0:1], v[4:5] op_sel_hi:[0,1]
	v_pk_mul_f32 v[24:25], v[0:1], v[2:3] op_sel_hi:[0,1]
	global_load_dwordx4 v[2:5], v[136:137], off offset:3072
	global_load_dwordx4 v[18:21], v146, s[6:7]
	s_add_u32 s6, s4, 0x3000
	s_addc_u32 s7, s5, 0
	s_waitcnt vmcnt(1)
	v_pk_mul_f32 v[2:3], v[24:25], v[2:3]
	v_pk_mul_f32 v[4:5], v[22:23], v[4:5]
	s_waitcnt vmcnt(0)
; __device__ __forceinline__ unsigned cvtpk(float lo, float hi) { unsigned r; asm volatile("v_cvt_pk_bf16_f32 %0, %1, %2" : "=v"(r) : "v"(lo), "v"(hi)); return r; }
; __device__ __forceinline__ void prenorm_store(const f32x4 (&v)[4], float rinv, const float* g, const float* shift, const float* scale, bf16_t* orow, int lane) {
; #pragma unroll
;     for (int j = 0; j < 4; ++j) { const int q = lane + 64 * j; const f32x4 gg = ((const f32x4*)g)[q], sh = ((const f32x4*)shift)[q], sc = ((const f32x4*)scale)[q];
;         const f32x4 h = (v[j] * rinv * gg) * (sc + 1.0f) + sh; u32x2 w; w.x = cvtpk(h.x, h.y); w.y = cvtpk(h.z, h.w); ((u32x2*)orow)[q] = w; }
; }
	v_pk_fma_f32 v[2:3], v[18:19], v[2:3], v[14:15]
	v_pk_fma_f32 v[4:5], v[20:21], v[4:5], v[16:17]
	v_pk_mul_f32 v[14:15], v[28:29], v[28:29]
	v_pk_mul_f32 v[16:17], v[26:27], v[26:27]
	v_mul_f32_e32 v0, v2, v2
	v_pk_mov_b32 v[18:19], v[16:17], v[14:15] op_sel:[1,0]
	v_mov_b32_e32 v17, v15
	v_pk_add_f32 v[14:15], v[18:19], v[16:17]
	v_pk_mul_f32 v[16:17], v[10:11], v[10:11]
	v_pk_mul_f32 v[18:19], v[12:13], v[12:13]
	v_pk_add_f32 v[14:15], v[14:15], v[14:15] op_sel:[0,1] op_sel_hi:[1,0]
	v_pk_mov_b32 v[20:21], v[16:17], v[18:19] op_sel:[1,0]
	v_mov_b32_e32 v17, v19
	v_pk_add_f32 v[16:17], v[20:21], v[16:17]
	v_mul_f32_e32 v18, v3, v3
	v_pk_add_f32 v[16:17], v[16:17], v[16:17] op_sel:[0,1] op_sel_hi:[1,0]
	v_mov_b32_e32 v15, v0
	v_mov_b32_e32 v17, v18
	v_mul_f32_e32 v0, v7, v7
	v_mul_f32_e32 v19, v4, v4
	v_pk_add_f32 v[14:15], v[14:15], v[16:17]
	v_pk_fma_f32 v[16:17], v[6:7], v[6:7], v[0:1] op_sel_hi:[1,1,0]
	v_mul_f32_e32 v0, v9, v9
	v_mul_f32_e32 v20, v5, v5
	v_mov_b32_e32 v17, v19
	v_pk_fma_f32 v[18:19], v[8:9], v[8:9], v[0:1] op_sel_hi:[1,1,0]
	global_store_dwordx4 v131, v[2:5], s[0:1] offset:3072 nt
	v_mov_b32_e32 v19, v20
	v_pk_add_f32 v[16:17], v[16:17], v[18:19]
	s_nop 0
	v_pk_add_f32 v[14:15], v[14:15], v[16:17]
	s_nop 0
	v_add_f32_e32 v0, v14, v15
	v_mov_b32_e32 v14, v1
	s_nop 0
	v_add_f32_dpp v0, v0, v0 quad_perm:[1,0,3,2] row_mask:0xf bank_mask:0xf bound_ctrl:1
	s_nop 1
	v_add_f32_dpp v0, v0, v0 quad_perm:[2,3,0,1] row_mask:0xf bank_mask:0xf bound_ctrl:1
	s_nop 1
	v_add_f32_dpp v0, v0, v0 row_half_mirror row_mask:0xf bank_mask:0xf bound_ctrl:1
	s_nop 1
	v_add_f32_dpp v0, v0, v0 row_mirror row_mask:0xf bank_mask:0xf bound_ctrl:1
	s_nop 1
	v_mov_b32_dpp v14, v0 row_bcast:15 row_mask:0xa bank_mask:0xf
	v_add_f32_e32 v0, v0, v14
	v_mov_b32_e32 v14, v1
	s_nop 1
	v_mov_b32_dpp v14, v0 row_bcast:31 row_mask:0xc bank_mask:0xf
	v_add_f32_e32 v0, v0, v14
	s_nop 0
	v_readlane_b32 s0, v0, 63
	s_nop 1
	v_cvt_i32_f32_e32 v0, s0
	s_add_u32 s0, s4, 0x4000
	s_addc_u32 s1, s5, 0
	s_lshl_b64 s[8:9], s[8:9], 11
	v_cvt_f32_i32_e32 v0, v0
	v_fmamk_f32 v0, v0, 0x3a800000, v211
	v_cmp_gt_f32_e32 vcc, s68, v0
	v_mul_f32_e32 v14, 0x4b800000, v0
	s_nop 0
	v_cndmask_b32_e32 v0, v0, v14, vcc
	v_rsq_f32_e32 v0, v0
	s_nop 0
	v_mul_f32_e32 v14, 0x45800000, v0
	v_cndmask_b32_e32 v0, v0, v14, vcc
	global_load_dwordx4 v[14:17], v[134:135], off
	global_load_dwordx4 v[18:21], v131, s[6:7]
	global_load_dwordx4 v[22:25], v131, s[0:1]
	v_pk_mul_f32 v[26:27], v[26:27], v[0:1] op_sel_hi:[1,0]
	v_pk_mul_f32 v[28:29], v[28:29], v[0:1] op_sel_hi:[1,0]
	v_pk_mul_f32 v[12:13], v[12:13], v[0:1] op_sel_hi:[1,0]
	v_pk_mul_f32 v[10:11], v[10:11], v[0:1] op_sel_hi:[1,0]
	v_pk_mul_f32 v[8:9], v[8:9], v[0:1] op_sel_hi:[1,0]
	v_pk_mul_f32 v[6:7], v[6:7], v[0:1] op_sel_hi:[1,0]
	v_pk_mul_f32 v[4:5], v[4:5], v[0:1] op_sel_hi:[1,0]
	v_pk_mul_f32 v[2:3], v[2:3], v[0:1] op_sel_hi:[1,0]
	s_waitcnt vmcnt(2)
	v_pk_mul_f32 v[14:15], v[14:15], v[26:27]
	v_pk_mul_f32 v[16:17], v[16:17], v[28:29]
	s_waitcnt vmcnt(0)
	v_pk_add_f32 v[22:23], v[22:23], 1.0 op_sel_hi:[1,0]
	v_pk_add_f32 v[24:25], v[24:25], 1.0 op_sel_hi:[1,0]
	v_pk_fma_f32 v[14:15], v[22:23], v[14:15], v[18:19]
	v_lshl_add_u64 v[26:27], v[140:141], 0, s[8:9]
	v_pk_fma_f32 v[16:17], v[24:25], v[16:17], v[20:21]
	v_cvt_pk_bf16_f32 v14, v14, v15
	s_nop 0
	v_cvt_pk_bf16_f32 v15, v16, v17
	global_store_dwordx2 v[26:27], v[14:15], off
	global_load_dwordx4 v[14:17], v[134:135], off offset:1024
	global_load_dwordx4 v[18:21], v144, s[6:7]
	global_load_dwordx4 v[22:25], v144, s[0:1]
	s_waitcnt vmcnt(2)
	v_pk_mul_f32 v[10:11], v[14:15], v[10:11]
	v_pk_mul_f32 v[12:13], v[16:17], v[12:13]
	s_waitcnt vmcnt(0)
	v_pk_add_f32 v[16:17], v[22:23], 1.0 op_sel_hi:[1,0]
	v_pk_add_f32 v[14:15], v[24:25], 1.0 op_sel_hi:[1,0]
	v_pk_fma_f32 v[10:11], v[16:17], v[10:11], v[18:19]
	v_pk_fma_f32 v[12:13], v[14:15], v[12:13], v[20:21]
	v_cvt_pk_bf16_f32 v10, v10, v11
	s_nop 0
	v_cvt_pk_bf16_f32 v11, v12, v13
	global_store_dwordx2 v[26:27], v[10:11], off offset:512
	global_load_dwordx4 v[10:13], v[134:135], off offset:2048
	global_load_dwordx4 v[14:17], v145, s[6:7]
	global_load_dwordx4 v[18:21], v145, s[0:1]
	s_waitcnt vmcnt(2)
	v_pk_mul_f32 v[6:7], v[6:7], v[10:11]
	v_pk_mul_f32 v[8:9], v[8:9], v[12:13]
	s_waitcnt vmcnt(0)
	v_pk_add_f32 v[12:13], v[18:19], 1.0 op_sel_hi:[1,0]
	v_pk_add_f32 v[10:11], v[20:21], 1.0 op_sel_hi:[1,0]
	v_pk_fma_f32 v[6:7], v[6:7], v[12:13], v[14:15]
	v_pk_fma_f32 v[8:9], v[8:9], v[10:11], v[16:17]
	v_cvt_pk_bf16_f32 v6, v6, v7
	s_nop 0
	v_cvt_pk_bf16_f32 v7, v8, v9
	global_store_dwordx2 v[26:27], v[6:7], off offset:1024
	global_load_dwordx4 v[6:9], v[134:135], off offset:3072
	global_load_dwordx4 v[10:13], v146, s[6:7]
	global_load_dwordx4 v[14:17], v146, s[0:1]
	s_waitcnt vmcnt(2)
	v_pk_mul_f32 v[2:3], v[2:3], v[6:7]
	v_pk_mul_f32 v[4:5], v[4:5], v[8:9]
	s_waitcnt vmcnt(0)
	v_pk_add_f32 v[8:9], v[14:15], 1.0 op_sel_hi:[1,0]
	v_pk_add_f32 v[6:7], v[16:17], 1.0 op_sel_hi:[1,0]
	v_pk_fma_f32 v[2:3], v[2:3], v[8:9], v[10:11]
	v_pk_fma_f32 v[4:5], v[4:5], v[6:7], v[12:13]
	v_cvt_pk_bf16_f32 v2, v2, v3
	s_nop 0
	v_cvt_pk_bf16_f32 v3, v4, v5
	global_store_dwordx2 v[26:27], v[2:3], off offset:1536

; template <int NS> __device__ __forceinline__ void load16part(const float* P, int rowrel, int lane, f32x4 (&v)[4]) {
; #pragma unroll
;     for (int j = 0; j < 4; ++j) v[j] = (f32x4){0.f, 0.f, 0.f, 0.f};
; #pragma unroll
;     for (int s0 = 0; s0 < NS; s0 += 4) { f32x4 t[4][4];
; #pragma unroll
;         for (int s = 0; s < 4; ++s) { const f32x4* q = (const f32x4*)(P + ((size_t)(s0 + s) * 1024 + rowrel) * 1024);
; #pragma unroll
;             for (int j = 0; j < 4; ++j) t[s][j] = q[lane + 64 * j]; }
; #pragma unroll
;         for (int s = 0; s < 4; ++s)
; #pragma unroll
;             for (int j = 0; j < 4; ++j) v[j] += t[s][j]; }
; }
.LBB0_775:
	s_andn2_b64 vcc, exec, s[6:7]
	s_cbranch_vccnz .LBB0_777
	s_lshl_b64 s[4:5], s[70:71], 12
	v_lshl_add_u64 v[14:15], v[138:139], 0, s[4:5]
	s_add_i32 s4, s70, 0x400
	s_mov_b32 s5, s71
	s_lshl_b64 s[4:5], s[4:5], 12
	v_lshl_add_u64 v[30:31], v[138:139], 0, s[4:5]
	s_add_i32 s4, s70, 0x800
	s_mov_b32 s5, s71
	s_lshl_b64 s[4:5], s[4:5], 12
	global_load_dwordx4 v[2:5], v[14:15], off
	global_load_dwordx4 v[6:9], v[14:15], off offset:1024
	global_load_dwordx4 v[10:13], v[14:15], off offset:2048
	global_load_dwordx4 v[18:21], v[30:31], off
	v_lshl_add_u64 v[46:47], v[138:139], 0, s[4:5]
	global_load_dwordx4 v[14:17], v[14:15], off offset:3072
	s_add_i32 s4, s70, 0xc00
	s_mov_b32 s5, s71
	global_load_dwordx4 v[22:25], v[30:31], off offset:1024
	global_load_dwordx4 v[26:29], v[30:31], off offset:2048
	global_load_dwordx4 v[34:37], v[46:47], off
	s_lshl_b64 s[4:5], s[4:5], 12
	global_load_dwordx4 v[30:33], v[30:31], off offset:3072
	v_lshl_add_u64 v[62:63], v[138:139], 0, s[4:5]
	global_load_dwordx4 v[38:41], v[46:47], off offset:1024
	global_load_dwordx4 v[42:45], v[46:47], off offset:2048
	s_waitcnt vmcnt(10)
	v_pk_add_f32 v[4:5], v[4:5], 0 op_sel_hi:[1,0]
	global_load_dwordx4 v[46:49], v[46:47], off offset:3072
	global_load_dwordx4 v[50:53], v[62:63], off
	global_load_dwordx4 v[54:57], v[62:63], off offset:1024
	global_load_dwordx4 v[58:61], v[62:63], off offset:2048
	global_load_dwordx4 v[62:65], v[62:63], off offset:3072
	v_pk_add_f32 v[2:3], v[2:3], 0 op_sel_hi:[1,0]
	s_waitcnt vmcnt(14)
	v_pk_add_f32 v[8:9], v[8:9], 0 op_sel_hi:[1,0]
	v_pk_add_f32 v[6:7], v[6:7], 0 op_sel_hi:[1,0]
	s_waitcnt vmcnt(13)
	v_pk_add_f32 v[12:13], v[12:13], 0 op_sel_hi:[1,0]
	v_pk_add_f32 v[10:11], v[10:11], 0 op_sel_hi:[1,0]
	s_waitcnt vmcnt(11)
	v_pk_add_f32 v[16:17], v[16:17], 0 op_sel_hi:[1,0]
	v_pk_add_f32 v[14:15], v[14:15], 0 op_sel_hi:[1,0]
	v_pk_add_f32 v[4:5], v[4:5], v[20:21]
	v_pk_add_f32 v[2:3], v[2:3], v[18:19]
	s_waitcnt vmcnt(10)
	v_pk_add_f32 v[8:9], v[8:9], v[24:25]
	v_pk_add_f32 v[6:7], v[6:7], v[22:23]
	s_waitcnt vmcnt(9)
	v_pk_add_f32 v[12:13], v[12:13], v[28:29]
	v_pk_add_f32 v[10:11], v[10:11], v[26:27]
	s_waitcnt vmcnt(7)
	v_pk_add_f32 v[16:17], v[16:17], v[32:33]
	v_pk_add_f32 v[14:15], v[14:15], v[30:31]
	v_pk_add_f32 v[4:5], v[4:5], v[36:37]
	v_pk_add_f32 v[2:3], v[2:3], v[34:35]
	s_waitcnt vmcnt(6)
	v_pk_add_f32 v[8:9], v[8:9], v[40:41]
	v_pk_add_f32 v[6:7], v[6:7], v[38:39]
	s_waitcnt vmcnt(5)
	v_pk_add_f32 v[12:13], v[12:13], v[44:45]
	v_pk_add_f32 v[10:11], v[10:11], v[42:43]
	s_waitcnt vmcnt(3)
	v_pk_add_f32 v[124:125], v[4:5], v[52:53]
	v_pk_add_f32 v[122:123], v[2:3], v[50:51]
	v_pk_add_f32 v[16:17], v[16:17], v[48:49]
	v_pk_add_f32 v[14:15], v[14:15], v[46:47]
	s_waitcnt vmcnt(2)
	v_pk_add_f32 v[108:109], v[8:9], v[56:57]
	v_pk_add_f32 v[106:107], v[6:7], v[54:55]
	s_waitcnt vmcnt(1)
	v_pk_add_f32 v[104:105], v[12:13], v[60:61]
	v_pk_add_f32 v[102:103], v[10:11], v[58:59]
	s_waitcnt vmcnt(0)
	v_pk_add_f32 v[100:101], v[16:17], v[64:65]
	v_pk_add_f32 v[98:99], v[14:15], v[62:63]

; __device__ __forceinline__ float bflo(unsigned w) { return __uint_as_float(w << 16); }
; __device__ __forceinline__ float bfhi(unsigned w) { return __uint_as_float(w & 0xffff0000u); }
; #define LOADY(m, y, ns) do { if ((m) >= NLAT) load16part<ns>(WSP(float, WS_PART), (m) - NLAT, lane, y); else load16bf(BY + (size_t)(m) * DM, lane, y); } while (0)
; #define R3_SRC(m) ((l == 0) ? ((m) < NLAT ? PIN(I_X) + (size_t)(m) * DM : PIN(I_CTX) + (size_t)((m) - NLAT) * DM) : (const float*)XS_ROW(m))
; __device__ __forceinline__ void load16(const float* row, int lane, f32x4 (&v)[4]) {
; #pragma unroll
;     for (int j = 0; j < 4; ++j) v[j] = __builtin_nontemporal_load((const f32x4*)row + lane + 64 * j);
; }
; __device__ __forceinline__ void load16bf(const bf16_t* row, int lane, f32x4 (&v)[4]) {
; #pragma unroll
;     for (int j = 0; j < 4; ++j) { const u32x2 w = __builtin_nontemporal_load((const u32x2*)row + lane + 64 * j); v[j] = (f32x4){bflo(w.x), bfhi(w.x), bflo(w.y), bfhi(w.y)}; }
; }
; template <int NS> __device__ __forceinline__ void load16part(const float* P, int rowrel, int lane, f32x4 (&v)[4]) {
; #pragma unroll
;     for (int j = 0; j < 4; ++j) v[j] = (f32x4){0.f, 0.f, 0.f, 0.f};
; #pragma unroll
;     for (int s0 = 0; s0 < NS; s0 += 4) { f32x4 t[4][4];
; #pragma unroll
;         for (int s = 0; s < 4; ++s) { const f32x4* q = (const f32x4*)(P + ((size_t)(s0 + s) * 1024 + rowrel) * 1024);
; #pragma unroll
;             for (int j = 0; j < 4; ++j) t[s][j] = q[lane + 64 * j]; }
; #pragma unroll
;         for (int s = 0; s < 4; ++s)
; #pragma unroll
;             for (int j = 0; j < 4; ++j) v[j] += t[s][j]; }
; }
; __global__ void __launch_bounds__(512, 2) fwd_megakernel(Params p) {
;     ...
;         for (int m0 = gw; m0 < Mact; m0 += 4 * NGW) { f32x4 yb[4][4], xb[4][4];
; #pragma unroll
;             for (int i = 0; i < 4; ++i) { const int mi = m0 + i * NGW, mc = mi < Mact ? mi : m0; LOADY(mc, yb[i], 4); load16(R3_SRC(mc), lane, xb[i]); }
.LBB0_788:
	s_lshl_b64 s[4:5], s[8:9], 12
	s_waitcnt lgkmcnt(0)
	s_add_u32 s4, s6, s4
	s_addc_u32 s5, s7, s5
	global_load_dwordx4 v[126:129], v131, s[4:5] nt
	global_load_dwordx4 v[118:121], v131, s[4:5] offset:1024 nt
	global_load_dwordx4 v[114:117], v131, s[4:5] offset:2048 nt
	global_load_dwordx4 v[110:113], v131, s[4:5] offset:3072 nt
	s_add_i32 s82, s58, s70
	s_add_i32 s80, s82, 0x8000
	s_cmp_lt_i32 s80, s53
	s_cselect_b64 s[84:85], -1, 0
	s_and_b64 s[4:5], s[84:85], exec
	s_cselect_b32 s28, s80, s0
	s_cmpk_gt_i32 s28, 0x7fff
	s_mov_b64 s[6:7], -1
	s_cbranch_scc1 .LBB0_790
	s_ashr_i32 s29, s28, 31
	s_lshl_b64 s[4:5], s[28:29], 11
	v_lshl_add_u64 v[2:3], v[132:133], 0, s[4:5]
	global_load_dwordx2 v[4:5], v[2:3], off nt
	global_load_dwordx2 v[6:7], v[2:3], off offset:512 nt
	global_load_dwordx2 v[8:9], v[2:3], off offset:1024 nt
	global_load_dwordx2 v[2:3], v[2:3], off offset:1536 nt
	s_mov_b64 s[6:7], 0
	s_waitcnt vmcnt(3)
	v_lshlrev_b32_e32 v94, 16, v4
	v_and_b32_e32 v95, 0xffff0000, v4
	v_lshlrev_b32_e32 v96, 16, v5
	v_and_b32_e32 v97, 0xffff0000, v5
	s_waitcnt vmcnt(2)
	v_lshlrev_b32_e32 v74, 16, v6
	v_and_b32_e32 v75, 0xffff0000, v6
	v_lshlrev_b32_e32 v76, 16, v7
	v_and_b32_e32 v77, 0xffff0000, v7
	s_waitcnt vmcnt(1)
	v_lshlrev_b32_e32 v70, 16, v8
	v_and_b32_e32 v71, 0xffff0000, v8
	v_lshlrev_b32_e32 v72, 16, v9
	v_and_b32_e32 v73, 0xffff0000, v9
	s_waitcnt vmcnt(0)
	v_lshlrev_b32_e32 v66, 16, v2
	v_and_b32_e32 v67, 0xffff0000, v2
	v_lshlrev_b32_e32 v68, 16, v3
	v_and_b32_e32 v69, 0xffff0000, v3
.LBB0_790:
	s_andn2_b64 vcc, exec, s[6:7]
	s_cbranch_vccnz .LBB0_792
	s_add_i32 s4, s28, 0xffff8000
	s_mov_b32 s5, s71
	s_lshl_b64 s[4:5], s[4:5], 12
	v_lshl_add_u64 v[14:15], v[138:139], 0, s[4:5]
	s_add_i32 s4, s28, 0xffff8400
	s_mov_b32 s5, s71
	s_lshl_b64 s[4:5], s[4:5], 12
	v_lshl_add_u64 v[30:31], v[138:139], 0, s[4:5]
	s_add_i32 s4, s28, 0xffff8800
	s_mov_b32 s5, s71
	s_lshl_b64 s[4:5], s[4:5], 12
	global_load_dwordx4 v[2:5], v[14:15], off
	global_load_dwordx4 v[6:9], v[14:15], off offset:1024
	global_load_dwordx4 v[10:13], v[14:15], off offset:2048
	global_load_dwordx4 v[14:17], v[14:15], off offset:3072
	v_lshl_add_u64 v[46:47], v[138:139], 0, s[4:5]
	s_add_i32 s4, s28, 0xffff8c00
	s_mov_b32 s5, s71
	global_load_dwordx4 v[18:21], v[30:31], off
	global_load_dwordx4 v[22:25], v[30:31], off offset:1024
	global_load_dwordx4 v[26:29], v[30:31], off offset:2048
	global_load_dwordx4 v[30:33], v[30:31], off offset:3072
	s_lshl_b64 s[4:5], s[4:5], 12
	global_load_dwordx4 v[34:37], v[46:47], off
	global_load_dwordx4 v[38:41], v[46:47], off offset:1024
	global_load_dwordx4 v[42:45], v[46:47], off offset:2048
	global_load_dwordx4 v[46:49], v[46:47], off offset:3072
	v_lshl_add_u64 v[62:63], v[138:139], 0, s[4:5]
	global_load_dwordx4 v[50:53], v[62:63], off
	global_load_dwordx4 v[54:57], v[62:63], off offset:1024
	global_load_dwordx4 v[58:61], v[62:63], off offset:2048
	global_load_dwordx4 v[62:65], v[62:63], off offset:3072
	s_waitcnt vmcnt(15)
	v_pk_add_f32 v[4:5], v[4:5], 0 op_sel_hi:[1,0]
	v_pk_add_f32 v[2:3], v[2:3], 0 op_sel_hi:[1,0]
	s_waitcnt vmcnt(14)
	v_pk_add_f32 v[8:9], v[8:9], 0 op_sel_hi:[1,0]
	v_pk_add_f32 v[6:7], v[6:7], 0 op_sel_hi:[1,0]
	s_waitcnt vmcnt(13)
	v_pk_add_f32 v[12:13], v[12:13], 0 op_sel_hi:[1,0]
	v_pk_add_f32 v[10:11], v[10:11], 0 op_sel_hi:[1,0]
	s_waitcnt vmcnt(12)
	v_pk_add_f32 v[16:17], v[16:17], 0 op_sel_hi:[1,0]
	v_pk_add_f32 v[14:15], v[14:15], 0 op_sel_hi:[1,0]
	s_waitcnt vmcnt(11)
	v_pk_add_f32 v[4:5], v[4:5], v[20:21]
	v_pk_add_f32 v[2:3], v[2:3], v[18:19]
	s_waitcnt vmcnt(10)
	v_pk_add_f32 v[8:9], v[8:9], v[24:25]
	v_pk_add_f32 v[6:7], v[6:7], v[22:23]
	s_waitcnt vmcnt(9)
	v_pk_add_f32 v[12:13], v[12:13], v[28:29]
	v_pk_add_f32 v[10:11], v[10:11], v[26:27]
	s_waitcnt vmcnt(8)
	v_pk_add_f32 v[16:17], v[16:17], v[32:33]
	v_pk_add_f32 v[14:15], v[14:15], v[30:31]
	s_waitcnt vmcnt(7)
	v_pk_add_f32 v[4:5], v[4:5], v[36:37]
	v_pk_add_f32 v[2:3], v[2:3], v[34:35]
	s_waitcnt vmcnt(6)
	v_pk_add_f32 v[8:9], v[8:9], v[40:41]
	v_pk_add_f32 v[6:7], v[6:7], v[38:39]
	s_waitcnt vmcnt(5)
	v_pk_add_f32 v[12:13], v[12:13], v[44:45]
	v_pk_add_f32 v[10:11], v[10:11], v[42:43]
	s_waitcnt vmcnt(4)
	v_pk_add_f32 v[16:17], v[16:17], v[48:49]
	v_pk_add_f32 v[14:15], v[14:15], v[46:47]
	s_waitcnt vmcnt(3)
	v_pk_add_f32 v[96:97], v[4:5], v[52:53]
	v_pk_add_f32 v[94:95], v[2:3], v[50:51]
	s_waitcnt vmcnt(2)
	v_pk_add_f32 v[76:77], v[8:9], v[56:57]
	v_pk_add_f32 v[74:75], v[6:7], v[54:55]
	s_waitcnt vmcnt(1)
	v_pk_add_f32 v[72:73], v[12:13], v[60:61]
	v_pk_add_f32 v[70:71], v[10:11], v[58:59]
	s_waitcnt vmcnt(0)
	v_pk_add_f32 v[68:69], v[16:17], v[64:65]
	v_pk_add_f32 v[66:67], v[14:15], v[62:63]

; __device__ __forceinline__ float bflo(unsigned w) { return __uint_as_float(w << 16); }
; __device__ __forceinline__ float bfhi(unsigned w) { return __uint_as_float(w & 0xffff0000u); }
; #define LOADY(m, y, ns) do { if ((m) >= NLAT) load16part<ns>(WSP(float, WS_PART), (m) - NLAT, lane, y); else load16bf(BY + (size_t)(m) * DM, lane, y); } while (0)
; #define R3_SRC(m) ((l == 0) ? ((m) < NLAT ? PIN(I_X) + (size_t)(m) * DM : PIN(I_CTX) + (size_t)((m) - NLAT) * DM) : (const float*)XS_ROW(m))
; __device__ __forceinline__ void load16(const float* row, int lane, f32x4 (&v)[4]) {
; #pragma unroll
;     for (int j = 0; j < 4; ++j) v[j] = __builtin_nontemporal_load((const f32x4*)row + lane + 64 * j);
; }
; __device__ __forceinline__ void load16bf(const bf16_t* row, int lane, f32x4 (&v)[4]) {
; #pragma unroll
;     for (int j = 0; j < 4; ++j) { const u32x2 w = __builtin_nontemporal_load((const u32x2*)row + lane + 64 * j); v[j] = (f32x4){bflo(w.x), bfhi(w.x), bflo(w.y), bfhi(w.y)}; }
; }
; template <int NS> __device__ __forceinline__ void load16part(const float* P, int rowrel, int lane, f32x4 (&v)[4]) {
; #pragma unroll
;     for (int j = 0; j < 4; ++j) v[j] = (f32x4){0.f, 0.f, 0.f, 0.f};
; #pragma unroll
;     for (int s0 = 0; s0 < NS; s0 += 4) { f32x4 t[4][4];
; #pragma unroll
;         for (int s = 0; s < 4; ++s) { const f32x4* q = (const f32x4*)(P + ((size_t)(s0 + s) * 1024 + rowrel) * 1024);
; #pragma unroll
;             for (int j = 0; j < 4; ++j) t[s][j] = q[lane + 64 * j]; }
; #pragma unroll
;         for (int s = 0; s < 4; ++s)
; #pragma unroll
;             for (int j = 0; j < 4; ++j) v[j] += t[s][j]; }
; }
; __global__ void __launch_bounds__(512, 2) fwd_megakernel(Params p) {
;     ...
;         for (int m0 = gw; m0 < Mact; m0 += 4 * NGW) { f32x4 yb[4][4], xb[4][4];
; #pragma unroll
;             for (int i = 0; i < 4; ++i) { const int mi = m0 + i * NGW, mc = mi < Mact ? mi : m0; LOADY(mc, yb[i], 4); load16(R3_SRC(mc), lane, xb[i]); }
.LBB0_803:
	s_lshl_b64 s[4:5], s[72:73], 12
	s_waitcnt lgkmcnt(0)
	s_add_u32 s4, s48, s4
	s_addc_u32 s5, s49, s5
	global_load_dwordx4 v[90:93], v131, s[4:5] nt
	global_load_dwordx4 v[86:89], v131, s[4:5] offset:1024 nt
	global_load_dwordx4 v[82:85], v131, s[4:5] offset:2048 nt
	global_load_dwordx4 v[78:81], v131, s[4:5] offset:3072 nt
	s_add_i32 s28, s16, s70
	s_add_i32 s78, s28, 0x8000
	s_cmp_lt_i32 s78, s53
	s_cselect_b64 s[48:49], -1, 0
	s_and_b64 s[4:5], s[48:49], exec
	s_cselect_b32 s72, s78, s0
	s_cmpk_gt_i32 s72, 0x7fff
	s_mov_b64 s[8:9], -1
	s_cbranch_scc1 .LBB0_805
	s_ashr_i32 s73, s72, 31
	s_lshl_b64 s[4:5], s[72:73], 11
	v_lshl_add_u64 v[2:3], v[132:133], 0, s[4:5]
	global_load_dwordx2 v[4:5], v[2:3], off nt
	global_load_dwordx2 v[6:7], v[2:3], off offset:512 nt
	global_load_dwordx2 v[8:9], v[2:3], off offset:1024 nt
	global_load_dwordx2 v[2:3], v[2:3], off offset:1536 nt
	s_mov_b64 s[8:9], 0
	s_waitcnt vmcnt(3)
	v_lshlrev_b32_e32 v62, 16, v4
	v_and_b32_e32 v63, 0xffff0000, v4
	v_lshlrev_b32_e32 v64, 16, v5
	v_and_b32_e32 v65, 0xffff0000, v5
	s_waitcnt vmcnt(2)
	v_lshlrev_b32_e32 v42, 16, v6
	v_and_b32_e32 v43, 0xffff0000, v6
	v_lshlrev_b32_e32 v44, 16, v7
	v_and_b32_e32 v45, 0xffff0000, v7
	s_waitcnt vmcnt(1)
	v_lshlrev_b32_e32 v38, 16, v8
	v_and_b32_e32 v39, 0xffff0000, v8
	v_lshlrev_b32_e32 v40, 16, v9
	v_and_b32_e32 v41, 0xffff0000, v9
	s_waitcnt vmcnt(0)
	v_lshlrev_b32_e32 v34, 16, v2
	v_and_b32_e32 v35, 0xffff0000, v2
	v_lshlrev_b32_e32 v36, 16, v3
	v_and_b32_e32 v37, 0xffff0000, v3
.LBB0_805:
	s_andn2_b64 vcc, exec, s[8:9]
	s_cbranch_vccnz .LBB0_807
	s_add_i32 s4, s72, 0xffff8000
	s_mov_b32 s5, s71
	s_lshl_b64 s[4:5], s[4:5], 12
	v_lshl_add_u64 v[14:15], v[138:139], 0, s[4:5]
	s_add_i32 s4, s72, 0xffff8400
	s_mov_b32 s5, s71
	s_lshl_b64 s[4:5], s[4:5], 12
	v_lshl_add_u64 v[30:31], v[138:139], 0, s[4:5]
	s_add_i32 s4, s72, 0xffff8800
	s_mov_b32 s5, s71
	s_lshl_b64 s[4:5], s[4:5], 12
	global_load_dwordx4 v[2:5], v[14:15], off
	global_load_dwordx4 v[6:9], v[14:15], off offset:1024
	global_load_dwordx4 v[10:13], v[14:15], off offset:2048
	global_load_dwordx4 v[14:17], v[14:15], off offset:3072
	v_lshl_add_u64 v[46:47], v[138:139], 0, s[4:5]
	s_add_i32 s4, s72, 0xffff8c00
	s_mov_b32 s5, s71
	global_load_dwordx4 v[18:21], v[30:31], off
	global_load_dwordx4 v[22:25], v[30:31], off offset:1024
	global_load_dwordx4 v[26:29], v[30:31], off offset:2048
	global_load_dwordx4 v[30:33], v[30:31], off offset:3072
	s_lshl_b64 s[4:5], s[4:5], 12
	global_load_dwordx4 v[34:37], v[46:47], off
	global_load_dwordx4 v[38:41], v[46:47], off offset:1024
	global_load_dwordx4 v[42:45], v[46:47], off offset:2048
	global_load_dwordx4 v[46:49], v[46:47], off offset:3072
	v_lshl_add_u64 v[62:63], v[138:139], 0, s[4:5]
	global_load_dwordx4 v[50:53], v[62:63], off
	global_load_dwordx4 v[54:57], v[62:63], off offset:1024
	global_load_dwordx4 v[58:61], v[62:63], off offset:2048
	global_load_dwordx4 v[148:151], v[62:63], off offset:3072
	s_waitcnt vmcnt(15)
	v_pk_add_f32 v[4:5], v[4:5], 0 op_sel_hi:[1,0]
	v_pk_add_f32 v[2:3], v[2:3], 0 op_sel_hi:[1,0]
	s_waitcnt vmcnt(14)
	v_pk_add_f32 v[8:9], v[8:9], 0 op_sel_hi:[1,0]
	v_pk_add_f32 v[6:7], v[6:7], 0 op_sel_hi:[1,0]
	s_waitcnt vmcnt(13)
	v_pk_add_f32 v[12:13], v[12:13], 0 op_sel_hi:[1,0]
	v_pk_add_f32 v[10:11], v[10:11], 0 op_sel_hi:[1,0]
	s_waitcnt vmcnt(12)
	v_pk_add_f32 v[16:17], v[16:17], 0 op_sel_hi:[1,0]
	v_pk_add_f32 v[14:15], v[14:15], 0 op_sel_hi:[1,0]
	s_waitcnt vmcnt(11)
	v_pk_add_f32 v[4:5], v[4:5], v[20:21]
	v_pk_add_f32 v[2:3], v[2:3], v[18:19]
	s_waitcnt vmcnt(10)
	v_pk_add_f32 v[8:9], v[8:9], v[24:25]
	v_pk_add_f32 v[6:7], v[6:7], v[22:23]
	s_waitcnt vmcnt(9)
	v_pk_add_f32 v[12:13], v[12:13], v[28:29]
	v_pk_add_f32 v[10:11], v[10:11], v[26:27]
	s_waitcnt vmcnt(8)
	v_pk_add_f32 v[16:17], v[16:17], v[32:33]
	v_pk_add_f32 v[14:15], v[14:15], v[30:31]
	s_waitcnt vmcnt(7)
	v_pk_add_f32 v[4:5], v[4:5], v[36:37]
	v_pk_add_f32 v[2:3], v[2:3], v[34:35]
	s_waitcnt vmcnt(6)
	v_pk_add_f32 v[8:9], v[8:9], v[40:41]
	v_pk_add_f32 v[6:7], v[6:7], v[38:39]
	s_waitcnt vmcnt(5)
	v_pk_add_f32 v[12:13], v[12:13], v[44:45]
	v_pk_add_f32 v[10:11], v[10:11], v[42:43]
	s_waitcnt vmcnt(4)
	v_pk_add_f32 v[16:17], v[16:17], v[48:49]
	v_pk_add_f32 v[14:15], v[14:15], v[46:47]
	s_waitcnt vmcnt(3)
	v_pk_add_f32 v[64:65], v[4:5], v[52:53]
	v_pk_add_f32 v[62:63], v[2:3], v[50:51]
	s_waitcnt vmcnt(2)
	v_pk_add_f32 v[44:45], v[8:9], v[56:57]
	v_pk_add_f32 v[42:43], v[6:7], v[54:55]
	s_waitcnt vmcnt(1)
	v_pk_add_f32 v[40:41], v[12:13], v[60:61]
	v_pk_add_f32 v[38:39], v[10:11], v[58:59]
	s_waitcnt vmcnt(0)
	v_pk_add_f32 v[36:37], v[16:17], v[150:151]
	v_pk_add_f32 v[34:35], v[14:15], v[148:149]

; template <int NS> __device__ __forceinline__ void load16part(const float* P, int rowrel, int lane, f32x4 (&v)[4]) {
; #pragma unroll
;     for (int j = 0; j < 4; ++j) v[j] = (f32x4){0.f, 0.f, 0.f, 0.f};
; #pragma unroll
;     for (int s0 = 0; s0 < NS; s0 += 4) { f32x4 t[4][4];
; #pragma unroll
;         for (int s = 0; s < 4; ++s) { const f32x4* q = (const f32x4*)(P + ((size_t)(s0 + s) * 1024 + rowrel) * 1024);
; #pragma unroll
;             for (int j = 0; j < 4; ++j) t[s][j] = q[lane + 64 * j]; }
; #pragma unroll
;         for (int s = 0; s < 4; ++s)
; #pragma unroll
;             for (int j = 0; j < 4; ++j) v[j] += t[s][j]; }
; }
.LBB0_820:
	s_andn2_b64 vcc, exec, s[50:51]
	s_cbranch_vccnz .LBB0_822
	s_add_i32 s4, s94, 0xffff8000
	s_mov_b32 s5, s71
	s_lshl_b64 s[4:5], s[4:5], 12
	v_lshl_add_u64 v[14:15], v[138:139], 0, s[4:5]
	s_add_i32 s4, s94, 0xffff8400
	s_mov_b32 s5, s71
	s_lshl_b64 s[4:5], s[4:5], 12
	v_lshl_add_u64 v[30:31], v[138:139], 0, s[4:5]
	s_add_i32 s4, s94, 0xffff8800
	s_mov_b32 s5, s71
	s_lshl_b64 s[4:5], s[4:5], 12
	global_load_dwordx4 v[2:5], v[14:15], off
	global_load_dwordx4 v[6:9], v[14:15], off offset:1024
	global_load_dwordx4 v[10:13], v[14:15], off offset:2048
	global_load_dwordx4 v[14:17], v[14:15], off offset:3072
	v_lshl_add_u64 v[160:161], v[138:139], 0, s[4:5]
	s_add_i32 s4, s94, 0xffff8c00
	s_mov_b32 s5, s71
	global_load_dwordx4 v[18:21], v[30:31], off
	global_load_dwordx4 v[22:25], v[30:31], off offset:1024
	global_load_dwordx4 v[26:29], v[30:31], off offset:2048
	global_load_dwordx4 v[30:33], v[30:31], off offset:3072
	s_lshl_b64 s[4:5], s[4:5], 12
	global_load_dwordx4 v[148:151], v[160:161], off
	global_load_dwordx4 v[152:155], v[160:161], off offset:1024
	global_load_dwordx4 v[156:159], v[160:161], off offset:2048
	global_load_dwordx4 v[160:163], v[160:161], off offset:3072
	v_lshl_add_u64 v[172:173], v[138:139], 0, s[4:5]
	global_load_dwordx4 v[164:167], v[172:173], off
	global_load_dwordx4 v[168:171], v[172:173], off offset:1024
	global_load_dwordx4 v[178:181], v[172:173], off offset:2048
	global_load_dwordx4 v[182:185], v[172:173], off offset:3072
	s_waitcnt vmcnt(15)
	v_pk_add_f32 v[4:5], v[4:5], 0 op_sel_hi:[1,0]
	v_pk_add_f32 v[2:3], v[2:3], 0 op_sel_hi:[1,0]
	s_waitcnt vmcnt(14)
	v_pk_add_f32 v[8:9], v[8:9], 0 op_sel_hi:[1,0]
	v_pk_add_f32 v[6:7], v[6:7], 0 op_sel_hi:[1,0]
	s_waitcnt vmcnt(13)
	v_pk_add_f32 v[12:13], v[12:13], 0 op_sel_hi:[1,0]
	v_pk_add_f32 v[10:11], v[10:11], 0 op_sel_hi:[1,0]
	s_waitcnt vmcnt(12)
	v_pk_add_f32 v[16:17], v[16:17], 0 op_sel_hi:[1,0]
	v_pk_add_f32 v[14:15], v[14:15], 0 op_sel_hi:[1,0]
	s_waitcnt vmcnt(11)
	v_pk_add_f32 v[4:5], v[4:5], v[20:21]
	v_pk_add_f32 v[2:3], v[2:3], v[18:19]
	s_waitcnt vmcnt(10)
	v_pk_add_f32 v[8:9], v[8:9], v[24:25]
	v_pk_add_f32 v[6:7], v[6:7], v[22:23]
	s_waitcnt vmcnt(9)
	v_pk_add_f32 v[12:13], v[12:13], v[28:29]
	v_pk_add_f32 v[10:11], v[10:11], v[26:27]
	s_waitcnt vmcnt(8)
	v_pk_add_f32 v[16:17], v[16:17], v[32:33]
	v_pk_add_f32 v[14:15], v[14:15], v[30:31]
	s_waitcnt vmcnt(7)
	v_pk_add_f32 v[4:5], v[4:5], v[150:151]
	v_pk_add_f32 v[2:3], v[2:3], v[148:149]
	s_waitcnt vmcnt(6)
	v_pk_add_f32 v[8:9], v[8:9], v[154:155]
	v_pk_add_f32 v[6:7], v[6:7], v[152:153]
	s_waitcnt vmcnt(5)
	v_pk_add_f32 v[18:19], v[12:13], v[158:159]
	v_pk_add_f32 v[20:21], v[10:11], v[156:157]
	s_waitcnt vmcnt(4)
	v_pk_add_f32 v[16:17], v[16:17], v[162:163]
	v_pk_add_f32 v[14:15], v[14:15], v[160:161]
	s_waitcnt vmcnt(3)
	v_pk_add_f32 v[32:33], v[4:5], v[166:167]
	v_pk_add_f32 v[30:31], v[2:3], v[164:165]
	s_waitcnt vmcnt(2)
	v_pk_add_f32 v[12:13], v[8:9], v[170:171]
	v_pk_add_f32 v[10:11], v[6:7], v[168:169]
	s_waitcnt vmcnt(1)
	v_pk_add_f32 v[8:9], v[18:19], v[180:181]
	v_pk_add_f32 v[6:7], v[20:21], v[178:179]
	s_waitcnt vmcnt(0)
	v_pk_add_f32 v[4:5], v[16:17], v[184:185]
	v_pk_add_f32 v[2:3], v[14:15], v[182:183]

; __device__ __forceinline__ float ssq16(const f32x4 (&v)[4]) {
;     float s = 0.f;
; #pragma unroll
;     for (int j = 0; j < 4; ++j) s += (v[j].x * v[j].x + v[j].y * v[j].y) + (v[j].z * v[j].z + v[j].w * v[j].w);
;     return wave_sum(s);
; }
.LBB0_837:
	v_pk_mul_f32 v[148:149], v[124:125], v[124:125]
	v_pk_mul_f32 v[150:151], v[122:123], v[122:123]
	v_mul_f32_e32 v0, v98, v98
	v_pk_mov_b32 v[152:153], v[150:151], v[148:149] op_sel:[1,0]
	v_mov_b32_e32 v151, v149
	v_pk_add_f32 v[148:149], v[152:153], v[150:151]
	v_pk_mul_f32 v[150:151], v[108:109], v[108:109]
	v_pk_mul_f32 v[152:153], v[106:107], v[106:107]
	v_mul_f32_e32 v147, v99, v99
	v_pk_mov_b32 v[154:155], v[152:153], v[150:151] op_sel:[1,0]
	v_mov_b32_e32 v153, v151
	v_pk_add_f32 v[150:151], v[154:155], v[152:153]
	v_pk_add_f32 v[148:149], v[148:149], v[148:149] op_sel:[0,1] op_sel_hi:[1,0]
	v_pk_add_f32 v[150:151], v[150:151], v[150:151] op_sel:[0,1] op_sel_hi:[1,0]
	v_mov_b32_e32 v149, v0
	v_mov_b32_e32 v151, v147
	v_mul_f32_e32 v0, v103, v103
	v_mul_f32_e32 v152, v100, v100
	v_pk_add_f32 v[148:149], v[148:149], v[150:151]
	v_pk_fma_f32 v[150:151], v[102:103], v[102:103], v[0:1] op_sel_hi:[1,1,0]
	v_mul_f32_e32 v0, v105, v105
	v_mul_f32_e32 v154, v101, v101
	v_mov_b32_e32 v151, v152
	v_pk_fma_f32 v[152:153], v[104:105], v[104:105], v[0:1] op_sel_hi:[1,1,0]
	s_ashr_i32 s1, s0, 31
	v_mov_b32_e32 v153, v154
	v_pk_add_f32 v[150:151], v[150:151], v[152:153]
	s_lshr_b32 s1, s1, 19
	v_pk_add_f32 v[148:149], v[148:149], v[150:151]
	s_add_i32 s0, s0, s1
	v_add_f32_e32 v0, v148, v149
	s_ashr_i32 s4, s0, 13
	s_and_b64 s[0:1], s[86:87], exec
	v_add_f32_dpp v0, v0, v0 quad_perm:[1,0,3,2] row_mask:0xf bank_mask:0xf bound_ctrl:1
	s_cselect_b32 s0, s4, 4
	v_mov_b32_e32 v147, v1
	v_add_f32_dpp v0, v0, v0 quad_perm:[2,3,0,1] row_mask:0xf bank_mask:0xf bound_ctrl:1
	s_add_i32 s0, s0, s92
	s_mulk_i32 s0, 0x1800
	v_add_f32_dpp v0, v0, v0 row_half_mirror row_mask:0xf bank_mask:0xf bound_ctrl:1
	s_ashr_i32 s1, s0, 31
	s_lshl_b64 s[0:1], s[0:1], 2
	v_add_f32_dpp v0, v0, v0 row_mirror row_mask:0xf bank_mask:0xf bound_ctrl:1
	s_add_u32 s4, s62, s0
	s_addc_u32 s5, s63, s1
	v_mov_b32_dpp v147, v0 row_bcast:15 row_mask:0xa bank_mask:0xf
	v_add_f32_e32 v0, v0, v147
	v_mov_b32_e32 v147, v1
	s_nop 1
	v_mov_b32_dpp v147, v0 row_bcast:31 row_mask:0xc bank_mask:0xf
	v_add_f32_e32 v0, v0, v147
	s_nop 0
	v_readlane_b32 s0, v0, 63
	s_nop 1
	v_cvt_i32_f32_e32 v0, s0
	s_add_u32 s0, s4, 0x2000
	s_addc_u32 s1, s5, 0
	global_load_dwordx4 v[148:151], v131, s[0:1]
	v_cvt_f32_i32_e32 v0, v0
	s_add_u32 s86, s4, 0x3000
	s_addc_u32 s87, s5, 0
	v_fmamk_f32 v0, v0, 0x3a800000, v211
	v_cmp_gt_f32_e32 vcc, s68, v0
	v_mul_f32_e32 v147, 0x4b800000, v0
	s_nop 0
	v_cndmask_b32_e32 v0, v0, v147, vcc
	v_rsq_f32_e32 v0, v0
	s_nop 0
	v_mul_f32_e32 v147, 0x45800000, v0
	v_cndmask_b32_e32 v0, v0, v147, vcc
	v_pk_mul_f32 v[152:153], v[0:1], v[124:125] op_sel_hi:[0,1]
	v_pk_mul_f32 v[154:155], v[0:1], v[122:123] op_sel_hi:[0,1]
	global_load_dwordx4 v[122:125], v[136:137], off
	s_waitcnt vmcnt(0)
	v_pk_mul_f32 v[122:123], v[154:155], v[122:123]
	v_pk_mul_f32 v[124:125], v[152:153], v[124:125]
	v_pk_fma_f32 v[122:123], v[148:149], v[122:123], v[126:127]
	v_pk_fma_f32 v[124:125], v[150:151], v[124:125], v[128:129]
	global_store_dwordx4 v131, v[122:125], s[88:89] nt
	v_pk_mul_f32 v[148:149], v[0:1], v[106:107] op_sel_hi:[0,1]
	v_pk_mul_f32 v[150:151], v[0:1], v[108:109] op_sel_hi:[0,1]
	global_load_dwordx4 v[106:109], v[136:137], off offset:1024
	global_load_dwordx4 v[126:129], v144, s[0:1]
	s_waitcnt vmcnt(1)
	v_pk_mul_f32 v[108:109], v[150:151], v[108:109]
	v_pk_mul_f32 v[106:107], v[148:149], v[106:107]
	s_waitcnt vmcnt(0)
	v_pk_fma_f32 v[108:109], v[128:129], v[108:109], v[120:121]
	v_pk_fma_f32 v[106:107], v[126:127], v[106:107], v[118:119]
	global_store_dwordx4 v131, v[106:109], s[88:89] offset:1024 nt
	v_pk_mul_f32 v[126:127], v[0:1], v[102:103] op_sel_hi:[0,1]
	v_pk_mul_f32 v[128:129], v[0:1], v[104:105] op_sel_hi:[0,1]
	global_load_dwordx4 v[102:105], v[136:137], off offset:2048
	global_load_dwordx4 v[118:121], v145, s[0:1]
	s_waitcnt vmcnt(1)
	v_pk_mul_f32 v[104:105], v[128:129], v[104:105]
	v_pk_mul_f32 v[102:103], v[126:127], v[102:103]
	s_waitcnt vmcnt(0)
	v_pk_fma_f32 v[104:105], v[120:121], v[104:105], v[116:117]
	v_pk_fma_f32 v[102:103], v[118:119], v[102:103], v[114:115]
	global_store_dwordx4 v131, v[102:105], s[88:89] offset:2048 nt
	v_pk_mul_f32 v[118:119], v[0:1], v[100:101] op_sel_hi:[0,1]
	v_pk_mul_f32 v[120:121], v[0:1], v[98:99] op_sel_hi:[0,1]
	global_load_dwordx4 v[98:101], v[136:137], off offset:3072
	global_load_dwordx4 v[114:117], v146, s[0:1]
	s_waitcnt vmcnt(1)
	v_pk_mul_f32 v[98:99], v[120:121], v[98:99]
	v_pk_mul_f32 v[100:101], v[118:119], v[100:101]
	s_waitcnt vmcnt(0)
; __device__ __forceinline__ unsigned cvtpk(float lo, float hi) { unsigned r; asm volatile("v_cvt_pk_bf16_f32 %0, %1, %2" : "=v"(r) : "v"(lo), "v"(hi)); return r; }
; __device__ __forceinline__ void prenorm_store(const f32x4 (&v)[4], float rinv, const float* g, const float* shift, const float* scale, bf16_t* orow, int lane) {
; #pragma unroll
;     for (int j = 0; j < 4; ++j) { const int q = lane + 64 * j; const f32x4 gg = ((const f32x4*)g)[q], sh = ((const f32x4*)shift)[q], sc = ((const f32x4*)scale)[q];
;         const f32x4 h = (v[j] * rinv * gg) * (sc + 1.0f) + sh; u32x2 w; w.x = cvtpk(h.x, h.y); w.y = cvtpk(h.z, h.w); ((u32x2*)orow)[q] = w; }
; }
	v_pk_fma_f32 v[98:99], v[114:115], v[98:99], v[110:111]
	v_pk_fma_f32 v[100:101], v[116:117], v[100:101], v[112:113]
	v_pk_mul_f32 v[110:111], v[124:125], v[124:125]
	v_pk_mul_f32 v[112:113], v[122:123], v[122:123]
	v_mul_f32_e32 v0, v98, v98
	v_pk_mov_b32 v[114:115], v[112:113], v[110:111] op_sel:[1,0]
	v_mov_b32_e32 v113, v111
	v_pk_add_f32 v[110:111], v[114:115], v[112:113]
	v_pk_mul_f32 v[112:113], v[106:107], v[106:107]
	v_pk_mul_f32 v[114:115], v[108:109], v[108:109]
	v_pk_add_f32 v[110:111], v[110:111], v[110:111] op_sel:[0,1] op_sel_hi:[1,0]
	v_pk_mov_b32 v[116:117], v[112:113], v[114:115] op_sel:[1,0]
	v_mov_b32_e32 v113, v115
	v_pk_add_f32 v[112:113], v[116:117], v[112:113]
	v_mul_f32_e32 v114, v99, v99
	v_pk_add_f32 v[112:113], v[112:113], v[112:113] op_sel:[0,1] op_sel_hi:[1,0]
	v_mov_b32_e32 v111, v0
	v_mov_b32_e32 v113, v114
	v_mul_f32_e32 v0, v103, v103
	v_mul_f32_e32 v115, v100, v100
	v_pk_add_f32 v[110:111], v[110:111], v[112:113]
	v_pk_fma_f32 v[112:113], v[102:103], v[102:103], v[0:1] op_sel_hi:[1,1,0]
	v_mul_f32_e32 v0, v105, v105
	v_mul_f32_e32 v116, v101, v101
	v_mov_b32_e32 v113, v115
	v_pk_fma_f32 v[114:115], v[104:105], v[104:105], v[0:1] op_sel_hi:[1,1,0]
	global_store_dwordx4 v131, v[98:101], s[88:89] offset:3072 nt
	v_mov_b32_e32 v115, v116
	v_pk_add_f32 v[112:113], v[112:113], v[114:115]
	s_nop 0
	v_pk_add_f32 v[110:111], v[110:111], v[112:113]
	s_nop 0
	v_add_f32_e32 v0, v110, v111
	v_mov_b32_e32 v110, v1
	s_nop 0
	v_add_f32_dpp v0, v0, v0 quad_perm:[1,0,3,2] row_mask:0xf bank_mask:0xf bound_ctrl:1
	s_nop 1
	v_add_f32_dpp v0, v0, v0 quad_perm:[2,3,0,1] row_mask:0xf bank_mask:0xf bound_ctrl:1
	s_nop 1
	v_add_f32_dpp v0, v0, v0 row_half_mirror row_mask:0xf bank_mask:0xf bound_ctrl:1
	s_nop 1
	v_add_f32_dpp v0, v0, v0 row_mirror row_mask:0xf bank_mask:0xf bound_ctrl:1
	s_nop 1
	v_mov_b32_dpp v110, v0 row_bcast:15 row_mask:0xa bank_mask:0xf
	v_add_f32_e32 v0, v0, v110
	v_mov_b32_e32 v110, v1
	s_nop 1
	v_mov_b32_dpp v110, v0 row_bcast:31 row_mask:0xc bank_mask:0xf
	v_add_f32_e32 v0, v0, v110
	s_nop 0
	v_readlane_b32 s0, v0, 63
	s_nop 1
	v_cvt_i32_f32_e32 v0, s0
	s_add_u32 s0, s4, 0x4000
	s_addc_u32 s1, s5, 0
	s_lshl_b64 s[6:7], s[6:7], 11
	v_cvt_f32_i32_e32 v0, v0
	v_fmamk_f32 v0, v0, 0x3a800000, v211
	v_cmp_gt_f32_e32 vcc, s68, v0
	v_mul_f32_e32 v110, 0x4b800000, v0
	s_nop 0
	v_cndmask_b32_e32 v0, v0, v110, vcc
	v_rsq_f32_e32 v0, v0
	s_nop 0
	v_mul_f32_e32 v110, 0x45800000, v0
	v_cndmask_b32_e32 v0, v0, v110, vcc
	global_load_dwordx4 v[110:113], v[134:135], off
	global_load_dwordx4 v[114:117], v131, s[86:87]
	global_load_dwordx4 v[118:121], v131, s[0:1]
	v_pk_mul_f32 v[122:123], v[122:123], v[0:1] op_sel_hi:[1,0]
	v_pk_mul_f32 v[124:125], v[124:125], v[0:1] op_sel_hi:[1,0]
	v_pk_mul_f32 v[108:109], v[108:109], v[0:1] op_sel_hi:[1,0]
	v_pk_mul_f32 v[106:107], v[106:107], v[0:1] op_sel_hi:[1,0]
	v_pk_mul_f32 v[104:105], v[104:105], v[0:1] op_sel_hi:[1,0]
	v_pk_mul_f32 v[102:103], v[102:103], v[0:1] op_sel_hi:[1,0]
	v_pk_mul_f32 v[100:101], v[100:101], v[0:1] op_sel_hi:[1,0]
	v_pk_mul_f32 v[98:99], v[98:99], v[0:1] op_sel_hi:[1,0]
	s_andn2_b64 vcc, exec, s[84:85]
	s_waitcnt vmcnt(2)
	v_pk_mul_f32 v[110:111], v[110:111], v[122:123]
	v_pk_mul_f32 v[112:113], v[112:113], v[124:125]
	s_waitcnt vmcnt(0)
	v_pk_add_f32 v[118:119], v[118:119], 1.0 op_sel_hi:[1,0]
	v_pk_add_f32 v[120:121], v[120:121], 1.0 op_sel_hi:[1,0]
	v_pk_fma_f32 v[110:111], v[118:119], v[110:111], v[114:115]
	v_lshl_add_u64 v[122:123], v[140:141], 0, s[6:7]
	v_pk_fma_f32 v[112:113], v[120:121], v[112:113], v[116:117]
	v_cvt_pk_bf16_f32 v110, v110, v111
	s_nop 0
	v_cvt_pk_bf16_f32 v111, v112, v113
	global_store_dwordx2 v[122:123], v[110:111], off
	global_load_dwordx4 v[110:113], v[134:135], off offset:1024
	global_load_dwordx4 v[114:117], v144, s[86:87]
	global_load_dwordx4 v[118:121], v144, s[0:1]
	s_waitcnt vmcnt(2)
	v_pk_mul_f32 v[106:107], v[110:111], v[106:107]
	v_pk_mul_f32 v[108:109], v[112:113], v[108:109]
	s_waitcnt vmcnt(0)
	v_pk_add_f32 v[112:113], v[118:119], 1.0 op_sel_hi:[1,0]
	v_pk_add_f32 v[110:111], v[120:121], 1.0 op_sel_hi:[1,0]
	v_pk_fma_f32 v[106:107], v[112:113], v[106:107], v[114:115]
	v_pk_fma_f32 v[108:109], v[110:111], v[108:109], v[116:117]
	v_cvt_pk_bf16_f32 v106, v106, v107
	s_nop 0
	v_cvt_pk_bf16_f32 v107, v108, v109
	global_store_dwordx2 v[122:123], v[106:107], off offset:512
	global_load_dwordx4 v[106:109], v[134:135], off offset:2048
	global_load_dwordx4 v[110:113], v145, s[86:87]
	global_load_dwordx4 v[114:117], v145, s[0:1]
	s_waitcnt vmcnt(2)
	v_pk_mul_f32 v[102:103], v[102:103], v[106:107]
	v_pk_mul_f32 v[104:105], v[104:105], v[108:109]
	s_waitcnt vmcnt(0)
	v_pk_add_f32 v[108:109], v[114:115], 1.0 op_sel_hi:[1,0]
	v_pk_add_f32 v[106:107], v[116:117], 1.0 op_sel_hi:[1,0]
	v_pk_fma_f32 v[102:103], v[102:103], v[108:109], v[110:111]
	v_pk_fma_f32 v[104:105], v[104:105], v[106:107], v[112:113]
	v_cvt_pk_bf16_f32 v102, v102, v103
	s_nop 0
	v_cvt_pk_bf16_f32 v103, v104, v105
	global_store_dwordx2 v[122:123], v[102:103], off offset:1024
	global_load_dwordx4 v[102:105], v[134:135], off offset:3072
	global_load_dwordx4 v[106:109], v146, s[86:87]
	global_load_dwordx4 v[110:113], v146, s[0:1]
	s_waitcnt vmcnt(2)
	v_pk_mul_f32 v[98:99], v[98:99], v[102:103]
	v_pk_mul_f32 v[100:101], v[100:101], v[104:105]
	s_waitcnt vmcnt(0)
	v_pk_add_f32 v[104:105], v[110:111], 1.0 op_sel_hi:[1,0]
	v_pk_add_f32 v[102:103], v[112:113], 1.0 op_sel_hi:[1,0]
	v_pk_fma_f32 v[98:99], v[98:99], v[104:105], v[106:107]
	v_pk_fma_f32 v[100:101], v[100:101], v[102:103], v[108:109]
	v_cvt_pk_bf16_f32 v98, v98, v99
	s_nop 0
	v_cvt_pk_bf16_f32 v99, v100, v101
	global_store_dwordx2 v[122:123], v[98:99], off offset:1536
	s_cbranch_vccnz .LBB0_844
	s_cmp_lt_i32 s80, 0x8000
	s_cselect_b64 s[6:7], -1, 0
	s_mov_b64 s[50:51], -1
	s_and_b64 vcc, exec, s[6:7]
	s_cbranch_vccnz .LBB0_840
	s_mov_b32 s83, s71
	s_lshl_b64 s[0:1], s[82:83], 12
	s_add_u32 s0, s22, s0
	s_addc_u32 s1, s23, s1
	s_mov_b32 s81, s71
	s_mov_b64 s[50:51], 0

; __device__ __forceinline__ float ssq16(const f32x4 (&v)[4]) {
;     float s = 0.f;
; #pragma unroll
;     for (int j = 0; j < 4; ++j) s += (v[j].x * v[j].x + v[j].y * v[j].y) + (v[j].z * v[j].z + v[j].w * v[j].w);
;     return wave_sum(s);
; }
.LBB0_842:
	v_pk_mul_f32 v[98:99], v[96:97], v[96:97]
	v_pk_mul_f32 v[100:101], v[94:95], v[94:95]
	v_mul_f32_e32 v0, v66, v66
	v_pk_mov_b32 v[102:103], v[100:101], v[98:99] op_sel:[1,0]
	v_mov_b32_e32 v101, v99
	v_pk_add_f32 v[98:99], v[102:103], v[100:101]
	v_pk_mul_f32 v[100:101], v[76:77], v[76:77]
	v_pk_mul_f32 v[102:103], v[74:75], v[74:75]
	v_pk_add_f32 v[98:99], v[98:99], v[98:99] op_sel:[0,1] op_sel_hi:[1,0]
	v_pk_mov_b32 v[104:105], v[102:103], v[100:101] op_sel:[1,0]
	v_mov_b32_e32 v103, v101
	v_pk_add_f32 v[100:101], v[104:105], v[102:103]
	v_mul_f32_e32 v102, v67, v67
	v_pk_add_f32 v[100:101], v[100:101], v[100:101] op_sel:[0,1] op_sel_hi:[1,0]
	v_mov_b32_e32 v99, v0
	v_mov_b32_e32 v101, v102
	v_mul_f32_e32 v0, v71, v71
	v_mul_f32_e32 v103, v68, v68
	v_pk_add_f32 v[98:99], v[98:99], v[100:101]
	v_pk_fma_f32 v[100:101], v[70:71], v[70:71], v[0:1] op_sel_hi:[1,1,0]
	v_mul_f32_e32 v0, v73, v73
	v_mul_f32_e32 v104, v69, v69
	v_mov_b32_e32 v101, v103
	v_pk_fma_f32 v[102:103], v[72:73], v[72:73], v[0:1] op_sel_hi:[1,1,0]
	s_ashr_i32 s4, s80, 31
	v_mov_b32_e32 v103, v104
	v_pk_add_f32 v[100:101], v[100:101], v[102:103]
	s_lshr_b32 s4, s4, 19
	v_pk_add_f32 v[98:99], v[98:99], v[100:101]
	s_add_i32 s4, s80, s4
	v_add_f32_e32 v0, v98, v99
	v_mov_b32_e32 v98, v1
	s_ashr_i32 s9, s4, 13
	v_add_f32_dpp v0, v0, v0 quad_perm:[1,0,3,2] row_mask:0xf bank_mask:0xf bound_ctrl:1
	s_and_b64 s[4:5], exec, s[6:7]
	s_cselect_b32 s4, s9, 4
	v_add_f32_dpp v0, v0, v0 quad_perm:[2,3,0,1] row_mask:0xf bank_mask:0xf bound_ctrl:1
	s_add_i32 s4, s4, s92
	s_mulk_i32 s4, 0x1800
	v_add_f32_dpp v0, v0, v0 row_half_mirror row_mask:0xf bank_mask:0xf bound_ctrl:1
	s_ashr_i32 s5, s4, 31
	s_lshl_b64 s[4:5], s[4:5], 2
	v_add_f32_dpp v0, v0, v0 row_mirror row_mask:0xf bank_mask:0xf bound_ctrl:1
	s_add_u32 s4, s62, s4
	s_addc_u32 s5, s63, s5
	v_mov_b32_dpp v98, v0 row_bcast:15 row_mask:0xa bank_mask:0xf
	v_add_f32_e32 v0, v0, v98
	v_mov_b32_e32 v98, v1
	s_nop 1
	v_mov_b32_dpp v98, v0 row_bcast:31 row_mask:0xc bank_mask:0xf
	v_add_f32_e32 v0, v0, v98
	s_nop 0
	v_readlane_b32 s6, v0, 63
	s_nop 1
	v_cvt_i32_f32_e32 v0, s6
	s_add_u32 s6, s4, 0x2000
	s_addc_u32 s7, s5, 0
	v_cvt_f32_i32_e32 v0, v0
	v_fmamk_f32 v0, v0, 0x3a800000, v211
	v_cmp_gt_f32_e32 vcc, s68, v0
	v_mul_f32_e32 v98, 0x4b800000, v0
	s_nop 0
	v_cndmask_b32_e32 v0, v0, v98, vcc
	v_rsq_f32_e32 v0, v0
	s_nop 0
	v_mul_f32_e32 v98, 0x45800000, v0
	v_cndmask_b32_e32 v0, v0, v98, vcc
	v_pk_mul_f32 v[102:103], v[0:1], v[96:97] op_sel_hi:[0,1]
	v_pk_mul_f32 v[104:105], v[0:1], v[94:95] op_sel_hi:[0,1]
	global_load_dwordx4 v[94:97], v[136:137], off
	global_load_dwordx4 v[98:101], v131, s[6:7]
	s_waitcnt vmcnt(1)
	v_pk_mul_f32 v[94:95], v[104:105], v[94:95]
	v_pk_mul_f32 v[96:97], v[102:103], v[96:97]
	s_waitcnt vmcnt(0)
	v_pk_fma_f32 v[90:91], v[98:99], v[94:95], v[90:91]
	v_pk_fma_f32 v[92:93], v[100:101], v[96:97], v[92:93]
	global_store_dwordx4 v131, v[90:93], s[0:1] nt
	v_pk_mul_f32 v[98:99], v[0:1], v[74:75] op_sel_hi:[0,1]
	v_pk_mul_f32 v[100:101], v[0:1], v[76:77] op_sel_hi:[0,1]
	global_load_dwordx4 v[74:77], v[136:137], off offset:1024
	global_load_dwordx4 v[94:97], v144, s[6:7]
	s_waitcnt vmcnt(1)
	v_pk_mul_f32 v[76:77], v[100:101], v[76:77]
	v_pk_mul_f32 v[74:75], v[98:99], v[74:75]
	s_waitcnt vmcnt(0)
	v_pk_fma_f32 v[76:77], v[96:97], v[76:77], v[88:89]
	v_pk_fma_f32 v[74:75], v[94:95], v[74:75], v[86:87]
	global_store_dwordx4 v131, v[74:77], s[0:1] offset:1024 nt
	v_pk_mul_f32 v[94:95], v[0:1], v[70:71] op_sel_hi:[0,1]
	v_pk_mul_f32 v[96:97], v[0:1], v[72:73] op_sel_hi:[0,1]
	global_load_dwordx4 v[70:73], v[136:137], off offset:2048
	global_load_dwordx4 v[86:89], v145, s[6:7]
	s_waitcnt vmcnt(1)
	v_pk_mul_f32 v[72:73], v[96:97], v[72:73]
	v_pk_mul_f32 v[70:71], v[94:95], v[70:71]
	s_waitcnt vmcnt(0)
	v_pk_fma_f32 v[72:73], v[88:89], v[72:73], v[84:85]
	v_pk_fma_f32 v[70:71], v[86:87], v[70:71], v[82:83]
	global_store_dwordx4 v131, v[70:73], s[0:1] offset:2048 nt
	v_pk_mul_f32 v[86:87], v[0:1], v[68:69] op_sel_hi:[0,1]
	v_pk_mul_f32 v[88:89], v[0:1], v[66:67] op_sel_hi:[0,1]
	global_load_dwordx4 v[66:69], v[136:137], off offset:3072
	global_load_dwordx4 v[82:85], v146, s[6:7]
	s_add_u32 s6, s4, 0x3000
	s_addc_u32 s7, s5, 0
	s_waitcnt vmcnt(1)
	v_pk_mul_f32 v[66:67], v[88:89], v[66:67]
	v_pk_mul_f32 v[68:69], v[86:87], v[68:69]
	s_waitcnt vmcnt(0)
; __device__ __forceinline__ unsigned cvtpk(float lo, float hi) { unsigned r; asm volatile("v_cvt_pk_bf16_f32 %0, %1, %2" : "=v"(r) : "v"(lo), "v"(hi)); return r; }
; __device__ __forceinline__ void prenorm_store(const f32x4 (&v)[4], float rinv, const float* g, const float* shift, const float* scale, bf16_t* orow, int lane) {
; #pragma unroll
;     for (int j = 0; j < 4; ++j) { const int q = lane + 64 * j; const f32x4 gg = ((const f32x4*)g)[q], sh = ((const f32x4*)shift)[q], sc = ((const f32x4*)scale)[q];
;         const f32x4 h = (v[j] * rinv * gg) * (sc + 1.0f) + sh; u32x2 w; w.x = cvtpk(h.x, h.y); w.y = cvtpk(h.z, h.w); ((u32x2*)orow)[q] = w; }
; }
	v_pk_fma_f32 v[66:67], v[82:83], v[66:67], v[78:79]
	v_pk_fma_f32 v[68:69], v[84:85], v[68:69], v[80:81]
	v_pk_mul_f32 v[78:79], v[92:93], v[92:93]
	v_pk_mul_f32 v[80:81], v[90:91], v[90:91]
	v_mul_f32_e32 v0, v66, v66
	v_pk_mov_b32 v[82:83], v[80:81], v[78:79] op_sel:[1,0]
	v_mov_b32_e32 v81, v79
	v_pk_add_f32 v[78:79], v[82:83], v[80:81]
	v_pk_mul_f32 v[80:81], v[74:75], v[74:75]
	v_pk_mul_f32 v[82:83], v[76:77], v[76:77]
	v_pk_add_f32 v[78:79], v[78:79], v[78:79] op_sel:[0,1] op_sel_hi:[1,0]
	v_pk_mov_b32 v[84:85], v[80:81], v[82:83] op_sel:[1,0]
	v_mov_b32_e32 v81, v83
	v_pk_add_f32 v[80:81], v[84:85], v[80:81]
	v_mul_f32_e32 v82, v67, v67
	v_pk_add_f32 v[80:81], v[80:81], v[80:81] op_sel:[0,1] op_sel_hi:[1,0]
	v_mov_b32_e32 v79, v0
	v_mov_b32_e32 v81, v82
	v_mul_f32_e32 v0, v71, v71
	v_mul_f32_e32 v83, v68, v68
	v_pk_add_f32 v[78:79], v[78:79], v[80:81]
	v_pk_fma_f32 v[80:81], v[70:71], v[70:71], v[0:1] op_sel_hi:[1,1,0]
	v_mul_f32_e32 v0, v73, v73
	v_mul_f32_e32 v84, v69, v69
	v_mov_b32_e32 v81, v83
	v_pk_fma_f32 v[82:83], v[72:73], v[72:73], v[0:1] op_sel_hi:[1,1,0]
	global_store_dwordx4 v131, v[66:69], s[0:1] offset:3072 nt
	v_mov_b32_e32 v83, v84
	v_pk_add_f32 v[80:81], v[80:81], v[82:83]
	s_nop 0
	v_pk_add_f32 v[78:79], v[78:79], v[80:81]
	s_nop 0
	v_add_f32_e32 v0, v78, v79
	v_mov_b32_e32 v78, v1
	s_nop 0
	v_add_f32_dpp v0, v0, v0 quad_perm:[1,0,3,2] row_mask:0xf bank_mask:0xf bound_ctrl:1
	s_nop 1
	v_add_f32_dpp v0, v0, v0 quad_perm:[2,3,0,1] row_mask:0xf bank_mask:0xf bound_ctrl:1
	s_nop 1
	v_add_f32_dpp v0, v0, v0 row_half_mirror row_mask:0xf bank_mask:0xf bound_ctrl:1
	s_nop 1
	v_add_f32_dpp v0, v0, v0 row_mirror row_mask:0xf bank_mask:0xf bound_ctrl:1
	s_nop 1
	v_mov_b32_dpp v78, v0 row_bcast:15 row_mask:0xa bank_mask:0xf
	v_add_f32_e32 v0, v0, v78
	v_mov_b32_e32 v78, v1
	s_nop 1
	v_mov_b32_dpp v78, v0 row_bcast:31 row_mask:0xc bank_mask:0xf
	v_add_f32_e32 v0, v0, v78
	s_nop 0
	v_readlane_b32 s0, v0, 63
	s_nop 1
	v_cvt_i32_f32_e32 v0, s0
	s_add_u32 s0, s4, 0x4000
	s_addc_u32 s1, s5, 0
	s_lshl_b64 s[80:81], s[80:81], 11
	v_cvt_f32_i32_e32 v0, v0
	v_fmamk_f32 v0, v0, 0x3a800000, v211
	v_cmp_gt_f32_e32 vcc, s68, v0
	v_mul_f32_e32 v78, 0x4b800000, v0
	s_nop 0
	v_cndmask_b32_e32 v0, v0, v78, vcc
	v_rsq_f32_e32 v0, v0
	s_nop 0
	v_mul_f32_e32 v78, 0x45800000, v0
	v_cndmask_b32_e32 v0, v0, v78, vcc
	global_load_dwordx4 v[78:81], v[134:135], off
	global_load_dwordx4 v[82:85], v131, s[6:7]
	global_load_dwordx4 v[86:89], v131, s[0:1]
	v_pk_mul_f32 v[90:91], v[90:91], v[0:1] op_sel_hi:[1,0]
	v_pk_mul_f32 v[92:93], v[92:93], v[0:1] op_sel_hi:[1,0]
	v_pk_mul_f32 v[76:77], v[76:77], v[0:1] op_sel_hi:[1,0]
	v_pk_mul_f32 v[74:75], v[74:75], v[0:1] op_sel_hi:[1,0]
	v_pk_mul_f32 v[72:73], v[72:73], v[0:1] op_sel_hi:[1,0]
	v_pk_mul_f32 v[70:71], v[70:71], v[0:1] op_sel_hi:[1,0]
	v_pk_mul_f32 v[68:69], v[68:69], v[0:1] op_sel_hi:[1,0]
	v_pk_mul_f32 v[66:67], v[66:67], v[0:1] op_sel_hi:[1,0]
	s_waitcnt vmcnt(2)
	v_pk_mul_f32 v[78:79], v[78:79], v[90:91]
	v_pk_mul_f32 v[80:81], v[80:81], v[92:93]
	s_waitcnt vmcnt(0)
	v_pk_add_f32 v[86:87], v[86:87], 1.0 op_sel_hi:[1,0]
	v_pk_add_f32 v[88:89], v[88:89], 1.0 op_sel_hi:[1,0]
	v_pk_fma_f32 v[78:79], v[86:87], v[78:79], v[82:83]
	v_lshl_add_u64 v[90:91], v[140:141], 0, s[80:81]
	v_pk_fma_f32 v[80:81], v[88:89], v[80:81], v[84:85]
	v_cvt_pk_bf16_f32 v78, v78, v79
	s_nop 0
	v_cvt_pk_bf16_f32 v79, v80, v81
	global_store_dwordx2 v[90:91], v[78:79], off
	global_load_dwordx4 v[78:81], v[134:135], off offset:1024
	global_load_dwordx4 v[82:85], v144, s[6:7]
	global_load_dwordx4 v[86:89], v144, s[0:1]
	s_waitcnt vmcnt(2)
	v_pk_mul_f32 v[74:75], v[78:79], v[74:75]
	v_pk_mul_f32 v[76:77], v[80:81], v[76:77]
	s_waitcnt vmcnt(0)
	v_pk_add_f32 v[80:81], v[86:87], 1.0 op_sel_hi:[1,0]
	v_pk_add_f32 v[78:79], v[88:89], 1.0 op_sel_hi:[1,0]
	v_pk_fma_f32 v[74:75], v[80:81], v[74:75], v[82:83]
	v_pk_fma_f32 v[76:77], v[78:79], v[76:77], v[84:85]
	v_cvt_pk_bf16_f32 v74, v74, v75
	s_nop 0
	v_cvt_pk_bf16_f32 v75, v76, v77
	global_store_dwordx2 v[90:91], v[74:75], off offset:512
	global_load_dwordx4 v[74:77], v[134:135], off offset:2048
	global_load_dwordx4 v[78:81], v145, s[6:7]
	global_load_dwordx4 v[82:85], v145, s[0:1]
	s_waitcnt vmcnt(2)
	v_pk_mul_f32 v[70:71], v[70:71], v[74:75]
	v_pk_mul_f32 v[72:73], v[72:73], v[76:77]
	s_waitcnt vmcnt(0)
	v_pk_add_f32 v[76:77], v[82:83], 1.0 op_sel_hi:[1,0]
	v_pk_add_f32 v[74:75], v[84:85], 1.0 op_sel_hi:[1,0]
	v_pk_fma_f32 v[70:71], v[70:71], v[76:77], v[78:79]
	v_pk_fma_f32 v[72:73], v[72:73], v[74:75], v[80:81]
	v_cvt_pk_bf16_f32 v70, v70, v71
	s_nop 0
	v_cvt_pk_bf16_f32 v71, v72, v73
	global_store_dwordx2 v[90:91], v[70:71], off offset:1024
	global_load_dwordx4 v[70:73], v[134:135], off offset:3072
	global_load_dwordx4 v[74:77], v146, s[6:7]
	global_load_dwordx4 v[78:81], v146, s[0:1]
	s_waitcnt vmcnt(2)
	v_pk_mul_f32 v[66:67], v[66:67], v[70:71]
	v_pk_mul_f32 v[68:69], v[68:69], v[72:73]
	s_waitcnt vmcnt(0)
	v_pk_add_f32 v[72:73], v[78:79], 1.0 op_sel_hi:[1,0]
	v_pk_add_f32 v[70:71], v[80:81], 1.0 op_sel_hi:[1,0]
	v_pk_fma_f32 v[66:67], v[66:67], v[72:73], v[74:75]
	v_pk_fma_f32 v[68:69], v[68:69], v[70:71], v[76:77]
	v_cvt_pk_bf16_f32 v66, v66, v67
	s_nop 0
	v_cvt_pk_bf16_f32 v67, v68, v69
	global_store_dwordx2 v[90:91], v[66:67], off offset:1536
	s_andn2_b64 vcc, exec, s[48:49]
	s_cbranch_vccz .LBB0_845

; __device__ __forceinline__ float ssq16(const f32x4 (&v)[4]) {
;     float s = 0.f;
; #pragma unroll
;     for (int j = 0; j < 4; ++j) s += (v[j].x * v[j].x + v[j].y * v[j].y) + (v[j].z * v[j].z + v[j].w * v[j].w);
;     return wave_sum(s);
; }
.LBB0_849:
	v_pk_mul_f32 v[66:67], v[64:65], v[64:65]
	v_pk_mul_f32 v[68:69], v[62:63], v[62:63]
	v_mul_f32_e32 v0, v34, v34
	v_pk_mov_b32 v[70:71], v[68:69], v[66:67] op_sel:[1,0]
	v_mov_b32_e32 v69, v67
	v_pk_add_f32 v[66:67], v[70:71], v[68:69]
	v_pk_mul_f32 v[68:69], v[44:45], v[44:45]
	v_pk_mul_f32 v[70:71], v[42:43], v[42:43]
	v_pk_add_f32 v[66:67], v[66:67], v[66:67] op_sel:[0,1] op_sel_hi:[1,0]
	v_pk_mov_b32 v[72:73], v[70:71], v[68:69] op_sel:[1,0]
	v_mov_b32_e32 v71, v69
	v_pk_add_f32 v[68:69], v[72:73], v[70:71]
	v_mul_f32_e32 v70, v35, v35
	v_pk_add_f32 v[68:69], v[68:69], v[68:69] op_sel:[0,1] op_sel_hi:[1,0]
	v_mov_b32_e32 v67, v0
	v_mov_b32_e32 v69, v70
	v_mul_f32_e32 v0, v39, v39
	v_mul_f32_e32 v71, v36, v36
	v_pk_add_f32 v[66:67], v[66:67], v[68:69]
	v_pk_fma_f32 v[68:69], v[38:39], v[38:39], v[0:1] op_sel_hi:[1,1,0]
	v_mul_f32_e32 v0, v41, v41
	v_mul_f32_e32 v72, v37, v37
	v_mov_b32_e32 v69, v71
	v_pk_fma_f32 v[70:71], v[40:41], v[40:41], v[0:1] op_sel_hi:[1,1,0]
	s_ashr_i32 s4, s78, 31
	v_mov_b32_e32 v71, v72
	v_pk_add_f32 v[68:69], v[68:69], v[70:71]
	s_lshr_b32 s4, s4, 19
	v_pk_add_f32 v[66:67], v[66:67], v[68:69]
	s_add_i32 s4, s78, s4
	v_add_f32_e32 v0, v66, v67
	v_mov_b32_e32 v66, v1
	s_ashr_i32 s9, s4, 13
	v_add_f32_dpp v0, v0, v0 quad_perm:[1,0,3,2] row_mask:0xf bank_mask:0xf bound_ctrl:1
	s_and_b64 s[4:5], exec, s[6:7]
	s_cselect_b32 s4, s9, 4
	v_add_f32_dpp v0, v0, v0 quad_perm:[2,3,0,1] row_mask:0xf bank_mask:0xf bound_ctrl:1
	s_add_i32 s4, s4, s92
	s_mulk_i32 s4, 0x1800
	v_add_f32_dpp v0, v0, v0 row_half_mirror row_mask:0xf bank_mask:0xf bound_ctrl:1
	s_ashr_i32 s5, s4, 31
	s_lshl_b64 s[4:5], s[4:5], 2
	v_add_f32_dpp v0, v0, v0 row_mirror row_mask:0xf bank_mask:0xf bound_ctrl:1
	s_add_u32 s4, s62, s4
	s_addc_u32 s5, s63, s5
	v_mov_b32_dpp v66, v0 row_bcast:15 row_mask:0xa bank_mask:0xf
	v_add_f32_e32 v0, v0, v66
	v_mov_b32_e32 v66, v1
	s_nop 1
	v_mov_b32_dpp v66, v0 row_bcast:31 row_mask:0xc bank_mask:0xf
	v_add_f32_e32 v0, v0, v66
	s_nop 0
	v_readlane_b32 s6, v0, 63
	s_nop 1
	v_cvt_i32_f32_e32 v0, s6
	s_add_u32 s6, s4, 0x2000
	s_addc_u32 s7, s5, 0
	v_cvt_f32_i32_e32 v0, v0
	v_fmamk_f32 v0, v0, 0x3a800000, v211
	v_cmp_gt_f32_e32 vcc, s68, v0
	v_mul_f32_e32 v66, 0x4b800000, v0
	s_nop 0
	v_cndmask_b32_e32 v0, v0, v66, vcc
	v_rsq_f32_e32 v0, v0
	s_nop 0
	v_mul_f32_e32 v66, 0x45800000, v0
	v_cndmask_b32_e32 v0, v0, v66, vcc
	v_pk_mul_f32 v[70:71], v[0:1], v[64:65] op_sel_hi:[0,1]
	v_pk_mul_f32 v[72:73], v[0:1], v[62:63] op_sel_hi:[0,1]
	global_load_dwordx4 v[62:65], v[136:137], off
	global_load_dwordx4 v[66:69], v131, s[6:7]
	s_waitcnt vmcnt(1)
	v_pk_mul_f32 v[62:63], v[72:73], v[62:63]
	v_pk_mul_f32 v[64:65], v[70:71], v[64:65]
	s_waitcnt vmcnt(0)
	v_pk_fma_f32 v[58:59], v[66:67], v[62:63], v[58:59]
	v_pk_fma_f32 v[60:61], v[68:69], v[64:65], v[60:61]
	global_store_dwordx4 v131, v[58:61], s[0:1] nt
	v_pk_mul_f32 v[66:67], v[0:1], v[42:43] op_sel_hi:[0,1]
	v_pk_mul_f32 v[68:69], v[0:1], v[44:45] op_sel_hi:[0,1]
	global_load_dwordx4 v[42:45], v[136:137], off offset:1024
	global_load_dwordx4 v[62:65], v144, s[6:7]
	s_waitcnt vmcnt(1)
	v_pk_mul_f32 v[44:45], v[68:69], v[44:45]
	v_pk_mul_f32 v[42:43], v[66:67], v[42:43]
	s_waitcnt vmcnt(0)
	v_pk_fma_f32 v[44:45], v[64:65], v[44:45], v[56:57]
	v_pk_fma_f32 v[42:43], v[62:63], v[42:43], v[54:55]
	global_store_dwordx4 v131, v[42:45], s[0:1] offset:1024 nt
	v_pk_mul_f32 v[62:63], v[0:1], v[38:39] op_sel_hi:[0,1]
	v_pk_mul_f32 v[64:65], v[0:1], v[40:41] op_sel_hi:[0,1]
	global_load_dwordx4 v[38:41], v[136:137], off offset:2048
	global_load_dwordx4 v[54:57], v145, s[6:7]
	s_waitcnt vmcnt(1)
	v_pk_mul_f32 v[40:41], v[64:65], v[40:41]
	v_pk_mul_f32 v[38:39], v[62:63], v[38:39]
	s_waitcnt vmcnt(0)
	v_pk_fma_f32 v[40:41], v[56:57], v[40:41], v[52:53]
	v_pk_fma_f32 v[38:39], v[54:55], v[38:39], v[50:51]
	global_store_dwordx4 v131, v[38:41], s[0:1] offset:2048 nt
	v_pk_mul_f32 v[54:55], v[0:1], v[36:37] op_sel_hi:[0,1]
	v_pk_mul_f32 v[56:57], v[0:1], v[34:35] op_sel_hi:[0,1]
	global_load_dwordx4 v[34:37], v[136:137], off offset:3072
	global_load_dwordx4 v[50:53], v146, s[6:7]
	s_add_u32 s6, s4, 0x3000
	s_addc_u32 s7, s5, 0
	s_waitcnt vmcnt(1)
	v_pk_mul_f32 v[34:35], v[56:57], v[34:35]
	v_pk_mul_f32 v[36:37], v[54:55], v[36:37]
	s_waitcnt vmcnt(0)
; __device__ __forceinline__ unsigned cvtpk(float lo, float hi) { unsigned r; asm volatile("v_cvt_pk_bf16_f32 %0, %1, %2" : "=v"(r) : "v"(lo), "v"(hi)); return r; }
; __device__ __forceinline__ void prenorm_store(const f32x4 (&v)[4], float rinv, const float* g, const float* shift, const float* scale, bf16_t* orow, int lane) {
; #pragma unroll
;     for (int j = 0; j < 4; ++j) { const int q = lane + 64 * j; const f32x4 gg = ((const f32x4*)g)[q], sh = ((const f32x4*)shift)[q], sc = ((const f32x4*)scale)[q];
;         const f32x4 h = (v[j] * rinv * gg) * (sc + 1.0f) + sh; u32x2 w; w.x = cvtpk(h.x, h.y); w.y = cvtpk(h.z, h.w); ((u32x2*)orow)[q] = w; }
; }
	v_pk_fma_f32 v[34:35], v[50:51], v[34:35], v[46:47]
	v_pk_fma_f32 v[36:37], v[52:53], v[36:37], v[48:49]
	v_pk_mul_f32 v[46:47], v[60:61], v[60:61]
	v_pk_mul_f32 v[48:49], v[58:59], v[58:59]
	v_mul_f32_e32 v0, v34, v34
	v_pk_mov_b32 v[50:51], v[48:49], v[46:47] op_sel:[1,0]
	v_mov_b32_e32 v49, v47
	v_pk_add_f32 v[46:47], v[50:51], v[48:49]
	v_pk_mul_f32 v[48:49], v[42:43], v[42:43]
	v_pk_mul_f32 v[50:51], v[44:45], v[44:45]
	v_pk_add_f32 v[46:47], v[46:47], v[46:47] op_sel:[0,1] op_sel_hi:[1,0]
	v_pk_mov_b32 v[52:53], v[48:49], v[50:51] op_sel:[1,0]
	v_mov_b32_e32 v49, v51
	v_pk_add_f32 v[48:49], v[52:53], v[48:49]
	v_mul_f32_e32 v50, v35, v35
	v_pk_add_f32 v[48:49], v[48:49], v[48:49] op_sel:[0,1] op_sel_hi:[1,0]
	v_mov_b32_e32 v47, v0
	v_mov_b32_e32 v49, v50
	v_mul_f32_e32 v0, v39, v39
	v_mul_f32_e32 v51, v36, v36
	v_pk_add_f32 v[46:47], v[46:47], v[48:49]
	v_pk_fma_f32 v[48:49], v[38:39], v[38:39], v[0:1] op_sel_hi:[1,1,0]
	v_mul_f32_e32 v0, v41, v41
	v_mul_f32_e32 v52, v37, v37
	v_mov_b32_e32 v49, v51
	v_pk_fma_f32 v[50:51], v[40:41], v[40:41], v[0:1] op_sel_hi:[1,1,0]
	global_store_dwordx4 v131, v[34:37], s[0:1] offset:3072 nt
	v_mov_b32_e32 v51, v52
	v_pk_add_f32 v[48:49], v[48:49], v[50:51]
	s_nop 0
	v_pk_add_f32 v[46:47], v[46:47], v[48:49]
	s_nop 0
	v_add_f32_e32 v0, v46, v47
	v_mov_b32_e32 v46, v1
	s_nop 0
	v_add_f32_dpp v0, v0, v0 quad_perm:[1,0,3,2] row_mask:0xf bank_mask:0xf bound_ctrl:1
	s_nop 1
	v_add_f32_dpp v0, v0, v0 quad_perm:[2,3,0,1] row_mask:0xf bank_mask:0xf bound_ctrl:1
	s_nop 1
	v_add_f32_dpp v0, v0, v0 row_half_mirror row_mask:0xf bank_mask:0xf bound_ctrl:1
	s_nop 1
	v_add_f32_dpp v0, v0, v0 row_mirror row_mask:0xf bank_mask:0xf bound_ctrl:1
	s_nop 1
	v_mov_b32_dpp v46, v0 row_bcast:15 row_mask:0xa bank_mask:0xf
	v_add_f32_e32 v0, v0, v46
	v_mov_b32_e32 v46, v1
	s_nop 1
	v_mov_b32_dpp v46, v0 row_bcast:31 row_mask:0xc bank_mask:0xf
	v_add_f32_e32 v0, v0, v46
	s_nop 0
	v_readlane_b32 s0, v0, 63
	s_nop 1
	v_cvt_i32_f32_e32 v0, s0
	s_add_u32 s0, s4, 0x4000
	s_addc_u32 s1, s5, 0
	s_lshl_b64 s[28:29], s[78:79], 11
	v_cvt_f32_i32_e32 v0, v0
	v_fmamk_f32 v0, v0, 0x3a800000, v211
	v_cmp_gt_f32_e32 vcc, s68, v0
	v_mul_f32_e32 v46, 0x4b800000, v0
	s_nop 0
	v_cndmask_b32_e32 v0, v0, v46, vcc
	v_rsq_f32_e32 v0, v0
	s_nop 0
	v_mul_f32_e32 v46, 0x45800000, v0
	v_cndmask_b32_e32 v0, v0, v46, vcc
	global_load_dwordx4 v[46:49], v[134:135], off
	global_load_dwordx4 v[50:53], v131, s[6:7]
	global_load_dwordx4 v[54:57], v131, s[0:1]
	v_pk_mul_f32 v[58:59], v[58:59], v[0:1] op_sel_hi:[1,0]
	v_pk_mul_f32 v[60:61], v[60:61], v[0:1] op_sel_hi:[1,0]
	v_pk_mul_f32 v[44:45], v[44:45], v[0:1] op_sel_hi:[1,0]
	v_pk_mul_f32 v[42:43], v[42:43], v[0:1] op_sel_hi:[1,0]
	v_pk_mul_f32 v[40:41], v[40:41], v[0:1] op_sel_hi:[1,0]
	v_pk_mul_f32 v[38:39], v[38:39], v[0:1] op_sel_hi:[1,0]
	v_pk_mul_f32 v[36:37], v[36:37], v[0:1] op_sel_hi:[1,0]
	v_pk_mul_f32 v[34:35], v[34:35], v[0:1] op_sel_hi:[1,0]
	s_waitcnt vmcnt(2)
	v_pk_mul_f32 v[46:47], v[46:47], v[58:59]
	v_pk_mul_f32 v[48:49], v[48:49], v[60:61]
	s_waitcnt vmcnt(0)
	v_pk_add_f32 v[54:55], v[54:55], 1.0 op_sel_hi:[1,0]
	v_pk_add_f32 v[56:57], v[56:57], 1.0 op_sel_hi:[1,0]
	v_pk_fma_f32 v[46:47], v[54:55], v[46:47], v[50:51]
	v_lshl_add_u64 v[58:59], v[140:141], 0, s[28:29]
	v_pk_fma_f32 v[48:49], v[56:57], v[48:49], v[52:53]
	v_cvt_pk_bf16_f32 v46, v46, v47
	s_nop 0
	v_cvt_pk_bf16_f32 v47, v48, v49
	global_store_dwordx2 v[58:59], v[46:47], off
	global_load_dwordx4 v[46:49], v[134:135], off offset:1024
	global_load_dwordx4 v[50:53], v144, s[6:7]
	global_load_dwordx4 v[54:57], v144, s[0:1]
	s_waitcnt vmcnt(2)
	v_pk_mul_f32 v[42:43], v[46:47], v[42:43]
	v_pk_mul_f32 v[44:45], v[48:49], v[44:45]
	s_waitcnt vmcnt(0)
	v_pk_add_f32 v[48:49], v[54:55], 1.0 op_sel_hi:[1,0]
	v_pk_add_f32 v[46:47], v[56:57], 1.0 op_sel_hi:[1,0]
	v_pk_fma_f32 v[42:43], v[48:49], v[42:43], v[50:51]
	v_pk_fma_f32 v[44:45], v[46:47], v[44:45], v[52:53]
	v_cvt_pk_bf16_f32 v42, v42, v43
	s_nop 0
	v_cvt_pk_bf16_f32 v43, v44, v45
	global_store_dwordx2 v[58:59], v[42:43], off offset:512
	global_load_dwordx4 v[42:45], v[134:135], off offset:2048
	global_load_dwordx4 v[46:49], v145, s[6:7]
	global_load_dwordx4 v[50:53], v145, s[0:1]
	s_waitcnt vmcnt(2)
	v_pk_mul_f32 v[38:39], v[38:39], v[42:43]
	v_pk_mul_f32 v[40:41], v[40:41], v[44:45]
	s_waitcnt vmcnt(0)
	v_pk_add_f32 v[44:45], v[50:51], 1.0 op_sel_hi:[1,0]
	v_pk_add_f32 v[42:43], v[52:53], 1.0 op_sel_hi:[1,0]
	v_pk_fma_f32 v[38:39], v[38:39], v[44:45], v[46:47]
	v_pk_fma_f32 v[40:41], v[40:41], v[42:43], v[48:49]
	v_cvt_pk_bf16_f32 v38, v38, v39
	s_nop 0
	v_cvt_pk_bf16_f32 v39, v40, v41
	global_store_dwordx2 v[58:59], v[38:39], off offset:1024
	global_load_dwordx4 v[38:41], v[134:135], off offset:3072
	global_load_dwordx4 v[42:45], v146, s[6:7]
	global_load_dwordx4 v[46:49], v146, s[0:1]
	s_waitcnt vmcnt(2)
	v_pk_mul_f32 v[34:35], v[34:35], v[38:39]
	v_pk_mul_f32 v[36:37], v[36:37], v[40:41]
	s_waitcnt vmcnt(0)
	v_pk_add_f32 v[40:41], v[46:47], 1.0 op_sel_hi:[1,0]
	v_pk_add_f32 v[38:39], v[48:49], 1.0 op_sel_hi:[1,0]
	v_pk_fma_f32 v[34:35], v[34:35], v[40:41], v[42:43]
	v_pk_fma_f32 v[36:37], v[36:37], v[38:39], v[44:45]
	v_cvt_pk_bf16_f32 v34, v34, v35
	s_nop 0
	v_cvt_pk_bf16_f32 v35, v36, v37
	global_store_dwordx2 v[58:59], v[34:35], off offset:1536
	s_andn2_b64 vcc, exec, s[74:75]
	s_cbranch_vccnz .LBB0_772

; #define LOADY(m, y, ns) do { if ((m) >= NLAT) load16part<ns>(WSP(float, WS_PART), (m) - NLAT, lane, y); else load16bf(BY + (size_t)(m) * DM, lane, y); } while (0)
; #define R3_SRC(m) ((l == 0) ? ((m) < NLAT ? PIN(I_X) + (size_t)(m) * DM : PIN(I_CTX) + (size_t)((m) - NLAT) * DM) : (const float*)XS_ROW(m))
; template <int NS> __device__ __forceinline__ void load16part(const float* P, int rowrel, int lane, f32x4 (&v)[4]) {
; #pragma unroll
;     for (int j = 0; j < 4; ++j) v[j] = (f32x4){0.f, 0.f, 0.f, 0.f};
; #pragma unroll
;     for (int s0 = 0; s0 < NS; s0 += 4) { f32x4 t[4][4];
; #pragma unroll
;         for (int s = 0; s < 4; ++s) { const f32x4* q = (const f32x4*)(P + ((size_t)(s0 + s) * 1024 + rowrel) * 1024);
; #pragma unroll
;             for (int j = 0; j < 4; ++j) t[s][j] = q[lane + 64 * j]; }
; #pragma unroll
;         for (int s = 0; s < 4; ++s)
; #pragma unroll
;             for (int j = 0; j < 4; ++j) v[j] += t[s][j]; }
; }
; __global__ void __launch_bounds__(512, 2) fwd_megakernel(Params p) {
;     ...
;             for (int i = 0; i < 4; ++i) { const int mi = m0 + i * NGW, mc = mi < Mact ? mi : m0; LOADY(mc, yb[i], 4); load16(R3_SRC(mc), lane, xb[i]); }
.LBB0_861:
	s_andn2_b64 vcc, exec, s[0:1]
	s_cbranch_vccnz .LBB0_863
	s_add_i32 s70, s12, 0xffff8000
	s_lshl_b64 s[0:1], s[70:71], 12
	s_add_i32 s70, s12, 0xffff8400
	v_lshl_add_u64 v[14:15], v[184:185], 0, s[0:1]
	s_lshl_b64 s[0:1], s[70:71], 12
	s_add_i32 s70, s12, 0xffff8800
	global_load_dwordx4 v[2:5], v[14:15], off
	global_load_dwordx4 v[6:9], v[14:15], off offset:1024
	global_load_dwordx4 v[10:13], v[14:15], off offset:2048
	v_lshl_add_u64 v[30:31], v[184:185], 0, s[0:1]
	global_load_dwordx4 v[14:17], v[14:15], off offset:3072
	s_lshl_b64 s[0:1], s[70:71], 12
	s_add_i32 s70, s12, 0xffff8c00
	global_load_dwordx4 v[18:21], v[30:31], off
	global_load_dwordx4 v[22:25], v[30:31], off offset:1024
	global_load_dwordx4 v[26:29], v[30:31], off offset:2048
	v_lshl_add_u64 v[46:47], v[184:185], 0, s[0:1]
	global_load_dwordx4 v[30:33], v[30:31], off offset:3072
	s_lshl_b64 s[0:1], s[70:71], 12
	global_load_dwordx4 v[34:37], v[46:47], off
	global_load_dwordx4 v[38:41], v[46:47], off offset:1024
	global_load_dwordx4 v[42:45], v[46:47], off offset:2048
	v_lshl_add_u64 v[58:59], v[184:185], 0, s[0:1]
	global_load_dwordx4 v[46:49], v[46:47], off offset:3072
	global_load_dwordx4 v[50:53], v[58:59], off
	global_load_dwordx4 v[54:57], v[58:59], off offset:1024
	global_load_dwordx4 v[66:69], v[58:59], off offset:2048
	global_load_dwordx4 v[70:73], v[58:59], off offset:3072
	s_waitcnt vmcnt(15)
	v_pk_add_f32 v[4:5], v[4:5], 0 op_sel_hi:[1,0]
	v_pk_add_f32 v[2:3], v[2:3], 0 op_sel_hi:[1,0]
	s_waitcnt vmcnt(14)
	v_pk_add_f32 v[8:9], v[8:9], 0 op_sel_hi:[1,0]
	v_pk_add_f32 v[6:7], v[6:7], 0 op_sel_hi:[1,0]
	s_waitcnt vmcnt(13)
	v_pk_add_f32 v[12:13], v[12:13], 0 op_sel_hi:[1,0]
	v_pk_add_f32 v[10:11], v[10:11], 0 op_sel_hi:[1,0]
	s_waitcnt vmcnt(12)
	v_pk_add_f32 v[16:17], v[16:17], 0 op_sel_hi:[1,0]
	v_pk_add_f32 v[14:15], v[14:15], 0 op_sel_hi:[1,0]
	s_waitcnt vmcnt(11)
	v_pk_add_f32 v[4:5], v[4:5], v[20:21]
	v_pk_add_f32 v[2:3], v[2:3], v[18:19]
	s_waitcnt vmcnt(10)
	v_pk_add_f32 v[8:9], v[8:9], v[24:25]
	v_pk_add_f32 v[6:7], v[6:7], v[22:23]
	s_waitcnt vmcnt(9)
	v_pk_add_f32 v[12:13], v[12:13], v[28:29]
	v_pk_add_f32 v[10:11], v[10:11], v[26:27]
	s_waitcnt vmcnt(8)
	v_pk_add_f32 v[16:17], v[16:17], v[32:33]
	v_pk_add_f32 v[14:15], v[14:15], v[30:31]
	s_waitcnt vmcnt(7)
	v_pk_add_f32 v[4:5], v[4:5], v[36:37]
	v_pk_add_f32 v[2:3], v[2:3], v[34:35]
	s_waitcnt vmcnt(6)
	v_pk_add_f32 v[8:9], v[8:9], v[40:41]
	v_pk_add_f32 v[6:7], v[6:7], v[38:39]
	s_waitcnt vmcnt(5)
	v_pk_add_f32 v[12:13], v[12:13], v[44:45]
	v_pk_add_f32 v[10:11], v[10:11], v[42:43]
	s_waitcnt vmcnt(4)
	v_pk_add_f32 v[16:17], v[16:17], v[48:49]
	v_pk_add_f32 v[14:15], v[14:15], v[46:47]
	s_waitcnt vmcnt(3)
	v_pk_add_f32 v[64:65], v[4:5], v[52:53]
	v_pk_add_f32 v[62:63], v[2:3], v[50:51]
	s_waitcnt vmcnt(2)
	v_pk_add_f32 v[60:61], v[8:9], v[56:57]
	v_pk_add_f32 v[58:59], v[6:7], v[54:55]
	s_waitcnt vmcnt(1)
	v_pk_add_f32 v[56:57], v[12:13], v[68:69]
	v_pk_add_f32 v[54:55], v[10:11], v[66:67]
	s_waitcnt vmcnt(0)
	v_pk_add_f32 v[52:53], v[16:17], v[72:73]
	v_pk_add_f32 v[50:51], v[14:15], v[70:71]

; __device__ __forceinline__ float bflo(unsigned w) { return __uint_as_float(w << 16); }
; __device__ __forceinline__ float bfhi(unsigned w) { return __uint_as_float(w & 0xffff0000u); }
; #define LOADY(m, y, ns) do { if ((m) >= NLAT) load16part<ns>(WSP(float, WS_PART), (m) - NLAT, lane, y); else load16bf(BY + (size_t)(m) * DM, lane, y); } while (0)
; #define R3_SRC(m) ((l == 0) ? ((m) < NLAT ? PIN(I_X) + (size_t)(m) * DM : PIN(I_CTX) + (size_t)((m) - NLAT) * DM) : (const float*)XS_ROW(m))
; __device__ __forceinline__ void load16(const float* row, int lane, f32x4 (&v)[4]) {
; #pragma unroll
;     for (int j = 0; j < 4; ++j) v[j] = __builtin_nontemporal_load((const f32x4*)row + lane + 64 * j);
; }
; __device__ __forceinline__ void load16bf(const bf16_t* row, int lane, f32x4 (&v)[4]) {
; #pragma unroll
;     for (int j = 0; j < 4; ++j) { const u32x2 w = __builtin_nontemporal_load((const u32x2*)row + lane + 64 * j); v[j] = (f32x4){bflo(w.x), bfhi(w.x), bflo(w.y), bfhi(w.y)}; }
; }
; template <int NS> __device__ __forceinline__ void load16part(const float* P, int rowrel, int lane, f32x4 (&v)[4]) {
; #pragma unroll
;     for (int j = 0; j < 4; ++j) v[j] = (f32x4){0.f, 0.f, 0.f, 0.f};
; #pragma unroll
;     for (int s0 = 0; s0 < NS; s0 += 4) { f32x4 t[4][4];
; #pragma unroll
;         for (int s = 0; s < 4; ++s) { const f32x4* q = (const f32x4*)(P + ((size_t)(s0 + s) * 1024 + rowrel) * 1024);
; #pragma unroll
;             for (int j = 0; j < 4; ++j) t[s][j] = q[lane + 64 * j]; }
; #pragma unroll
;         for (int s = 0; s < 4; ++s)
; #pragma unroll
;             for (int j = 0; j < 4; ++j) v[j] += t[s][j]; }
; }
; __global__ void __launch_bounds__(512, 2) fwd_megakernel(Params p) {
;     ...
;         for (int m0 = gw; m0 < Mact; m0 += 4 * NGW) { f32x4 yb[4][4], xb[4][4]; const float* mod = MOD_ROW(l, m0);
; #pragma unroll
;             for (int i = 0; i < 4; ++i) { const int mi = m0 + i * NGW, mc = mi < Mact ? mi : m0; LOADY(mc, yb[i], 4); load16(R3_SRC(mc), lane, xb[i]); }
.LBB0_874:
	s_lshl_b64 s[4:5], s[4:5], 12
	s_waitcnt lgkmcnt(0)
	s_add_u32 s0, s0, s4
	s_addc_u32 s1, s1, s5
	global_load_dwordx4 v[110:113], v190, s[0:1] nt
	global_load_dwordx4 v[102:105], v190, s[0:1] offset:1024 nt
	global_load_dwordx4 v[90:93], v190, s[0:1] offset:2048 nt
	global_load_dwordx4 v[82:85], v190, s[0:1] offset:3072 nt
	s_add_i32 s16, s12, 0x800
	s_cmp_lt_i32 s16, s53
	s_cselect_b64 s[8:9], -1, 0
	s_and_b64 s[0:1], s[8:9], exec
	s_cselect_b32 s0, s16, s12
	s_cmpk_gt_i32 s0, 0x7fff
	s_mov_b64 s[4:5], -1
	s_cbranch_scc1 .LBB0_876
	s_ashr_i32 s1, s0, 31
	s_lshl_b64 s[4:5], s[0:1], 11
	v_lshl_add_u64 v[2:3], v[178:179], 0, s[4:5]
	global_load_dwordx2 v[4:5], v[2:3], off nt
	global_load_dwordx2 v[6:7], v[2:3], off offset:512 nt
	global_load_dwordx2 v[8:9], v[2:3], off offset:1024 nt
	global_load_dwordx2 v[2:3], v[2:3], off offset:1536 nt
	s_mov_b64 s[4:5], 0
	s_waitcnt vmcnt(3)
	v_lshlrev_b32_e32 v78, 16, v4
	v_and_b32_e32 v79, 0xffff0000, v4
	v_lshlrev_b32_e32 v80, 16, v5
	v_and_b32_e32 v81, 0xffff0000, v5
	s_waitcnt vmcnt(2)
	v_lshlrev_b32_e32 v74, 16, v6
	v_and_b32_e32 v75, 0xffff0000, v6
	v_lshlrev_b32_e32 v76, 16, v7
	v_and_b32_e32 v77, 0xffff0000, v7
	s_waitcnt vmcnt(1)
	v_lshlrev_b32_e32 v70, 16, v8
	v_and_b32_e32 v71, 0xffff0000, v8
	v_lshlrev_b32_e32 v72, 16, v9
	v_and_b32_e32 v73, 0xffff0000, v9
	s_waitcnt vmcnt(0)
	v_lshlrev_b32_e32 v66, 16, v2
	v_and_b32_e32 v67, 0xffff0000, v2
	v_lshlrev_b32_e32 v68, 16, v3
	v_and_b32_e32 v69, 0xffff0000, v3
.LBB0_876:
	s_andn2_b64 vcc, exec, s[4:5]
	s_cbranch_vccnz .LBB0_878
	s_add_i32 s70, s0, 0xffff8000
	s_lshl_b64 s[4:5], s[70:71], 12
	s_add_i32 s70, s0, 0xffff8400
	v_lshl_add_u64 v[14:15], v[184:185], 0, s[4:5]
	s_lshl_b64 s[4:5], s[70:71], 12
	s_add_i32 s70, s0, 0xffff8800
	global_load_dwordx4 v[2:5], v[14:15], off
	global_load_dwordx4 v[6:9], v[14:15], off offset:1024
	global_load_dwordx4 v[10:13], v[14:15], off offset:2048
	v_lshl_add_u64 v[30:31], v[184:185], 0, s[4:5]
	global_load_dwordx4 v[14:17], v[14:15], off offset:3072
	s_lshl_b64 s[4:5], s[70:71], 12
	s_add_i32 s70, s0, 0xffff8c00
	global_load_dwordx4 v[18:21], v[30:31], off
	global_load_dwordx4 v[22:25], v[30:31], off offset:1024
	global_load_dwordx4 v[26:29], v[30:31], off offset:2048
	v_lshl_add_u64 v[46:47], v[184:185], 0, s[4:5]
	global_load_dwordx4 v[30:33], v[30:31], off offset:3072
	s_lshl_b64 s[4:5], s[70:71], 12
	global_load_dwordx4 v[34:37], v[46:47], off
	global_load_dwordx4 v[38:41], v[46:47], off offset:1024
	global_load_dwordx4 v[42:45], v[46:47], off offset:2048
	v_lshl_add_u64 v[74:75], v[184:185], 0, s[4:5]
	global_load_dwordx4 v[46:49], v[46:47], off offset:3072
	global_load_dwordx4 v[66:69], v[74:75], off
	global_load_dwordx4 v[70:73], v[74:75], off offset:1024
	global_load_dwordx4 v[86:89], v[74:75], off offset:2048
	global_load_dwordx4 v[94:97], v[74:75], off offset:3072
	s_waitcnt vmcnt(15)
	v_pk_add_f32 v[4:5], v[4:5], 0 op_sel_hi:[1,0]
	v_pk_add_f32 v[2:3], v[2:3], 0 op_sel_hi:[1,0]
	s_waitcnt vmcnt(14)
	v_pk_add_f32 v[8:9], v[8:9], 0 op_sel_hi:[1,0]
	v_pk_add_f32 v[6:7], v[6:7], 0 op_sel_hi:[1,0]
	s_waitcnt vmcnt(13)
	v_pk_add_f32 v[12:13], v[12:13], 0 op_sel_hi:[1,0]
	v_pk_add_f32 v[10:11], v[10:11], 0 op_sel_hi:[1,0]
	s_waitcnt vmcnt(12)
	v_pk_add_f32 v[16:17], v[16:17], 0 op_sel_hi:[1,0]
	v_pk_add_f32 v[14:15], v[14:15], 0 op_sel_hi:[1,0]
	s_waitcnt vmcnt(11)
	v_pk_add_f32 v[4:5], v[4:5], v[20:21]
	v_pk_add_f32 v[2:3], v[2:3], v[18:19]
	s_waitcnt vmcnt(10)
	v_pk_add_f32 v[8:9], v[8:9], v[24:25]
	v_pk_add_f32 v[6:7], v[6:7], v[22:23]
	s_waitcnt vmcnt(9)
	v_pk_add_f32 v[12:13], v[12:13], v[28:29]
	v_pk_add_f32 v[10:11], v[10:11], v[26:27]
	s_waitcnt vmcnt(8)
	v_pk_add_f32 v[16:17], v[16:17], v[32:33]
	v_pk_add_f32 v[14:15], v[14:15], v[30:31]
	s_waitcnt vmcnt(7)
	v_pk_add_f32 v[4:5], v[4:5], v[36:37]
	v_pk_add_f32 v[2:3], v[2:3], v[34:35]
	s_waitcnt vmcnt(6)
	v_pk_add_f32 v[8:9], v[8:9], v[40:41]
	v_pk_add_f32 v[6:7], v[6:7], v[38:39]
	s_waitcnt vmcnt(5)
	v_pk_add_f32 v[12:13], v[12:13], v[44:45]
	v_pk_add_f32 v[10:11], v[10:11], v[42:43]
	s_waitcnt vmcnt(4)
	v_pk_add_f32 v[16:17], v[16:17], v[48:49]
	v_pk_add_f32 v[14:15], v[14:15], v[46:47]
	s_waitcnt vmcnt(3)
	v_pk_add_f32 v[80:81], v[4:5], v[68:69]
	v_pk_add_f32 v[78:79], v[2:3], v[66:67]
	s_waitcnt vmcnt(2)
	v_pk_add_f32 v[76:77], v[8:9], v[72:73]
	v_pk_add_f32 v[74:75], v[6:7], v[70:71]
	s_waitcnt vmcnt(1)
	v_pk_add_f32 v[72:73], v[12:13], v[88:89]
	v_pk_add_f32 v[70:71], v[10:11], v[86:87]
	s_waitcnt vmcnt(0)
	v_pk_add_f32 v[68:69], v[16:17], v[96:97]
	v_pk_add_f32 v[66:67], v[14:15], v[94:95]

; __device__ __forceinline__ float bflo(unsigned w) { return __uint_as_float(w << 16); }
; __device__ __forceinline__ float bfhi(unsigned w) { return __uint_as_float(w & 0xffff0000u); }
; #define LOADY(m, y, ns) do { if ((m) >= NLAT) load16part<ns>(WSP(float, WS_PART), (m) - NLAT, lane, y); else load16bf(BY + (size_t)(m) * DM, lane, y); } while (0)
; #define R3_SRC(m) ((l == 0) ? ((m) < NLAT ? PIN(I_X) + (size_t)(m) * DM : PIN(I_CTX) + (size_t)((m) - NLAT) * DM) : (const float*)XS_ROW(m))
; __device__ __forceinline__ void load16(const float* row, int lane, f32x4 (&v)[4]) {
; #pragma unroll
;     for (int j = 0; j < 4; ++j) v[j] = __builtin_nontemporal_load((const f32x4*)row + lane + 64 * j);
; }
; __device__ __forceinline__ void load16bf(const bf16_t* row, int lane, f32x4 (&v)[4]) {
; #pragma unroll
;     for (int j = 0; j < 4; ++j) { const u32x2 w = __builtin_nontemporal_load((const u32x2*)row + lane + 64 * j); v[j] = (f32x4){bflo(w.x), bfhi(w.x), bflo(w.y), bfhi(w.y)}; }
; }
; template <int NS> __device__ __forceinline__ void load16part(const float* P, int rowrel, int lane, f32x4 (&v)[4]) {
; #pragma unroll
;     for (int j = 0; j < 4; ++j) v[j] = (f32x4){0.f, 0.f, 0.f, 0.f};
; #pragma unroll
;     for (int s0 = 0; s0 < NS; s0 += 4) { f32x4 t[4][4];
; #pragma unroll
;         for (int s = 0; s < 4; ++s) { const f32x4* q = (const f32x4*)(P + ((size_t)(s0 + s) * 1024 + rowrel) * 1024);
; #pragma unroll
;             for (int j = 0; j < 4; ++j) t[s][j] = q[lane + 64 * j]; }
; #pragma unroll
;         for (int s = 0; s < 4; ++s)
; #pragma unroll
;             for (int j = 0; j < 4; ++j) v[j] += t[s][j]; }
; }
; __global__ void __launch_bounds__(512, 2) fwd_megakernel(Params p) {
;     ...
;         for (int m0 = gw; m0 < Mact; m0 += 4 * NGW) { f32x4 yb[4][4], xb[4][4]; const float* mod = MOD_ROW(l, m0);
; #pragma unroll
;             for (int i = 0; i < 4; ++i) { const int mi = m0 + i * NGW, mc = mi < Mact ? mi : m0; LOADY(mc, yb[i], 4); load16(R3_SRC(mc), lane, xb[i]); }
.LBB0_889:
	s_lshl_b64 s[0:1], s[20:21], 12
	s_waitcnt lgkmcnt(0)
	s_add_u32 s0, s18, s0
	s_addc_u32 s1, s19, s1
	global_load_dwordx4 v[14:17], v190, s[0:1] nt
	global_load_dwordx4 v[10:13], v190, s[0:1] offset:1024 nt
	global_load_dwordx4 v[6:9], v190, s[0:1] offset:2048 nt
	global_load_dwordx4 v[2:5], v190, s[0:1] offset:3072 nt
	s_add_i32 s18, s12, 0x1000
	s_cmp_lt_i32 s18, s53
	s_cselect_b64 s[20:21], -1, 0
	s_and_b64 s[0:1], s[20:21], exec
	s_cselect_b32 s0, s18, s12
	s_cmpk_gt_i32 s0, 0x7fff
	s_mov_b64 s[6:7], -1
	s_cbranch_scc1 .LBB0_891
	s_ashr_i32 s1, s0, 31
	s_lshl_b64 s[6:7], s[0:1], 11
	v_lshl_add_u64 v[18:19], v[178:179], 0, s[6:7]
	global_load_dwordx2 v[20:21], v[18:19], off nt
	global_load_dwordx2 v[22:23], v[18:19], off offset:512 nt
	global_load_dwordx2 v[24:25], v[18:19], off offset:1024 nt
	global_load_dwordx2 v[18:19], v[18:19], off offset:1536 nt
	s_mov_b64 s[6:7], 0
	s_waitcnt vmcnt(3)
	v_lshlrev_b32_e32 v106, 16, v20
	v_and_b32_e32 v107, 0xffff0000, v20
	v_lshlrev_b32_e32 v108, 16, v21
	v_and_b32_e32 v109, 0xffff0000, v21
	s_waitcnt vmcnt(2)
	v_lshlrev_b32_e32 v98, 16, v22
	v_and_b32_e32 v99, 0xffff0000, v22
	v_lshlrev_b32_e32 v100, 16, v23
	v_and_b32_e32 v101, 0xffff0000, v23
	s_waitcnt vmcnt(1)
	v_lshlrev_b32_e32 v94, 16, v24
	v_and_b32_e32 v95, 0xffff0000, v24
	v_lshlrev_b32_e32 v96, 16, v25
	v_and_b32_e32 v97, 0xffff0000, v25
	s_waitcnt vmcnt(0)
	v_lshlrev_b32_e32 v86, 16, v18
	v_and_b32_e32 v87, 0xffff0000, v18
	v_lshlrev_b32_e32 v88, 16, v19
	v_and_b32_e32 v89, 0xffff0000, v19
.LBB0_891:
	s_andn2_b64 vcc, exec, s[6:7]
	s_cbranch_vccnz .LBB0_893
	s_add_i32 s70, s0, 0xffff8000
	s_lshl_b64 s[6:7], s[70:71], 12
	s_add_i32 s70, s0, 0xffff8400
	v_lshl_add_u64 v[30:31], v[184:185], 0, s[6:7]
	s_lshl_b64 s[6:7], s[70:71], 12
	s_add_i32 s70, s0, 0xffff8800
	global_load_dwordx4 v[18:21], v[30:31], off
	global_load_dwordx4 v[22:25], v[30:31], off offset:1024
	global_load_dwordx4 v[26:29], v[30:31], off offset:2048
	v_lshl_add_u64 v[46:47], v[184:185], 0, s[6:7]
	global_load_dwordx4 v[30:33], v[30:31], off offset:3072
	s_lshl_b64 s[6:7], s[70:71], 12
	s_add_i32 s70, s0, 0xffff8c00
	global_load_dwordx4 v[34:37], v[46:47], off
	global_load_dwordx4 v[38:41], v[46:47], off offset:1024
	global_load_dwordx4 v[42:45], v[46:47], off offset:2048
	v_lshl_add_u64 v[106:107], v[184:185], 0, s[6:7]
	global_load_dwordx4 v[46:49], v[46:47], off offset:3072
	s_lshl_b64 s[6:7], s[70:71], 12
	global_load_dwordx4 v[86:89], v[106:107], off
	global_load_dwordx4 v[94:97], v[106:107], off offset:1024
	global_load_dwordx4 v[98:101], v[106:107], off offset:2048
	v_lshl_add_u64 v[126:127], v[184:185], 0, s[6:7]
	global_load_dwordx4 v[106:109], v[106:107], off offset:3072
	global_load_dwordx4 v[114:117], v[126:127], off
	global_load_dwordx4 v[118:121], v[126:127], off offset:1024
	global_load_dwordx4 v[122:125], v[126:127], off offset:2048
	global_load_dwordx4 v[126:129], v[126:127], off offset:3072
	s_waitcnt vmcnt(15)
	v_pk_add_f32 v[20:21], v[20:21], 0 op_sel_hi:[1,0]
	v_pk_add_f32 v[18:19], v[18:19], 0 op_sel_hi:[1,0]
	s_waitcnt vmcnt(14)
	v_pk_add_f32 v[24:25], v[24:25], 0 op_sel_hi:[1,0]
	v_pk_add_f32 v[22:23], v[22:23], 0 op_sel_hi:[1,0]
	s_waitcnt vmcnt(13)
	v_pk_add_f32 v[28:29], v[28:29], 0 op_sel_hi:[1,0]
	v_pk_add_f32 v[26:27], v[26:27], 0 op_sel_hi:[1,0]
	s_waitcnt vmcnt(12)
	v_pk_add_f32 v[32:33], v[32:33], 0 op_sel_hi:[1,0]
	v_pk_add_f32 v[30:31], v[30:31], 0 op_sel_hi:[1,0]
	s_waitcnt vmcnt(11)
	v_pk_add_f32 v[20:21], v[20:21], v[36:37]
	v_pk_add_f32 v[18:19], v[18:19], v[34:35]
	s_waitcnt vmcnt(10)
	v_pk_add_f32 v[24:25], v[24:25], v[40:41]
	v_pk_add_f32 v[22:23], v[22:23], v[38:39]
	s_waitcnt vmcnt(9)
	v_pk_add_f32 v[28:29], v[28:29], v[44:45]
	v_pk_add_f32 v[26:27], v[26:27], v[42:43]
	s_waitcnt vmcnt(8)
	v_pk_add_f32 v[32:33], v[32:33], v[48:49]
	v_pk_add_f32 v[30:31], v[30:31], v[46:47]
	s_waitcnt vmcnt(7)
	v_pk_add_f32 v[20:21], v[20:21], v[88:89]
	v_pk_add_f32 v[18:19], v[18:19], v[86:87]
	s_waitcnt vmcnt(6)
	v_pk_add_f32 v[24:25], v[24:25], v[96:97]
	v_pk_add_f32 v[22:23], v[22:23], v[94:95]
	s_waitcnt vmcnt(5)
	v_pk_add_f32 v[28:29], v[28:29], v[100:101]
	v_pk_add_f32 v[26:27], v[26:27], v[98:99]
	s_waitcnt vmcnt(4)
	v_pk_add_f32 v[32:33], v[32:33], v[108:109]
	v_pk_add_f32 v[30:31], v[30:31], v[106:107]
	s_waitcnt vmcnt(3)
	v_pk_add_f32 v[108:109], v[20:21], v[116:117]
	v_pk_add_f32 v[106:107], v[18:19], v[114:115]
	s_waitcnt vmcnt(2)
	v_pk_add_f32 v[100:101], v[24:25], v[120:121]
	v_pk_add_f32 v[98:99], v[22:23], v[118:119]
	s_waitcnt vmcnt(1)
	v_pk_add_f32 v[96:97], v[28:29], v[124:125]
	v_pk_add_f32 v[94:95], v[26:27], v[122:123]
	s_waitcnt vmcnt(0)
	v_pk_add_f32 v[88:89], v[32:33], v[128:129]
	v_pk_add_f32 v[86:87], v[30:31], v[126:127]

; __device__ __forceinline__ float bflo(unsigned w) { return __uint_as_float(w << 16); }
; __device__ __forceinline__ float bfhi(unsigned w) { return __uint_as_float(w & 0xffff0000u); }
; #define LOADY(m, y, ns) do { if ((m) >= NLAT) load16part<ns>(WSP(float, WS_PART), (m) - NLAT, lane, y); else load16bf(BY + (size_t)(m) * DM, lane, y); } while (0)
; #define R3_SRC(m) ((l == 0) ? ((m) < NLAT ? PIN(I_X) + (size_t)(m) * DM : PIN(I_CTX) + (size_t)((m) - NLAT) * DM) : (const float*)XS_ROW(m))
; __device__ __forceinline__ void load16(const float* row, int lane, f32x4 (&v)[4]) {
; #pragma unroll
;     for (int j = 0; j < 4; ++j) v[j] = __builtin_nontemporal_load((const f32x4*)row + lane + 64 * j);
; }
; __device__ __forceinline__ void load16bf(const bf16_t* row, int lane, f32x4 (&v)[4]) {
; #pragma unroll
;     for (int j = 0; j < 4; ++j) { const u32x2 w = __builtin_nontemporal_load((const u32x2*)row + lane + 64 * j); v[j] = (f32x4){bflo(w.x), bfhi(w.x), bflo(w.y), bfhi(w.y)}; }
; }
; template <int NS> __device__ __forceinline__ void load16part(const float* P, int rowrel, int lane, f32x4 (&v)[4]) {
; #pragma unroll
;     for (int j = 0; j < 4; ++j) v[j] = (f32x4){0.f, 0.f, 0.f, 0.f};
; #pragma unroll
;     for (int s0 = 0; s0 < NS; s0 += 4) { f32x4 t[4][4];
; #pragma unroll
;         for (int s = 0; s < 4; ++s) { const f32x4* q = (const f32x4*)(P + ((size_t)(s0 + s) * 1024 + rowrel) * 1024);
; #pragma unroll
;             for (int j = 0; j < 4; ++j) t[s][j] = q[lane + 64 * j]; }
; #pragma unroll
;         for (int s = 0; s < 4; ++s)
; #pragma unroll
;             for (int j = 0; j < 4; ++j) v[j] += t[s][j]; }
; }
; __global__ void __launch_bounds__(512, 2) fwd_megakernel(Params p) {
;     ...
;         for (int m0 = gw; m0 < Mact; m0 += 4 * NGW) { f32x4 yb[4][4], xb[4][4]; const float* mod = MOD_ROW(l, m0);
; #pragma unroll
;             for (int i = 0; i < 4; ++i) { const int mi = m0 + i * NGW, mc = mi < Mact ? mi : m0; LOADY(mc, yb[i], 4); load16(R3_SRC(mc), lane, xb[i]); }
.LBB0_904:
	s_lshl_b64 s[0:1], s[34:35], 12
	s_waitcnt lgkmcnt(0)
	s_add_u32 s0, s28, s0
	s_addc_u32 s1, s29, s1
	global_load_dwordx4 v[30:33], v190, s[0:1] nt
	global_load_dwordx4 v[26:29], v190, s[0:1] offset:1024 nt
	global_load_dwordx4 v[22:25], v190, s[0:1] offset:2048 nt
	global_load_dwordx4 v[18:21], v190, s[0:1] offset:3072 nt
	s_add_i32 s0, s12, 0x1800
	s_cmp_lt_i32 s0, s53
	s_cselect_b64 s[28:29], -1, 0
	s_and_b64 s[6:7], s[28:29], exec
	s_cselect_b32 s6, s0, s12
	s_cmpk_gt_i32 s6, 0x7fff
	s_mov_b64 s[34:35], -1
	s_cbranch_scc1 .LBB0_906
	s_ashr_i32 s7, s6, 31
	s_lshl_b64 s[34:35], s[6:7], 11
	v_lshl_add_u64 v[34:35], v[178:179], 0, s[34:35]
	global_load_dwordx2 v[36:37], v[34:35], off nt
	global_load_dwordx2 v[38:39], v[34:35], off offset:512 nt
	global_load_dwordx2 v[40:41], v[34:35], off offset:1024 nt
	global_load_dwordx2 v[34:35], v[34:35], off offset:1536 nt
	s_mov_b64 s[34:35], 0
	s_waitcnt vmcnt(3)
	v_lshlrev_b32_e32 v126, 16, v36
	v_and_b32_e32 v127, 0xffff0000, v36
	v_lshlrev_b32_e32 v128, 16, v37
	v_and_b32_e32 v129, 0xffff0000, v37
	s_waitcnt vmcnt(2)
	v_lshlrev_b32_e32 v122, 16, v38
	v_and_b32_e32 v123, 0xffff0000, v38
	v_lshlrev_b32_e32 v124, 16, v39
	v_and_b32_e32 v125, 0xffff0000, v39
	s_waitcnt vmcnt(1)
	v_lshlrev_b32_e32 v118, 16, v40
	v_and_b32_e32 v119, 0xffff0000, v40
	v_lshlrev_b32_e32 v120, 16, v41
	v_and_b32_e32 v121, 0xffff0000, v41
	s_waitcnt vmcnt(0)
	v_lshlrev_b32_e32 v114, 16, v34
	v_and_b32_e32 v115, 0xffff0000, v34
	v_lshlrev_b32_e32 v116, 16, v35
	v_and_b32_e32 v117, 0xffff0000, v35
.LBB0_906:
	s_andn2_b64 vcc, exec, s[34:35]
	s_cbranch_vccnz .LBB0_908
	s_add_i32 s70, s6, 0xffff8000
	s_lshl_b64 s[34:35], s[70:71], 12
	s_add_i32 s70, s6, 0xffff8400
	v_lshl_add_u64 v[46:47], v[184:185], 0, s[34:35]
	s_lshl_b64 s[34:35], s[70:71], 12
	s_add_i32 s70, s6, 0xffff8800
	global_load_dwordx4 v[34:37], v[46:47], off
	global_load_dwordx4 v[38:41], v[46:47], off offset:1024
	global_load_dwordx4 v[42:45], v[46:47], off offset:2048
	v_lshl_add_u64 v[126:127], v[184:185], 0, s[34:35]
	global_load_dwordx4 v[46:49], v[46:47], off offset:3072
	s_lshl_b64 s[34:35], s[70:71], 12
	s_add_i32 s70, s6, 0xffff8c00
	global_load_dwordx4 v[114:117], v[126:127], off
	global_load_dwordx4 v[118:121], v[126:127], off offset:1024
	global_load_dwordx4 v[122:125], v[126:127], off offset:2048
	v_lshl_add_u64 v[142:143], v[184:185], 0, s[34:35]
	global_load_dwordx4 v[126:129], v[126:127], off offset:3072
	s_lshl_b64 s[34:35], s[70:71], 12
	global_load_dwordx4 v[130:133], v[142:143], off
	global_load_dwordx4 v[134:137], v[142:143], off offset:1024
	global_load_dwordx4 v[138:141], v[142:143], off offset:2048
	v_lshl_add_u64 v[158:159], v[184:185], 0, s[34:35]
	global_load_dwordx4 v[142:145], v[142:143], off offset:3072
	global_load_dwordx4 v[146:149], v[158:159], off
	global_load_dwordx4 v[150:153], v[158:159], off offset:1024
	global_load_dwordx4 v[154:157], v[158:159], off offset:2048
	global_load_dwordx4 v[158:161], v[158:159], off offset:3072
	s_waitcnt vmcnt(15)
	v_pk_add_f32 v[36:37], v[36:37], 0 op_sel_hi:[1,0]
	v_pk_add_f32 v[34:35], v[34:35], 0 op_sel_hi:[1,0]
	s_waitcnt vmcnt(14)
	v_pk_add_f32 v[40:41], v[40:41], 0 op_sel_hi:[1,0]
	v_pk_add_f32 v[38:39], v[38:39], 0 op_sel_hi:[1,0]
	s_waitcnt vmcnt(13)
	v_pk_add_f32 v[44:45], v[44:45], 0 op_sel_hi:[1,0]
	v_pk_add_f32 v[42:43], v[42:43], 0 op_sel_hi:[1,0]
	s_waitcnt vmcnt(12)
	v_pk_add_f32 v[48:49], v[48:49], 0 op_sel_hi:[1,0]
	v_pk_add_f32 v[46:47], v[46:47], 0 op_sel_hi:[1,0]
	s_waitcnt vmcnt(11)
	v_pk_add_f32 v[36:37], v[36:37], v[116:117]
	v_pk_add_f32 v[34:35], v[34:35], v[114:115]
	s_waitcnt vmcnt(10)
	v_pk_add_f32 v[40:41], v[40:41], v[120:121]
	v_pk_add_f32 v[38:39], v[38:39], v[118:119]
	s_waitcnt vmcnt(9)
	v_pk_add_f32 v[44:45], v[44:45], v[124:125]
	v_pk_add_f32 v[42:43], v[42:43], v[122:123]
	s_waitcnt vmcnt(8)
	v_pk_add_f32 v[48:49], v[48:49], v[128:129]
	v_pk_add_f32 v[46:47], v[46:47], v[126:127]
	s_waitcnt vmcnt(7)
	v_pk_add_f32 v[36:37], v[36:37], v[132:133]
	v_pk_add_f32 v[34:35], v[34:35], v[130:131]
	s_waitcnt vmcnt(6)
	v_pk_add_f32 v[40:41], v[40:41], v[136:137]
	v_pk_add_f32 v[38:39], v[38:39], v[134:135]
	s_waitcnt vmcnt(5)
	v_pk_add_f32 v[44:45], v[44:45], v[140:141]
	v_pk_add_f32 v[42:43], v[42:43], v[138:139]
	s_waitcnt vmcnt(4)
	v_pk_add_f32 v[48:49], v[48:49], v[144:145]
	v_pk_add_f32 v[46:47], v[46:47], v[142:143]
	s_waitcnt vmcnt(3)
	v_pk_add_f32 v[128:129], v[36:37], v[148:149]
	v_pk_add_f32 v[126:127], v[34:35], v[146:147]
	s_waitcnt vmcnt(2)
	v_pk_add_f32 v[124:125], v[40:41], v[152:153]
	v_pk_add_f32 v[122:123], v[38:39], v[150:151]
	s_waitcnt vmcnt(1)
	v_pk_add_f32 v[120:121], v[44:45], v[156:157]
	v_pk_add_f32 v[118:119], v[42:43], v[154:155]
	s_waitcnt vmcnt(0)
	v_pk_add_f32 v[116:117], v[48:49], v[160:161]
	v_pk_add_f32 v[114:115], v[46:47], v[158:159]

; #define LOADY(m, y, ns) do { if ((m) >= NLAT) load16part<ns>(WSP(float, WS_PART), (m) - NLAT, lane, y); else load16bf(BY + (size_t)(m) * DM, lane, y); } while (0)
; template <int NS> __device__ __forceinline__ void load16part(const float* P, int rowrel, int lane, f32x4 (&v)[4]) {
; #pragma unroll
;     for (int j = 0; j < 4; ++j) v[j] = (f32x4){0.f, 0.f, 0.f, 0.f};
; #pragma unroll
;     for (int s0 = 0; s0 < NS; s0 += 4) { f32x4 t[4][4];
; #pragma unroll
;         for (int s = 0; s < 4; ++s) { const f32x4* q = (const f32x4*)(P + ((size_t)(s0 + s) * 1024 + rowrel) * 1024);
; #pragma unroll
;             for (int j = 0; j < 4; ++j) t[s][j] = q[lane + 64 * j]; }
; #pragma unroll
;         for (int s = 0; s < 4; ++s)
; #pragma unroll
;             for (int j = 0; j < 4; ++j) v[j] += t[s][j]; }
; }
; __global__ void __launch_bounds__(512, 2) fwd_megakernel(Params p) {
;     ...
;             for (int i = 0; i < 4; ++i) { const int mi = m0 + i * NGW, mc = mi < Mact ? mi : m0; LOADY(mc, yb[i], 16); load16(XS_ROW(mc), lane, xb[i]); }
.LBB0_1168:
	s_andn2_b64 vcc, exec, s[0:1]
	s_cbranch_vccnz .LBB0_1170
	s_lshl_b64 s[0:1], s[70:71], 12
	v_lshl_add_u64 v[14:15], v[146:147], 0, s[0:1]
	s_add_i32 s0, s70, 0x400
	s_mov_b32 s1, s71
	s_lshl_b64 s[0:1], s[0:1], 12
	global_load_dwordx4 v[2:5], v[14:15], off
	global_load_dwordx4 v[6:9], v[14:15], off offset:1024
	global_load_dwordx4 v[10:13], v[14:15], off offset:2048
	global_load_dwordx4 v[14:17], v[14:15], off offset:3072
	v_lshl_add_u64 v[30:31], v[146:147], 0, s[0:1]
	s_add_i32 s0, s70, 0x800
	s_mov_b32 s1, s71
	global_load_dwordx4 v[18:21], v[30:31], off
	global_load_dwordx4 v[22:25], v[30:31], off offset:1024
	global_load_dwordx4 v[26:29], v[30:31], off offset:2048
	global_load_dwordx4 v[30:33], v[30:31], off offset:3072
	s_lshl_b64 s[0:1], s[0:1], 12
	v_lshl_add_u64 v[46:47], v[146:147], 0, s[0:1]
	s_add_i32 s0, s70, 0xc00
	s_mov_b32 s1, s71
	global_load_dwordx4 v[34:37], v[46:47], off
	global_load_dwordx4 v[38:41], v[46:47], off offset:1024
	global_load_dwordx4 v[42:45], v[46:47], off offset:2048
	global_load_dwordx4 v[46:49], v[46:47], off offset:3072
	s_lshl_b64 s[0:1], s[0:1], 12
	v_lshl_add_u64 v[62:63], v[146:147], 0, s[0:1]
	global_load_dwordx4 v[50:53], v[62:63], off
	global_load_dwordx4 v[54:57], v[62:63], off offset:1024
	global_load_dwordx4 v[58:61], v[62:63], off offset:2048
	global_load_dwordx4 v[62:65], v[62:63], off offset:3072
	s_add_i32 s0, s70, 0x1000
	s_mov_b32 s1, s71
	s_lshl_b64 s[0:1], s[0:1], 12
	s_waitcnt vmcnt(15)
	v_pk_add_f32 v[4:5], v[4:5], 0 op_sel_hi:[1,0]
	v_pk_add_f32 v[2:3], v[2:3], 0 op_sel_hi:[1,0]
	s_waitcnt vmcnt(14)
	v_pk_add_f32 v[8:9], v[8:9], 0 op_sel_hi:[1,0]
	s_waitcnt vmcnt(12)
	v_pk_add_f32 v[14:15], v[14:15], 0 op_sel_hi:[1,0]
	v_pk_add_f32 v[6:7], v[6:7], 0 op_sel_hi:[1,0]
	v_pk_add_f32 v[12:13], v[12:13], 0 op_sel_hi:[1,0]
	v_pk_add_f32 v[10:11], v[10:11], 0 op_sel_hi:[1,0]
	s_waitcnt vmcnt(8)
	v_pk_add_f32 v[14:15], v[14:15], v[30:31]
	v_lshl_add_u64 v[30:31], v[146:147], 0, s[0:1]
	s_add_i32 s0, s70, 0x1400
	s_mov_b32 s1, s71
	v_pk_add_f32 v[16:17], v[16:17], 0 op_sel_hi:[1,0]
	s_lshl_b64 s[0:1], s[0:1], 12
	v_pk_add_f32 v[4:5], v[4:5], v[20:21]
	v_pk_add_f32 v[2:3], v[2:3], v[18:19]
	v_pk_add_f32 v[8:9], v[8:9], v[24:25]
	v_pk_add_f32 v[6:7], v[6:7], v[22:23]
	v_pk_add_f32 v[12:13], v[12:13], v[28:29]
	v_pk_add_f32 v[10:11], v[10:11], v[26:27]
	v_pk_add_f32 v[16:17], v[16:17], v[32:33]
	s_waitcnt vmcnt(4)
	v_pk_add_f32 v[24:25], v[14:15], v[46:47]
	v_lshl_add_u64 v[46:47], v[146:147], 0, s[0:1]
	s_add_i32 s0, s70, 0x1800
	s_mov_b32 s1, s71
	v_pk_add_f32 v[4:5], v[4:5], v[36:37]
	v_pk_add_f32 v[2:3], v[2:3], v[34:35]
	v_pk_add_f32 v[8:9], v[8:9], v[40:41]
	v_pk_add_f32 v[6:7], v[6:7], v[38:39]
	v_pk_add_f32 v[18:19], v[12:13], v[44:45]
	v_pk_add_f32 v[20:21], v[10:11], v[42:43]
	v_pk_add_f32 v[22:23], v[16:17], v[48:49]
	s_lshl_b64 s[0:1], s[0:1], 12
	s_waitcnt vmcnt(3)
	v_pk_add_f32 v[14:15], v[4:5], v[52:53]
	v_pk_add_f32 v[16:17], v[2:3], v[50:51]
	s_waitcnt vmcnt(2)
	v_pk_add_f32 v[10:11], v[8:9], v[56:57]
	v_pk_add_f32 v[12:13], v[6:7], v[54:55]
	s_waitcnt vmcnt(1)
	v_pk_add_f32 v[6:7], v[18:19], v[60:61]
	v_pk_add_f32 v[8:9], v[20:21], v[58:59]
	s_waitcnt vmcnt(0)
	v_pk_add_f32 v[2:3], v[22:23], v[64:65]
	v_pk_add_f32 v[4:5], v[24:25], v[62:63]
	global_load_dwordx4 v[18:21], v[30:31], off
	global_load_dwordx4 v[22:25], v[30:31], off offset:1024
	global_load_dwordx4 v[26:29], v[30:31], off offset:2048
	global_load_dwordx4 v[30:33], v[30:31], off offset:3072
	v_lshl_add_u64 v[62:63], v[146:147], 0, s[0:1]
	s_add_i32 s0, s70, 0x1c00
	s_mov_b32 s1, s71
	global_load_dwordx4 v[34:37], v[46:47], off
	global_load_dwordx4 v[38:41], v[46:47], off offset:1024
	global_load_dwordx4 v[42:45], v[46:47], off offset:2048
	global_load_dwordx4 v[46:49], v[46:47], off offset:3072
	s_lshl_b64 s[0:1], s[0:1], 12
	global_load_dwordx4 v[50:53], v[62:63], off
	global_load_dwordx4 v[54:57], v[62:63], off offset:1024
	global_load_dwordx4 v[58:61], v[62:63], off offset:2048
	global_load_dwordx4 v[62:65], v[62:63], off offset:3072
	v_lshl_add_u64 v[78:79], v[146:147], 0, s[0:1]
	global_load_dwordx4 v[66:69], v[78:79], off
	global_load_dwordx4 v[70:73], v[78:79], off offset:1024
	global_load_dwordx4 v[74:77], v[78:79], off offset:2048
	global_load_dwordx4 v[78:81], v[78:79], off offset:3072
	s_add_i32 s0, s70, 0x2000
	s_mov_b32 s1, s71
	s_lshl_b64 s[0:1], s[0:1], 12
	s_waitcnt vmcnt(15)
	v_pk_add_f32 v[14:15], v[14:15], v[20:21]
	s_waitcnt vmcnt(14)
	v_pk_add_f32 v[12:13], v[12:13], v[22:23]
	v_pk_add_f32 v[16:17], v[16:17], v[18:19]
	v_pk_add_f32 v[10:11], v[10:11], v[24:25]
	s_waitcnt vmcnt(11)
	v_pk_add_f32 v[14:15], v[14:15], v[36:37]
	s_waitcnt vmcnt(10)
	v_pk_add_f32 v[12:13], v[12:13], v[38:39]
	s_waitcnt vmcnt(7)
	v_pk_add_f32 v[14:15], v[14:15], v[52:53]
	s_waitcnt vmcnt(6)
	v_pk_add_f32 v[12:13], v[12:13], v[54:55]
	s_waitcnt vmcnt(3)
	v_pk_add_f32 v[54:55], v[14:15], v[68:69]
	v_lshl_add_u64 v[14:15], v[146:147], 0, s[0:1]
	s_add_i32 s0, s70, 0x2400
	s_mov_b32 s1, s71
	v_pk_add_f32 v[6:7], v[6:7], v[28:29]
	v_pk_add_f32 v[8:9], v[8:9], v[26:27]
	v_pk_add_f32 v[2:3], v[2:3], v[32:33]
	v_pk_add_f32 v[4:5], v[4:5], v[30:31]
	s_lshl_b64 s[0:1], s[0:1], 12
	v_pk_add_f32 v[16:17], v[16:17], v[34:35]
	v_pk_add_f32 v[10:11], v[10:11], v[40:41]
	v_pk_add_f32 v[6:7], v[6:7], v[44:45]
	v_pk_add_f32 v[8:9], v[8:9], v[42:43]
	v_pk_add_f32 v[2:3], v[2:3], v[48:49]
	v_pk_add_f32 v[4:5], v[4:5], v[46:47]
	v_lshl_add_u64 v[30:31], v[146:147], 0, s[0:1]
	s_add_i32 s0, s70, 0x2800
	s_mov_b32 s1, s71
	v_pk_add_f32 v[16:17], v[16:17], v[50:51]
	v_pk_add_f32 v[10:11], v[10:11], v[56:57]
	v_pk_add_f32 v[6:7], v[6:7], v[60:61]
	v_pk_add_f32 v[8:9], v[8:9], v[58:59]
	v_pk_add_f32 v[2:3], v[2:3], v[64:65]
	v_pk_add_f32 v[4:5], v[4:5], v[62:63]
	s_lshl_b64 s[0:1], s[0:1], 12
	v_pk_add_f32 v[56:57], v[16:17], v[66:67]
	s_waitcnt vmcnt(2)
; template <int NS> __device__ __forceinline__ void load16part(const float* P, int rowrel, int lane, f32x4 (&v)[4]) {
; #pragma unroll
;     for (int j = 0; j < 4; ++j) v[j] = (f32x4){0.f, 0.f, 0.f, 0.f};
; #pragma unroll
;     for (int s0 = 0; s0 < NS; s0 += 4) { f32x4 t[4][4];
; #pragma unroll
;         for (int s = 0; s < 4; ++s) { const f32x4* q = (const f32x4*)(P + ((size_t)(s0 + s) * 1024 + rowrel) * 1024);
; #pragma unroll
;             for (int j = 0; j < 4; ++j) t[s][j] = q[lane + 64 * j]; }
; #pragma unroll
;         for (int s = 0; s < 4; ++s)
; #pragma unroll
;             for (int j = 0; j < 4; ++j) v[j] += t[s][j]; }
; }
	v_pk_add_f32 v[72:73], v[10:11], v[72:73]
	v_pk_add_f32 v[70:71], v[12:13], v[70:71]
	s_waitcnt vmcnt(1)
	v_pk_add_f32 v[76:77], v[6:7], v[76:77]
	v_pk_add_f32 v[74:75], v[8:9], v[74:75]
	s_waitcnt vmcnt(0)
	v_pk_add_f32 v[80:81], v[2:3], v[80:81]
	v_pk_add_f32 v[78:79], v[4:5], v[78:79]
	global_load_dwordx4 v[2:5], v[14:15], off
	global_load_dwordx4 v[6:9], v[14:15], off offset:1024
	global_load_dwordx4 v[10:13], v[14:15], off offset:2048
	global_load_dwordx4 v[14:17], v[14:15], off offset:3072
	v_lshl_add_u64 v[46:47], v[146:147], 0, s[0:1]
	s_add_i32 s0, s70, 0x2c00
	s_mov_b32 s1, s71
	global_load_dwordx4 v[18:21], v[30:31], off
	global_load_dwordx4 v[22:25], v[30:31], off offset:1024
	global_load_dwordx4 v[26:29], v[30:31], off offset:2048
	global_load_dwordx4 v[30:33], v[30:31], off offset:3072
	s_lshl_b64 s[0:1], s[0:1], 12
	global_load_dwordx4 v[34:37], v[46:47], off
	global_load_dwordx4 v[38:41], v[46:47], off offset:1024
	global_load_dwordx4 v[42:45], v[46:47], off offset:2048
	global_load_dwordx4 v[46:49], v[46:47], off offset:3072
	v_lshl_add_u64 v[66:67], v[146:147], 0, s[0:1]
	global_load_dwordx4 v[50:53], v[66:67], off
	global_load_dwordx4 v[58:61], v[66:67], off offset:1024
	global_load_dwordx4 v[62:65], v[66:67], off offset:2048
	global_load_dwordx4 v[66:69], v[66:67], off offset:3072
	s_add_i32 s0, s70, 0x3000
	s_mov_b32 s1, s71
	s_lshl_b64 s[0:1], s[0:1], 12
	s_waitcnt vmcnt(15)
	v_pk_add_f32 v[2:3], v[56:57], v[2:3]
	v_pk_add_f32 v[4:5], v[54:55], v[4:5]
	s_waitcnt vmcnt(14)
	v_pk_add_f32 v[8:9], v[72:73], v[8:9]
	v_pk_add_f32 v[6:7], v[70:71], v[6:7]
	s_waitcnt vmcnt(11)
	v_pk_add_f32 v[2:3], v[2:3], v[18:19]
	v_pk_add_f32 v[12:13], v[76:77], v[12:13]
	v_pk_add_f32 v[10:11], v[74:75], v[10:11]
	v_pk_add_f32 v[16:17], v[80:81], v[16:17]
	v_pk_add_f32 v[14:15], v[78:79], v[14:15]
	s_waitcnt vmcnt(7)
	v_pk_add_f32 v[2:3], v[2:3], v[34:35]
	v_pk_add_f32 v[4:5], v[4:5], v[20:21]
	v_pk_add_f32 v[8:9], v[8:9], v[24:25]
	v_pk_add_f32 v[6:7], v[6:7], v[22:23]
	v_pk_add_f32 v[12:13], v[12:13], v[28:29]
	v_pk_add_f32 v[10:11], v[10:11], v[26:27]
	v_pk_add_f32 v[16:17], v[16:17], v[32:33]
	v_pk_add_f32 v[14:15], v[14:15], v[30:31]
	s_waitcnt vmcnt(3)
	v_pk_add_f32 v[56:57], v[2:3], v[50:51]
	v_lshl_add_u64 v[2:3], v[146:147], 0, s[0:1]
	s_add_i32 s0, s70, 0x3400
	s_mov_b32 s1, s71
	v_pk_add_f32 v[4:5], v[4:5], v[36:37]
	v_pk_add_f32 v[8:9], v[8:9], v[40:41]
	v_pk_add_f32 v[6:7], v[6:7], v[38:39]
	v_pk_add_f32 v[12:13], v[12:13], v[44:45]
	v_pk_add_f32 v[10:11], v[10:11], v[42:43]
	v_pk_add_f32 v[16:17], v[16:17], v[48:49]
	v_pk_add_f32 v[14:15], v[14:15], v[46:47]
	s_lshl_b64 s[0:1], s[0:1], 12
	v_pk_add_f32 v[54:55], v[4:5], v[52:53]
	s_waitcnt vmcnt(2)
	v_pk_add_f32 v[50:51], v[8:9], v[60:61]
	v_pk_add_f32 v[52:53], v[6:7], v[58:59]
	s_waitcnt vmcnt(1)
	v_pk_add_f32 v[46:47], v[12:13], v[64:65]
	v_pk_add_f32 v[48:49], v[10:11], v[62:63]
	s_waitcnt vmcnt(0)
	v_pk_add_f32 v[42:43], v[16:17], v[68:69]
	v_pk_add_f32 v[44:45], v[14:15], v[66:67]
	global_load_dwordx4 v[58:61], v[2:3], off
	global_load_dwordx4 v[62:65], v[2:3], off offset:1024
	global_load_dwordx4 v[66:69], v[2:3], off offset:2048
	global_load_dwordx4 v[70:73], v[2:3], off offset:3072
	v_lshl_add_u64 v[2:3], v[146:147], 0, s[0:1]
	s_add_i32 s0, s70, 0x3800
	s_mov_b32 s1, s71
	s_lshl_b64 s[0:1], s[0:1], 12
	global_load_dwordx4 v[74:77], v[2:3], off
	global_load_dwordx4 v[78:81], v[2:3], off offset:1024
	global_load_dwordx4 v[38:41], v[2:3], off offset:2048
	global_load_dwordx4 v[30:33], v[2:3], off offset:3072
	v_lshl_add_u64 v[2:3], v[146:147], 0, s[0:1]
	s_add_i32 s0, s70, 0x3c00
	s_mov_b32 s1, s71
	s_lshl_b64 s[0:1], s[0:1], 12
	global_load_dwordx4 v[34:37], v[2:3], off
	global_load_dwordx4 v[26:29], v[2:3], off offset:1024
	global_load_dwordx4 v[22:25], v[2:3], off offset:2048
	global_load_dwordx4 v[14:17], v[2:3], off offset:3072
	v_lshl_add_u64 v[2:3], v[146:147], 0, s[0:1]
	global_load_dwordx4 v[18:21], v[2:3], off
	global_load_dwordx4 v[10:13], v[2:3], off offset:1024
	global_load_dwordx4 v[6:9], v[2:3], off offset:2048
	global_load_dwordx4 v[2:5], v[2:3], off offset:3072
	s_waitcnt vmcnt(15)
	v_pk_add_f32 v[54:55], v[54:55], v[60:61]
	v_pk_add_f32 v[56:57], v[56:57], v[58:59]
	s_waitcnt vmcnt(14)
	v_pk_add_f32 v[50:51], v[50:51], v[64:65]
	v_pk_add_f32 v[52:53], v[52:53], v[62:63]
	s_waitcnt vmcnt(13)
	v_pk_add_f32 v[46:47], v[46:47], v[68:69]
	v_pk_add_f32 v[48:49], v[48:49], v[66:67]
	s_waitcnt vmcnt(12)
	v_pk_add_f32 v[42:43], v[42:43], v[72:73]
	v_pk_add_f32 v[44:45], v[44:45], v[70:71]
	s_waitcnt vmcnt(11)
	v_pk_add_f32 v[54:55], v[54:55], v[76:77]
	v_pk_add_f32 v[56:57], v[56:57], v[74:75]
	s_waitcnt vmcnt(10)
	v_pk_add_f32 v[50:51], v[50:51], v[80:81]
	v_pk_add_f32 v[52:53], v[52:53], v[78:79]
	s_waitcnt vmcnt(9)
	v_pk_add_f32 v[40:41], v[46:47], v[40:41]
	v_pk_add_f32 v[38:39], v[48:49], v[38:39]
	s_waitcnt vmcnt(8)
	v_pk_add_f32 v[32:33], v[42:43], v[32:33]
	v_pk_add_f32 v[30:31], v[44:45], v[30:31]
	s_waitcnt vmcnt(7)
	v_pk_add_f32 v[36:37], v[54:55], v[36:37]
	v_pk_add_f32 v[34:35], v[56:57], v[34:35]
	s_waitcnt vmcnt(6)
	v_pk_add_f32 v[28:29], v[50:51], v[28:29]
	v_pk_add_f32 v[26:27], v[52:53], v[26:27]
	s_waitcnt vmcnt(5)
	v_pk_add_f32 v[24:25], v[40:41], v[24:25]
	v_pk_add_f32 v[22:23], v[38:39], v[22:23]
	s_waitcnt vmcnt(4)
	v_pk_add_f32 v[16:17], v[32:33], v[16:17]
	v_pk_add_f32 v[14:15], v[30:31], v[14:15]
	s_waitcnt vmcnt(3)
	v_pk_add_f32 v[128:129], v[36:37], v[20:21]
	v_pk_add_f32 v[126:127], v[34:35], v[18:19]
	s_waitcnt vmcnt(2)
	v_pk_add_f32 v[100:101], v[28:29], v[12:13]
	v_pk_add_f32 v[98:99], v[26:27], v[10:11]
	s_waitcnt vmcnt(1)
	v_pk_add_f32 v[88:89], v[24:25], v[8:9]
	v_pk_add_f32 v[86:87], v[22:23], v[6:7]
	s_waitcnt vmcnt(0)
	v_pk_add_f32 v[80:81], v[16:17], v[4:5]
	v_pk_add_f32 v[78:79], v[14:15], v[2:3]

; __device__ __forceinline__ float bflo(unsigned w) { return __uint_as_float(w << 16); }
; __device__ __forceinline__ float bfhi(unsigned w) { return __uint_as_float(w & 0xffff0000u); }
; #define LOADY(m, y, ns) do { if ((m) >= NLAT) load16part<ns>(WSP(float, WS_PART), (m) - NLAT, lane, y); else load16bf(BY + (size_t)(m) * DM, lane, y); } while (0)
; __device__ __forceinline__ void load16(const float* row, int lane, f32x4 (&v)[4]) {
; #pragma unroll
;     for (int j = 0; j < 4; ++j) v[j] = __builtin_nontemporal_load((const f32x4*)row + lane + 64 * j);
; }
; __device__ __forceinline__ void load16bf(const bf16_t* row, int lane, f32x4 (&v)[4]) {
; #pragma unroll
;     for (int j = 0; j < 4; ++j) { const u32x2 w = __builtin_nontemporal_load((const u32x2*)row + lane + 64 * j); v[j] = (f32x4){bflo(w.x), bfhi(w.x), bflo(w.y), bfhi(w.y)}; }
; }
; __global__ void __launch_bounds__(512, 2) fwd_megakernel(Params p) {
;     ...
;             for (int i = 0; i < 4; ++i) { const int mi = m0 + i * NGW, mc = mi < Mact ? mi : m0; LOADY(mc, yb[i], 16); load16(XS_ROW(mc), lane, xb[i]); }
.LBB0_1174:
	s_lshl_b64 s[0:1], s[0:1], 12
	s_waitcnt lgkmcnt(0)
	s_add_u32 s0, s24, s0
	s_addc_u32 s1, s25, s1
	global_load_dwordx4 v[122:125], v139, s[0:1] nt
	global_load_dwordx4 v[114:117], v139, s[0:1] offset:1024 nt
	global_load_dwordx4 v[110:113], v139, s[0:1] offset:2048 nt
	global_load_dwordx4 v[102:105], v139, s[0:1] offset:3072 nt
	s_add_i32 s78, s58, s70
	s_add_i32 s34, s78, 0x8000
	s_cmp_lt_i32 s34, s53
	s_cselect_b64 s[80:81], -1, 0
	s_and_b64 s[0:1], s[80:81], exec
	s_cselect_b32 s0, s34, s13
	s_cmpk_gt_i32 s0, 0x7fff
	s_mov_b64 s[24:25], -1
	s_cbranch_scc1 .LBB0_1178
	s_ashr_i32 s1, s0, 31
	s_lshl_b64 s[24:25], s[0:1], 11
	v_lshl_add_u64 v[2:3], v[140:141], 0, s[24:25]
	global_load_dwordx2 v[4:5], v[2:3], off nt
	global_load_dwordx2 v[6:7], v[2:3], off offset:512 nt
	global_load_dwordx2 v[8:9], v[2:3], off offset:1024 nt
	global_load_dwordx2 v[2:3], v[2:3], off offset:1536 nt
	s_waitcnt vmcnt(3)
	v_lshlrev_b32_e32 v118, 16, v4
	v_and_b32_e32 v119, 0xffff0000, v4
	v_lshlrev_b32_e32 v120, 16, v5
	v_and_b32_e32 v121, 0xffff0000, v5
	s_waitcnt vmcnt(2)
	v_lshlrev_b32_e32 v66, 16, v6
	v_and_b32_e32 v67, 0xffff0000, v6
	v_lshlrev_b32_e32 v68, 16, v7
	v_and_b32_e32 v69, 0xffff0000, v7
	s_waitcnt vmcnt(1)
	v_lshlrev_b32_e32 v54, 16, v8
	v_and_b32_e32 v55, 0xffff0000, v8
	v_lshlrev_b32_e32 v56, 16, v9
	v_and_b32_e32 v57, 0xffff0000, v9
	s_waitcnt vmcnt(0)
	v_lshlrev_b32_e32 v50, 16, v2
	v_and_b32_e32 v51, 0xffff0000, v2
	v_lshlrev_b32_e32 v52, 16, v3
	v_and_b32_e32 v53, 0xffff0000, v3
	s_cbranch_execz .LBB0_1179

; template <int NS> __device__ __forceinline__ void load16part(const float* P, int rowrel, int lane, f32x4 (&v)[4]) {
; #pragma unroll
;     for (int j = 0; j < 4; ++j) v[j] = (f32x4){0.f, 0.f, 0.f, 0.f};
; #pragma unroll
;     for (int s0 = 0; s0 < NS; s0 += 4) { f32x4 t[4][4];
; #pragma unroll
;         for (int s = 0; s < 4; ++s) { const f32x4* q = (const f32x4*)(P + ((size_t)(s0 + s) * 1024 + rowrel) * 1024);
; #pragma unroll
;             for (int j = 0; j < 4; ++j) t[s][j] = q[lane + 64 * j]; }
; #pragma unroll
;         for (int s = 0; s < 4; ++s)
; #pragma unroll
;             for (int j = 0; j < 4; ++j) v[j] += t[s][j]; }
; }
.LBB0_1179:
	s_add_i32 s24, s0, 0xffff8000
	s_mov_b32 s25, s71
	s_lshl_b64 s[24:25], s[24:25], 12
	v_lshl_add_u64 v[14:15], v[146:147], 0, s[24:25]
	s_add_i32 s24, s0, 0xffff8400
	s_mov_b32 s25, s71
	s_lshl_b64 s[24:25], s[24:25], 12
	global_load_dwordx4 v[2:5], v[14:15], off
	global_load_dwordx4 v[6:9], v[14:15], off offset:1024
	global_load_dwordx4 v[10:13], v[14:15], off offset:2048
	global_load_dwordx4 v[14:17], v[14:15], off offset:3072
	v_lshl_add_u64 v[30:31], v[146:147], 0, s[24:25]
	s_add_i32 s24, s0, 0xffff8800
	s_mov_b32 s25, s71
	global_load_dwordx4 v[18:21], v[30:31], off
	global_load_dwordx4 v[22:25], v[30:31], off offset:1024
	global_load_dwordx4 v[26:29], v[30:31], off offset:2048
	global_load_dwordx4 v[30:33], v[30:31], off offset:3072
	s_lshl_b64 s[24:25], s[24:25], 12
	v_lshl_add_u64 v[46:47], v[146:147], 0, s[24:25]
	s_add_i32 s24, s0, 0xffff8c00
	s_mov_b32 s25, s71
	global_load_dwordx4 v[34:37], v[46:47], off
	global_load_dwordx4 v[38:41], v[46:47], off offset:1024
	global_load_dwordx4 v[42:45], v[46:47], off offset:2048
	global_load_dwordx4 v[46:49], v[46:47], off offset:3072
	s_lshl_b64 s[24:25], s[24:25], 12
	v_lshl_add_u64 v[62:63], v[146:147], 0, s[24:25]
	global_load_dwordx4 v[50:53], v[62:63], off
	global_load_dwordx4 v[54:57], v[62:63], off offset:1024
	global_load_dwordx4 v[58:61], v[62:63], off offset:2048
	global_load_dwordx4 v[62:65], v[62:63], off offset:3072
	s_add_i32 s24, s0, 0xffff9000
	s_mov_b32 s25, s71
	s_lshl_b64 s[24:25], s[24:25], 12
	s_waitcnt vmcnt(15)
	v_pk_add_f32 v[4:5], v[4:5], 0 op_sel_hi:[1,0]
	v_pk_add_f32 v[2:3], v[2:3], 0 op_sel_hi:[1,0]
	s_waitcnt vmcnt(14)
	v_pk_add_f32 v[8:9], v[8:9], 0 op_sel_hi:[1,0]
	s_waitcnt vmcnt(12)
	v_pk_add_f32 v[14:15], v[14:15], 0 op_sel_hi:[1,0]
	v_pk_add_f32 v[6:7], v[6:7], 0 op_sel_hi:[1,0]
	v_pk_add_f32 v[12:13], v[12:13], 0 op_sel_hi:[1,0]
	v_pk_add_f32 v[10:11], v[10:11], 0 op_sel_hi:[1,0]
	s_waitcnt vmcnt(8)
	v_pk_add_f32 v[14:15], v[14:15], v[30:31]
	v_lshl_add_u64 v[30:31], v[146:147], 0, s[24:25]
	s_add_i32 s24, s0, 0xffff9400
	s_mov_b32 s25, s71
	v_pk_add_f32 v[16:17], v[16:17], 0 op_sel_hi:[1,0]
	s_lshl_b64 s[24:25], s[24:25], 12
	v_pk_add_f32 v[4:5], v[4:5], v[20:21]
	v_pk_add_f32 v[2:3], v[2:3], v[18:19]
	v_pk_add_f32 v[8:9], v[8:9], v[24:25]
	v_pk_add_f32 v[6:7], v[6:7], v[22:23]
	v_pk_add_f32 v[12:13], v[12:13], v[28:29]
	v_pk_add_f32 v[10:11], v[10:11], v[26:27]
	v_pk_add_f32 v[16:17], v[16:17], v[32:33]
	s_waitcnt vmcnt(4)
	v_pk_add_f32 v[24:25], v[14:15], v[46:47]
	v_lshl_add_u64 v[46:47], v[146:147], 0, s[24:25]
	s_add_i32 s24, s0, 0xffff9800
	s_mov_b32 s25, s71
	v_pk_add_f32 v[4:5], v[4:5], v[36:37]
	v_pk_add_f32 v[2:3], v[2:3], v[34:35]
	v_pk_add_f32 v[8:9], v[8:9], v[40:41]
	v_pk_add_f32 v[6:7], v[6:7], v[38:39]
	v_pk_add_f32 v[18:19], v[12:13], v[44:45]
	v_pk_add_f32 v[20:21], v[10:11], v[42:43]
	v_pk_add_f32 v[22:23], v[16:17], v[48:49]
	s_lshl_b64 s[24:25], s[24:25], 12
	s_waitcnt vmcnt(3)
	v_pk_add_f32 v[14:15], v[4:5], v[52:53]
	v_pk_add_f32 v[16:17], v[2:3], v[50:51]
	s_waitcnt vmcnt(2)
	v_pk_add_f32 v[10:11], v[8:9], v[56:57]
	v_pk_add_f32 v[12:13], v[6:7], v[54:55]
	s_waitcnt vmcnt(1)
	v_pk_add_f32 v[6:7], v[18:19], v[60:61]
	v_pk_add_f32 v[8:9], v[20:21], v[58:59]
	s_waitcnt vmcnt(0)
	v_pk_add_f32 v[2:3], v[22:23], v[64:65]
	v_pk_add_f32 v[4:5], v[24:25], v[62:63]
	global_load_dwordx4 v[18:21], v[30:31], off
	global_load_dwordx4 v[22:25], v[30:31], off offset:1024
	global_load_dwordx4 v[26:29], v[30:31], off offset:2048
	global_load_dwordx4 v[30:33], v[30:31], off offset:3072
	v_lshl_add_u64 v[62:63], v[146:147], 0, s[24:25]
	s_add_i32 s24, s0, 0xffff9c00
	s_mov_b32 s25, s71
	global_load_dwordx4 v[34:37], v[46:47], off
	global_load_dwordx4 v[38:41], v[46:47], off offset:1024
	global_load_dwordx4 v[42:45], v[46:47], off offset:2048
	global_load_dwordx4 v[46:49], v[46:47], off offset:3072
	s_lshl_b64 s[24:25], s[24:25], 12
	global_load_dwordx4 v[50:53], v[62:63], off
	global_load_dwordx4 v[54:57], v[62:63], off offset:1024
	global_load_dwordx4 v[58:61], v[62:63], off offset:2048
	global_load_dwordx4 v[62:65], v[62:63], off offset:3072
	v_lshl_add_u64 v[82:83], v[146:147], 0, s[24:25]
	global_load_dwordx4 v[66:69], v[82:83], off
	global_load_dwordx4 v[70:73], v[82:83], off offset:1024
	global_load_dwordx4 v[74:77], v[82:83], off offset:2048
	global_load_dwordx4 v[82:85], v[82:83], off offset:3072
	s_add_i32 s24, s0, 0xffffa000
	s_mov_b32 s25, s71
	s_lshl_b64 s[24:25], s[24:25], 12
	s_waitcnt vmcnt(15)
	v_pk_add_f32 v[14:15], v[14:15], v[20:21]
	s_waitcnt vmcnt(14)
	v_pk_add_f32 v[12:13], v[12:13], v[22:23]
	v_pk_add_f32 v[16:17], v[16:17], v[18:19]
	v_pk_add_f32 v[10:11], v[10:11], v[24:25]
	s_waitcnt vmcnt(11)
	v_pk_add_f32 v[14:15], v[14:15], v[36:37]
	s_waitcnt vmcnt(10)
	v_pk_add_f32 v[12:13], v[12:13], v[38:39]
	s_waitcnt vmcnt(7)
	v_pk_add_f32 v[14:15], v[14:15], v[52:53]
	s_waitcnt vmcnt(6)
	v_pk_add_f32 v[12:13], v[12:13], v[54:55]
	s_waitcnt vmcnt(3)
	v_pk_add_f32 v[54:55], v[14:15], v[68:69]
	v_lshl_add_u64 v[14:15], v[146:147], 0, s[24:25]
	s_add_i32 s24, s0, 0xffffa400
	s_mov_b32 s25, s71
	v_pk_add_f32 v[6:7], v[6:7], v[28:29]
	v_pk_add_f32 v[8:9], v[8:9], v[26:27]
	v_pk_add_f32 v[2:3], v[2:3], v[32:33]
	v_pk_add_f32 v[4:5], v[4:5], v[30:31]
	s_lshl_b64 s[24:25], s[24:25], 12
	v_pk_add_f32 v[16:17], v[16:17], v[34:35]
	v_pk_add_f32 v[10:11], v[10:11], v[40:41]
	v_pk_add_f32 v[6:7], v[6:7], v[44:45]
	v_pk_add_f32 v[8:9], v[8:9], v[42:43]
	v_pk_add_f32 v[2:3], v[2:3], v[48:49]
	v_pk_add_f32 v[4:5], v[4:5], v[46:47]
	v_lshl_add_u64 v[30:31], v[146:147], 0, s[24:25]
	s_add_i32 s24, s0, 0xffffa800
	s_mov_b32 s25, s71
	v_pk_add_f32 v[16:17], v[16:17], v[50:51]
	v_pk_add_f32 v[10:11], v[10:11], v[56:57]
	v_pk_add_f32 v[6:7], v[6:7], v[60:61]
	v_pk_add_f32 v[8:9], v[8:9], v[58:59]
	v_pk_add_f32 v[2:3], v[2:3], v[64:65]
	v_pk_add_f32 v[4:5], v[4:5], v[62:63]
	s_lshl_b64 s[24:25], s[24:25], 12
	v_pk_add_f32 v[56:57], v[16:17], v[66:67]
	s_waitcnt vmcnt(2)
; template <int NS> __device__ __forceinline__ void load16part(const float* P, int rowrel, int lane, f32x4 (&v)[4]) {
; #pragma unroll
;     for (int j = 0; j < 4; ++j) v[j] = (f32x4){0.f, 0.f, 0.f, 0.f};
; #pragma unroll
;     for (int s0 = 0; s0 < NS; s0 += 4) { f32x4 t[4][4];
; #pragma unroll
;         for (int s = 0; s < 4; ++s) { const f32x4* q = (const f32x4*)(P + ((size_t)(s0 + s) * 1024 + rowrel) * 1024);
; #pragma unroll
;             for (int j = 0; j < 4; ++j) t[s][j] = q[lane + 64 * j]; }
; #pragma unroll
;         for (int s = 0; s < 4; ++s)
; #pragma unroll
;             for (int j = 0; j < 4; ++j) v[j] += t[s][j]; }
; }
	v_pk_add_f32 v[72:73], v[10:11], v[72:73]
	v_pk_add_f32 v[70:71], v[12:13], v[70:71]
	s_waitcnt vmcnt(1)
	v_pk_add_f32 v[76:77], v[6:7], v[76:77]
	v_pk_add_f32 v[74:75], v[8:9], v[74:75]
	s_waitcnt vmcnt(0)
	v_pk_add_f32 v[84:85], v[2:3], v[84:85]
	v_pk_add_f32 v[82:83], v[4:5], v[82:83]
	global_load_dwordx4 v[2:5], v[14:15], off
	global_load_dwordx4 v[6:9], v[14:15], off offset:1024
	global_load_dwordx4 v[10:13], v[14:15], off offset:2048
	global_load_dwordx4 v[14:17], v[14:15], off offset:3072
	v_lshl_add_u64 v[46:47], v[146:147], 0, s[24:25]
	s_add_i32 s24, s0, 0xffffac00
	s_mov_b32 s25, s71
	global_load_dwordx4 v[18:21], v[30:31], off
	global_load_dwordx4 v[22:25], v[30:31], off offset:1024
	global_load_dwordx4 v[26:29], v[30:31], off offset:2048
	global_load_dwordx4 v[30:33], v[30:31], off offset:3072
	s_lshl_b64 s[24:25], s[24:25], 12
	global_load_dwordx4 v[34:37], v[46:47], off
	global_load_dwordx4 v[38:41], v[46:47], off offset:1024
	global_load_dwordx4 v[42:45], v[46:47], off offset:2048
	global_load_dwordx4 v[46:49], v[46:47], off offset:3072
	v_lshl_add_u64 v[66:67], v[146:147], 0, s[24:25]
	global_load_dwordx4 v[50:53], v[66:67], off
	global_load_dwordx4 v[58:61], v[66:67], off offset:1024
	global_load_dwordx4 v[62:65], v[66:67], off offset:2048
	global_load_dwordx4 v[66:69], v[66:67], off offset:3072
	s_add_i32 s24, s0, 0xffffb000
	s_mov_b32 s25, s71
	s_lshl_b64 s[24:25], s[24:25], 12
	s_waitcnt vmcnt(15)
	v_pk_add_f32 v[2:3], v[56:57], v[2:3]
	v_pk_add_f32 v[4:5], v[54:55], v[4:5]
	s_waitcnt vmcnt(14)
	v_pk_add_f32 v[8:9], v[72:73], v[8:9]
	v_pk_add_f32 v[6:7], v[70:71], v[6:7]
	s_waitcnt vmcnt(11)
	v_pk_add_f32 v[2:3], v[2:3], v[18:19]
	v_pk_add_f32 v[12:13], v[76:77], v[12:13]
	v_pk_add_f32 v[10:11], v[74:75], v[10:11]
	v_pk_add_f32 v[16:17], v[84:85], v[16:17]
	v_pk_add_f32 v[14:15], v[82:83], v[14:15]
	s_waitcnt vmcnt(7)
	v_pk_add_f32 v[2:3], v[2:3], v[34:35]
	v_pk_add_f32 v[4:5], v[4:5], v[20:21]
	v_pk_add_f32 v[8:9], v[8:9], v[24:25]
	v_pk_add_f32 v[6:7], v[6:7], v[22:23]
	v_pk_add_f32 v[12:13], v[12:13], v[28:29]
	v_pk_add_f32 v[10:11], v[10:11], v[26:27]
	v_pk_add_f32 v[16:17], v[16:17], v[32:33]
	v_pk_add_f32 v[14:15], v[14:15], v[30:31]
	s_waitcnt vmcnt(3)
	v_pk_add_f32 v[56:57], v[2:3], v[50:51]
	v_lshl_add_u64 v[2:3], v[146:147], 0, s[24:25]
	s_add_i32 s24, s0, 0xffffb400
	s_mov_b32 s25, s71
	v_pk_add_f32 v[4:5], v[4:5], v[36:37]
	v_pk_add_f32 v[8:9], v[8:9], v[40:41]
	v_pk_add_f32 v[6:7], v[6:7], v[38:39]
	v_pk_add_f32 v[12:13], v[12:13], v[44:45]
	v_pk_add_f32 v[10:11], v[10:11], v[42:43]
	v_pk_add_f32 v[16:17], v[16:17], v[48:49]
	v_pk_add_f32 v[14:15], v[14:15], v[46:47]
	s_lshl_b64 s[24:25], s[24:25], 12
	v_pk_add_f32 v[54:55], v[4:5], v[52:53]
	s_waitcnt vmcnt(2)
	v_pk_add_f32 v[50:51], v[8:9], v[60:61]
	v_pk_add_f32 v[52:53], v[6:7], v[58:59]
	s_waitcnt vmcnt(1)
	v_pk_add_f32 v[46:47], v[12:13], v[64:65]
	v_pk_add_f32 v[48:49], v[10:11], v[62:63]
	s_waitcnt vmcnt(0)
	v_pk_add_f32 v[42:43], v[16:17], v[68:69]
	v_pk_add_f32 v[44:45], v[14:15], v[66:67]
	global_load_dwordx4 v[58:61], v[2:3], off
	global_load_dwordx4 v[62:65], v[2:3], off offset:1024
	global_load_dwordx4 v[66:69], v[2:3], off offset:2048
	global_load_dwordx4 v[70:73], v[2:3], off offset:3072
	v_lshl_add_u64 v[2:3], v[146:147], 0, s[24:25]
	s_add_i32 s24, s0, 0xffffb800
	s_mov_b32 s25, s71
	s_lshl_b64 s[24:25], s[24:25], 12
	global_load_dwordx4 v[74:77], v[2:3], off
	global_load_dwordx4 v[82:85], v[2:3], off offset:1024
	global_load_dwordx4 v[38:41], v[2:3], off offset:2048
	global_load_dwordx4 v[30:33], v[2:3], off offset:3072
	v_lshl_add_u64 v[2:3], v[146:147], 0, s[24:25]
	s_add_i32 s24, s0, 0xffffbc00
	s_mov_b32 s25, s71
	s_lshl_b64 s[24:25], s[24:25], 12
	global_load_dwordx4 v[34:37], v[2:3], off
	global_load_dwordx4 v[26:29], v[2:3], off offset:1024
	global_load_dwordx4 v[22:25], v[2:3], off offset:2048
	global_load_dwordx4 v[14:17], v[2:3], off offset:3072
	v_lshl_add_u64 v[2:3], v[146:147], 0, s[24:25]
	global_load_dwordx4 v[18:21], v[2:3], off
	global_load_dwordx4 v[10:13], v[2:3], off offset:1024
	global_load_dwordx4 v[6:9], v[2:3], off offset:2048
	global_load_dwordx4 v[2:5], v[2:3], off offset:3072
	s_waitcnt vmcnt(15)
	v_pk_add_f32 v[54:55], v[54:55], v[60:61]
	v_pk_add_f32 v[56:57], v[56:57], v[58:59]
	s_waitcnt vmcnt(14)
	v_pk_add_f32 v[50:51], v[50:51], v[64:65]
	v_pk_add_f32 v[52:53], v[52:53], v[62:63]
	s_waitcnt vmcnt(13)
	v_pk_add_f32 v[46:47], v[46:47], v[68:69]
	v_pk_add_f32 v[48:49], v[48:49], v[66:67]
	s_waitcnt vmcnt(12)
	v_pk_add_f32 v[42:43], v[42:43], v[72:73]
	v_pk_add_f32 v[44:45], v[44:45], v[70:71]
	s_waitcnt vmcnt(11)
	v_pk_add_f32 v[54:55], v[54:55], v[76:77]
	v_pk_add_f32 v[56:57], v[56:57], v[74:75]
	s_waitcnt vmcnt(10)
	v_pk_add_f32 v[50:51], v[50:51], v[84:85]
	v_pk_add_f32 v[52:53], v[52:53], v[82:83]
	s_waitcnt vmcnt(9)
	v_pk_add_f32 v[40:41], v[46:47], v[40:41]
	v_pk_add_f32 v[38:39], v[48:49], v[38:39]
	s_waitcnt vmcnt(8)
	v_pk_add_f32 v[32:33], v[42:43], v[32:33]
	v_pk_add_f32 v[30:31], v[44:45], v[30:31]
	s_waitcnt vmcnt(7)
	v_pk_add_f32 v[36:37], v[54:55], v[36:37]
	v_pk_add_f32 v[34:35], v[56:57], v[34:35]
	s_waitcnt vmcnt(6)
	v_pk_add_f32 v[28:29], v[50:51], v[28:29]
	v_pk_add_f32 v[26:27], v[52:53], v[26:27]
	s_waitcnt vmcnt(5)
	v_pk_add_f32 v[24:25], v[40:41], v[24:25]
	v_pk_add_f32 v[22:23], v[38:39], v[22:23]
	s_waitcnt vmcnt(4)
	v_pk_add_f32 v[16:17], v[32:33], v[16:17]
	v_pk_add_f32 v[14:15], v[30:31], v[14:15]
	s_waitcnt vmcnt(3)
	v_pk_add_f32 v[120:121], v[36:37], v[20:21]
	v_pk_add_f32 v[118:119], v[34:35], v[18:19]
	s_waitcnt vmcnt(2)
	v_pk_add_f32 v[68:69], v[28:29], v[12:13]
	v_pk_add_f32 v[66:67], v[26:27], v[10:11]
	s_waitcnt vmcnt(1)
	v_pk_add_f32 v[56:57], v[24:25], v[8:9]
	v_pk_add_f32 v[54:55], v[22:23], v[6:7]
	s_waitcnt vmcnt(0)
	v_pk_add_f32 v[52:53], v[16:17], v[4:5]
	v_pk_add_f32 v[50:51], v[14:15], v[2:3]
	s_cmp_lt_i32 s0, 0x8000
	s_mov_b64 s[26:27], -1
	s_cbranch_scc0 .LBB0_1177

; __device__ __forceinline__ float bflo(unsigned w) { return __uint_as_float(w << 16); }
; __device__ __forceinline__ float bfhi(unsigned w) { return __uint_as_float(w & 0xffff0000u); }
; #define LOADY(m, y, ns) do { if ((m) >= NLAT) load16part<ns>(WSP(float, WS_PART), (m) - NLAT, lane, y); else load16bf(BY + (size_t)(m) * DM, lane, y); } while (0)
; __device__ __forceinline__ void load16(const float* row, int lane, f32x4 (&v)[4]) {
; #pragma unroll
;     for (int j = 0; j < 4; ++j) v[j] = __builtin_nontemporal_load((const f32x4*)row + lane + 64 * j);
; }
; __device__ __forceinline__ void load16bf(const bf16_t* row, int lane, f32x4 (&v)[4]) {
; #pragma unroll
;     for (int j = 0; j < 4; ++j) { const u32x2 w = __builtin_nontemporal_load((const u32x2*)row + lane + 64 * j); v[j] = (f32x4){bflo(w.x), bfhi(w.x), bflo(w.y), bfhi(w.y)}; }
; }
; __global__ void __launch_bounds__(512, 2) fwd_megakernel(Params p) {
;     ...
;             for (int i = 0; i < 4; ++i) { const int mi = m0 + i * NGW, mc = mi < Mact ? mi : m0; LOADY(mc, yb[i], 16); load16(XS_ROW(mc), lane, xb[i]); }
.LBB0_1182:
	s_lshl_b64 s[0:1], s[24:25], 12
	s_waitcnt lgkmcnt(0)
	s_add_u32 s0, s26, s0
	s_addc_u32 s1, s27, s1
	global_load_dwordx4 v[106:109], v139, s[0:1] nt
	global_load_dwordx4 v[90:93], v139, s[0:1] offset:1024 nt
	global_load_dwordx4 v[82:85], v139, s[0:1] offset:2048 nt
	global_load_dwordx4 v[70:73], v139, s[0:1] offset:3072 nt
	s_add_i32 s72, s87, s70
	s_add_i32 s26, s72, 0x8000
	s_cmp_lt_i32 s26, s53
	s_cselect_b64 s[74:75], -1, 0
	s_and_b64 s[0:1], s[74:75], exec
	s_cselect_b32 s0, s26, s13
	s_cmpk_gt_i32 s0, 0x7fff
	s_mov_b64 s[24:25], -1
	s_cbranch_scc1 .LBB0_1186
	s_ashr_i32 s1, s0, 31
	s_lshl_b64 s[24:25], s[0:1], 11
	v_lshl_add_u64 v[2:3], v[140:141], 0, s[24:25]
	global_load_dwordx2 v[4:5], v[2:3], off nt
	global_load_dwordx2 v[6:7], v[2:3], off offset:512 nt
	global_load_dwordx2 v[8:9], v[2:3], off offset:1024 nt
	global_load_dwordx2 v[2:3], v[2:3], off offset:1536 nt
	s_waitcnt vmcnt(3)
	v_lshlrev_b32_e32 v94, 16, v4
	v_and_b32_e32 v95, 0xffff0000, v4
	v_lshlrev_b32_e32 v96, 16, v5
	v_and_b32_e32 v97, 0xffff0000, v5
	s_waitcnt vmcnt(2)
	v_lshlrev_b32_e32 v34, 16, v6
	v_and_b32_e32 v35, 0xffff0000, v6
	v_lshlrev_b32_e32 v36, 16, v7
	v_and_b32_e32 v37, 0xffff0000, v7
	s_waitcnt vmcnt(1)
	v_lshlrev_b32_e32 v26, 16, v8
	v_and_b32_e32 v27, 0xffff0000, v8
	v_lshlrev_b32_e32 v28, 16, v9
	v_and_b32_e32 v29, 0xffff0000, v9
	s_waitcnt vmcnt(0)
	v_lshlrev_b32_e32 v22, 16, v2
	v_and_b32_e32 v23, 0xffff0000, v2
	v_lshlrev_b32_e32 v24, 16, v3
	v_and_b32_e32 v25, 0xffff0000, v3
	s_cbranch_execz .LBB0_1187

; template <int NS> __device__ __forceinline__ void load16part(const float* P, int rowrel, int lane, f32x4 (&v)[4]) {
; #pragma unroll
;     for (int j = 0; j < 4; ++j) v[j] = (f32x4){0.f, 0.f, 0.f, 0.f};
; #pragma unroll
;     for (int s0 = 0; s0 < NS; s0 += 4) { f32x4 t[4][4];
; #pragma unroll
;         for (int s = 0; s < 4; ++s) { const f32x4* q = (const f32x4*)(P + ((size_t)(s0 + s) * 1024 + rowrel) * 1024);
; #pragma unroll
;             for (int j = 0; j < 4; ++j) t[s][j] = q[lane + 64 * j]; }
; #pragma unroll
;         for (int s = 0; s < 4; ++s)
; #pragma unroll
;             for (int j = 0; j < 4; ++j) v[j] += t[s][j]; }
; }
.LBB0_1187:
	s_add_i32 s24, s0, 0xffff8000
	s_mov_b32 s25, s71
	s_lshl_b64 s[24:25], s[24:25], 12
	v_lshl_add_u64 v[14:15], v[146:147], 0, s[24:25]
	s_add_i32 s24, s0, 0xffff8400
	s_mov_b32 s25, s71
	s_lshl_b64 s[24:25], s[24:25], 12
	global_load_dwordx4 v[2:5], v[14:15], off
	global_load_dwordx4 v[6:9], v[14:15], off offset:1024
	global_load_dwordx4 v[10:13], v[14:15], off offset:2048
	global_load_dwordx4 v[14:17], v[14:15], off offset:3072
	v_lshl_add_u64 v[30:31], v[146:147], 0, s[24:25]
	s_add_i32 s24, s0, 0xffff8800
	s_mov_b32 s25, s71
	global_load_dwordx4 v[18:21], v[30:31], off
	global_load_dwordx4 v[22:25], v[30:31], off offset:1024
	global_load_dwordx4 v[26:29], v[30:31], off offset:2048
	global_load_dwordx4 v[30:33], v[30:31], off offset:3072
	s_lshl_b64 s[24:25], s[24:25], 12
	v_lshl_add_u64 v[46:47], v[146:147], 0, s[24:25]
	s_add_i32 s24, s0, 0xffff8c00
	s_mov_b32 s25, s71
	global_load_dwordx4 v[34:37], v[46:47], off
	global_load_dwordx4 v[38:41], v[46:47], off offset:1024
	global_load_dwordx4 v[42:45], v[46:47], off offset:2048
	global_load_dwordx4 v[46:49], v[46:47], off offset:3072
	s_lshl_b64 s[24:25], s[24:25], 12
	v_lshl_add_u64 v[94:95], v[146:147], 0, s[24:25]
	global_load_dwordx4 v[58:61], v[94:95], off
	global_load_dwordx4 v[62:65], v[94:95], off offset:1024
	global_load_dwordx4 v[74:77], v[94:95], off offset:2048
	global_load_dwordx4 v[94:97], v[94:95], off offset:3072
	s_add_i32 s24, s0, 0xffff9000
	s_mov_b32 s25, s71
	s_lshl_b64 s[24:25], s[24:25], 12
	s_waitcnt vmcnt(15)
	v_pk_add_f32 v[4:5], v[4:5], 0 op_sel_hi:[1,0]
	v_pk_add_f32 v[2:3], v[2:3], 0 op_sel_hi:[1,0]
	s_waitcnt vmcnt(14)
	v_pk_add_f32 v[8:9], v[8:9], 0 op_sel_hi:[1,0]
	s_waitcnt vmcnt(12)
	v_pk_add_f32 v[14:15], v[14:15], 0 op_sel_hi:[1,0]
	v_pk_add_f32 v[6:7], v[6:7], 0 op_sel_hi:[1,0]
	v_pk_add_f32 v[12:13], v[12:13], 0 op_sel_hi:[1,0]
	v_pk_add_f32 v[10:11], v[10:11], 0 op_sel_hi:[1,0]
	s_waitcnt vmcnt(8)
	v_pk_add_f32 v[14:15], v[14:15], v[30:31]
	v_lshl_add_u64 v[30:31], v[146:147], 0, s[24:25]
	s_add_i32 s24, s0, 0xffff9400
	s_mov_b32 s25, s71
	v_pk_add_f32 v[16:17], v[16:17], 0 op_sel_hi:[1,0]
	s_lshl_b64 s[24:25], s[24:25], 12
	v_pk_add_f32 v[4:5], v[4:5], v[20:21]
	v_pk_add_f32 v[2:3], v[2:3], v[18:19]
	v_pk_add_f32 v[8:9], v[8:9], v[24:25]
	v_pk_add_f32 v[6:7], v[6:7], v[22:23]
	v_pk_add_f32 v[12:13], v[12:13], v[28:29]
	v_pk_add_f32 v[10:11], v[10:11], v[26:27]
	v_pk_add_f32 v[16:17], v[16:17], v[32:33]
	s_waitcnt vmcnt(4)
	v_pk_add_f32 v[24:25], v[14:15], v[46:47]
	v_lshl_add_u64 v[46:47], v[146:147], 0, s[24:25]
	s_add_i32 s24, s0, 0xffff9800
	s_mov_b32 s25, s71
	v_pk_add_f32 v[4:5], v[4:5], v[36:37]
	v_pk_add_f32 v[2:3], v[2:3], v[34:35]
	v_pk_add_f32 v[8:9], v[8:9], v[40:41]
	v_pk_add_f32 v[6:7], v[6:7], v[38:39]
	v_pk_add_f32 v[18:19], v[12:13], v[44:45]
	v_pk_add_f32 v[20:21], v[10:11], v[42:43]
	v_pk_add_f32 v[22:23], v[16:17], v[48:49]
	s_lshl_b64 s[24:25], s[24:25], 12
	s_waitcnt vmcnt(3)
	v_pk_add_f32 v[14:15], v[4:5], v[60:61]
	v_pk_add_f32 v[16:17], v[2:3], v[58:59]
	s_waitcnt vmcnt(2)
	v_pk_add_f32 v[10:11], v[8:9], v[64:65]
	v_pk_add_f32 v[12:13], v[6:7], v[62:63]
	s_waitcnt vmcnt(1)
	v_pk_add_f32 v[6:7], v[18:19], v[76:77]
	v_pk_add_f32 v[8:9], v[20:21], v[74:75]
	s_waitcnt vmcnt(0)
	v_pk_add_f32 v[2:3], v[22:23], v[96:97]
	v_pk_add_f32 v[4:5], v[24:25], v[94:95]
	global_load_dwordx4 v[18:21], v[30:31], off
	global_load_dwordx4 v[22:25], v[30:31], off offset:1024
	global_load_dwordx4 v[26:29], v[30:31], off offset:2048
	global_load_dwordx4 v[30:33], v[30:31], off offset:3072
	v_lshl_add_u64 v[94:95], v[146:147], 0, s[24:25]
	s_add_i32 s24, s0, 0xffff9c00
	s_mov_b32 s25, s71
	global_load_dwordx4 v[34:37], v[46:47], off
	global_load_dwordx4 v[38:41], v[46:47], off offset:1024
	global_load_dwordx4 v[42:45], v[46:47], off offset:2048
	global_load_dwordx4 v[46:49], v[46:47], off offset:3072
	s_lshl_b64 s[24:25], s[24:25], 12
	global_load_dwordx4 v[58:61], v[94:95], off
	global_load_dwordx4 v[62:65], v[94:95], off offset:1024
	global_load_dwordx4 v[74:77], v[94:95], off offset:2048
	global_load_dwordx4 v[94:97], v[94:95], off offset:3072
	v_lshl_add_u64 v[156:157], v[146:147], 0, s[24:25]
	global_load_dwordx4 v[130:133], v[156:157], off
	global_load_dwordx4 v[134:137], v[156:157], off offset:1024
	global_load_dwordx4 v[152:155], v[156:157], off offset:2048
	global_load_dwordx4 v[156:159], v[156:157], off offset:3072
	s_add_i32 s24, s0, 0xffffa000
	s_mov_b32 s25, s71
	s_lshl_b64 s[24:25], s[24:25], 12
	s_waitcnt vmcnt(15)
	v_pk_add_f32 v[14:15], v[14:15], v[20:21]
	s_waitcnt vmcnt(14)
	v_pk_add_f32 v[12:13], v[12:13], v[22:23]
	v_pk_add_f32 v[16:17], v[16:17], v[18:19]
	v_pk_add_f32 v[10:11], v[10:11], v[24:25]
	s_waitcnt vmcnt(11)
	v_pk_add_f32 v[14:15], v[14:15], v[36:37]
	s_waitcnt vmcnt(10)
	v_pk_add_f32 v[12:13], v[12:13], v[38:39]
	s_waitcnt vmcnt(7)
	v_pk_add_f32 v[14:15], v[14:15], v[60:61]
	s_waitcnt vmcnt(6)
	v_pk_add_f32 v[12:13], v[12:13], v[62:63]
	s_waitcnt vmcnt(3)
	v_pk_add_f32 v[62:63], v[14:15], v[132:133]
	v_lshl_add_u64 v[14:15], v[146:147], 0, s[24:25]
	s_add_i32 s24, s0, 0xffffa400
	s_mov_b32 s25, s71
	v_pk_add_f32 v[6:7], v[6:7], v[28:29]
	v_pk_add_f32 v[8:9], v[8:9], v[26:27]
	v_pk_add_f32 v[2:3], v[2:3], v[32:33]
	v_pk_add_f32 v[4:5], v[4:5], v[30:31]
	s_lshl_b64 s[24:25], s[24:25], 12
	v_pk_add_f32 v[16:17], v[16:17], v[34:35]
	v_pk_add_f32 v[10:11], v[10:11], v[40:41]
	v_pk_add_f32 v[6:7], v[6:7], v[44:45]
	v_pk_add_f32 v[8:9], v[8:9], v[42:43]
	v_pk_add_f32 v[2:3], v[2:3], v[48:49]
	v_pk_add_f32 v[4:5], v[4:5], v[46:47]
	v_lshl_add_u64 v[30:31], v[146:147], 0, s[24:25]
	s_add_i32 s24, s0, 0xffffa800
	s_mov_b32 s25, s71
	v_pk_add_f32 v[16:17], v[16:17], v[58:59]
	v_pk_add_f32 v[10:11], v[10:11], v[64:65]
	v_pk_add_f32 v[6:7], v[6:7], v[76:77]
	v_pk_add_f32 v[8:9], v[8:9], v[74:75]
	v_pk_add_f32 v[2:3], v[2:3], v[96:97]
	v_pk_add_f32 v[4:5], v[4:5], v[94:95]
	s_lshl_b64 s[24:25], s[24:25], 12
	v_pk_add_f32 v[64:65], v[16:17], v[130:131]
	s_waitcnt vmcnt(2)
; template <int NS> __device__ __forceinline__ void load16part(const float* P, int rowrel, int lane, f32x4 (&v)[4]) {
; #pragma unroll
;     for (int j = 0; j < 4; ++j) v[j] = (f32x4){0.f, 0.f, 0.f, 0.f};
; #pragma unroll
;     for (int s0 = 0; s0 < NS; s0 += 4) { f32x4 t[4][4];
; #pragma unroll
;         for (int s = 0; s < 4; ++s) { const f32x4* q = (const f32x4*)(P + ((size_t)(s0 + s) * 1024 + rowrel) * 1024);
; #pragma unroll
;             for (int j = 0; j < 4; ++j) t[s][j] = q[lane + 64 * j]; }
; #pragma unroll
;         for (int s = 0; s < 4; ++s)
; #pragma unroll
;             for (int j = 0; j < 4; ++j) v[j] += t[s][j]; }
; }
	v_pk_add_f32 v[136:137], v[10:11], v[136:137]
	v_pk_add_f32 v[134:135], v[12:13], v[134:135]
	s_waitcnt vmcnt(1)
	v_pk_add_f32 v[154:155], v[6:7], v[154:155]
	v_pk_add_f32 v[152:153], v[8:9], v[152:153]
	s_waitcnt vmcnt(0)
	v_pk_add_f32 v[158:159], v[2:3], v[158:159]
	v_pk_add_f32 v[156:157], v[4:5], v[156:157]
	global_load_dwordx4 v[2:5], v[14:15], off
	global_load_dwordx4 v[6:9], v[14:15], off offset:1024
	global_load_dwordx4 v[10:13], v[14:15], off offset:2048
	global_load_dwordx4 v[14:17], v[14:15], off offset:3072
	v_lshl_add_u64 v[46:47], v[146:147], 0, s[24:25]
	s_add_i32 s24, s0, 0xffffac00
	s_mov_b32 s25, s71
	global_load_dwordx4 v[18:21], v[30:31], off
	global_load_dwordx4 v[22:25], v[30:31], off offset:1024
	global_load_dwordx4 v[26:29], v[30:31], off offset:2048
	global_load_dwordx4 v[30:33], v[30:31], off offset:3072
	s_lshl_b64 s[24:25], s[24:25], 12
	global_load_dwordx4 v[34:37], v[46:47], off
	global_load_dwordx4 v[38:41], v[46:47], off offset:1024
	global_load_dwordx4 v[42:45], v[46:47], off offset:2048
	global_load_dwordx4 v[46:49], v[46:47], off offset:3072
	v_lshl_add_u64 v[130:131], v[146:147], 0, s[24:25]
	global_load_dwordx4 v[58:61], v[130:131], off
	global_load_dwordx4 v[74:77], v[130:131], off offset:1024
	global_load_dwordx4 v[94:97], v[130:131], off offset:2048
	global_load_dwordx4 v[130:133], v[130:131], off offset:3072
	s_add_i32 s24, s0, 0xffffb000
	s_mov_b32 s25, s71
	s_lshl_b64 s[24:25], s[24:25], 12
	s_waitcnt vmcnt(15)
	v_pk_add_f32 v[2:3], v[64:65], v[2:3]
	v_pk_add_f32 v[4:5], v[62:63], v[4:5]
	s_waitcnt vmcnt(14)
	v_pk_add_f32 v[8:9], v[136:137], v[8:9]
	v_pk_add_f32 v[6:7], v[134:135], v[6:7]
	s_waitcnt vmcnt(11)
	v_pk_add_f32 v[2:3], v[2:3], v[18:19]
	v_pk_add_f32 v[12:13], v[154:155], v[12:13]
	v_pk_add_f32 v[10:11], v[152:153], v[10:11]
	v_pk_add_f32 v[16:17], v[158:159], v[16:17]
	v_pk_add_f32 v[14:15], v[156:157], v[14:15]
	s_waitcnt vmcnt(7)
	v_pk_add_f32 v[2:3], v[2:3], v[34:35]
	v_pk_add_f32 v[4:5], v[4:5], v[20:21]
	v_pk_add_f32 v[8:9], v[8:9], v[24:25]
	v_pk_add_f32 v[6:7], v[6:7], v[22:23]
	v_pk_add_f32 v[12:13], v[12:13], v[28:29]
	v_pk_add_f32 v[10:11], v[10:11], v[26:27]
	v_pk_add_f32 v[16:17], v[16:17], v[32:33]
	v_pk_add_f32 v[14:15], v[14:15], v[30:31]
	s_waitcnt vmcnt(3)
	v_pk_add_f32 v[64:65], v[2:3], v[58:59]
	v_lshl_add_u64 v[2:3], v[146:147], 0, s[24:25]
	s_add_i32 s24, s0, 0xffffb400
	s_mov_b32 s25, s71
	v_pk_add_f32 v[4:5], v[4:5], v[36:37]
	v_pk_add_f32 v[8:9], v[8:9], v[40:41]
	v_pk_add_f32 v[6:7], v[6:7], v[38:39]
	v_pk_add_f32 v[12:13], v[12:13], v[44:45]
	v_pk_add_f32 v[10:11], v[10:11], v[42:43]
	v_pk_add_f32 v[16:17], v[16:17], v[48:49]
	v_pk_add_f32 v[14:15], v[14:15], v[46:47]
	s_lshl_b64 s[24:25], s[24:25], 12
	v_pk_add_f32 v[62:63], v[4:5], v[60:61]
	s_waitcnt vmcnt(2)
	v_pk_add_f32 v[58:59], v[8:9], v[76:77]
	v_pk_add_f32 v[60:61], v[6:7], v[74:75]
	s_waitcnt vmcnt(1)
	v_pk_add_f32 v[46:47], v[12:13], v[96:97]
	v_pk_add_f32 v[48:49], v[10:11], v[94:95]
	s_waitcnt vmcnt(0)
	v_pk_add_f32 v[42:43], v[16:17], v[132:133]
	v_pk_add_f32 v[44:45], v[14:15], v[130:131]
	global_load_dwordx4 v[74:77], v[2:3], off
	global_load_dwordx4 v[94:97], v[2:3], off offset:1024
	global_load_dwordx4 v[130:133], v[2:3], off offset:2048
	global_load_dwordx4 v[134:137], v[2:3], off offset:3072
	v_lshl_add_u64 v[2:3], v[146:147], 0, s[24:25]
	s_add_i32 s24, s0, 0xffffb800
	s_mov_b32 s25, s71
	s_lshl_b64 s[24:25], s[24:25], 12
	global_load_dwordx4 v[152:155], v[2:3], off
	global_load_dwordx4 v[156:159], v[2:3], off offset:1024
	global_load_dwordx4 v[38:41], v[2:3], off offset:2048
	global_load_dwordx4 v[30:33], v[2:3], off offset:3072
	v_lshl_add_u64 v[2:3], v[146:147], 0, s[24:25]
	s_add_i32 s24, s0, 0xffffbc00
	s_mov_b32 s25, s71
	s_lshl_b64 s[24:25], s[24:25], 12
	global_load_dwordx4 v[34:37], v[2:3], off
	global_load_dwordx4 v[26:29], v[2:3], off offset:1024
	global_load_dwordx4 v[22:25], v[2:3], off offset:2048
	global_load_dwordx4 v[14:17], v[2:3], off offset:3072
	v_lshl_add_u64 v[2:3], v[146:147], 0, s[24:25]
	global_load_dwordx4 v[18:21], v[2:3], off
	global_load_dwordx4 v[10:13], v[2:3], off offset:1024
	global_load_dwordx4 v[6:9], v[2:3], off offset:2048
	global_load_dwordx4 v[2:5], v[2:3], off offset:3072
	s_waitcnt vmcnt(15)
	v_pk_add_f32 v[62:63], v[62:63], v[76:77]
	v_pk_add_f32 v[64:65], v[64:65], v[74:75]
	s_waitcnt vmcnt(14)
	v_pk_add_f32 v[58:59], v[58:59], v[96:97]
	v_pk_add_f32 v[60:61], v[60:61], v[94:95]
	s_waitcnt vmcnt(13)
	v_pk_add_f32 v[46:47], v[46:47], v[132:133]
	v_pk_add_f32 v[48:49], v[48:49], v[130:131]
	s_waitcnt vmcnt(12)
	v_pk_add_f32 v[42:43], v[42:43], v[136:137]
	v_pk_add_f32 v[44:45], v[44:45], v[134:135]
	s_waitcnt vmcnt(11)
	v_pk_add_f32 v[62:63], v[62:63], v[154:155]
	v_pk_add_f32 v[64:65], v[64:65], v[152:153]
	s_waitcnt vmcnt(10)
	v_pk_add_f32 v[58:59], v[58:59], v[158:159]
	v_pk_add_f32 v[60:61], v[60:61], v[156:157]
	s_waitcnt vmcnt(9)
	v_pk_add_f32 v[40:41], v[46:47], v[40:41]
	v_pk_add_f32 v[38:39], v[48:49], v[38:39]
	s_waitcnt vmcnt(8)
	v_pk_add_f32 v[32:33], v[42:43], v[32:33]
	v_pk_add_f32 v[30:31], v[44:45], v[30:31]
	s_waitcnt vmcnt(7)
	v_pk_add_f32 v[36:37], v[62:63], v[36:37]
	v_pk_add_f32 v[34:35], v[64:65], v[34:35]
	s_waitcnt vmcnt(6)
	v_pk_add_f32 v[28:29], v[58:59], v[28:29]
	v_pk_add_f32 v[26:27], v[60:61], v[26:27]
	s_waitcnt vmcnt(5)
	v_pk_add_f32 v[24:25], v[40:41], v[24:25]
	v_pk_add_f32 v[22:23], v[38:39], v[22:23]
	s_waitcnt vmcnt(4)
	v_pk_add_f32 v[16:17], v[32:33], v[16:17]
	v_pk_add_f32 v[14:15], v[30:31], v[14:15]
	s_waitcnt vmcnt(3)
	v_pk_add_f32 v[96:97], v[36:37], v[20:21]
	v_pk_add_f32 v[94:95], v[34:35], v[18:19]
	s_waitcnt vmcnt(2)
	v_pk_add_f32 v[36:37], v[28:29], v[12:13]
	v_pk_add_f32 v[34:35], v[26:27], v[10:11]
	s_waitcnt vmcnt(1)
	v_pk_add_f32 v[28:29], v[24:25], v[8:9]
	v_pk_add_f32 v[26:27], v[22:23], v[6:7]
	s_waitcnt vmcnt(0)
	v_pk_add_f32 v[24:25], v[16:17], v[4:5]
	v_pk_add_f32 v[22:23], v[14:15], v[2:3]
	s_cmp_lt_i32 s0, 0x8000
	s_mov_b64 s[46:47], -1
	s_cbranch_scc0 .LBB0_1185

; template <int NS> __device__ __forceinline__ void load16part(const float* P, int rowrel, int lane, f32x4 (&v)[4]) {
; #pragma unroll
;     for (int j = 0; j < 4; ++j) v[j] = (f32x4){0.f, 0.f, 0.f, 0.f};
; #pragma unroll
;     for (int s0 = 0; s0 < NS; s0 += 4) { f32x4 t[4][4];
; #pragma unroll
;         for (int s = 0; s < 4; ++s) { const f32x4* q = (const f32x4*)(P + ((size_t)(s0 + s) * 1024 + rowrel) * 1024);
; #pragma unroll
;             for (int j = 0; j < 4; ++j) t[s][j] = q[lane + 64 * j]; }
; #pragma unroll
;         for (int s = 0; s < 4; ++s)
; #pragma unroll
;             for (int j = 0; j < 4; ++j) v[j] += t[s][j]; }
; }
.LBB0_1195:
	s_add_i32 s36, s0, 0xffff8000
	s_mov_b32 s37, s71
	s_lshl_b64 s[36:37], s[36:37], 12
	v_lshl_add_u64 v[14:15], v[146:147], 0, s[36:37]
	s_add_i32 s36, s0, 0xffff8400
	s_mov_b32 s37, s71
	s_lshl_b64 s[36:37], s[36:37], 12
	global_load_dwordx4 v[2:5], v[14:15], off
	global_load_dwordx4 v[6:9], v[14:15], off offset:1024
	global_load_dwordx4 v[10:13], v[14:15], off offset:2048
	global_load_dwordx4 v[14:17], v[14:15], off offset:3072
	v_lshl_add_u64 v[62:63], v[146:147], 0, s[36:37]
	s_add_i32 s36, s0, 0xffff8800
	s_mov_b32 s37, s71
	global_load_dwordx4 v[18:21], v[62:63], off
	global_load_dwordx4 v[30:33], v[62:63], off offset:1024
	global_load_dwordx4 v[42:45], v[62:63], off offset:2048
	global_load_dwordx4 v[62:65], v[62:63], off offset:3072
	s_lshl_b64 s[36:37], s[36:37], 12
	v_lshl_add_u64 v[156:157], v[146:147], 0, s[36:37]
	s_add_i32 s36, s0, 0xffff8c00
	s_mov_b32 s37, s71
	global_load_dwordx4 v[130:133], v[156:157], off
	global_load_dwordx4 v[134:137], v[156:157], off offset:1024
	global_load_dwordx4 v[152:155], v[156:157], off offset:2048
	global_load_dwordx4 v[156:159], v[156:157], off offset:3072
	s_lshl_b64 s[36:37], s[36:37], 12
	v_lshl_add_u64 v[172:173], v[146:147], 0, s[36:37]
	global_load_dwordx4 v[160:163], v[172:173], off
	global_load_dwordx4 v[164:167], v[172:173], off offset:1024
	global_load_dwordx4 v[168:171], v[172:173], off offset:2048
	global_load_dwordx4 v[178:181], v[172:173], off offset:3072
	s_add_i32 s36, s0, 0xffff9000
	s_mov_b32 s37, s71
	s_lshl_b64 s[36:37], s[36:37], 12
	s_waitcnt vmcnt(15)
	v_pk_add_f32 v[4:5], v[4:5], 0 op_sel_hi:[1,0]
	v_pk_add_f32 v[2:3], v[2:3], 0 op_sel_hi:[1,0]
	s_waitcnt vmcnt(14)
	v_pk_add_f32 v[8:9], v[8:9], 0 op_sel_hi:[1,0]
	s_waitcnt vmcnt(12)
	v_pk_add_f32 v[14:15], v[14:15], 0 op_sel_hi:[1,0]
	v_pk_add_f32 v[6:7], v[6:7], 0 op_sel_hi:[1,0]
	v_pk_add_f32 v[12:13], v[12:13], 0 op_sel_hi:[1,0]
	v_pk_add_f32 v[10:11], v[10:11], 0 op_sel_hi:[1,0]
	s_waitcnt vmcnt(8)
	v_pk_add_f32 v[14:15], v[14:15], v[62:63]
	v_lshl_add_u64 v[62:63], v[146:147], 0, s[36:37]
	s_add_i32 s36, s0, 0xffff9400
	s_mov_b32 s37, s71
	v_pk_add_f32 v[16:17], v[16:17], 0 op_sel_hi:[1,0]
	s_lshl_b64 s[36:37], s[36:37], 12
	v_pk_add_f32 v[4:5], v[4:5], v[20:21]
	v_pk_add_f32 v[2:3], v[2:3], v[18:19]
	v_pk_add_f32 v[8:9], v[8:9], v[32:33]
	v_pk_add_f32 v[6:7], v[6:7], v[30:31]
	v_pk_add_f32 v[12:13], v[12:13], v[44:45]
	v_pk_add_f32 v[10:11], v[10:11], v[42:43]
	v_pk_add_f32 v[16:17], v[16:17], v[64:65]
	s_waitcnt vmcnt(4)
	v_pk_add_f32 v[32:33], v[14:15], v[156:157]
	v_lshl_add_u64 v[156:157], v[146:147], 0, s[36:37]
	s_add_i32 s36, s0, 0xffff9800
	s_mov_b32 s37, s71
	v_pk_add_f32 v[4:5], v[4:5], v[132:133]
	v_pk_add_f32 v[2:3], v[2:3], v[130:131]
	v_pk_add_f32 v[8:9], v[8:9], v[136:137]
	v_pk_add_f32 v[6:7], v[6:7], v[134:135]
	v_pk_add_f32 v[18:19], v[12:13], v[154:155]
	v_pk_add_f32 v[20:21], v[10:11], v[152:153]
	v_pk_add_f32 v[30:31], v[16:17], v[158:159]
	s_lshl_b64 s[36:37], s[36:37], 12
	s_waitcnt vmcnt(3)
	v_pk_add_f32 v[14:15], v[4:5], v[162:163]
	v_pk_add_f32 v[16:17], v[2:3], v[160:161]
	s_waitcnt vmcnt(2)
	v_pk_add_f32 v[10:11], v[8:9], v[166:167]
	v_pk_add_f32 v[12:13], v[6:7], v[164:165]
	s_waitcnt vmcnt(1)
	v_pk_add_f32 v[6:7], v[18:19], v[170:171]
	v_pk_add_f32 v[8:9], v[20:21], v[168:169]
	s_waitcnt vmcnt(0)
	v_pk_add_f32 v[2:3], v[30:31], v[180:181]
	v_pk_add_f32 v[4:5], v[32:33], v[178:179]
	global_load_dwordx4 v[18:21], v[62:63], off
	global_load_dwordx4 v[30:33], v[62:63], off offset:1024
	global_load_dwordx4 v[42:45], v[62:63], off offset:2048
	global_load_dwordx4 v[62:65], v[62:63], off offset:3072
	v_lshl_add_u64 v[172:173], v[146:147], 0, s[36:37]
	s_add_i32 s36, s0, 0xffff9c00
	s_mov_b32 s37, s71
	global_load_dwordx4 v[130:133], v[156:157], off
	global_load_dwordx4 v[134:137], v[156:157], off offset:1024
	global_load_dwordx4 v[152:155], v[156:157], off offset:2048
	global_load_dwordx4 v[156:159], v[156:157], off offset:3072
	s_lshl_b64 s[36:37], s[36:37], 12
	global_load_dwordx4 v[160:163], v[172:173], off
	global_load_dwordx4 v[164:167], v[172:173], off offset:1024
	global_load_dwordx4 v[168:171], v[172:173], off offset:2048
	global_load_dwordx4 v[178:181], v[172:173], off offset:3072
	v_lshl_add_u64 v[172:173], v[146:147], 0, s[36:37]
	global_load_dwordx4 v[188:191], v[172:173], off
	global_load_dwordx4 v[192:195], v[172:173], off offset:1024
	global_load_dwordx4 v[196:199], v[172:173], off offset:2048
	global_load_dwordx4 v[200:203], v[172:173], off offset:3072
	s_add_i32 s36, s0, 0xffffa000
	s_mov_b32 s37, s71
	s_lshl_b64 s[36:37], s[36:37], 12
	s_waitcnt vmcnt(15)
	v_pk_add_f32 v[14:15], v[14:15], v[20:21]
	v_pk_add_f32 v[16:17], v[16:17], v[18:19]
	s_waitcnt vmcnt(14)
	v_pk_add_f32 v[10:11], v[10:11], v[32:33]
	v_pk_add_f32 v[12:13], v[12:13], v[30:31]
	s_waitcnt vmcnt(11)
	v_pk_add_f32 v[14:15], v[14:15], v[132:133]
	v_pk_add_f32 v[6:7], v[6:7], v[44:45]
	s_waitcnt vmcnt(7)
	v_pk_add_f32 v[14:15], v[14:15], v[162:163]
	v_pk_add_f32 v[8:9], v[8:9], v[42:43]
	s_waitcnt vmcnt(3)
	v_pk_add_f32 v[172:173], v[14:15], v[190:191]
	v_lshl_add_u64 v[14:15], v[146:147], 0, s[36:37]
	s_add_i32 s36, s0, 0xffffa400
	s_mov_b32 s37, s71
	v_pk_add_f32 v[2:3], v[2:3], v[64:65]
	v_pk_add_f32 v[4:5], v[4:5], v[62:63]
	s_lshl_b64 s[36:37], s[36:37], 12
	v_pk_add_f32 v[16:17], v[16:17], v[130:131]
	v_pk_add_f32 v[10:11], v[10:11], v[136:137]
	v_pk_add_f32 v[12:13], v[12:13], v[134:135]
	v_pk_add_f32 v[6:7], v[6:7], v[154:155]
	v_pk_add_f32 v[8:9], v[8:9], v[152:153]
	v_pk_add_f32 v[2:3], v[2:3], v[158:159]
	v_pk_add_f32 v[4:5], v[4:5], v[156:157]
	v_lshl_add_u64 v[62:63], v[146:147], 0, s[36:37]
	s_add_i32 s36, s0, 0xffffa800
	s_mov_b32 s37, s71
	v_pk_add_f32 v[16:17], v[16:17], v[160:161]
	v_pk_add_f32 v[10:11], v[10:11], v[166:167]
	v_pk_add_f32 v[12:13], v[12:13], v[164:165]
	v_pk_add_f32 v[6:7], v[6:7], v[170:171]
	v_pk_add_f32 v[8:9], v[8:9], v[168:169]
	v_pk_add_f32 v[2:3], v[2:3], v[180:181]
	v_pk_add_f32 v[4:5], v[4:5], v[178:179]
	s_lshl_b64 s[36:37], s[36:37], 12
	v_pk_add_f32 v[174:175], v[16:17], v[188:189]
	s_waitcnt vmcnt(2)
; template <int NS> __device__ __forceinline__ void load16part(const float* P, int rowrel, int lane, f32x4 (&v)[4]) {
; #pragma unroll
;     for (int j = 0; j < 4; ++j) v[j] = (f32x4){0.f, 0.f, 0.f, 0.f};
; #pragma unroll
;     for (int s0 = 0; s0 < NS; s0 += 4) { f32x4 t[4][4];
; #pragma unroll
;         for (int s = 0; s < 4; ++s) { const f32x4* q = (const f32x4*)(P + ((size_t)(s0 + s) * 1024 + rowrel) * 1024);
; #pragma unroll
;             for (int j = 0; j < 4; ++j) t[s][j] = q[lane + 64 * j]; }
; #pragma unroll
;         for (int s = 0; s < 4; ++s)
; #pragma unroll
;             for (int j = 0; j < 4; ++j) v[j] += t[s][j]; }
; }
	v_pk_add_f32 v[178:179], v[10:11], v[194:195]
	v_pk_add_f32 v[180:181], v[12:13], v[192:193]
	s_waitcnt vmcnt(1)
	v_pk_add_f32 v[182:183], v[6:7], v[198:199]
	v_pk_add_f32 v[192:193], v[8:9], v[196:197]
	s_waitcnt vmcnt(0)
	v_pk_add_f32 v[194:195], v[2:3], v[202:203]
	v_pk_add_f32 v[196:197], v[4:5], v[200:201]
	global_load_dwordx4 v[2:5], v[14:15], off
	global_load_dwordx4 v[6:9], v[14:15], off offset:1024
	global_load_dwordx4 v[10:13], v[14:15], off offset:2048
	global_load_dwordx4 v[14:17], v[14:15], off offset:3072
	v_lshl_add_u64 v[156:157], v[146:147], 0, s[36:37]
	s_add_i32 s36, s0, 0xffffac00
	s_mov_b32 s37, s71
	global_load_dwordx4 v[18:21], v[62:63], off
	global_load_dwordx4 v[30:33], v[62:63], off offset:1024
	global_load_dwordx4 v[42:45], v[62:63], off offset:2048
	global_load_dwordx4 v[62:65], v[62:63], off offset:3072
	s_lshl_b64 s[36:37], s[36:37], 12
	global_load_dwordx4 v[130:133], v[156:157], off
	global_load_dwordx4 v[134:137], v[156:157], off offset:1024
	global_load_dwordx4 v[152:155], v[156:157], off offset:2048
	global_load_dwordx4 v[156:159], v[156:157], off offset:3072
	v_lshl_add_u64 v[188:189], v[146:147], 0, s[36:37]
	global_load_dwordx4 v[160:163], v[188:189], off
	global_load_dwordx4 v[164:167], v[188:189], off offset:1024
	global_load_dwordx4 v[168:171], v[188:189], off offset:2048
	global_load_dwordx4 v[188:191], v[188:189], off offset:3072
	s_add_i32 s36, s0, 0xffffb000
	s_mov_b32 s37, s71
	s_lshl_b64 s[36:37], s[36:37], 12
	s_waitcnt vmcnt(15)
	v_pk_add_f32 v[2:3], v[174:175], v[2:3]
	v_pk_add_f32 v[4:5], v[172:173], v[4:5]
	s_waitcnt vmcnt(14)
	v_pk_add_f32 v[8:9], v[178:179], v[8:9]
	v_pk_add_f32 v[6:7], v[180:181], v[6:7]
	s_waitcnt vmcnt(11)
	v_pk_add_f32 v[2:3], v[2:3], v[18:19]
	v_pk_add_f32 v[12:13], v[182:183], v[12:13]
	v_pk_add_f32 v[10:11], v[192:193], v[10:11]
	v_pk_add_f32 v[16:17], v[194:195], v[16:17]
	v_pk_add_f32 v[14:15], v[196:197], v[14:15]
	s_waitcnt vmcnt(7)
	v_pk_add_f32 v[2:3], v[2:3], v[130:131]
	v_pk_add_f32 v[4:5], v[4:5], v[20:21]
	v_pk_add_f32 v[8:9], v[8:9], v[32:33]
	v_pk_add_f32 v[6:7], v[6:7], v[30:31]
	v_pk_add_f32 v[12:13], v[12:13], v[44:45]
	v_pk_add_f32 v[10:11], v[10:11], v[42:43]
	v_pk_add_f32 v[16:17], v[16:17], v[64:65]
	v_pk_add_f32 v[14:15], v[14:15], v[62:63]
	s_waitcnt vmcnt(3)
	v_pk_add_f32 v[182:183], v[2:3], v[160:161]
	v_lshl_add_u64 v[2:3], v[146:147], 0, s[36:37]
	s_add_i32 s36, s0, 0xffffb400
	s_mov_b32 s37, s71
	v_pk_add_f32 v[4:5], v[4:5], v[132:133]
	v_pk_add_f32 v[8:9], v[8:9], v[136:137]
	v_pk_add_f32 v[6:7], v[6:7], v[134:135]
	v_pk_add_f32 v[12:13], v[12:13], v[154:155]
	v_pk_add_f32 v[10:11], v[10:11], v[152:153]
	v_pk_add_f32 v[16:17], v[16:17], v[158:159]
	v_pk_add_f32 v[14:15], v[14:15], v[156:157]
	s_lshl_b64 s[36:37], s[36:37], 12
	v_pk_add_f32 v[180:181], v[4:5], v[162:163]
	s_waitcnt vmcnt(2)
	v_pk_add_f32 v[160:161], v[8:9], v[166:167]
	v_pk_add_f32 v[178:179], v[6:7], v[164:165]
	s_waitcnt vmcnt(1)
	v_pk_add_f32 v[156:157], v[12:13], v[170:171]
	v_pk_add_f32 v[158:159], v[10:11], v[168:169]
	s_waitcnt vmcnt(0)
	v_pk_add_f32 v[152:153], v[16:17], v[190:191]
	v_pk_add_f32 v[154:155], v[14:15], v[188:189]
	global_load_dwordx4 v[162:165], v[2:3], off
	global_load_dwordx4 v[166:169], v[2:3], off offset:1024
	global_load_dwordx4 v[170:173], v[2:3], off offset:2048
	global_load_dwordx4 v[188:191], v[2:3], off offset:3072
	v_lshl_add_u64 v[2:3], v[146:147], 0, s[36:37]
	s_add_i32 s36, s0, 0xffffb800
	s_mov_b32 s37, s71
	s_lshl_b64 s[36:37], s[36:37], 12
	global_load_dwordx4 v[192:195], v[2:3], off
	global_load_dwordx4 v[196:199], v[2:3], off offset:1024
	global_load_dwordx4 v[134:137], v[2:3], off offset:2048
	global_load_dwordx4 v[62:65], v[2:3], off offset:3072
	v_lshl_add_u64 v[2:3], v[146:147], 0, s[36:37]
	s_add_i32 s36, s0, 0xffffbc00
	s_mov_b32 s37, s71
	s_lshl_b64 s[36:37], s[36:37], 12
	global_load_dwordx4 v[130:133], v[2:3], off
	global_load_dwordx4 v[42:45], v[2:3], off offset:1024
	global_load_dwordx4 v[30:33], v[2:3], off offset:2048
	global_load_dwordx4 v[14:17], v[2:3], off offset:3072
	v_lshl_add_u64 v[2:3], v[146:147], 0, s[36:37]
	global_load_dwordx4 v[18:21], v[2:3], off
	global_load_dwordx4 v[10:13], v[2:3], off offset:1024
	global_load_dwordx4 v[6:9], v[2:3], off offset:2048
	global_load_dwordx4 v[2:5], v[2:3], off offset:3072
	s_waitcnt vmcnt(15)
	v_pk_add_f32 v[164:165], v[180:181], v[164:165]
	v_pk_add_f32 v[162:163], v[182:183], v[162:163]
	s_waitcnt vmcnt(14)
	v_pk_add_f32 v[160:161], v[160:161], v[168:169]
	v_pk_add_f32 v[166:167], v[178:179], v[166:167]
	s_waitcnt vmcnt(13)
	v_pk_add_f32 v[156:157], v[156:157], v[172:173]
	v_pk_add_f32 v[158:159], v[158:159], v[170:171]
	s_waitcnt vmcnt(12)
	v_pk_add_f32 v[152:153], v[152:153], v[190:191]
	v_pk_add_f32 v[154:155], v[154:155], v[188:189]
	s_waitcnt vmcnt(11)
	v_pk_add_f32 v[164:165], v[164:165], v[194:195]
	v_pk_add_f32 v[162:163], v[162:163], v[192:193]
	s_waitcnt vmcnt(10)
	v_pk_add_f32 v[160:161], v[160:161], v[198:199]
	v_pk_add_f32 v[166:167], v[166:167], v[196:197]
	s_waitcnt vmcnt(9)
	v_pk_add_f32 v[136:137], v[156:157], v[136:137]
	v_pk_add_f32 v[134:135], v[158:159], v[134:135]
	s_waitcnt vmcnt(8)
	v_pk_add_f32 v[64:65], v[152:153], v[64:65]
	v_pk_add_f32 v[62:63], v[154:155], v[62:63]
	s_waitcnt vmcnt(7)
	v_pk_add_f32 v[132:133], v[164:165], v[132:133]
	v_pk_add_f32 v[130:131], v[162:163], v[130:131]
	s_waitcnt vmcnt(6)
	v_pk_add_f32 v[44:45], v[160:161], v[44:45]
	v_pk_add_f32 v[42:43], v[166:167], v[42:43]
	s_waitcnt vmcnt(5)
	v_pk_add_f32 v[32:33], v[136:137], v[32:33]
	v_pk_add_f32 v[30:31], v[134:135], v[30:31]
	s_waitcnt vmcnt(4)
	v_pk_add_f32 v[16:17], v[64:65], v[16:17]
	v_pk_add_f32 v[14:15], v[62:63], v[14:15]
	s_waitcnt vmcnt(3)
	v_pk_add_f32 v[64:65], v[132:133], v[20:21]
	v_pk_add_f32 v[62:63], v[130:131], v[18:19]
	s_waitcnt vmcnt(2)
	v_pk_add_f32 v[12:13], v[44:45], v[12:13]
	v_pk_add_f32 v[10:11], v[42:43], v[10:11]
	s_waitcnt vmcnt(1)
	v_pk_add_f32 v[8:9], v[32:33], v[8:9]
	v_pk_add_f32 v[6:7], v[30:31], v[6:7]
	s_waitcnt vmcnt(0)
	v_pk_add_f32 v[4:5], v[16:17], v[4:5]
	v_pk_add_f32 v[2:3], v[14:15], v[2:3]
	s_cmp_lt_i32 s0, 0x8000
	s_mov_b64 s[50:51], -1
	s_cbranch_scc0 .LBB0_1193

; __device__ __forceinline__ float ssq16(const f32x4 (&v)[4]) {
;     float s = 0.f;
; #pragma unroll
;     for (int j = 0; j < 4; ++j) s += (v[j].x * v[j].x + v[j].y * v[j].y) + (v[j].z * v[j].z + v[j].w * v[j].w);
;     return wave_sum(s);
; }
.LBB0_1202:
	v_pk_mul_f32 v[130:131], v[128:129], v[128:129]
	v_pk_mul_f32 v[132:133], v[126:127], v[126:127]
	v_mul_f32_e32 v0, v78, v78
	v_pk_mov_b32 v[134:135], v[132:133], v[130:131] op_sel:[1,0]
	v_mov_b32_e32 v133, v131
	v_pk_add_f32 v[130:131], v[134:135], v[132:133]
	v_pk_mul_f32 v[132:133], v[100:101], v[100:101]
	v_pk_mul_f32 v[134:135], v[98:99], v[98:99]
	v_pk_add_f32 v[130:131], v[130:131], v[130:131] op_sel:[0,1] op_sel_hi:[1,0]
	v_pk_mov_b32 v[136:137], v[134:135], v[132:133] op_sel:[1,0]
	v_mov_b32_e32 v135, v133
	v_pk_add_f32 v[132:133], v[136:137], v[134:135]
	v_mul_f32_e32 v134, v79, v79
	v_pk_add_f32 v[132:133], v[132:133], v[132:133] op_sel:[0,1] op_sel_hi:[1,0]
	v_mov_b32_e32 v131, v0
	v_mov_b32_e32 v133, v134
	v_mul_f32_e32 v0, v87, v87
	v_mul_f32_e32 v135, v80, v80
	v_pk_add_f32 v[130:131], v[130:131], v[132:133]
	v_pk_fma_f32 v[132:133], v[86:87], v[86:87], v[0:1] op_sel_hi:[1,1,0]
	v_mul_f32_e32 v0, v89, v89
	v_mul_f32_e32 v136, v81, v81
	v_mov_b32_e32 v133, v135
	v_pk_fma_f32 v[134:135], v[88:89], v[88:89], v[0:1] op_sel_hi:[1,1,0]
	s_ashr_i32 s25, s13, 31
	v_mov_b32_e32 v135, v136
	s_lshr_b32 s25, s25, 19
	v_pk_add_f32 v[132:133], v[132:133], v[134:135]
	s_add_i32 s13, s13, s25
	v_pk_add_f32 v[130:131], v[130:131], v[132:133]
	s_ashr_i32 s13, s13, 13
	v_add_f32_e32 v0, v130, v131
	s_and_b64 s[36:37], s[82:83], exec
	s_cselect_b32 s25, s13, 4
	v_add_f32_dpp v0, v0, v0 quad_perm:[1,0,3,2] row_mask:0xf bank_mask:0xf bound_ctrl:1
	s_add_i32 s25, s25, s86
	s_mul_i32 s36, s25, 0x1800
	v_add_f32_dpp v0, v0, v0 quad_perm:[2,3,0,1] row_mask:0xf bank_mask:0xf bound_ctrl:1
	v_mov_b32_e32 v130, v1
	s_ashr_i32 s37, s36, 31
	v_add_f32_dpp v0, v0, v0 row_half_mirror row_mask:0xf bank_mask:0xf bound_ctrl:1
	s_lshl_b64 s[36:37], s[36:37], 2
	s_add_u32 s25, s84, s36
	v_add_f32_dpp v0, v0, v0 row_mirror row_mask:0xf bank_mask:0xf bound_ctrl:1
	s_addc_u32 s27, s85, s37
	s_lshl_b64 s[0:1], s[0:1], 12
	v_mov_b32_dpp v130, v0 row_bcast:15 row_mask:0xa bank_mask:0xf
	v_add_f32_e32 v0, v0, v130
	v_mov_b32_e32 v130, v1
	s_waitcnt lgkmcnt(0)
	s_add_u32 s0, s28, s0
	s_addc_u32 s1, s29, s1
	v_mov_b32_dpp v130, v0 row_bcast:31 row_mask:0xc bank_mask:0xf
	v_add_f32_e32 v0, v0, v130
	s_nop 0
	v_readlane_b32 s28, v0, 63
	s_nop 1
	v_cvt_i32_f32_e32 v0, s28
	s_add_u32 s28, s25, 0x5000
	s_addc_u32 s29, s27, 0
	v_cvt_f32_i32_e32 v0, v0
	v_fmamk_f32 v0, v0, 0x3a800000, v211
	v_cmp_gt_f32_e32 vcc, s68, v0
	v_mul_f32_e32 v130, 0x4b800000, v0
	s_nop 0
	v_cndmask_b32_e32 v0, v0, v130, vcc
	v_rsq_f32_e32 v0, v0
	s_nop 0
	v_mul_f32_e32 v130, 0x45800000, v0
	v_cndmask_b32_e32 v0, v0, v130, vcc
	v_pk_mul_f32 v[134:135], v[0:1], v[128:129] op_sel_hi:[0,1]
	v_pk_mul_f32 v[136:137], v[0:1], v[126:127] op_sel_hi:[0,1]
	global_load_dwordx4 v[126:129], v[144:145], off
	global_load_dwordx4 v[130:133], v139, s[28:29]
	s_and_b64 vcc, exec, s[2:3]
	s_waitcnt vmcnt(1)
	v_pk_mul_f32 v[126:127], v[136:137], v[126:127]
	v_pk_mul_f32 v[128:129], v[134:135], v[128:129]
	s_waitcnt vmcnt(0)
	v_pk_fma_f32 v[122:123], v[130:131], v[126:127], v[122:123]
	v_pk_fma_f32 v[124:125], v[132:133], v[128:129], v[124:125]
	global_store_dwordx4 v139, v[122:125], s[0:1] nt
	v_pk_mul_f32 v[130:131], v[0:1], v[98:99] op_sel_hi:[0,1]
	v_pk_mul_f32 v[132:133], v[0:1], v[100:101] op_sel_hi:[0,1]
	global_load_dwordx4 v[98:101], v[144:145], off offset:1024
	global_load_dwordx4 v[126:129], v184, s[28:29]
	s_waitcnt vmcnt(1)
	v_pk_mul_f32 v[100:101], v[132:133], v[100:101]
	v_pk_mul_f32 v[98:99], v[130:131], v[98:99]
	s_waitcnt vmcnt(0)
	v_pk_fma_f32 v[100:101], v[128:129], v[100:101], v[116:117]
	v_pk_fma_f32 v[98:99], v[126:127], v[98:99], v[114:115]
	global_store_dwordx4 v139, v[98:101], s[0:1] offset:1024 nt
	v_pk_mul_f32 v[126:127], v[0:1], v[86:87] op_sel_hi:[0,1]
	v_pk_mul_f32 v[128:129], v[0:1], v[88:89] op_sel_hi:[0,1]
	global_load_dwordx4 v[86:89], v[144:145], off offset:2048
	global_load_dwordx4 v[114:117], v185, s[28:29]
	s_waitcnt vmcnt(1)
	v_pk_mul_f32 v[88:89], v[128:129], v[88:89]
	v_pk_mul_f32 v[86:87], v[126:127], v[86:87]
	s_waitcnt vmcnt(0)
	v_pk_fma_f32 v[88:89], v[116:117], v[88:89], v[112:113]
	v_pk_fma_f32 v[86:87], v[114:115], v[86:87], v[110:111]
	global_store_dwordx4 v139, v[86:89], s[0:1] offset:2048 nt
	v_pk_mul_f32 v[114:115], v[0:1], v[78:79] op_sel_hi:[0,1]
	v_pk_mul_f32 v[116:117], v[0:1], v[80:81] op_sel_hi:[0,1]
	global_load_dwordx4 v[78:81], v[144:145], off offset:3072
	global_load_dwordx4 v[110:113], v186, s[28:29]
	s_waitcnt vmcnt(1)
	v_pk_mul_f32 v[80:81], v[116:117], v[80:81]
	v_pk_mul_f32 v[78:79], v[114:115], v[78:79]
	s_waitcnt vmcnt(0)
	v_pk_fma_f32 v[80:81], v[112:113], v[80:81], v[104:105]
	v_pk_fma_f32 v[78:79], v[110:111], v[78:79], v[102:103]
	global_store_dwordx4 v139, v[78:81], s[0:1] offset:3072 nt
	s_cbranch_vccnz .LBB0_1204
; __device__ __forceinline__ unsigned cvtpk(float lo, float hi) { unsigned r; asm volatile("v_cvt_pk_bf16_f32 %0, %1, %2" : "=v"(r) : "v"(lo), "v"(hi)); return r; }
; __device__ __forceinline__ void prenorm_store(const f32x4 (&v)[4], float rinv, const float* g, const float* shift, const float* scale, bf16_t* orow, int lane) {
; #pragma unroll
;     for (int j = 0; j < 4; ++j) { const int q = lane + 64 * j; const f32x4 gg = ((const f32x4*)g)[q], sh = ((const f32x4*)shift)[q], sc = ((const f32x4*)scale)[q];
;         const f32x4 h = (v[j] * rinv * gg) * (sc + 1.0f) + sh; u32x2 w; w.x = cvtpk(h.x, h.y); w.y = cvtpk(h.z, h.w); ((u32x2*)orow)[q] = w; }
; }
	v_pk_mul_f32 v[102:103], v[124:125], v[124:125]
	v_pk_mul_f32 v[104:105], v[122:123], v[122:123]
	v_mul_f32_e32 v0, v78, v78
	v_pk_mov_b32 v[110:111], v[104:105], v[102:103] op_sel:[1,0]
	v_mov_b32_e32 v105, v103
	v_pk_add_f32 v[102:103], v[110:111], v[104:105]
	v_pk_mul_f32 v[104:105], v[100:101], v[100:101]
	v_pk_mul_f32 v[110:111], v[98:99], v[98:99]
	v_pk_add_f32 v[102:103], v[102:103], v[102:103] op_sel:[0,1] op_sel_hi:[1,0]
	v_pk_mov_b32 v[112:113], v[110:111], v[104:105] op_sel:[1,0]
	v_mov_b32_e32 v111, v105
	v_pk_add_f32 v[104:105], v[112:113], v[110:111]
	v_mul_f32_e32 v110, v79, v79
	v_pk_add_f32 v[104:105], v[104:105], v[104:105] op_sel:[0,1] op_sel_hi:[1,0]
	v_mov_b32_e32 v103, v0
	v_mov_b32_e32 v105, v110
	v_mul_f32_e32 v0, v87, v87
	v_mul_f32_e32 v111, v80, v80
	v_pk_add_f32 v[102:103], v[102:103], v[104:105]
	v_pk_fma_f32 v[104:105], v[86:87], v[86:87], v[0:1] op_sel_hi:[1,1,0]
	v_mul_f32_e32 v0, v89, v89
	v_mul_f32_e32 v112, v81, v81
	v_mov_b32_e32 v105, v111
	v_pk_fma_f32 v[110:111], v[88:89], v[88:89], v[0:1] op_sel_hi:[1,1,0]
	s_mul_i32 s0, s13, 0x1800
	v_mov_b32_e32 v111, v112
	v_pk_add_f32 v[104:105], v[104:105], v[110:111]
	s_add_i32 s13, s0, 0x7800
	v_pk_add_f32 v[102:103], v[102:103], v[104:105]
	s_and_b64 s[0:1], s[82:83], exec
	v_add_f32_e32 v0, v102, v103
	v_mov_b32_e32 v102, v1
	s_cselect_b32 s0, s13, 0xd800
	v_add_f32_dpp v0, v0, v0 quad_perm:[1,0,3,2] row_mask:0xf bank_mask:0xf bound_ctrl:1
	s_ashr_i32 s1, s0, 31
	s_lshl_b64 s[0:1], s[0:1], 2
	v_add_f32_dpp v0, v0, v0 quad_perm:[2,3,0,1] row_mask:0xf bank_mask:0xf bound_ctrl:1
	s_add_u32 s0, s84, s0
	s_addc_u32 s1, s85, s1
	v_add_f32_dpp v0, v0, v0 row_half_mirror row_mask:0xf bank_mask:0xf bound_ctrl:1
	s_add_u32 s28, s0, 0x1000
	s_addc_u32 s29, s1, 0
	v_add_f32_dpp v0, v0, v0 row_mirror row_mask:0xf bank_mask:0xf bound_ctrl:1
	s_nop 1
	v_mov_b32_dpp v102, v0 row_bcast:15 row_mask:0xa bank_mask:0xf
	v_add_f32_e32 v0, v0, v102
	v_mov_b32_e32 v102, v1
	s_nop 1
	v_mov_b32_dpp v102, v0 row_bcast:31 row_mask:0xc bank_mask:0xf
	v_add_f32_e32 v0, v0, v102
	s_nop 0
	v_readlane_b32 s13, v0, 63
	s_nop 1
	v_cvt_i32_f32_e32 v0, s13
	s_mov_b32 s13, 0xeb600000
	v_cvt_f32_i32_e32 v0, v0
	v_fmamk_f32 v0, v0, 0x3a800000, v211
	v_cmp_gt_f32_e32 vcc, s68, v0
	v_mul_f32_e32 v102, 0x4b800000, v0
	s_nop 0
	v_cndmask_b32_e32 v0, v0, v102, vcc
	v_rsq_f32_e32 v0, v0
	s_nop 0
	v_mul_f32_e32 v102, 0x45800000, v0
	v_cndmask_b32_e32 v0, v0, v102, vcc
	global_load_dwordx4 v[102:105], v[142:143], off
	global_load_dwordx4 v[110:113], v139, s[0:1]
	global_load_dwordx4 v[114:117], v139, s[28:29]
	v_pk_mul_f32 v[122:123], v[122:123], v[0:1] op_sel_hi:[1,0]
	v_pk_mul_f32 v[124:125], v[124:125], v[0:1] op_sel_hi:[1,0]
	v_pk_mul_f32 v[100:101], v[100:101], v[0:1] op_sel_hi:[1,0]
	v_pk_mul_f32 v[98:99], v[98:99], v[0:1] op_sel_hi:[1,0]
	v_pk_mul_f32 v[88:89], v[88:89], v[0:1] op_sel_hi:[1,0]
	v_pk_mul_f32 v[86:87], v[86:87], v[0:1] op_sel_hi:[1,0]
	v_pk_mul_f32 v[80:81], v[80:81], v[0:1] op_sel_hi:[1,0]
	v_pk_mul_f32 v[78:79], v[78:79], v[0:1] op_sel_hi:[1,0]
	s_waitcnt vmcnt(2)
	v_pk_mul_f32 v[102:103], v[102:103], v[122:123]
	v_add_co_u32_e32 v122, vcc, s13, v150
	s_waitcnt vmcnt(0)
	v_pk_add_f32 v[114:115], v[114:115], 1.0 op_sel_hi:[1,0]
	v_pk_mul_f32 v[104:105], v[104:105], v[124:125]
	v_pk_add_f32 v[116:117], v[116:117], 1.0 op_sel_hi:[1,0]
	v_pk_fma_f32 v[102:103], v[114:115], v[102:103], v[110:111]
	v_addc_co_u32_e32 v123, vcc, -1, v151, vcc
	v_pk_fma_f32 v[104:105], v[116:117], v[104:105], v[112:113]
	v_cvt_pk_bf16_f32 v102, v102, v103
	s_nop 0
	v_cvt_pk_bf16_f32 v103, v104, v105
	global_store_dwordx2 v[122:123], v[102:103], off offset:-1536
	global_load_dwordx4 v[102:105], v[142:143], off offset:1024
	global_load_dwordx4 v[110:113], v139, s[0:1] offset:1024
	global_load_dwordx4 v[114:117], v184, s[28:29]
	s_waitcnt vmcnt(2)
	v_pk_mul_f32 v[98:99], v[102:103], v[98:99]
	v_pk_mul_f32 v[100:101], v[104:105], v[100:101]
	s_waitcnt vmcnt(0)
	v_pk_add_f32 v[104:105], v[114:115], 1.0 op_sel_hi:[1,0]
	v_pk_add_f32 v[102:103], v[116:117], 1.0 op_sel_hi:[1,0]
	v_pk_fma_f32 v[98:99], v[104:105], v[98:99], v[110:111]
	v_pk_fma_f32 v[100:101], v[102:103], v[100:101], v[112:113]
	v_cvt_pk_bf16_f32 v98, v98, v99
	s_nop 0
	v_cvt_pk_bf16_f32 v99, v100, v101
	global_store_dwordx2 v[122:123], v[98:99], off offset:-1024
	global_load_dwordx4 v[98:101], v[142:143], off offset:2048
	global_load_dwordx4 v[102:105], v139, s[0:1] offset:2048
	global_load_dwordx4 v[110:113], v185, s[28:29]
	s_waitcnt vmcnt(2)
	v_pk_mul_f32 v[86:87], v[86:87], v[98:99]
	v_pk_mul_f32 v[88:89], v[88:89], v[100:101]
	s_waitcnt vmcnt(0)
	v_pk_add_f32 v[100:101], v[110:111], 1.0 op_sel_hi:[1,0]
	v_pk_add_f32 v[98:99], v[112:113], 1.0 op_sel_hi:[1,0]
	v_pk_fma_f32 v[86:87], v[86:87], v[100:101], v[102:103]
	v_pk_fma_f32 v[88:89], v[88:89], v[98:99], v[104:105]
	v_cvt_pk_bf16_f32 v86, v86, v87
	s_nop 0
	v_cvt_pk_bf16_f32 v87, v88, v89
	global_store_dwordx2 v[122:123], v[86:87], off offset:-512
	global_load_dwordx4 v[86:89], v[142:143], off offset:3072
	global_load_dwordx4 v[98:101], v139, s[0:1] offset:3072
	global_load_dwordx4 v[102:105], v186, s[28:29]
	s_waitcnt vmcnt(2)
	v_pk_mul_f32 v[78:79], v[78:79], v[86:87]
	v_pk_mul_f32 v[80:81], v[80:81], v[88:89]
	s_waitcnt vmcnt(0)
	v_pk_add_f32 v[88:89], v[102:103], 1.0 op_sel_hi:[1,0]
	v_pk_add_f32 v[86:87], v[104:105], 1.0 op_sel_hi:[1,0]
	v_pk_fma_f32 v[78:79], v[78:79], v[88:89], v[98:99]
	v_pk_fma_f32 v[80:81], v[80:81], v[86:87], v[100:101]
	v_cvt_pk_bf16_f32 v78, v78, v79
	s_nop 0
	v_cvt_pk_bf16_f32 v79, v80, v81
	global_store_dwordx2 v[122:123], v[78:79], off

; __device__ __forceinline__ float ssq16(const f32x4 (&v)[4]) {
;     float s = 0.f;
; #pragma unroll
;     for (int j = 0; j < 4; ++j) s += (v[j].x * v[j].x + v[j].y * v[j].y) + (v[j].z * v[j].z + v[j].w * v[j].w);
;     return wave_sum(s);
; }
.LBB0_1209:
	v_pk_mul_f32 v[78:79], v[120:121], v[120:121]
	v_pk_mul_f32 v[80:81], v[118:119], v[118:119]
	v_mul_f32_e32 v0, v50, v50
	v_pk_mov_b32 v[86:87], v[80:81], v[78:79] op_sel:[1,0]
	v_mov_b32_e32 v81, v79
	v_pk_add_f32 v[78:79], v[86:87], v[80:81]
	v_pk_mul_f32 v[80:81], v[68:69], v[68:69]
	v_pk_mul_f32 v[86:87], v[66:67], v[66:67]
	v_pk_add_f32 v[78:79], v[78:79], v[78:79] op_sel:[0,1] op_sel_hi:[1,0]
	v_pk_mov_b32 v[88:89], v[86:87], v[80:81] op_sel:[1,0]
	v_mov_b32_e32 v87, v81
	v_pk_add_f32 v[80:81], v[88:89], v[86:87]
	v_mul_f32_e32 v86, v51, v51
	v_pk_add_f32 v[80:81], v[80:81], v[80:81] op_sel:[0,1] op_sel_hi:[1,0]
	v_mov_b32_e32 v79, v0
	v_mov_b32_e32 v81, v86
	v_mul_f32_e32 v0, v55, v55
	v_mul_f32_e32 v87, v52, v52
	v_pk_add_f32 v[78:79], v[78:79], v[80:81]
	v_pk_fma_f32 v[80:81], v[54:55], v[54:55], v[0:1] op_sel_hi:[1,1,0]
	v_mul_f32_e32 v0, v57, v57
	v_mul_f32_e32 v88, v53, v53
	v_mov_b32_e32 v81, v87
	v_pk_fma_f32 v[86:87], v[56:57], v[56:57], v[0:1] op_sel_hi:[1,1,0]
	s_ashr_i32 s35, s34, 31
	v_mov_b32_e32 v87, v88
	s_lshr_b32 s13, s35, 19
	v_pk_add_f32 v[80:81], v[80:81], v[86:87]
	s_add_i32 s13, s34, s13
	v_pk_add_f32 v[78:79], v[78:79], v[80:81]
	s_ashr_i32 s13, s13, 13
	v_add_f32_e32 v0, v78, v79
	s_and_b64 s[36:37], exec, s[0:1]
	s_cselect_b32 s25, s13, 4
	v_add_f32_dpp v0, v0, v0 quad_perm:[1,0,3,2] row_mask:0xf bank_mask:0xf bound_ctrl:1
	s_add_i32 s25, s25, s86
	s_mul_i32 s36, s25, 0x1800
	v_add_f32_dpp v0, v0, v0 quad_perm:[2,3,0,1] row_mask:0xf bank_mask:0xf bound_ctrl:1
	v_mov_b32_e32 v78, v1
	s_ashr_i32 s37, s36, 31
	v_add_f32_dpp v0, v0, v0 row_half_mirror row_mask:0xf bank_mask:0xf bound_ctrl:1
	s_lshl_b64 s[36:37], s[36:37], 2
	s_add_u32 s25, s84, s36
	v_add_f32_dpp v0, v0, v0 row_mirror row_mask:0xf bank_mask:0xf bound_ctrl:1
	s_addc_u32 s27, s85, s37
	s_lshl_b64 s[36:37], s[78:79], 12
	v_mov_b32_dpp v78, v0 row_bcast:15 row_mask:0xa bank_mask:0xf
	v_add_f32_e32 v0, v0, v78
	v_mov_b32_e32 v78, v1
	s_waitcnt lgkmcnt(0)
	s_add_u32 s28, s28, s36
	s_addc_u32 s29, s29, s37
	v_mov_b32_dpp v78, v0 row_bcast:31 row_mask:0xc bank_mask:0xf
	v_add_f32_e32 v0, v0, v78
	s_add_u32 s48, s25, 0x5000
	v_readlane_b32 s36, v0, 63
	s_addc_u32 s49, s27, 0
	global_load_dwordx4 v[86:89], v[144:145], off
	v_cvt_i32_f32_e32 v0, s36
	v_cvt_f32_i32_e32 v0, v0
	v_fmamk_f32 v0, v0, 0x3a800000, v211
	v_cmp_gt_f32_e32 vcc, s68, v0
	v_mul_f32_e32 v78, 0x4b800000, v0
	s_nop 0
	v_cndmask_b32_e32 v0, v0, v78, vcc
	v_rsq_f32_e32 v0, v0
	s_nop 0
	v_mul_f32_e32 v78, 0x45800000, v0
	v_cndmask_b32_e32 v0, v0, v78, vcc
	global_load_dwordx4 v[78:81], v139, s[48:49]
	v_pk_mul_f32 v[98:99], v[0:1], v[120:121] op_sel_hi:[0,1]
	v_pk_mul_f32 v[100:101], v[0:1], v[118:119] op_sel_hi:[0,1]
	s_and_b64 vcc, exec, s[2:3]
	s_waitcnt vmcnt(1)
	v_pk_mul_f32 v[86:87], v[100:101], v[86:87]
	v_pk_mul_f32 v[88:89], v[98:99], v[88:89]
	v_pk_mul_f32 v[98:99], v[0:1], v[66:67] op_sel_hi:[0,1]
	v_pk_mul_f32 v[100:101], v[0:1], v[68:69] op_sel_hi:[0,1]
	s_waitcnt vmcnt(0)
	v_pk_fma_f32 v[80:81], v[80:81], v[88:89], v[108:109]
	v_pk_fma_f32 v[78:79], v[78:79], v[86:87], v[106:107]
	global_store_dwordx4 v139, v[78:81], s[28:29] nt
	global_load_dwordx4 v[66:69], v[144:145], off offset:1024
	global_load_dwordx4 v[86:89], v184, s[48:49]
	s_waitcnt vmcnt(1)
	v_pk_mul_f32 v[68:69], v[100:101], v[68:69]
	v_pk_mul_f32 v[66:67], v[98:99], v[66:67]
	s_waitcnt vmcnt(0)
	v_pk_fma_f32 v[68:69], v[88:89], v[68:69], v[92:93]
	v_pk_fma_f32 v[66:67], v[86:87], v[66:67], v[90:91]
	global_store_dwordx4 v139, v[66:69], s[28:29] offset:1024 nt
	v_pk_mul_f32 v[90:91], v[0:1], v[54:55] op_sel_hi:[0,1]
	v_pk_mul_f32 v[92:93], v[0:1], v[56:57] op_sel_hi:[0,1]
	global_load_dwordx4 v[54:57], v[144:145], off offset:2048
	global_load_dwordx4 v[86:89], v185, s[48:49]
	s_waitcnt vmcnt(1)
	v_pk_mul_f32 v[56:57], v[92:93], v[56:57]
	v_pk_mul_f32 v[54:55], v[90:91], v[54:55]
	s_waitcnt vmcnt(0)
	v_pk_fma_f32 v[56:57], v[88:89], v[56:57], v[84:85]
	v_pk_fma_f32 v[54:55], v[86:87], v[54:55], v[82:83]
	global_store_dwordx4 v139, v[54:57], s[28:29] offset:2048 nt
	v_pk_mul_f32 v[86:87], v[0:1], v[50:51] op_sel_hi:[0,1]
	v_pk_mul_f32 v[88:89], v[0:1], v[52:53] op_sel_hi:[0,1]
	global_load_dwordx4 v[50:53], v[144:145], off offset:3072
	global_load_dwordx4 v[82:85], v186, s[48:49]
	s_waitcnt vmcnt(1)
	v_pk_mul_f32 v[52:53], v[88:89], v[52:53]
	v_pk_mul_f32 v[50:51], v[86:87], v[50:51]
	s_waitcnt vmcnt(0)
	v_pk_fma_f32 v[52:53], v[84:85], v[52:53], v[72:73]
	v_pk_fma_f32 v[50:51], v[82:83], v[50:51], v[70:71]
	global_store_dwordx4 v139, v[50:53], s[28:29] offset:3072 nt
	s_cbranch_vccnz .LBB0_1211
; __device__ __forceinline__ unsigned cvtpk(float lo, float hi) { unsigned r; asm volatile("v_cvt_pk_bf16_f32 %0, %1, %2" : "=v"(r) : "v"(lo), "v"(hi)); return r; }
; __device__ __forceinline__ float ssq16(const f32x4 (&v)[4]) {
;     float s = 0.f;
; #pragma unroll
;     for (int j = 0; j < 4; ++j) s += (v[j].x * v[j].x + v[j].y * v[j].y) + (v[j].z * v[j].z + v[j].w * v[j].w);
;     return wave_sum(s);
; }
; __device__ __forceinline__ void prenorm_store(const f32x4 (&v)[4], float rinv, const float* g, const float* shift, const float* scale, bf16_t* orow, int lane) {
; #pragma unroll
;     for (int j = 0; j < 4; ++j) { const int q = lane + 64 * j; const f32x4 gg = ((const f32x4*)g)[q], sh = ((const f32x4*)shift)[q], sc = ((const f32x4*)scale)[q];
;         const f32x4 h = (v[j] * rinv * gg) * (sc + 1.0f) + sh; u32x2 w; w.x = cvtpk(h.x, h.y); w.y = cvtpk(h.z, h.w); ((u32x2*)orow)[q] = w; }
; }
	v_pk_mul_f32 v[70:71], v[80:81], v[80:81]
	v_pk_mul_f32 v[72:73], v[78:79], v[78:79]
	v_mul_f32_e32 v0, v50, v50
	v_pk_mov_b32 v[82:83], v[72:73], v[70:71] op_sel:[1,0]
	v_mov_b32_e32 v73, v71
	v_pk_add_f32 v[70:71], v[82:83], v[72:73]
	v_pk_mul_f32 v[72:73], v[68:69], v[68:69]
	v_pk_mul_f32 v[82:83], v[66:67], v[66:67]
	v_pk_add_f32 v[70:71], v[70:71], v[70:71] op_sel:[0,1] op_sel_hi:[1,0]
	v_pk_mov_b32 v[84:85], v[82:83], v[72:73] op_sel:[1,0]
	v_mov_b32_e32 v83, v73
	v_pk_add_f32 v[72:73], v[84:85], v[82:83]
	v_mul_f32_e32 v82, v51, v51
	v_pk_add_f32 v[72:73], v[72:73], v[72:73] op_sel:[0,1] op_sel_hi:[1,0]
	v_mov_b32_e32 v71, v0
	v_mov_b32_e32 v73, v82
	v_mul_f32_e32 v0, v55, v55
	v_mul_f32_e32 v83, v52, v52
	v_pk_add_f32 v[70:71], v[70:71], v[72:73]
	v_pk_fma_f32 v[72:73], v[54:55], v[54:55], v[0:1] op_sel_hi:[1,1,0]
	v_mul_f32_e32 v0, v57, v57
	v_mul_f32_e32 v84, v53, v53
	v_mov_b32_e32 v73, v83
	v_pk_fma_f32 v[82:83], v[56:57], v[56:57], v[0:1] op_sel_hi:[1,1,0]
	s_mulk_i32 s13, 0x1800
	v_mov_b32_e32 v83, v84
	v_pk_add_f32 v[72:73], v[72:73], v[82:83]
	s_addk_i32 s13, 0x7800
	v_pk_add_f32 v[70:71], v[70:71], v[72:73]
	s_and_b64 s[0:1], exec, s[0:1]
	v_add_f32_e32 v0, v70, v71
	v_mov_b32_e32 v70, v1
	s_cselect_b32 s0, s13, 0xd800
	v_add_f32_dpp v0, v0, v0 quad_perm:[1,0,3,2] row_mask:0xf bank_mask:0xf bound_ctrl:1
	s_ashr_i32 s1, s0, 31
	s_lshl_b64 s[0:1], s[0:1], 2
	v_add_f32_dpp v0, v0, v0 quad_perm:[2,3,0,1] row_mask:0xf bank_mask:0xf bound_ctrl:1
	s_add_u32 s0, s84, s0
	s_addc_u32 s1, s85, s1
	v_add_f32_dpp v0, v0, v0 row_half_mirror row_mask:0xf bank_mask:0xf bound_ctrl:1
	s_add_u32 s28, s0, 0x1000
	s_addc_u32 s29, s1, 0
	v_add_f32_dpp v0, v0, v0 row_mirror row_mask:0xf bank_mask:0xf bound_ctrl:1
	s_lshl_b64 s[34:35], s[34:35], 11
	s_nop 0
	v_mov_b32_dpp v70, v0 row_bcast:15 row_mask:0xa bank_mask:0xf
	v_add_f32_e32 v0, v0, v70
	v_mov_b32_e32 v70, v1
	s_nop 1
	v_mov_b32_dpp v70, v0 row_bcast:31 row_mask:0xc bank_mask:0xf
	v_add_f32_e32 v0, v0, v70
	s_nop 0
	v_readlane_b32 s13, v0, 63
	s_nop 1
	v_cvt_i32_f32_e32 v0, s13
	v_cvt_f32_i32_e32 v0, v0
	v_fmamk_f32 v0, v0, 0x3a800000, v211
	v_cmp_gt_f32_e32 vcc, s68, v0
	v_mul_f32_e32 v70, 0x4b800000, v0
	s_nop 0
	v_cndmask_b32_e32 v0, v0, v70, vcc
	v_rsq_f32_e32 v0, v0
	s_nop 0
	v_mul_f32_e32 v70, 0x45800000, v0
	v_cndmask_b32_e32 v0, v0, v70, vcc
	global_load_dwordx4 v[70:73], v[142:143], off
	global_load_dwordx4 v[82:85], v139, s[0:1]
	global_load_dwordx4 v[86:89], v139, s[28:29]
	v_pk_mul_f32 v[80:81], v[80:81], v[0:1] op_sel_hi:[1,0]
	v_pk_mul_f32 v[78:79], v[78:79], v[0:1] op_sel_hi:[1,0]
	v_pk_mul_f32 v[68:69], v[68:69], v[0:1] op_sel_hi:[1,0]
	v_pk_mul_f32 v[66:67], v[66:67], v[0:1] op_sel_hi:[1,0]
	v_pk_mul_f32 v[56:57], v[56:57], v[0:1] op_sel_hi:[1,0]
	v_pk_mul_f32 v[54:55], v[54:55], v[0:1] op_sel_hi:[1,0]
	v_pk_mul_f32 v[52:53], v[52:53], v[0:1] op_sel_hi:[1,0]
	v_pk_mul_f32 v[50:51], v[50:51], v[0:1] op_sel_hi:[1,0]
	s_waitcnt vmcnt(2)
	v_pk_mul_f32 v[70:71], v[70:71], v[78:79]
	v_pk_mul_f32 v[72:73], v[72:73], v[80:81]
	s_waitcnt vmcnt(0)
	v_pk_add_f32 v[80:81], v[86:87], 1.0 op_sel_hi:[1,0]
	v_pk_add_f32 v[78:79], v[88:89], 1.0 op_sel_hi:[1,0]
	v_pk_fma_f32 v[70:71], v[80:81], v[70:71], v[82:83]
	v_lshl_add_u64 v[86:87], v[148:149], 0, s[34:35]
	v_pk_fma_f32 v[72:73], v[78:79], v[72:73], v[84:85]
	v_cvt_pk_bf16_f32 v70, v70, v71
	s_nop 0
	v_cvt_pk_bf16_f32 v71, v72, v73
	global_store_dwordx2 v[86:87], v[70:71], off
	global_load_dwordx4 v[70:73], v[142:143], off offset:1024
	global_load_dwordx4 v[78:81], v139, s[0:1] offset:1024
	global_load_dwordx4 v[82:85], v184, s[28:29]
	s_waitcnt vmcnt(2)
	v_pk_mul_f32 v[66:67], v[70:71], v[66:67]
	v_pk_mul_f32 v[68:69], v[72:73], v[68:69]
	s_waitcnt vmcnt(0)
	v_pk_add_f32 v[72:73], v[82:83], 1.0 op_sel_hi:[1,0]
	v_pk_add_f32 v[70:71], v[84:85], 1.0 op_sel_hi:[1,0]
	v_pk_fma_f32 v[66:67], v[72:73], v[66:67], v[78:79]
	v_pk_fma_f32 v[68:69], v[70:71], v[68:69], v[80:81]
	v_cvt_pk_bf16_f32 v66, v66, v67
	s_nop 0
	v_cvt_pk_bf16_f32 v67, v68, v69
	global_store_dwordx2 v[86:87], v[66:67], off offset:512
	global_load_dwordx4 v[66:69], v[142:143], off offset:2048
	global_load_dwordx4 v[70:73], v139, s[0:1] offset:2048
	global_load_dwordx4 v[78:81], v185, s[28:29]
	s_waitcnt vmcnt(2)
	v_pk_mul_f32 v[54:55], v[54:55], v[66:67]
	v_pk_mul_f32 v[56:57], v[56:57], v[68:69]
	s_waitcnt vmcnt(0)
	v_pk_add_f32 v[68:69], v[78:79], 1.0 op_sel_hi:[1,0]
	v_pk_add_f32 v[66:67], v[80:81], 1.0 op_sel_hi:[1,0]
	v_pk_fma_f32 v[54:55], v[54:55], v[68:69], v[70:71]
	v_pk_fma_f32 v[56:57], v[56:57], v[66:67], v[72:73]
	v_cvt_pk_bf16_f32 v54, v54, v55
	s_nop 0
	v_cvt_pk_bf16_f32 v55, v56, v57
	global_store_dwordx2 v[86:87], v[54:55], off offset:1024
	global_load_dwordx4 v[54:57], v[142:143], off offset:3072
	global_load_dwordx4 v[66:69], v139, s[0:1] offset:3072
	global_load_dwordx4 v[70:73], v186, s[28:29]
	s_waitcnt vmcnt(2)
	v_pk_mul_f32 v[50:51], v[50:51], v[54:55]
	v_pk_mul_f32 v[52:53], v[52:53], v[56:57]
	s_waitcnt vmcnt(0)
	v_pk_add_f32 v[56:57], v[70:71], 1.0 op_sel_hi:[1,0]
	v_pk_add_f32 v[54:55], v[72:73], 1.0 op_sel_hi:[1,0]
	v_pk_fma_f32 v[50:51], v[50:51], v[56:57], v[66:67]
	v_pk_fma_f32 v[52:53], v[52:53], v[54:55], v[68:69]
	v_cvt_pk_bf16_f32 v50, v50, v51
	s_nop 0
	v_cvt_pk_bf16_f32 v51, v52, v53
	global_store_dwordx2 v[86:87], v[50:51], off offset:1536

; __device__ __forceinline__ float ssq16(const f32x4 (&v)[4]) {
;     float s = 0.f;
; #pragma unroll
;     for (int j = 0; j < 4; ++j) s += (v[j].x * v[j].x + v[j].y * v[j].y) + (v[j].z * v[j].z + v[j].w * v[j].w);
;     return wave_sum(s);
; }
.LBB0_1216:
	v_pk_mul_f32 v[50:51], v[96:97], v[96:97]
	v_pk_mul_f32 v[52:53], v[94:95], v[94:95]
	v_mul_f32_e32 v0, v22, v22
	v_pk_mov_b32 v[54:55], v[52:53], v[50:51] op_sel:[1,0]
	v_mov_b32_e32 v53, v51
	v_pk_add_f32 v[50:51], v[54:55], v[52:53]
	v_pk_mul_f32 v[52:53], v[36:37], v[36:37]
	v_pk_mul_f32 v[54:55], v[34:35], v[34:35]
	v_pk_add_f32 v[50:51], v[50:51], v[50:51] op_sel:[0,1] op_sel_hi:[1,0]
	v_pk_mov_b32 v[56:57], v[54:55], v[52:53] op_sel:[1,0]
	v_mov_b32_e32 v55, v53
	v_pk_add_f32 v[52:53], v[56:57], v[54:55]
	v_mul_f32_e32 v54, v23, v23
	v_pk_add_f32 v[52:53], v[52:53], v[52:53] op_sel:[0,1] op_sel_hi:[1,0]
	v_mov_b32_e32 v51, v0
	v_mov_b32_e32 v53, v54
	v_mul_f32_e32 v0, v27, v27
	v_mul_f32_e32 v55, v24, v24
	v_pk_add_f32 v[50:51], v[50:51], v[52:53]
	v_pk_fma_f32 v[52:53], v[26:27], v[26:27], v[0:1] op_sel_hi:[1,1,0]
	v_mul_f32_e32 v0, v29, v29
	v_mul_f32_e32 v56, v25, v25
	v_mov_b32_e32 v53, v55
	v_pk_fma_f32 v[54:55], v[28:29], v[28:29], v[0:1] op_sel_hi:[1,1,0]
	s_ashr_i32 s27, s26, 31
	v_mov_b32_e32 v55, v56
	v_pk_add_f32 v[52:53], v[52:53], v[54:55]
	s_lshr_b32 s13, s27, 19
	v_pk_add_f32 v[50:51], v[50:51], v[52:53]
	s_add_i32 s13, s26, s13
	v_add_f32_e32 v0, v50, v51
	s_ashr_i32 s13, s13, 13
	s_and_b64 s[34:35], exec, s[0:1]
	v_add_f32_dpp v0, v0, v0 quad_perm:[1,0,3,2] row_mask:0xf bank_mask:0xf bound_ctrl:1
	s_cselect_b32 s25, s13, 4
	v_mov_b32_e32 v50, v1
	v_add_f32_dpp v0, v0, v0 quad_perm:[2,3,0,1] row_mask:0xf bank_mask:0xf bound_ctrl:1
	s_add_i32 s25, s25, s86
	s_mul_i32 s34, s25, 0x1800
	v_add_f32_dpp v0, v0, v0 row_half_mirror row_mask:0xf bank_mask:0xf bound_ctrl:1
	s_ashr_i32 s35, s34, 31
	s_lshl_b64 s[34:35], s[34:35], 2
	v_add_f32_dpp v0, v0, v0 row_mirror row_mask:0xf bank_mask:0xf bound_ctrl:1
	s_add_u32 s25, s84, s34
	s_addc_u32 s35, s85, s35
	v_mov_b32_dpp v50, v0 row_bcast:15 row_mask:0xa bank_mask:0xf
	v_add_f32_e32 v0, v0, v50
	v_mov_b32_e32 v50, v1
	s_lshl_b64 s[36:37], s[72:73], 12
	s_waitcnt lgkmcnt(0)
	s_add_u32 s28, s28, s36
	v_mov_b32_dpp v50, v0 row_bcast:31 row_mask:0xc bank_mask:0xf
	v_add_f32_e32 v0, v0, v50
	s_addc_u32 s29, s29, s37
	v_readlane_b32 s34, v0, 63
	global_load_dwordx4 v[54:57], v[144:145], off
	s_nop 0
	v_cvt_i32_f32_e32 v0, s34
	s_add_u32 s34, s25, 0x5000
	s_addc_u32 s35, s35, 0
	v_cvt_f32_i32_e32 v0, v0
	v_fmamk_f32 v0, v0, 0x3a800000, v211
	v_cmp_gt_f32_e32 vcc, s68, v0
	v_mul_f32_e32 v50, 0x4b800000, v0
	s_nop 0
	v_cndmask_b32_e32 v0, v0, v50, vcc
	v_rsq_f32_e32 v0, v0
	s_nop 0
	v_mul_f32_e32 v50, 0x45800000, v0
	v_cndmask_b32_e32 v0, v0, v50, vcc
	global_load_dwordx4 v[50:53], v139, s[34:35]
	v_pk_mul_f32 v[66:67], v[0:1], v[96:97] op_sel_hi:[0,1]
	v_pk_mul_f32 v[68:69], v[0:1], v[94:95] op_sel_hi:[0,1]
	s_and_b64 vcc, exec, s[2:3]
	s_waitcnt vmcnt(1)
	v_pk_mul_f32 v[54:55], v[68:69], v[54:55]
	v_pk_mul_f32 v[56:57], v[66:67], v[56:57]
	v_pk_mul_f32 v[66:67], v[0:1], v[34:35] op_sel_hi:[0,1]
	v_pk_mul_f32 v[68:69], v[0:1], v[36:37] op_sel_hi:[0,1]
	s_waitcnt vmcnt(0)
	v_pk_fma_f32 v[52:53], v[52:53], v[56:57], v[76:77]
	v_pk_fma_f32 v[50:51], v[50:51], v[54:55], v[74:75]
	global_store_dwordx4 v139, v[50:53], s[28:29] nt
	global_load_dwordx4 v[34:37], v[144:145], off offset:1024
	global_load_dwordx4 v[54:57], v184, s[34:35]
	s_waitcnt vmcnt(1)
	v_pk_mul_f32 v[36:37], v[68:69], v[36:37]
	v_pk_mul_f32 v[34:35], v[66:67], v[34:35]
	s_waitcnt vmcnt(0)
	v_pk_fma_f32 v[36:37], v[56:57], v[36:37], v[60:61]
	v_pk_fma_f32 v[34:35], v[54:55], v[34:35], v[58:59]
	global_store_dwordx4 v139, v[34:37], s[28:29] offset:1024 nt
	v_pk_mul_f32 v[58:59], v[0:1], v[26:27] op_sel_hi:[0,1]
	v_pk_mul_f32 v[60:61], v[0:1], v[28:29] op_sel_hi:[0,1]
	global_load_dwordx4 v[26:29], v[144:145], off offset:2048
	global_load_dwordx4 v[54:57], v185, s[34:35]
	s_waitcnt vmcnt(1)
	v_pk_mul_f32 v[28:29], v[60:61], v[28:29]
	v_pk_mul_f32 v[26:27], v[58:59], v[26:27]
	s_waitcnt vmcnt(0)
	v_pk_fma_f32 v[28:29], v[56:57], v[28:29], v[48:49]
	v_pk_fma_f32 v[26:27], v[54:55], v[26:27], v[46:47]
	global_store_dwordx4 v139, v[26:29], s[28:29] offset:2048 nt
	v_pk_mul_f32 v[54:55], v[0:1], v[22:23] op_sel_hi:[0,1]
	v_pk_mul_f32 v[56:57], v[0:1], v[24:25] op_sel_hi:[0,1]
	global_load_dwordx4 v[22:25], v[144:145], off offset:3072
	global_load_dwordx4 v[46:49], v186, s[34:35]
	s_waitcnt vmcnt(1)
	v_pk_mul_f32 v[24:25], v[56:57], v[24:25]
	v_pk_mul_f32 v[22:23], v[54:55], v[22:23]
	s_waitcnt vmcnt(0)
	v_pk_fma_f32 v[24:25], v[48:49], v[24:25], v[40:41]
	v_pk_fma_f32 v[22:23], v[46:47], v[22:23], v[38:39]
	global_store_dwordx4 v139, v[22:25], s[28:29] offset:3072 nt
	s_cbranch_vccnz .LBB0_1218
; __device__ __forceinline__ unsigned cvtpk(float lo, float hi) { unsigned r; asm volatile("v_cvt_pk_bf16_f32 %0, %1, %2" : "=v"(r) : "v"(lo), "v"(hi)); return r; }
; __device__ __forceinline__ float ssq16(const f32x4 (&v)[4]) {
;     float s = 0.f;
; #pragma unroll
;     for (int j = 0; j < 4; ++j) s += (v[j].x * v[j].x + v[j].y * v[j].y) + (v[j].z * v[j].z + v[j].w * v[j].w);
;     return wave_sum(s);
; }
; __device__ __forceinline__ void prenorm_store(const f32x4 (&v)[4], float rinv, const float* g, const float* shift, const float* scale, bf16_t* orow, int lane) {
; #pragma unroll
;     for (int j = 0; j < 4; ++j) { const int q = lane + 64 * j; const f32x4 gg = ((const f32x4*)g)[q], sh = ((const f32x4*)shift)[q], sc = ((const f32x4*)scale)[q];
;         const f32x4 h = (v[j] * rinv * gg) * (sc + 1.0f) + sh; u32x2 w; w.x = cvtpk(h.x, h.y); w.y = cvtpk(h.z, h.w); ((u32x2*)orow)[q] = w; }
; }
	v_pk_mul_f32 v[38:39], v[52:53], v[52:53]
	v_pk_mul_f32 v[40:41], v[50:51], v[50:51]
	v_mul_f32_e32 v0, v22, v22
	v_pk_mov_b32 v[46:47], v[40:41], v[38:39] op_sel:[1,0]
	v_mov_b32_e32 v41, v39
	v_pk_add_f32 v[38:39], v[46:47], v[40:41]
	v_pk_mul_f32 v[40:41], v[36:37], v[36:37]
	v_pk_mul_f32 v[46:47], v[34:35], v[34:35]
	v_pk_add_f32 v[38:39], v[38:39], v[38:39] op_sel:[0,1] op_sel_hi:[1,0]
	v_pk_mov_b32 v[48:49], v[46:47], v[40:41] op_sel:[1,0]
	v_mov_b32_e32 v47, v41
	v_pk_add_f32 v[40:41], v[48:49], v[46:47]
	v_mul_f32_e32 v46, v23, v23
	v_pk_add_f32 v[40:41], v[40:41], v[40:41] op_sel:[0,1] op_sel_hi:[1,0]
	v_mov_b32_e32 v39, v0
	v_mov_b32_e32 v41, v46
	v_mul_f32_e32 v0, v27, v27
	v_mul_f32_e32 v47, v24, v24
	v_pk_add_f32 v[38:39], v[38:39], v[40:41]
	v_pk_fma_f32 v[40:41], v[26:27], v[26:27], v[0:1] op_sel_hi:[1,1,0]
	v_mul_f32_e32 v0, v29, v29
	v_mul_f32_e32 v48, v25, v25
	v_mov_b32_e32 v41, v47
	v_pk_fma_f32 v[46:47], v[28:29], v[28:29], v[0:1] op_sel_hi:[1,1,0]
	s_mulk_i32 s13, 0x1800
	v_mov_b32_e32 v47, v48
	v_pk_add_f32 v[40:41], v[40:41], v[46:47]
	s_addk_i32 s13, 0x7800
	v_pk_add_f32 v[38:39], v[38:39], v[40:41]
	s_and_b64 s[0:1], exec, s[0:1]
	v_add_f32_e32 v0, v38, v39
	v_mov_b32_e32 v38, v1
	s_cselect_b32 s0, s13, 0xd800
	v_add_f32_dpp v0, v0, v0 quad_perm:[1,0,3,2] row_mask:0xf bank_mask:0xf bound_ctrl:1
	s_ashr_i32 s1, s0, 31
	s_lshl_b64 s[0:1], s[0:1], 2
	v_add_f32_dpp v0, v0, v0 quad_perm:[2,3,0,1] row_mask:0xf bank_mask:0xf bound_ctrl:1
	s_add_u32 s0, s84, s0
	s_addc_u32 s1, s85, s1
	v_add_f32_dpp v0, v0, v0 row_half_mirror row_mask:0xf bank_mask:0xf bound_ctrl:1
	s_add_u32 s28, s0, 0x1000
	s_addc_u32 s29, s1, 0
	v_add_f32_dpp v0, v0, v0 row_mirror row_mask:0xf bank_mask:0xf bound_ctrl:1
	s_lshl_b64 s[26:27], s[26:27], 11
	s_nop 0
	v_mov_b32_dpp v38, v0 row_bcast:15 row_mask:0xa bank_mask:0xf
	v_add_f32_e32 v0, v0, v38
	v_mov_b32_e32 v38, v1
	s_nop 1
	v_mov_b32_dpp v38, v0 row_bcast:31 row_mask:0xc bank_mask:0xf
	v_add_f32_e32 v0, v0, v38
	s_nop 0
	v_readlane_b32 s13, v0, 63
	s_nop 1
	v_cvt_i32_f32_e32 v0, s13
	v_cvt_f32_i32_e32 v0, v0
	v_fmamk_f32 v0, v0, 0x3a800000, v211
	v_cmp_gt_f32_e32 vcc, s68, v0
	v_mul_f32_e32 v38, 0x4b800000, v0
	s_nop 0
	v_cndmask_b32_e32 v0, v0, v38, vcc
	v_rsq_f32_e32 v0, v0
	s_nop 0
	v_mul_f32_e32 v38, 0x45800000, v0
	v_cndmask_b32_e32 v0, v0, v38, vcc
	global_load_dwordx4 v[38:41], v[142:143], off
	global_load_dwordx4 v[46:49], v139, s[0:1]
	global_load_dwordx4 v[54:57], v139, s[28:29]
	v_pk_mul_f32 v[52:53], v[52:53], v[0:1] op_sel_hi:[1,0]
	v_pk_mul_f32 v[50:51], v[50:51], v[0:1] op_sel_hi:[1,0]
	v_pk_mul_f32 v[36:37], v[36:37], v[0:1] op_sel_hi:[1,0]
	v_pk_mul_f32 v[34:35], v[34:35], v[0:1] op_sel_hi:[1,0]
	v_pk_mul_f32 v[28:29], v[28:29], v[0:1] op_sel_hi:[1,0]
	v_pk_mul_f32 v[26:27], v[26:27], v[0:1] op_sel_hi:[1,0]
	v_pk_mul_f32 v[24:25], v[24:25], v[0:1] op_sel_hi:[1,0]
	v_pk_mul_f32 v[22:23], v[22:23], v[0:1] op_sel_hi:[1,0]
	s_waitcnt vmcnt(2)
	v_pk_mul_f32 v[38:39], v[38:39], v[50:51]
	v_pk_mul_f32 v[40:41], v[40:41], v[52:53]
	s_waitcnt vmcnt(0)
	v_pk_add_f32 v[52:53], v[54:55], 1.0 op_sel_hi:[1,0]
	v_pk_add_f32 v[50:51], v[56:57], 1.0 op_sel_hi:[1,0]
	v_pk_fma_f32 v[38:39], v[52:53], v[38:39], v[46:47]
	v_lshl_add_u64 v[54:55], v[148:149], 0, s[26:27]
	v_pk_fma_f32 v[40:41], v[50:51], v[40:41], v[48:49]
	v_cvt_pk_bf16_f32 v38, v38, v39
	s_nop 0
	v_cvt_pk_bf16_f32 v39, v40, v41
	global_store_dwordx2 v[54:55], v[38:39], off
	global_load_dwordx4 v[38:41], v[142:143], off offset:1024
	global_load_dwordx4 v[46:49], v139, s[0:1] offset:1024
	global_load_dwordx4 v[50:53], v184, s[28:29]
	s_waitcnt vmcnt(2)
	v_pk_mul_f32 v[34:35], v[38:39], v[34:35]
	v_pk_mul_f32 v[36:37], v[40:41], v[36:37]
	s_waitcnt vmcnt(0)
	v_pk_add_f32 v[40:41], v[50:51], 1.0 op_sel_hi:[1,0]
	v_pk_add_f32 v[38:39], v[52:53], 1.0 op_sel_hi:[1,0]
	v_pk_fma_f32 v[34:35], v[40:41], v[34:35], v[46:47]
	v_pk_fma_f32 v[36:37], v[38:39], v[36:37], v[48:49]
	v_cvt_pk_bf16_f32 v34, v34, v35
	s_nop 0
	v_cvt_pk_bf16_f32 v35, v36, v37
	global_store_dwordx2 v[54:55], v[34:35], off offset:512
	global_load_dwordx4 v[34:37], v[142:143], off offset:2048
	global_load_dwordx4 v[38:41], v139, s[0:1] offset:2048
	global_load_dwordx4 v[46:49], v185, s[28:29]
	s_waitcnt vmcnt(2)
	v_pk_mul_f32 v[26:27], v[26:27], v[34:35]
	v_pk_mul_f32 v[28:29], v[28:29], v[36:37]
	s_waitcnt vmcnt(0)
	v_pk_add_f32 v[36:37], v[46:47], 1.0 op_sel_hi:[1,0]
	v_pk_add_f32 v[34:35], v[48:49], 1.0 op_sel_hi:[1,0]
	v_pk_fma_f32 v[26:27], v[26:27], v[36:37], v[38:39]
	v_pk_fma_f32 v[28:29], v[28:29], v[34:35], v[40:41]
	v_cvt_pk_bf16_f32 v26, v26, v27
	s_nop 0
	v_cvt_pk_bf16_f32 v27, v28, v29
	global_store_dwordx2 v[54:55], v[26:27], off offset:1024
	global_load_dwordx4 v[26:29], v[142:143], off offset:3072
	global_load_dwordx4 v[34:37], v139, s[0:1] offset:3072
	global_load_dwordx4 v[38:41], v186, s[28:29]
	s_waitcnt vmcnt(2)
	v_pk_mul_f32 v[22:23], v[22:23], v[26:27]
	v_pk_mul_f32 v[24:25], v[24:25], v[28:29]
	s_waitcnt vmcnt(0)
	v_pk_add_f32 v[28:29], v[38:39], 1.0 op_sel_hi:[1,0]
	v_pk_add_f32 v[26:27], v[40:41], 1.0 op_sel_hi:[1,0]
	v_pk_fma_f32 v[22:23], v[22:23], v[28:29], v[34:35]
	v_pk_fma_f32 v[24:25], v[24:25], v[26:27], v[36:37]
	v_cvt_pk_bf16_f32 v22, v22, v23
	s_nop 0
	v_cvt_pk_bf16_f32 v23, v24, v25
	global_store_dwordx2 v[54:55], v[22:23], off offset:1536

; __device__ __forceinline__ float ssq16(const f32x4 (&v)[4]) {
;     float s = 0.f;
; #pragma unroll
;     for (int j = 0; j < 4; ++j) s += (v[j].x * v[j].x + v[j].y * v[j].y) + (v[j].z * v[j].z + v[j].w * v[j].w);
;     return wave_sum(s);
; }
.LBB0_1223:
	v_pk_mul_f32 v[22:23], v[64:65], v[64:65]
	v_pk_mul_f32 v[24:25], v[62:63], v[62:63]
	v_mul_f32_e32 v0, v2, v2
	v_pk_mov_b32 v[26:27], v[24:25], v[22:23] op_sel:[1,0]
	v_mov_b32_e32 v25, v23
	v_pk_add_f32 v[22:23], v[26:27], v[24:25]
	v_pk_mul_f32 v[24:25], v[12:13], v[12:13]
	v_pk_mul_f32 v[26:27], v[10:11], v[10:11]
	v_pk_add_f32 v[22:23], v[22:23], v[22:23] op_sel:[0,1] op_sel_hi:[1,0]
	v_pk_mov_b32 v[28:29], v[26:27], v[24:25] op_sel:[1,0]
	v_mov_b32_e32 v27, v25
	v_pk_add_f32 v[24:25], v[28:29], v[26:27]
	v_mul_f32_e32 v26, v3, v3
	v_pk_add_f32 v[24:25], v[24:25], v[24:25] op_sel:[0,1] op_sel_hi:[1,0]
	v_mov_b32_e32 v23, v0
	v_mov_b32_e32 v25, v26
	v_mul_f32_e32 v0, v7, v7
	v_mul_f32_e32 v27, v4, v4
	v_pk_add_f32 v[22:23], v[22:23], v[24:25]
	v_pk_fma_f32 v[24:25], v[6:7], v[6:7], v[0:1] op_sel_hi:[1,1,0]
	v_mul_f32_e32 v0, v9, v9
	v_mul_f32_e32 v28, v5, v5
	v_mov_b32_e32 v25, v27
	v_pk_fma_f32 v[26:27], v[8:9], v[8:9], v[0:1] op_sel_hi:[1,1,0]
	s_ashr_i32 s25, s24, 31
	v_mov_b32_e32 v27, v28
	s_lshr_b32 s13, s25, 19
	v_pk_add_f32 v[24:25], v[24:25], v[26:27]
	s_add_i32 s13, s24, s13
	v_pk_add_f32 v[22:23], v[22:23], v[24:25]
	s_ashr_i32 s13, s13, 13
	v_add_f32_e32 v0, v22, v23
	s_and_b64 s[28:29], exec, s[0:1]
	s_cselect_b32 s28, s13, 4
	v_add_f32_dpp v0, v0, v0 quad_perm:[1,0,3,2] row_mask:0xf bank_mask:0xf bound_ctrl:1
	s_add_i32 s28, s28, s86
	s_mulk_i32 s28, 0x1800
	v_add_f32_dpp v0, v0, v0 quad_perm:[2,3,0,1] row_mask:0xf bank_mask:0xf bound_ctrl:1
	v_mov_b32_e32 v22, v1
	s_ashr_i32 s29, s28, 31
	v_add_f32_dpp v0, v0, v0 row_half_mirror row_mask:0xf bank_mask:0xf bound_ctrl:1
	s_lshl_b64 s[28:29], s[28:29], 2
	s_add_u32 s28, s84, s28
	v_add_f32_dpp v0, v0, v0 row_mirror row_mask:0xf bank_mask:0xf bound_ctrl:1
	s_addc_u32 s29, s85, s29
	s_lshl_b64 s[34:35], s[46:47], 12
	v_mov_b32_dpp v22, v0 row_bcast:15 row_mask:0xa bank_mask:0xf
	v_add_f32_e32 v0, v0, v22
	v_mov_b32_e32 v22, v1
	s_waitcnt lgkmcnt(0)
	s_add_u32 s26, s26, s34
	s_addc_u32 s27, s27, s35
	v_mov_b32_dpp v22, v0 row_bcast:31 row_mask:0xc bank_mask:0xf
	v_add_f32_e32 v0, v0, v22
	s_add_u32 s28, s28, 0x5000
	v_readlane_b32 s34, v0, 63
	s_addc_u32 s29, s29, 0
	global_load_dwordx4 v[26:29], v[144:145], off
	v_cvt_i32_f32_e32 v0, s34
	v_cvt_f32_i32_e32 v0, v0
	v_fmamk_f32 v0, v0, 0x3a800000, v211
	v_cmp_gt_f32_e32 vcc, s68, v0
	v_mul_f32_e32 v22, 0x4b800000, v0
	s_nop 0
	v_cndmask_b32_e32 v0, v0, v22, vcc
	v_rsq_f32_e32 v0, v0
	s_nop 0
	v_mul_f32_e32 v22, 0x45800000, v0
	v_cndmask_b32_e32 v0, v0, v22, vcc
	global_load_dwordx4 v[22:25], v139, s[28:29]
	v_pk_mul_f32 v[34:35], v[0:1], v[64:65] op_sel_hi:[0,1]
	v_pk_mul_f32 v[36:37], v[0:1], v[62:63] op_sel_hi:[0,1]
	s_and_b64 vcc, exec, s[2:3]
	s_waitcnt vmcnt(1)
	v_pk_mul_f32 v[26:27], v[36:37], v[26:27]
	v_pk_mul_f32 v[28:29], v[34:35], v[28:29]
	v_pk_mul_f32 v[34:35], v[0:1], v[10:11] op_sel_hi:[0,1]
	v_pk_mul_f32 v[36:37], v[0:1], v[12:13] op_sel_hi:[0,1]
	s_waitcnt vmcnt(0)
	v_pk_fma_f32 v[24:25], v[24:25], v[28:29], v[44:45]
	v_pk_fma_f32 v[22:23], v[22:23], v[26:27], v[42:43]
	global_store_dwordx4 v139, v[22:25], s[26:27] nt
	global_load_dwordx4 v[10:13], v[144:145], off offset:1024
	global_load_dwordx4 v[26:29], v184, s[28:29]
	s_waitcnt vmcnt(1)
	v_pk_mul_f32 v[12:13], v[36:37], v[12:13]
	v_pk_mul_f32 v[10:11], v[34:35], v[10:11]
	s_waitcnt vmcnt(0)
	v_pk_fma_f32 v[12:13], v[28:29], v[12:13], v[32:33]
	v_pk_fma_f32 v[10:11], v[26:27], v[10:11], v[30:31]
	global_store_dwordx4 v139, v[10:13], s[26:27] offset:1024 nt
	v_pk_mul_f32 v[30:31], v[0:1], v[6:7] op_sel_hi:[0,1]
	v_pk_mul_f32 v[32:33], v[0:1], v[8:9] op_sel_hi:[0,1]
	global_load_dwordx4 v[6:9], v[144:145], off offset:2048
	global_load_dwordx4 v[26:29], v185, s[28:29]
	s_waitcnt vmcnt(1)
	v_pk_mul_f32 v[8:9], v[32:33], v[8:9]
	v_pk_mul_f32 v[6:7], v[30:31], v[6:7]
	s_waitcnt vmcnt(0)
	v_pk_fma_f32 v[8:9], v[28:29], v[8:9], v[20:21]
	v_pk_fma_f32 v[6:7], v[26:27], v[6:7], v[18:19]
	global_store_dwordx4 v139, v[6:9], s[26:27] offset:2048 nt
	v_pk_mul_f32 v[26:27], v[0:1], v[2:3] op_sel_hi:[0,1]
	v_pk_mul_f32 v[28:29], v[0:1], v[4:5] op_sel_hi:[0,1]
	global_load_dwordx4 v[2:5], v[144:145], off offset:3072
	global_load_dwordx4 v[18:21], v186, s[28:29]
	s_waitcnt vmcnt(1)
	v_pk_mul_f32 v[4:5], v[28:29], v[4:5]
	v_pk_mul_f32 v[2:3], v[26:27], v[2:3]
	s_waitcnt vmcnt(0)
	v_pk_fma_f32 v[4:5], v[20:21], v[4:5], v[16:17]
	v_pk_fma_f32 v[2:3], v[18:19], v[2:3], v[14:15]
	global_store_dwordx4 v139, v[2:5], s[26:27] offset:3072 nt
	s_cbranch_vccnz .LBB0_1165
; __device__ __forceinline__ unsigned cvtpk(float lo, float hi) { unsigned r; asm volatile("v_cvt_pk_bf16_f32 %0, %1, %2" : "=v"(r) : "v"(lo), "v"(hi)); return r; }
; __device__ __forceinline__ float ssq16(const f32x4 (&v)[4]) {
;     float s = 0.f;
; #pragma unroll
;     for (int j = 0; j < 4; ++j) s += (v[j].x * v[j].x + v[j].y * v[j].y) + (v[j].z * v[j].z + v[j].w * v[j].w);
;     return wave_sum(s);
; }
; __device__ __forceinline__ void prenorm_store(const f32x4 (&v)[4], float rinv, const float* g, const float* shift, const float* scale, bf16_t* orow, int lane) {
; #pragma unroll
;     for (int j = 0; j < 4; ++j) { const int q = lane + 64 * j; const f32x4 gg = ((const f32x4*)g)[q], sh = ((const f32x4*)shift)[q], sc = ((const f32x4*)scale)[q];
;         const f32x4 h = (v[j] * rinv * gg) * (sc + 1.0f) + sh; u32x2 w; w.x = cvtpk(h.x, h.y); w.y = cvtpk(h.z, h.w); ((u32x2*)orow)[q] = w; }
; }
	v_pk_mul_f32 v[14:15], v[24:25], v[24:25]
	v_pk_mul_f32 v[16:17], v[22:23], v[22:23]
	v_mul_f32_e32 v0, v2, v2
	v_pk_mov_b32 v[18:19], v[16:17], v[14:15] op_sel:[1,0]
	v_mov_b32_e32 v17, v15
	v_pk_add_f32 v[14:15], v[18:19], v[16:17]
	v_pk_mul_f32 v[16:17], v[12:13], v[12:13]
	v_pk_mul_f32 v[18:19], v[10:11], v[10:11]
	v_pk_add_f32 v[14:15], v[14:15], v[14:15] op_sel:[0,1] op_sel_hi:[1,0]
	v_pk_mov_b32 v[20:21], v[18:19], v[16:17] op_sel:[1,0]
	v_mov_b32_e32 v19, v17
	v_pk_add_f32 v[16:17], v[20:21], v[18:19]
	v_mul_f32_e32 v18, v3, v3
	v_pk_add_f32 v[16:17], v[16:17], v[16:17] op_sel:[0,1] op_sel_hi:[1,0]
	v_mov_b32_e32 v15, v0
	v_mov_b32_e32 v17, v18
	v_mul_f32_e32 v0, v7, v7
	v_mul_f32_e32 v19, v4, v4
	v_pk_add_f32 v[14:15], v[14:15], v[16:17]
	v_pk_fma_f32 v[16:17], v[6:7], v[6:7], v[0:1] op_sel_hi:[1,1,0]
	v_mul_f32_e32 v0, v9, v9
	v_mul_f32_e32 v20, v5, v5
	v_mov_b32_e32 v17, v19
	v_pk_fma_f32 v[18:19], v[8:9], v[8:9], v[0:1] op_sel_hi:[1,1,0]
	s_mulk_i32 s13, 0x1800
	v_mov_b32_e32 v19, v20
	v_pk_add_f32 v[16:17], v[16:17], v[18:19]
	s_addk_i32 s13, 0x7800
	v_pk_add_f32 v[14:15], v[14:15], v[16:17]
	s_and_b64 s[0:1], exec, s[0:1]
	v_add_f32_e32 v0, v14, v15
	v_mov_b32_e32 v14, v1
	s_cselect_b32 s0, s13, 0xd800
	v_add_f32_dpp v0, v0, v0 quad_perm:[1,0,3,2] row_mask:0xf bank_mask:0xf bound_ctrl:1
	s_ashr_i32 s1, s0, 31
	s_lshl_b64 s[0:1], s[0:1], 2
	v_add_f32_dpp v0, v0, v0 quad_perm:[2,3,0,1] row_mask:0xf bank_mask:0xf bound_ctrl:1
	s_add_u32 s0, s84, s0
	s_addc_u32 s1, s85, s1
	v_add_f32_dpp v0, v0, v0 row_half_mirror row_mask:0xf bank_mask:0xf bound_ctrl:1
	s_add_u32 s26, s0, 0x1000
	s_addc_u32 s27, s1, 0
	v_add_f32_dpp v0, v0, v0 row_mirror row_mask:0xf bank_mask:0xf bound_ctrl:1
	s_lshl_b64 s[24:25], s[24:25], 11
	s_nop 0
	v_mov_b32_dpp v14, v0 row_bcast:15 row_mask:0xa bank_mask:0xf
	v_add_f32_e32 v0, v0, v14
	v_mov_b32_e32 v14, v1
	s_nop 1
	v_mov_b32_dpp v14, v0 row_bcast:31 row_mask:0xc bank_mask:0xf
	v_add_f32_e32 v0, v0, v14
	s_nop 0
	v_readlane_b32 s13, v0, 63
	s_nop 1
	v_cvt_i32_f32_e32 v0, s13
	v_cvt_f32_i32_e32 v0, v0
	v_fmamk_f32 v0, v0, 0x3a800000, v211
	v_cmp_gt_f32_e32 vcc, s68, v0
	v_mul_f32_e32 v14, 0x4b800000, v0
	s_nop 0
	v_cndmask_b32_e32 v0, v0, v14, vcc
	v_rsq_f32_e32 v0, v0
	s_nop 0
	v_mul_f32_e32 v14, 0x45800000, v0
	v_cndmask_b32_e32 v0, v0, v14, vcc
	global_load_dwordx4 v[14:17], v[142:143], off
	global_load_dwordx4 v[18:21], v139, s[0:1]
	global_load_dwordx4 v[26:29], v139, s[26:27]
	v_pk_mul_f32 v[24:25], v[24:25], v[0:1] op_sel_hi:[1,0]
	v_pk_mul_f32 v[22:23], v[22:23], v[0:1] op_sel_hi:[1,0]
	v_pk_mul_f32 v[12:13], v[12:13], v[0:1] op_sel_hi:[1,0]
	v_pk_mul_f32 v[10:11], v[10:11], v[0:1] op_sel_hi:[1,0]
	v_pk_mul_f32 v[8:9], v[8:9], v[0:1] op_sel_hi:[1,0]
	v_pk_mul_f32 v[6:7], v[6:7], v[0:1] op_sel_hi:[1,0]
	v_pk_mul_f32 v[4:5], v[4:5], v[0:1] op_sel_hi:[1,0]
	v_pk_mul_f32 v[2:3], v[2:3], v[0:1] op_sel_hi:[1,0]
	s_waitcnt vmcnt(2)
	v_pk_mul_f32 v[14:15], v[14:15], v[22:23]
	v_pk_mul_f32 v[16:17], v[16:17], v[24:25]
	s_waitcnt vmcnt(0)
	v_pk_add_f32 v[24:25], v[26:27], 1.0 op_sel_hi:[1,0]
	v_pk_add_f32 v[22:23], v[28:29], 1.0 op_sel_hi:[1,0]
	v_pk_fma_f32 v[14:15], v[24:25], v[14:15], v[18:19]
	v_lshl_add_u64 v[26:27], v[148:149], 0, s[24:25]
	v_pk_fma_f32 v[16:17], v[22:23], v[16:17], v[20:21]
	v_cvt_pk_bf16_f32 v14, v14, v15
	s_nop 0
	v_cvt_pk_bf16_f32 v15, v16, v17
	global_store_dwordx2 v[26:27], v[14:15], off
	global_load_dwordx4 v[14:17], v[142:143], off offset:1024
	global_load_dwordx4 v[18:21], v139, s[0:1] offset:1024
	global_load_dwordx4 v[22:25], v184, s[26:27]
	s_waitcnt vmcnt(2)
	v_pk_mul_f32 v[10:11], v[14:15], v[10:11]
	v_pk_mul_f32 v[12:13], v[16:17], v[12:13]
	s_waitcnt vmcnt(0)
	v_pk_add_f32 v[16:17], v[22:23], 1.0 op_sel_hi:[1,0]
	v_pk_add_f32 v[14:15], v[24:25], 1.0 op_sel_hi:[1,0]
	v_pk_fma_f32 v[10:11], v[16:17], v[10:11], v[18:19]
	v_pk_fma_f32 v[12:13], v[14:15], v[12:13], v[20:21]
	v_cvt_pk_bf16_f32 v10, v10, v11
	s_nop 0
	v_cvt_pk_bf16_f32 v11, v12, v13
	global_store_dwordx2 v[26:27], v[10:11], off offset:512
	global_load_dwordx4 v[10:13], v[142:143], off offset:2048
	global_load_dwordx4 v[14:17], v139, s[0:1] offset:2048
	global_load_dwordx4 v[18:21], v185, s[26:27]
	s_waitcnt vmcnt(2)
	v_pk_mul_f32 v[6:7], v[6:7], v[10:11]
	v_pk_mul_f32 v[8:9], v[8:9], v[12:13]
	s_waitcnt vmcnt(0)
	v_pk_add_f32 v[12:13], v[18:19], 1.0 op_sel_hi:[1,0]
	v_pk_add_f32 v[10:11], v[20:21], 1.0 op_sel_hi:[1,0]
	v_pk_fma_f32 v[6:7], v[6:7], v[12:13], v[14:15]
	v_pk_fma_f32 v[8:9], v[8:9], v[10:11], v[16:17]
	v_cvt_pk_bf16_f32 v6, v6, v7
	s_nop 0
	v_cvt_pk_bf16_f32 v7, v8, v9
	global_store_dwordx2 v[26:27], v[6:7], off offset:1024
	global_load_dwordx4 v[6:9], v[142:143], off offset:3072
	global_load_dwordx4 v[10:13], v139, s[0:1] offset:3072
	global_load_dwordx4 v[14:17], v186, s[26:27]
	s_waitcnt vmcnt(2)
	v_pk_mul_f32 v[2:3], v[2:3], v[6:7]
	v_pk_mul_f32 v[4:5], v[4:5], v[8:9]
	s_waitcnt vmcnt(0)
	v_pk_add_f32 v[8:9], v[14:15], 1.0 op_sel_hi:[1,0]
	v_pk_add_f32 v[6:7], v[16:17], 1.0 op_sel_hi:[1,0]
	v_pk_fma_f32 v[2:3], v[2:3], v[8:9], v[10:11]
	v_pk_fma_f32 v[4:5], v[4:5], v[6:7], v[12:13]
	v_cvt_pk_bf16_f32 v2, v2, v3
	s_nop 0
	v_cvt_pk_bf16_f32 v3, v4, v5
	global_store_dwordx2 v[26:27], v[2:3], off offset:1536
	s_branch .LBB0_1165

; template <int NS> __device__ __forceinline__ void load16part(const float* P, int rowrel, int lane, f32x4 (&v)[4]) {
; #pragma unroll
;     for (int j = 0; j < 4; ++j) v[j] = (f32x4){0.f, 0.f, 0.f, 0.f};
; #pragma unroll
;     for (int s0 = 0; s0 < NS; s0 += 4) { f32x4 t[4][4];
; #pragma unroll
;         for (int s = 0; s < 4; ++s) { const f32x4* q = (const f32x4*)(P + ((size_t)(s0 + s) * 1024 + rowrel) * 1024);
; #pragma unroll
;             for (int j = 0; j < 4; ++j) t[s][j] = q[lane + 64 * j]; }
; #pragma unroll
;         for (int s = 0; s < 4; ++s)
; #pragma unroll
;             for (int j = 0; j < 4; ++j) v[j] += t[s][j]; }
; }
.LBB0_1232:
	s_andn2_b64 vcc, exec, s[0:1]
	s_cbranch_vccnz .LBB0_1234
	s_add_i32 s70, s12, 0xffff8000
	s_lshl_b64 s[0:1], s[70:71], 12
	s_add_i32 s70, s12, 0xffff8400
	v_lshl_add_u64 v[14:15], v[184:185], 0, s[0:1]
	s_lshl_b64 s[0:1], s[70:71], 12
	s_add_i32 s70, s12, 0xffff8800
	global_load_dwordx4 v[2:5], v[14:15], off
	global_load_dwordx4 v[6:9], v[14:15], off offset:1024
	global_load_dwordx4 v[10:13], v[14:15], off offset:2048
	global_load_dwordx4 v[14:17], v[14:15], off offset:3072
	v_lshl_add_u64 v[30:31], v[184:185], 0, s[0:1]
	s_lshl_b64 s[0:1], s[70:71], 12
	s_add_i32 s70, s12, 0xffff8c00
	global_load_dwordx4 v[18:21], v[30:31], off
	global_load_dwordx4 v[22:25], v[30:31], off offset:1024
	global_load_dwordx4 v[26:29], v[30:31], off offset:2048
	global_load_dwordx4 v[30:33], v[30:31], off offset:3072
	v_lshl_add_u64 v[46:47], v[184:185], 0, s[0:1]
	s_lshl_b64 s[0:1], s[70:71], 12
	global_load_dwordx4 v[34:37], v[46:47], off
	global_load_dwordx4 v[38:41], v[46:47], off offset:1024
	global_load_dwordx4 v[42:45], v[46:47], off offset:2048
	global_load_dwordx4 v[46:49], v[46:47], off offset:3072
	v_lshl_add_u64 v[62:63], v[184:185], 0, s[0:1]
	global_load_dwordx4 v[50:53], v[62:63], off
	global_load_dwordx4 v[54:57], v[62:63], off offset:1024
	global_load_dwordx4 v[58:61], v[62:63], off offset:2048
	global_load_dwordx4 v[62:65], v[62:63], off offset:3072
	s_add_i32 s70, s12, 0xffff9000
	s_lshl_b64 s[0:1], s[70:71], 12
	s_add_i32 s70, s12, 0xffff9400
	s_waitcnt vmcnt(15)
	v_pk_add_f32 v[4:5], v[4:5], 0 op_sel_hi:[1,0]
	v_pk_add_f32 v[2:3], v[2:3], 0 op_sel_hi:[1,0]
	s_waitcnt vmcnt(14)
	v_pk_add_f32 v[8:9], v[8:9], 0 op_sel_hi:[1,0]
	v_pk_add_f32 v[6:7], v[6:7], 0 op_sel_hi:[1,0]
	s_waitcnt vmcnt(13)
	v_pk_add_f32 v[12:13], v[12:13], 0 op_sel_hi:[1,0]
	v_pk_add_f32 v[10:11], v[10:11], 0 op_sel_hi:[1,0]
	s_waitcnt vmcnt(12)
	v_pk_add_f32 v[16:17], v[16:17], 0 op_sel_hi:[1,0]
	v_pk_add_f32 v[14:15], v[14:15], 0 op_sel_hi:[1,0]
	s_waitcnt vmcnt(11)
	v_pk_add_f32 v[4:5], v[4:5], v[20:21]
	v_pk_add_f32 v[2:3], v[2:3], v[18:19]
	s_waitcnt vmcnt(10)
	v_pk_add_f32 v[8:9], v[8:9], v[24:25]
	v_pk_add_f32 v[6:7], v[6:7], v[22:23]
	s_waitcnt vmcnt(9)
	v_pk_add_f32 v[12:13], v[12:13], v[28:29]
	v_pk_add_f32 v[10:11], v[10:11], v[26:27]
	s_waitcnt vmcnt(8)
	v_pk_add_f32 v[16:17], v[16:17], v[32:33]
	v_pk_add_f32 v[14:15], v[14:15], v[30:31]
	s_waitcnt vmcnt(7)
	v_pk_add_f32 v[4:5], v[4:5], v[36:37]
	v_pk_add_f32 v[2:3], v[2:3], v[34:35]
	s_waitcnt vmcnt(6)
	v_pk_add_f32 v[8:9], v[8:9], v[40:41]
	v_pk_add_f32 v[6:7], v[6:7], v[38:39]
	s_waitcnt vmcnt(5)
	v_pk_add_f32 v[18:19], v[12:13], v[44:45]
	v_pk_add_f32 v[20:21], v[10:11], v[42:43]
	s_waitcnt vmcnt(4)
	v_pk_add_f32 v[22:23], v[16:17], v[48:49]
	v_pk_add_f32 v[24:25], v[14:15], v[46:47]
	v_lshl_add_u64 v[30:31], v[184:185], 0, s[0:1]
	s_lshl_b64 s[0:1], s[70:71], 12
	s_add_i32 s70, s12, 0xffff9800
	s_waitcnt vmcnt(3)
	v_pk_add_f32 v[14:15], v[4:5], v[52:53]
	v_pk_add_f32 v[16:17], v[2:3], v[50:51]
	s_waitcnt vmcnt(2)
	v_pk_add_f32 v[10:11], v[8:9], v[56:57]
	v_pk_add_f32 v[12:13], v[6:7], v[54:55]
	s_waitcnt vmcnt(1)
	v_pk_add_f32 v[2:3], v[18:19], v[60:61]
	v_pk_add_f32 v[4:5], v[20:21], v[58:59]
	s_waitcnt vmcnt(0)
	v_pk_add_f32 v[6:7], v[22:23], v[64:65]
	v_pk_add_f32 v[8:9], v[24:25], v[62:63]
	global_load_dwordx4 v[18:21], v[30:31], off
	global_load_dwordx4 v[22:25], v[30:31], off offset:1024
	global_load_dwordx4 v[26:29], v[30:31], off offset:2048
	global_load_dwordx4 v[30:33], v[30:31], off offset:3072
	v_lshl_add_u64 v[46:47], v[184:185], 0, s[0:1]
	s_lshl_b64 s[0:1], s[70:71], 12
	s_add_i32 s70, s12, 0xffff9c00
	global_load_dwordx4 v[34:37], v[46:47], off
	global_load_dwordx4 v[38:41], v[46:47], off offset:1024
	global_load_dwordx4 v[42:45], v[46:47], off offset:2048
	global_load_dwordx4 v[46:49], v[46:47], off offset:3072
	v_lshl_add_u64 v[62:63], v[184:185], 0, s[0:1]
	s_lshl_b64 s[0:1], s[70:71], 12
	global_load_dwordx4 v[50:53], v[62:63], off
	global_load_dwordx4 v[54:57], v[62:63], off offset:1024
	global_load_dwordx4 v[58:61], v[62:63], off offset:2048
	global_load_dwordx4 v[62:65], v[62:63], off offset:3072
	v_lshl_add_u64 v[78:79], v[184:185], 0, s[0:1]
	global_load_dwordx4 v[66:69], v[78:79], off
	global_load_dwordx4 v[70:73], v[78:79], off offset:1024
	global_load_dwordx4 v[74:77], v[78:79], off offset:2048
	global_load_dwordx4 v[78:81], v[78:79], off offset:3072
	s_add_i32 s70, s12, 0xffffa000
	s_lshl_b64 s[0:1], s[70:71], 12
	s_add_i32 s70, s12, 0xffffa400
	s_waitcnt vmcnt(15)
	v_pk_add_f32 v[14:15], v[14:15], v[20:21]
	v_pk_add_f32 v[16:17], v[16:17], v[18:19]
	s_waitcnt vmcnt(14)
	v_pk_add_f32 v[10:11], v[10:11], v[24:25]
	v_pk_add_f32 v[12:13], v[12:13], v[22:23]
	s_waitcnt vmcnt(13)
	v_pk_add_f32 v[2:3], v[2:3], v[28:29]
	v_pk_add_f32 v[4:5], v[4:5], v[26:27]
	s_waitcnt vmcnt(12)
	v_pk_add_f32 v[6:7], v[6:7], v[32:33]
	v_pk_add_f32 v[8:9], v[8:9], v[30:31]
	s_waitcnt vmcnt(11)
	v_pk_add_f32 v[14:15], v[14:15], v[36:37]
	v_pk_add_f32 v[16:17], v[16:17], v[34:35]
	s_waitcnt vmcnt(10)
	v_pk_add_f32 v[10:11], v[10:11], v[40:41]
	v_pk_add_f32 v[12:13], v[12:13], v[38:39]
	s_waitcnt vmcnt(9)
	v_pk_add_f32 v[2:3], v[2:3], v[44:45]
	v_pk_add_f32 v[4:5], v[4:5], v[42:43]
	s_waitcnt vmcnt(8)
	v_pk_add_f32 v[6:7], v[6:7], v[48:49]
	v_pk_add_f32 v[8:9], v[8:9], v[46:47]
	s_waitcnt vmcnt(7)
	v_pk_add_f32 v[14:15], v[14:15], v[52:53]
	v_pk_add_f32 v[16:17], v[16:17], v[50:51]
	s_waitcnt vmcnt(6)
	v_pk_add_f32 v[10:11], v[10:11], v[56:57]
	v_pk_add_f32 v[12:13], v[12:13], v[54:55]
	s_waitcnt vmcnt(5)
	v_pk_add_f32 v[2:3], v[2:3], v[60:61]
	v_pk_add_f32 v[4:5], v[4:5], v[58:59]
	s_waitcnt vmcnt(4)
; template <int NS> __device__ __forceinline__ void load16part(const float* P, int rowrel, int lane, f32x4 (&v)[4]) {
; #pragma unroll
;     for (int j = 0; j < 4; ++j) v[j] = (f32x4){0.f, 0.f, 0.f, 0.f};
; #pragma unroll
;     for (int s0 = 0; s0 < NS; s0 += 4) { f32x4 t[4][4];
; #pragma unroll
;         for (int s = 0; s < 4; ++s) { const f32x4* q = (const f32x4*)(P + ((size_t)(s0 + s) * 1024 + rowrel) * 1024);
; #pragma unroll
;             for (int j = 0; j < 4; ++j) t[s][j] = q[lane + 64 * j]; }
; #pragma unroll
;         for (int s = 0; s < 4; ++s)
; #pragma unroll
;             for (int j = 0; j < 4; ++j) v[j] += t[s][j]; }
; }
	v_pk_add_f32 v[6:7], v[6:7], v[64:65]
	v_pk_add_f32 v[8:9], v[8:9], v[62:63]
	s_waitcnt vmcnt(3)
	v_pk_add_f32 v[68:69], v[14:15], v[68:69]
	v_lshl_add_u64 v[14:15], v[184:185], 0, s[0:1]
	s_lshl_b64 s[0:1], s[70:71], 12
	s_add_i32 s70, s12, 0xffffa800
	v_pk_add_f32 v[66:67], v[16:17], v[66:67]
	s_waitcnt vmcnt(2)
	v_pk_add_f32 v[72:73], v[10:11], v[72:73]
	v_pk_add_f32 v[70:71], v[12:13], v[70:71]
	s_waitcnt vmcnt(1)
	v_pk_add_f32 v[76:77], v[2:3], v[76:77]
	v_pk_add_f32 v[74:75], v[4:5], v[74:75]
	s_waitcnt vmcnt(0)
	v_pk_add_f32 v[80:81], v[6:7], v[80:81]
	v_pk_add_f32 v[78:79], v[8:9], v[78:79]
	global_load_dwordx4 v[2:5], v[14:15], off
	global_load_dwordx4 v[6:9], v[14:15], off offset:1024
	global_load_dwordx4 v[10:13], v[14:15], off offset:2048
	global_load_dwordx4 v[14:17], v[14:15], off offset:3072
	v_lshl_add_u64 v[30:31], v[184:185], 0, s[0:1]
	s_lshl_b64 s[0:1], s[70:71], 12
	s_add_i32 s70, s12, 0xffffac00
	global_load_dwordx4 v[18:21], v[30:31], off
	global_load_dwordx4 v[22:25], v[30:31], off offset:1024
	global_load_dwordx4 v[26:29], v[30:31], off offset:2048
	global_load_dwordx4 v[30:33], v[30:31], off offset:3072
	v_lshl_add_u64 v[46:47], v[184:185], 0, s[0:1]
	s_lshl_b64 s[0:1], s[70:71], 12
	global_load_dwordx4 v[34:37], v[46:47], off
	global_load_dwordx4 v[38:41], v[46:47], off offset:1024
	global_load_dwordx4 v[42:45], v[46:47], off offset:2048
	global_load_dwordx4 v[46:49], v[46:47], off offset:3072
	v_lshl_add_u64 v[62:63], v[184:185], 0, s[0:1]
	global_load_dwordx4 v[50:53], v[62:63], off
	global_load_dwordx4 v[54:57], v[62:63], off offset:1024
	global_load_dwordx4 v[58:61], v[62:63], off offset:2048
	global_load_dwordx4 v[62:65], v[62:63], off offset:3072
	s_add_i32 s70, s12, 0xffffb000
	s_lshl_b64 s[0:1], s[70:71], 12
	s_add_i32 s70, s12, 0xffffb400
	s_waitcnt vmcnt(15)
	v_pk_add_f32 v[2:3], v[66:67], v[2:3]
	v_pk_add_f32 v[4:5], v[68:69], v[4:5]
	s_waitcnt vmcnt(13)
	v_pk_add_f32 v[12:13], v[76:77], v[12:13]
	v_pk_add_f32 v[10:11], v[74:75], v[10:11]
	s_waitcnt vmcnt(12)
	v_pk_add_f32 v[16:17], v[80:81], v[16:17]
	v_pk_add_f32 v[14:15], v[78:79], v[14:15]
	s_waitcnt vmcnt(11)
	v_pk_add_f32 v[2:3], v[2:3], v[18:19]
	v_pk_add_f32 v[8:9], v[72:73], v[8:9]
	v_pk_add_f32 v[6:7], v[70:71], v[6:7]
	v_pk_add_f32 v[4:5], v[4:5], v[20:21]
	s_waitcnt vmcnt(9)
	v_pk_add_f32 v[12:13], v[12:13], v[28:29]
	v_pk_add_f32 v[10:11], v[10:11], v[26:27]
	s_waitcnt vmcnt(8)
	v_pk_add_f32 v[16:17], v[16:17], v[32:33]
	v_pk_add_f32 v[14:15], v[14:15], v[30:31]
	s_waitcnt vmcnt(7)
	v_pk_add_f32 v[2:3], v[2:3], v[34:35]
	v_pk_add_f32 v[8:9], v[8:9], v[24:25]
	v_pk_add_f32 v[6:7], v[6:7], v[22:23]
	v_pk_add_f32 v[4:5], v[4:5], v[36:37]
	s_waitcnt vmcnt(5)
	v_pk_add_f32 v[12:13], v[12:13], v[44:45]
	v_pk_add_f32 v[10:11], v[10:11], v[42:43]
	s_waitcnt vmcnt(4)
	v_pk_add_f32 v[16:17], v[16:17], v[48:49]
	v_pk_add_f32 v[14:15], v[14:15], v[46:47]
	s_waitcnt vmcnt(3)
	v_pk_add_f32 v[80:81], v[2:3], v[50:51]
	v_lshl_add_u64 v[2:3], v[184:185], 0, s[0:1]
	s_lshl_b64 s[0:1], s[70:71], 12
	s_add_i32 s70, s12, 0xffffb800
	v_pk_add_f32 v[8:9], v[8:9], v[40:41]
	v_pk_add_f32 v[6:7], v[6:7], v[38:39]
	v_pk_add_f32 v[78:79], v[4:5], v[52:53]
	s_waitcnt vmcnt(1)
	v_pk_add_f32 v[70:71], v[12:13], v[60:61]
	v_pk_add_f32 v[72:73], v[10:11], v[58:59]
	s_waitcnt vmcnt(0)
	v_pk_add_f32 v[66:67], v[16:17], v[64:65]
	v_pk_add_f32 v[68:69], v[14:15], v[62:63]
	global_load_dwordx4 v[58:61], v[2:3], off
	global_load_dwordx4 v[62:65], v[2:3], off offset:1024
	global_load_dwordx4 v[50:53], v[2:3], off offset:2048
	global_load_dwordx4 v[34:37], v[2:3], off offset:3072
	v_lshl_add_u64 v[2:3], v[184:185], 0, s[0:1]
	s_lshl_b64 s[0:1], s[70:71], 12
	s_add_i32 s70, s12, 0xffffbc00
	v_pk_add_f32 v[74:75], v[8:9], v[56:57]
	v_pk_add_f32 v[76:77], v[6:7], v[54:55]
	global_load_dwordx4 v[46:49], v[2:3], off
	global_load_dwordx4 v[54:57], v[2:3], off offset:1024
	global_load_dwordx4 v[38:41], v[2:3], off offset:2048
	global_load_dwordx4 v[22:25], v[2:3], off offset:3072
	v_lshl_add_u64 v[2:3], v[184:185], 0, s[0:1]
	s_lshl_b64 s[0:1], s[70:71], 12
	global_load_dwordx4 v[30:33], v[2:3], off
	global_load_dwordx4 v[42:45], v[2:3], off offset:1024
	global_load_dwordx4 v[26:29], v[2:3], off offset:2048
	global_load_dwordx4 v[14:17], v[2:3], off offset:3072
	v_lshl_add_u64 v[2:3], v[184:185], 0, s[0:1]
	global_load_dwordx4 v[18:21], v[2:3], off
	global_load_dwordx4 v[10:13], v[2:3], off offset:1024
	global_load_dwordx4 v[6:9], v[2:3], off offset:2048
	global_load_dwordx4 v[2:5], v[2:3], off offset:3072
	s_waitcnt vmcnt(15)
	v_pk_add_f32 v[60:61], v[78:79], v[60:61]
	v_pk_add_f32 v[58:59], v[80:81], v[58:59]
	s_waitcnt vmcnt(14)
	v_pk_add_f32 v[64:65], v[74:75], v[64:65]
	v_pk_add_f32 v[62:63], v[76:77], v[62:63]
	s_waitcnt vmcnt(13)
	v_pk_add_f32 v[52:53], v[70:71], v[52:53]
	v_pk_add_f32 v[50:51], v[72:73], v[50:51]
	s_waitcnt vmcnt(12)
	v_pk_add_f32 v[36:37], v[66:67], v[36:37]
	v_pk_add_f32 v[34:35], v[68:69], v[34:35]
	s_waitcnt vmcnt(11)
	v_pk_add_f32 v[48:49], v[60:61], v[48:49]
	v_pk_add_f32 v[46:47], v[58:59], v[46:47]
	s_waitcnt vmcnt(10)
	v_pk_add_f32 v[56:57], v[64:65], v[56:57]
	v_pk_add_f32 v[54:55], v[62:63], v[54:55]
	s_waitcnt vmcnt(9)
	v_pk_add_f32 v[40:41], v[52:53], v[40:41]
	v_pk_add_f32 v[38:39], v[50:51], v[38:39]
	s_waitcnt vmcnt(8)
	v_pk_add_f32 v[24:25], v[36:37], v[24:25]
	v_pk_add_f32 v[22:23], v[34:35], v[22:23]
	s_waitcnt vmcnt(7)
	v_pk_add_f32 v[32:33], v[48:49], v[32:33]
	v_pk_add_f32 v[30:31], v[46:47], v[30:31]
	s_waitcnt vmcnt(6)
	v_pk_add_f32 v[34:35], v[56:57], v[44:45]
	v_pk_add_f32 v[36:37], v[54:55], v[42:43]
	s_waitcnt vmcnt(5)
	v_pk_add_f32 v[40:41], v[40:41], v[28:29]
	v_pk_add_f32 v[38:39], v[38:39], v[26:27]
	s_waitcnt vmcnt(4)
	v_pk_add_f32 v[16:17], v[24:25], v[16:17]
	v_pk_add_f32 v[14:15], v[22:23], v[14:15]
	s_waitcnt vmcnt(3)
	v_pk_add_f32 v[32:33], v[32:33], v[20:21]
	v_pk_add_f32 v[30:31], v[30:31], v[18:19]
	s_waitcnt vmcnt(2)
	v_pk_add_f32 v[28:29], v[34:35], v[12:13]
	v_pk_add_f32 v[26:27], v[36:37], v[10:11]
	s_waitcnt vmcnt(1)
	v_pk_add_f32 v[20:21], v[40:41], v[8:9]
	v_pk_add_f32 v[18:19], v[38:39], v[6:7]
	s_waitcnt vmcnt(0)
	v_pk_add_f32 v[16:17], v[16:17], v[4:5]
	v_pk_add_f32 v[14:15], v[14:15], v[2:3]

; __device__ __forceinline__ float bflo(unsigned w) { return __uint_as_float(w << 16); }
; __device__ __forceinline__ float bfhi(unsigned w) { return __uint_as_float(w & 0xffff0000u); }
; #define LOADY(m, y, ns) do { if ((m) >= NLAT) load16part<ns>(WSP(float, WS_PART), (m) - NLAT, lane, y); else load16bf(BY + (size_t)(m) * DM, lane, y); } while (0)
; __device__ __forceinline__ void load16(const float* row, int lane, f32x4 (&v)[4]) {
; #pragma unroll
;     for (int j = 0; j < 4; ++j) v[j] = __builtin_nontemporal_load((const f32x4*)row + lane + 64 * j);
; }
; __device__ __forceinline__ void load16bf(const bf16_t* row, int lane, f32x4 (&v)[4]) {
; #pragma unroll
;     for (int j = 0; j < 4; ++j) { const u32x2 w = __builtin_nontemporal_load((const u32x2*)row + lane + 64 * j); v[j] = (f32x4){bflo(w.x), bfhi(w.x), bflo(w.y), bfhi(w.y)}; }
; }
; __global__ void __launch_bounds__(512, 2) fwd_megakernel(Params p) {
;     ...
;             for (int i = 0; i < 4; ++i) { const int mi = m0 + i * NGW, mc = mi < Mact ? mi : m0; LOADY(mc, yb[i], 16); load16(XS_ROW(mc), lane, xb[i]); }
.LBB0_1238:
	s_lshl_b64 s[0:1], s[0:1], 12
	s_waitcnt lgkmcnt(0)
	s_add_u32 s0, s6, s0
	s_addc_u32 s1, s7, s1
	global_load_dwordx4 v[46:49], v214, s[0:1] nt
	global_load_dwordx4 v[42:45], v214, s[0:1] offset:1024 nt
	global_load_dwordx4 v[38:41], v214, s[0:1] offset:2048 nt
	global_load_dwordx4 v[34:37], v214, s[0:1] offset:3072 nt
	s_add_i32 s14, s12, 0x800
	s_cmp_lt_i32 s14, s53
	s_cselect_b64 s[6:7], -1, 0
	s_and_b64 s[0:1], s[6:7], exec
	s_cselect_b32 s0, s14, s12
	s_cmpk_gt_i32 s0, 0x7fff
	s_mov_b64 s[8:9], -1
	s_cbranch_scc1 .LBB0_1242
	s_ashr_i32 s1, s0, 31
	s_lshl_b64 s[8:9], s[0:1], 11
	v_lshl_add_u64 v[2:3], v[178:179], 0, s[8:9]
	global_load_dwordx2 v[4:5], v[2:3], off nt
	global_load_dwordx2 v[6:7], v[2:3], off offset:512 nt
	global_load_dwordx2 v[8:9], v[2:3], off offset:1024 nt
	global_load_dwordx2 v[2:3], v[2:3], off offset:1536 nt
	s_waitcnt vmcnt(3)
	v_lshlrev_b32_e32 v62, 16, v4
	v_and_b32_e32 v63, 0xffff0000, v4
	v_lshlrev_b32_e32 v64, 16, v5
	v_and_b32_e32 v65, 0xffff0000, v5
	s_waitcnt vmcnt(2)
	v_lshlrev_b32_e32 v58, 16, v6
	v_and_b32_e32 v59, 0xffff0000, v6
	v_lshlrev_b32_e32 v60, 16, v7
	v_and_b32_e32 v61, 0xffff0000, v7
	s_waitcnt vmcnt(1)
	v_lshlrev_b32_e32 v54, 16, v8
	v_and_b32_e32 v55, 0xffff0000, v8
	v_lshlrev_b32_e32 v56, 16, v9
	v_and_b32_e32 v57, 0xffff0000, v9
	s_waitcnt vmcnt(0)
	v_lshlrev_b32_e32 v50, 16, v2
	v_and_b32_e32 v51, 0xffff0000, v2
	v_lshlrev_b32_e32 v52, 16, v3
	v_and_b32_e32 v53, 0xffff0000, v3
	s_cbranch_execz .LBB0_1243

; template <int NS> __device__ __forceinline__ void load16part(const float* P, int rowrel, int lane, f32x4 (&v)[4]) {
; #pragma unroll
;     for (int j = 0; j < 4; ++j) v[j] = (f32x4){0.f, 0.f, 0.f, 0.f};
; #pragma unroll
;     for (int s0 = 0; s0 < NS; s0 += 4) { f32x4 t[4][4];
; #pragma unroll
;         for (int s = 0; s < 4; ++s) { const f32x4* q = (const f32x4*)(P + ((size_t)(s0 + s) * 1024 + rowrel) * 1024);
; #pragma unroll
;             for (int j = 0; j < 4; ++j) t[s][j] = q[lane + 64 * j]; }
; #pragma unroll
;         for (int s = 0; s < 4; ++s)
; #pragma unroll
;             for (int j = 0; j < 4; ++j) v[j] += t[s][j]; }
; }
.LBB0_1243:
	s_add_i32 s70, s0, 0xffff8000
	s_lshl_b64 s[8:9], s[70:71], 12
	s_add_i32 s70, s0, 0xffff8400
	v_lshl_add_u64 v[22:23], v[184:185], 0, s[8:9]
	s_lshl_b64 s[8:9], s[70:71], 12
	s_add_i32 s70, s0, 0xffff8800
	global_load_dwordx4 v[2:5], v[22:23], off
	global_load_dwordx4 v[6:9], v[22:23], off offset:1024
	global_load_dwordx4 v[10:13], v[22:23], off offset:2048
	global_load_dwordx4 v[22:25], v[22:23], off offset:3072
	v_lshl_add_u64 v[62:63], v[184:185], 0, s[8:9]
	s_lshl_b64 s[8:9], s[70:71], 12
	s_add_i32 s70, s0, 0xffff8c00
	global_load_dwordx4 v[50:53], v[62:63], off
	global_load_dwordx4 v[54:57], v[62:63], off offset:1024
	global_load_dwordx4 v[58:61], v[62:63], off offset:2048
	global_load_dwordx4 v[62:65], v[62:63], off offset:3072
	v_lshl_add_u64 v[78:79], v[184:185], 0, s[8:9]
	s_lshl_b64 s[8:9], s[70:71], 12
	global_load_dwordx4 v[66:69], v[78:79], off
	global_load_dwordx4 v[70:73], v[78:79], off offset:1024
	global_load_dwordx4 v[74:77], v[78:79], off offset:2048
	global_load_dwordx4 v[78:81], v[78:79], off offset:3072
	v_lshl_add_u64 v[94:95], v[184:185], 0, s[8:9]
	global_load_dwordx4 v[82:85], v[94:95], off
	global_load_dwordx4 v[86:89], v[94:95], off offset:1024
	global_load_dwordx4 v[90:93], v[94:95], off offset:2048
	global_load_dwordx4 v[94:97], v[94:95], off offset:3072
	s_add_i32 s70, s0, 0xffff9000
	s_lshl_b64 s[8:9], s[70:71], 12
	s_add_i32 s70, s0, 0xffff9400
	s_waitcnt vmcnt(15)
	v_pk_add_f32 v[4:5], v[4:5], 0 op_sel_hi:[1,0]
	v_pk_add_f32 v[2:3], v[2:3], 0 op_sel_hi:[1,0]
	s_waitcnt vmcnt(14)
	v_pk_add_f32 v[8:9], v[8:9], 0 op_sel_hi:[1,0]
	v_pk_add_f32 v[6:7], v[6:7], 0 op_sel_hi:[1,0]
	s_waitcnt vmcnt(13)
	v_pk_add_f32 v[12:13], v[12:13], 0 op_sel_hi:[1,0]
	v_pk_add_f32 v[10:11], v[10:11], 0 op_sel_hi:[1,0]
	s_waitcnt vmcnt(12)
	v_pk_add_f32 v[24:25], v[24:25], 0 op_sel_hi:[1,0]
	v_pk_add_f32 v[22:23], v[22:23], 0 op_sel_hi:[1,0]
	s_waitcnt vmcnt(11)
	v_pk_add_f32 v[4:5], v[4:5], v[52:53]
	v_pk_add_f32 v[2:3], v[2:3], v[50:51]
	s_waitcnt vmcnt(10)
	v_pk_add_f32 v[8:9], v[8:9], v[56:57]
	v_pk_add_f32 v[6:7], v[6:7], v[54:55]
	s_waitcnt vmcnt(9)
	v_pk_add_f32 v[12:13], v[12:13], v[60:61]
	v_pk_add_f32 v[10:11], v[10:11], v[58:59]
	s_waitcnt vmcnt(8)
	v_pk_add_f32 v[24:25], v[24:25], v[64:65]
	v_pk_add_f32 v[22:23], v[22:23], v[62:63]
	s_waitcnt vmcnt(7)
	v_pk_add_f32 v[4:5], v[4:5], v[68:69]
	v_pk_add_f32 v[2:3], v[2:3], v[66:67]
	s_waitcnt vmcnt(6)
	v_pk_add_f32 v[8:9], v[8:9], v[72:73]
	v_pk_add_f32 v[6:7], v[6:7], v[70:71]
	s_waitcnt vmcnt(5)
	v_pk_add_f32 v[50:51], v[12:13], v[76:77]
	v_pk_add_f32 v[52:53], v[10:11], v[74:75]
	s_waitcnt vmcnt(4)
	v_pk_add_f32 v[54:55], v[24:25], v[80:81]
	v_pk_add_f32 v[56:57], v[22:23], v[78:79]
	v_lshl_add_u64 v[62:63], v[184:185], 0, s[8:9]
	s_lshl_b64 s[8:9], s[70:71], 12
	s_add_i32 s70, s0, 0xffff9800
	s_waitcnt vmcnt(3)
	v_pk_add_f32 v[22:23], v[4:5], v[84:85]
	v_pk_add_f32 v[24:25], v[2:3], v[82:83]
	s_waitcnt vmcnt(2)
	v_pk_add_f32 v[10:11], v[8:9], v[88:89]
	v_pk_add_f32 v[12:13], v[6:7], v[86:87]
	s_waitcnt vmcnt(1)
	v_pk_add_f32 v[2:3], v[50:51], v[92:93]
	v_pk_add_f32 v[4:5], v[52:53], v[90:91]
	s_waitcnt vmcnt(0)
	v_pk_add_f32 v[6:7], v[54:55], v[96:97]
	v_pk_add_f32 v[8:9], v[56:57], v[94:95]
	global_load_dwordx4 v[50:53], v[62:63], off
	global_load_dwordx4 v[54:57], v[62:63], off offset:1024
	global_load_dwordx4 v[58:61], v[62:63], off offset:2048
	global_load_dwordx4 v[62:65], v[62:63], off offset:3072
	v_lshl_add_u64 v[78:79], v[184:185], 0, s[8:9]
	s_lshl_b64 s[8:9], s[70:71], 12
	s_add_i32 s70, s0, 0xffff9c00
	global_load_dwordx4 v[66:69], v[78:79], off
	global_load_dwordx4 v[70:73], v[78:79], off offset:1024
	global_load_dwordx4 v[74:77], v[78:79], off offset:2048
	global_load_dwordx4 v[78:81], v[78:79], off offset:3072
	v_lshl_add_u64 v[94:95], v[184:185], 0, s[8:9]
	s_lshl_b64 s[8:9], s[70:71], 12
	global_load_dwordx4 v[82:85], v[94:95], off
	global_load_dwordx4 v[86:89], v[94:95], off offset:1024
	global_load_dwordx4 v[90:93], v[94:95], off offset:2048
	global_load_dwordx4 v[94:97], v[94:95], off offset:3072
	v_lshl_add_u64 v[110:111], v[184:185], 0, s[8:9]
	global_load_dwordx4 v[98:101], v[110:111], off
	global_load_dwordx4 v[102:105], v[110:111], off offset:1024
	global_load_dwordx4 v[106:109], v[110:111], off offset:2048
	global_load_dwordx4 v[110:113], v[110:111], off offset:3072
	s_add_i32 s70, s0, 0xffffa000
	s_lshl_b64 s[8:9], s[70:71], 12
	s_add_i32 s70, s0, 0xffffa400
	s_waitcnt vmcnt(15)
	v_pk_add_f32 v[22:23], v[22:23], v[52:53]
	v_pk_add_f32 v[24:25], v[24:25], v[50:51]
	s_waitcnt vmcnt(14)
	v_pk_add_f32 v[10:11], v[10:11], v[56:57]
	v_pk_add_f32 v[12:13], v[12:13], v[54:55]
	s_waitcnt vmcnt(13)
	v_pk_add_f32 v[2:3], v[2:3], v[60:61]
	v_pk_add_f32 v[4:5], v[4:5], v[58:59]
	s_waitcnt vmcnt(12)
	v_pk_add_f32 v[6:7], v[6:7], v[64:65]
	v_pk_add_f32 v[8:9], v[8:9], v[62:63]
	s_waitcnt vmcnt(11)
	v_pk_add_f32 v[22:23], v[22:23], v[68:69]
	v_pk_add_f32 v[24:25], v[24:25], v[66:67]
	s_waitcnt vmcnt(10)
	v_pk_add_f32 v[10:11], v[10:11], v[72:73]
	v_pk_add_f32 v[12:13], v[12:13], v[70:71]
	s_waitcnt vmcnt(9)
	v_pk_add_f32 v[2:3], v[2:3], v[76:77]
	v_pk_add_f32 v[4:5], v[4:5], v[74:75]
	s_waitcnt vmcnt(8)
	v_pk_add_f32 v[6:7], v[6:7], v[80:81]
	v_pk_add_f32 v[8:9], v[8:9], v[78:79]
	s_waitcnt vmcnt(7)
	v_pk_add_f32 v[22:23], v[22:23], v[84:85]
	v_pk_add_f32 v[24:25], v[24:25], v[82:83]
	s_waitcnt vmcnt(6)
	v_pk_add_f32 v[10:11], v[10:11], v[88:89]
	v_pk_add_f32 v[12:13], v[12:13], v[86:87]
	s_waitcnt vmcnt(5)
	v_pk_add_f32 v[2:3], v[2:3], v[92:93]
	v_pk_add_f32 v[4:5], v[4:5], v[90:91]
	s_waitcnt vmcnt(4)
; template <int NS> __device__ __forceinline__ void load16part(const float* P, int rowrel, int lane, f32x4 (&v)[4]) {
; #pragma unroll
;     for (int j = 0; j < 4; ++j) v[j] = (f32x4){0.f, 0.f, 0.f, 0.f};
; #pragma unroll
;     for (int s0 = 0; s0 < NS; s0 += 4) { f32x4 t[4][4];
; #pragma unroll
;         for (int s = 0; s < 4; ++s) { const f32x4* q = (const f32x4*)(P + ((size_t)(s0 + s) * 1024 + rowrel) * 1024);
; #pragma unroll
;             for (int j = 0; j < 4; ++j) t[s][j] = q[lane + 64 * j]; }
; #pragma unroll
;         for (int s = 0; s < 4; ++s)
; #pragma unroll
;             for (int j = 0; j < 4; ++j) v[j] += t[s][j]; }
; }
	v_pk_add_f32 v[6:7], v[6:7], v[96:97]
	v_pk_add_f32 v[8:9], v[8:9], v[94:95]
	s_waitcnt vmcnt(3)
	v_pk_add_f32 v[100:101], v[22:23], v[100:101]
	v_lshl_add_u64 v[22:23], v[184:185], 0, s[8:9]
	s_lshl_b64 s[8:9], s[70:71], 12
	s_add_i32 s70, s0, 0xffffa800
	v_pk_add_f32 v[98:99], v[24:25], v[98:99]
	s_waitcnt vmcnt(2)
	v_pk_add_f32 v[104:105], v[10:11], v[104:105]
	v_pk_add_f32 v[102:103], v[12:13], v[102:103]
	s_waitcnt vmcnt(1)
	v_pk_add_f32 v[108:109], v[2:3], v[108:109]
	v_pk_add_f32 v[106:107], v[4:5], v[106:107]
	s_waitcnt vmcnt(0)
	v_pk_add_f32 v[112:113], v[6:7], v[112:113]
	v_pk_add_f32 v[110:111], v[8:9], v[110:111]
	global_load_dwordx4 v[2:5], v[22:23], off
	global_load_dwordx4 v[6:9], v[22:23], off offset:1024
	global_load_dwordx4 v[10:13], v[22:23], off offset:2048
	global_load_dwordx4 v[22:25], v[22:23], off offset:3072
	v_lshl_add_u64 v[62:63], v[184:185], 0, s[8:9]
	s_lshl_b64 s[8:9], s[70:71], 12
	s_add_i32 s70, s0, 0xffffac00
	global_load_dwordx4 v[50:53], v[62:63], off
	global_load_dwordx4 v[54:57], v[62:63], off offset:1024
	global_load_dwordx4 v[58:61], v[62:63], off offset:2048
	global_load_dwordx4 v[62:65], v[62:63], off offset:3072
	v_lshl_add_u64 v[78:79], v[184:185], 0, s[8:9]
	s_lshl_b64 s[8:9], s[70:71], 12
	global_load_dwordx4 v[66:69], v[78:79], off
	global_load_dwordx4 v[70:73], v[78:79], off offset:1024
	global_load_dwordx4 v[74:77], v[78:79], off offset:2048
	global_load_dwordx4 v[78:81], v[78:79], off offset:3072
	v_lshl_add_u64 v[94:95], v[184:185], 0, s[8:9]
	global_load_dwordx4 v[82:85], v[94:95], off
	global_load_dwordx4 v[86:89], v[94:95], off offset:1024
	global_load_dwordx4 v[90:93], v[94:95], off offset:2048
	global_load_dwordx4 v[94:97], v[94:95], off offset:3072
	s_add_i32 s70, s0, 0xffffb000
	s_lshl_b64 s[8:9], s[70:71], 12
	s_add_i32 s70, s0, 0xffffb400
	s_waitcnt vmcnt(15)
	v_pk_add_f32 v[2:3], v[98:99], v[2:3]
	v_pk_add_f32 v[4:5], v[100:101], v[4:5]
	s_waitcnt vmcnt(13)
	v_pk_add_f32 v[12:13], v[108:109], v[12:13]
	v_pk_add_f32 v[10:11], v[106:107], v[10:11]
	s_waitcnt vmcnt(12)
	v_pk_add_f32 v[24:25], v[112:113], v[24:25]
	v_pk_add_f32 v[22:23], v[110:111], v[22:23]
	s_waitcnt vmcnt(11)
	v_pk_add_f32 v[2:3], v[2:3], v[50:51]
	v_pk_add_f32 v[8:9], v[104:105], v[8:9]
	v_pk_add_f32 v[6:7], v[102:103], v[6:7]
	v_pk_add_f32 v[4:5], v[4:5], v[52:53]
	s_waitcnt vmcnt(9)
	v_pk_add_f32 v[12:13], v[12:13], v[60:61]
	v_pk_add_f32 v[10:11], v[10:11], v[58:59]
	s_waitcnt vmcnt(8)
	v_pk_add_f32 v[24:25], v[24:25], v[64:65]
	v_pk_add_f32 v[22:23], v[22:23], v[62:63]
	s_waitcnt vmcnt(7)
	v_pk_add_f32 v[2:3], v[2:3], v[66:67]
	v_pk_add_f32 v[8:9], v[8:9], v[56:57]
	v_pk_add_f32 v[6:7], v[6:7], v[54:55]
	v_pk_add_f32 v[4:5], v[4:5], v[68:69]
	s_waitcnt vmcnt(5)
	v_pk_add_f32 v[12:13], v[12:13], v[76:77]
	v_pk_add_f32 v[10:11], v[10:11], v[74:75]
	s_waitcnt vmcnt(4)
	v_pk_add_f32 v[24:25], v[24:25], v[80:81]
	v_pk_add_f32 v[22:23], v[22:23], v[78:79]
	s_waitcnt vmcnt(3)
	v_pk_add_f32 v[112:113], v[2:3], v[82:83]
	v_lshl_add_u64 v[2:3], v[184:185], 0, s[8:9]
	s_lshl_b64 s[8:9], s[70:71], 12
	s_add_i32 s70, s0, 0xffffb800
	v_pk_add_f32 v[8:9], v[8:9], v[72:73]
	v_pk_add_f32 v[6:7], v[6:7], v[70:71]
	v_pk_add_f32 v[110:111], v[4:5], v[84:85]
	s_waitcnt vmcnt(1)
	v_pk_add_f32 v[102:103], v[12:13], v[92:93]
	v_pk_add_f32 v[104:105], v[10:11], v[90:91]
	s_waitcnt vmcnt(0)
	v_pk_add_f32 v[98:99], v[24:25], v[96:97]
	v_pk_add_f32 v[100:101], v[22:23], v[94:95]
	global_load_dwordx4 v[90:93], v[2:3], off
	global_load_dwordx4 v[94:97], v[2:3], off offset:1024
	global_load_dwordx4 v[82:85], v[2:3], off offset:2048
	global_load_dwordx4 v[66:69], v[2:3], off offset:3072
	v_lshl_add_u64 v[2:3], v[184:185], 0, s[8:9]
	s_lshl_b64 s[8:9], s[70:71], 12
	s_add_i32 s70, s0, 0xffffbc00
	v_pk_add_f32 v[106:107], v[8:9], v[88:89]
	v_pk_add_f32 v[108:109], v[6:7], v[86:87]
	global_load_dwordx4 v[78:81], v[2:3], off
	global_load_dwordx4 v[86:89], v[2:3], off offset:1024
	global_load_dwordx4 v[70:73], v[2:3], off offset:2048
	global_load_dwordx4 v[54:57], v[2:3], off offset:3072
	v_lshl_add_u64 v[2:3], v[184:185], 0, s[8:9]
	s_lshl_b64 s[8:9], s[70:71], 12
	global_load_dwordx4 v[62:65], v[2:3], off
	global_load_dwordx4 v[74:77], v[2:3], off offset:1024
	global_load_dwordx4 v[58:61], v[2:3], off offset:2048
	global_load_dwordx4 v[22:25], v[2:3], off offset:3072
	v_lshl_add_u64 v[2:3], v[184:185], 0, s[8:9]
	global_load_dwordx4 v[50:53], v[2:3], off
	global_load_dwordx4 v[10:13], v[2:3], off offset:1024
	global_load_dwordx4 v[6:9], v[2:3], off offset:2048
	global_load_dwordx4 v[2:5], v[2:3], off offset:3072
	s_waitcnt vmcnt(15)
	v_pk_add_f32 v[92:93], v[110:111], v[92:93]
	v_pk_add_f32 v[90:91], v[112:113], v[90:91]
	s_waitcnt vmcnt(14)
	v_pk_add_f32 v[96:97], v[106:107], v[96:97]
	v_pk_add_f32 v[94:95], v[108:109], v[94:95]
	s_waitcnt vmcnt(13)
	v_pk_add_f32 v[84:85], v[102:103], v[84:85]
	v_pk_add_f32 v[82:83], v[104:105], v[82:83]
	s_waitcnt vmcnt(12)
	v_pk_add_f32 v[68:69], v[98:99], v[68:69]
	v_pk_add_f32 v[66:67], v[100:101], v[66:67]
	s_waitcnt vmcnt(11)
	v_pk_add_f32 v[80:81], v[92:93], v[80:81]
	v_pk_add_f32 v[78:79], v[90:91], v[78:79]
	s_waitcnt vmcnt(10)
	v_pk_add_f32 v[88:89], v[96:97], v[88:89]
	v_pk_add_f32 v[86:87], v[94:95], v[86:87]
	s_waitcnt vmcnt(9)
	v_pk_add_f32 v[72:73], v[84:85], v[72:73]
	v_pk_add_f32 v[70:71], v[82:83], v[70:71]
	s_waitcnt vmcnt(8)
	v_pk_add_f32 v[56:57], v[68:69], v[56:57]
	v_pk_add_f32 v[54:55], v[66:67], v[54:55]
	s_waitcnt vmcnt(7)
	v_pk_add_f32 v[64:65], v[80:81], v[64:65]
	v_pk_add_f32 v[62:63], v[78:79], v[62:63]
	s_waitcnt vmcnt(6)
	v_pk_add_f32 v[66:67], v[88:89], v[76:77]
	v_pk_add_f32 v[68:69], v[86:87], v[74:75]
	s_waitcnt vmcnt(5)
	v_pk_add_f32 v[72:73], v[72:73], v[60:61]
	v_pk_add_f32 v[70:71], v[70:71], v[58:59]
	s_waitcnt vmcnt(4)
	v_pk_add_f32 v[24:25], v[56:57], v[24:25]
	v_pk_add_f32 v[22:23], v[54:55], v[22:23]
	s_waitcnt vmcnt(3)
	v_pk_add_f32 v[64:65], v[64:65], v[52:53]
	v_pk_add_f32 v[62:63], v[62:63], v[50:51]
	s_waitcnt vmcnt(2)
	v_pk_add_f32 v[60:61], v[66:67], v[12:13]
	v_pk_add_f32 v[58:59], v[68:69], v[10:11]
	s_waitcnt vmcnt(1)
	v_pk_add_f32 v[56:57], v[72:73], v[8:9]
	v_pk_add_f32 v[54:55], v[70:71], v[6:7]
	s_waitcnt vmcnt(0)
	v_pk_add_f32 v[52:53], v[24:25], v[4:5]
	v_pk_add_f32 v[50:51], v[22:23], v[2:3]
	s_cmp_lt_i32 s0, 0x8000
	s_mov_b64 s[20:21], -1
	s_cbranch_scc0 .LBB0_1241

; __device__ __forceinline__ float bflo(unsigned w) { return __uint_as_float(w << 16); }
; __device__ __forceinline__ float bfhi(unsigned w) { return __uint_as_float(w & 0xffff0000u); }
; #define LOADY(m, y, ns) do { if ((m) >= NLAT) load16part<ns>(WSP(float, WS_PART), (m) - NLAT, lane, y); else load16bf(BY + (size_t)(m) * DM, lane, y); } while (0)
; __device__ __forceinline__ void load16(const float* row, int lane, f32x4 (&v)[4]) {
; #pragma unroll
;     for (int j = 0; j < 4; ++j) v[j] = __builtin_nontemporal_load((const f32x4*)row + lane + 64 * j);
; }
; __device__ __forceinline__ void load16bf(const bf16_t* row, int lane, f32x4 (&v)[4]) {
; #pragma unroll
;     for (int j = 0; j < 4; ++j) { const u32x2 w = __builtin_nontemporal_load((const u32x2*)row + lane + 64 * j); v[j] = (f32x4){bflo(w.x), bfhi(w.x), bflo(w.y), bfhi(w.y)}; }
; }
; __global__ void __launch_bounds__(512, 2) fwd_megakernel(Params p) {
;     ...
;             for (int i = 0; i < 4; ++i) { const int mi = m0 + i * NGW, mc = mi < Mact ? mi : m0; LOADY(mc, yb[i], 16); load16(XS_ROW(mc), lane, xb[i]); }
.LBB0_1246:
	s_lshl_b64 s[0:1], s[8:9], 12
	s_waitcnt lgkmcnt(0)
	s_add_u32 s0, s20, s0
	s_addc_u32 s1, s21, s1
	global_load_dwordx4 v[22:25], v214, s[0:1] nt
	global_load_dwordx4 v[10:13], v214, s[0:1] offset:1024 nt
	global_load_dwordx4 v[6:9], v214, s[0:1] offset:2048 nt
	global_load_dwordx4 v[2:5], v214, s[0:1] offset:3072 nt
	s_add_i32 s20, s12, 0x1000
	s_cmp_lt_i32 s20, s53
	s_cselect_b64 s[8:9], -1, 0
	s_and_b64 s[0:1], s[8:9], exec
	s_cselect_b32 s0, s20, s12
	s_cmpk_gt_i32 s0, 0x7fff
	s_mov_b64 s[22:23], -1
	s_cbranch_scc1 .LBB0_1250
	s_ashr_i32 s1, s0, 31
	s_lshl_b64 s[22:23], s[0:1], 11
	v_lshl_add_u64 v[66:67], v[178:179], 0, s[22:23]
	global_load_dwordx2 v[68:69], v[66:67], off nt
	global_load_dwordx2 v[70:71], v[66:67], off offset:512 nt
	global_load_dwordx2 v[72:73], v[66:67], off offset:1024 nt
	global_load_dwordx2 v[66:67], v[66:67], off offset:1536 nt
	s_waitcnt vmcnt(3)
	v_lshlrev_b32_e32 v94, 16, v68
	v_and_b32_e32 v95, 0xffff0000, v68
	v_lshlrev_b32_e32 v96, 16, v69
	v_and_b32_e32 v97, 0xffff0000, v69
	s_waitcnt vmcnt(2)
	v_lshlrev_b32_e32 v90, 16, v70
	v_and_b32_e32 v91, 0xffff0000, v70
	v_lshlrev_b32_e32 v92, 16, v71
	v_and_b32_e32 v93, 0xffff0000, v71
	s_waitcnt vmcnt(1)
	v_lshlrev_b32_e32 v86, 16, v72
	v_and_b32_e32 v87, 0xffff0000, v72
	v_lshlrev_b32_e32 v88, 16, v73
	v_and_b32_e32 v89, 0xffff0000, v73
	s_waitcnt vmcnt(0)
	v_lshlrev_b32_e32 v82, 16, v66
	v_and_b32_e32 v83, 0xffff0000, v66
	v_lshlrev_b32_e32 v84, 16, v67
	v_and_b32_e32 v85, 0xffff0000, v67
	s_cbranch_execz .LBB0_1251

; template <int NS> __device__ __forceinline__ void load16part(const float* P, int rowrel, int lane, f32x4 (&v)[4]) {
; #pragma unroll
;     for (int j = 0; j < 4; ++j) v[j] = (f32x4){0.f, 0.f, 0.f, 0.f};
; #pragma unroll
;     for (int s0 = 0; s0 < NS; s0 += 4) { f32x4 t[4][4];
; #pragma unroll
;         for (int s = 0; s < 4; ++s) { const f32x4* q = (const f32x4*)(P + ((size_t)(s0 + s) * 1024 + rowrel) * 1024);
; #pragma unroll
;             for (int j = 0; j < 4; ++j) t[s][j] = q[lane + 64 * j]; }
; #pragma unroll
;         for (int s = 0; s < 4; ++s)
; #pragma unroll
;             for (int j = 0; j < 4; ++j) v[j] += t[s][j]; }
; }
.LBB0_1251:
	s_add_i32 s70, s0, 0xffff8000
	s_lshl_b64 s[22:23], s[70:71], 12
	s_add_i32 s70, s0, 0xffff8400
	v_lshl_add_u64 v[78:79], v[184:185], 0, s[22:23]
	s_lshl_b64 s[22:23], s[70:71], 12
	s_add_i32 s70, s0, 0xffff8800
	global_load_dwordx4 v[66:69], v[78:79], off
	global_load_dwordx4 v[70:73], v[78:79], off offset:1024
	global_load_dwordx4 v[74:77], v[78:79], off offset:2048
	global_load_dwordx4 v[78:81], v[78:79], off offset:3072
	v_lshl_add_u64 v[94:95], v[184:185], 0, s[22:23]
	s_lshl_b64 s[22:23], s[70:71], 12
	s_add_i32 s70, s0, 0xffff8c00
	global_load_dwordx4 v[82:85], v[94:95], off
	global_load_dwordx4 v[86:89], v[94:95], off offset:1024
	global_load_dwordx4 v[90:93], v[94:95], off offset:2048
	global_load_dwordx4 v[94:97], v[94:95], off offset:3072
	v_lshl_add_u64 v[110:111], v[184:185], 0, s[22:23]
	s_lshl_b64 s[22:23], s[70:71], 12
	global_load_dwordx4 v[98:101], v[110:111], off
	global_load_dwordx4 v[102:105], v[110:111], off offset:1024
	global_load_dwordx4 v[106:109], v[110:111], off offset:2048
	global_load_dwordx4 v[110:113], v[110:111], off offset:3072
	v_lshl_add_u64 v[126:127], v[184:185], 0, s[22:23]
	global_load_dwordx4 v[114:117], v[126:127], off
	global_load_dwordx4 v[118:121], v[126:127], off offset:1024
	global_load_dwordx4 v[122:125], v[126:127], off offset:2048
	global_load_dwordx4 v[126:129], v[126:127], off offset:3072
	s_add_i32 s70, s0, 0xffff9000
	s_lshl_b64 s[22:23], s[70:71], 12
	s_add_i32 s70, s0, 0xffff9400
	s_waitcnt vmcnt(15)
	v_pk_add_f32 v[68:69], v[68:69], 0 op_sel_hi:[1,0]
	v_pk_add_f32 v[66:67], v[66:67], 0 op_sel_hi:[1,0]
	s_waitcnt vmcnt(14)
	v_pk_add_f32 v[72:73], v[72:73], 0 op_sel_hi:[1,0]
	v_pk_add_f32 v[70:71], v[70:71], 0 op_sel_hi:[1,0]
	s_waitcnt vmcnt(13)
	v_pk_add_f32 v[76:77], v[76:77], 0 op_sel_hi:[1,0]
	v_pk_add_f32 v[74:75], v[74:75], 0 op_sel_hi:[1,0]
	s_waitcnt vmcnt(12)
	v_pk_add_f32 v[80:81], v[80:81], 0 op_sel_hi:[1,0]
	v_pk_add_f32 v[78:79], v[78:79], 0 op_sel_hi:[1,0]
	s_waitcnt vmcnt(11)
	v_pk_add_f32 v[68:69], v[68:69], v[84:85]
	v_pk_add_f32 v[66:67], v[66:67], v[82:83]
	s_waitcnt vmcnt(10)
	v_pk_add_f32 v[72:73], v[72:73], v[88:89]
	v_pk_add_f32 v[70:71], v[70:71], v[86:87]
	s_waitcnt vmcnt(9)
	v_pk_add_f32 v[76:77], v[76:77], v[92:93]
	v_pk_add_f32 v[74:75], v[74:75], v[90:91]
	s_waitcnt vmcnt(8)
	v_pk_add_f32 v[80:81], v[80:81], v[96:97]
	v_pk_add_f32 v[78:79], v[78:79], v[94:95]
	s_waitcnt vmcnt(7)
	v_pk_add_f32 v[68:69], v[68:69], v[100:101]
	v_pk_add_f32 v[66:67], v[66:67], v[98:99]
	s_waitcnt vmcnt(6)
	v_pk_add_f32 v[72:73], v[72:73], v[104:105]
	v_pk_add_f32 v[70:71], v[70:71], v[102:103]
	s_waitcnt vmcnt(5)
	v_pk_add_f32 v[82:83], v[76:77], v[108:109]
	v_pk_add_f32 v[84:85], v[74:75], v[106:107]
	s_waitcnt vmcnt(4)
	v_pk_add_f32 v[86:87], v[80:81], v[112:113]
	v_pk_add_f32 v[88:89], v[78:79], v[110:111]
	v_lshl_add_u64 v[94:95], v[184:185], 0, s[22:23]
	s_lshl_b64 s[22:23], s[70:71], 12
	s_add_i32 s70, s0, 0xffff9800
	s_waitcnt vmcnt(3)
	v_pk_add_f32 v[78:79], v[68:69], v[116:117]
	v_pk_add_f32 v[80:81], v[66:67], v[114:115]
	s_waitcnt vmcnt(2)
	v_pk_add_f32 v[74:75], v[72:73], v[120:121]
	v_pk_add_f32 v[76:77], v[70:71], v[118:119]
	s_waitcnt vmcnt(1)
	v_pk_add_f32 v[66:67], v[82:83], v[124:125]
	v_pk_add_f32 v[68:69], v[84:85], v[122:123]
	s_waitcnt vmcnt(0)
	v_pk_add_f32 v[70:71], v[86:87], v[128:129]
	v_pk_add_f32 v[72:73], v[88:89], v[126:127]
	global_load_dwordx4 v[82:85], v[94:95], off
	global_load_dwordx4 v[86:89], v[94:95], off offset:1024
	global_load_dwordx4 v[90:93], v[94:95], off offset:2048
	global_load_dwordx4 v[94:97], v[94:95], off offset:3072
	v_lshl_add_u64 v[110:111], v[184:185], 0, s[22:23]
	s_lshl_b64 s[22:23], s[70:71], 12
	s_add_i32 s70, s0, 0xffff9c00
	global_load_dwordx4 v[98:101], v[110:111], off
	global_load_dwordx4 v[102:105], v[110:111], off offset:1024
	global_load_dwordx4 v[106:109], v[110:111], off offset:2048
	global_load_dwordx4 v[110:113], v[110:111], off offset:3072
	v_lshl_add_u64 v[126:127], v[184:185], 0, s[22:23]
	s_lshl_b64 s[22:23], s[70:71], 12
	global_load_dwordx4 v[114:117], v[126:127], off
	global_load_dwordx4 v[118:121], v[126:127], off offset:1024
	global_load_dwordx4 v[122:125], v[126:127], off offset:2048
	global_load_dwordx4 v[126:129], v[126:127], off offset:3072
	v_lshl_add_u64 v[142:143], v[184:185], 0, s[22:23]
	global_load_dwordx4 v[130:133], v[142:143], off
	global_load_dwordx4 v[134:137], v[142:143], off offset:1024
	global_load_dwordx4 v[138:141], v[142:143], off offset:2048
	global_load_dwordx4 v[142:145], v[142:143], off offset:3072
	s_add_i32 s70, s0, 0xffffa000
	s_lshl_b64 s[22:23], s[70:71], 12
	s_add_i32 s70, s0, 0xffffa400
	s_waitcnt vmcnt(15)
	v_pk_add_f32 v[78:79], v[78:79], v[84:85]
	v_pk_add_f32 v[80:81], v[80:81], v[82:83]
	s_waitcnt vmcnt(14)
	v_pk_add_f32 v[74:75], v[74:75], v[88:89]
	v_pk_add_f32 v[76:77], v[76:77], v[86:87]
	s_waitcnt vmcnt(13)
	v_pk_add_f32 v[66:67], v[66:67], v[92:93]
	v_pk_add_f32 v[68:69], v[68:69], v[90:91]
	s_waitcnt vmcnt(12)
	v_pk_add_f32 v[70:71], v[70:71], v[96:97]
	v_pk_add_f32 v[72:73], v[72:73], v[94:95]
	s_waitcnt vmcnt(11)
	v_pk_add_f32 v[78:79], v[78:79], v[100:101]
	v_pk_add_f32 v[80:81], v[80:81], v[98:99]
	s_waitcnt vmcnt(10)
	v_pk_add_f32 v[74:75], v[74:75], v[104:105]
	v_pk_add_f32 v[76:77], v[76:77], v[102:103]
	s_waitcnt vmcnt(9)
	v_pk_add_f32 v[66:67], v[66:67], v[108:109]
	v_pk_add_f32 v[68:69], v[68:69], v[106:107]
	s_waitcnt vmcnt(8)
	v_pk_add_f32 v[70:71], v[70:71], v[112:113]
	v_pk_add_f32 v[72:73], v[72:73], v[110:111]
	s_waitcnt vmcnt(7)
	v_pk_add_f32 v[78:79], v[78:79], v[116:117]
	v_pk_add_f32 v[80:81], v[80:81], v[114:115]
	s_waitcnt vmcnt(6)
; template <int NS> __device__ __forceinline__ void load16part(const float* P, int rowrel, int lane, f32x4 (&v)[4]) {
; #pragma unroll
;     for (int j = 0; j < 4; ++j) v[j] = (f32x4){0.f, 0.f, 0.f, 0.f};
; #pragma unroll
;     for (int s0 = 0; s0 < NS; s0 += 4) { f32x4 t[4][4];
; #pragma unroll
;         for (int s = 0; s < 4; ++s) { const f32x4* q = (const f32x4*)(P + ((size_t)(s0 + s) * 1024 + rowrel) * 1024);
; #pragma unroll
;             for (int j = 0; j < 4; ++j) t[s][j] = q[lane + 64 * j]; }
; #pragma unroll
;         for (int s = 0; s < 4; ++s)
; #pragma unroll
;             for (int j = 0; j < 4; ++j) v[j] += t[s][j]; }
; }
	v_pk_add_f32 v[74:75], v[74:75], v[120:121]
	v_pk_add_f32 v[76:77], v[76:77], v[118:119]
	s_waitcnt vmcnt(5)
	v_pk_add_f32 v[66:67], v[66:67], v[124:125]
	v_pk_add_f32 v[68:69], v[68:69], v[122:123]
	s_waitcnt vmcnt(4)
	v_pk_add_f32 v[70:71], v[70:71], v[128:129]
	v_pk_add_f32 v[72:73], v[72:73], v[126:127]
	s_waitcnt vmcnt(3)
	v_pk_add_f32 v[132:133], v[78:79], v[132:133]
	v_lshl_add_u64 v[78:79], v[184:185], 0, s[22:23]
	s_lshl_b64 s[22:23], s[70:71], 12
	s_add_i32 s70, s0, 0xffffa800
	v_pk_add_f32 v[130:131], v[80:81], v[130:131]
	s_waitcnt vmcnt(2)
	v_pk_add_f32 v[136:137], v[74:75], v[136:137]
	v_pk_add_f32 v[134:135], v[76:77], v[134:135]
	s_waitcnt vmcnt(1)
	v_pk_add_f32 v[140:141], v[66:67], v[140:141]
	v_pk_add_f32 v[138:139], v[68:69], v[138:139]
	s_waitcnt vmcnt(0)
	v_pk_add_f32 v[144:145], v[70:71], v[144:145]
	v_pk_add_f32 v[142:143], v[72:73], v[142:143]
	global_load_dwordx4 v[66:69], v[78:79], off
	global_load_dwordx4 v[70:73], v[78:79], off offset:1024
	global_load_dwordx4 v[74:77], v[78:79], off offset:2048
	global_load_dwordx4 v[78:81], v[78:79], off offset:3072
	v_lshl_add_u64 v[94:95], v[184:185], 0, s[22:23]
	s_lshl_b64 s[22:23], s[70:71], 12
	s_add_i32 s70, s0, 0xffffac00
	global_load_dwordx4 v[82:85], v[94:95], off
	global_load_dwordx4 v[86:89], v[94:95], off offset:1024
	global_load_dwordx4 v[90:93], v[94:95], off offset:2048
	global_load_dwordx4 v[94:97], v[94:95], off offset:3072
	v_lshl_add_u64 v[110:111], v[184:185], 0, s[22:23]
	s_lshl_b64 s[22:23], s[70:71], 12
	global_load_dwordx4 v[98:101], v[110:111], off
	global_load_dwordx4 v[102:105], v[110:111], off offset:1024
	global_load_dwordx4 v[106:109], v[110:111], off offset:2048
	global_load_dwordx4 v[110:113], v[110:111], off offset:3072
	v_lshl_add_u64 v[126:127], v[184:185], 0, s[22:23]
	global_load_dwordx4 v[114:117], v[126:127], off
	global_load_dwordx4 v[118:121], v[126:127], off offset:1024
	global_load_dwordx4 v[122:125], v[126:127], off offset:2048
	global_load_dwordx4 v[126:129], v[126:127], off offset:3072
	s_add_i32 s70, s0, 0xffffb000
	s_lshl_b64 s[22:23], s[70:71], 12
	s_add_i32 s70, s0, 0xffffb400
	s_waitcnt vmcnt(15)
	v_pk_add_f32 v[66:67], v[130:131], v[66:67]
	v_pk_add_f32 v[68:69], v[132:133], v[68:69]
	s_waitcnt vmcnt(13)
	v_pk_add_f32 v[76:77], v[140:141], v[76:77]
	v_pk_add_f32 v[74:75], v[138:139], v[74:75]
	s_waitcnt vmcnt(12)
	v_pk_add_f32 v[80:81], v[144:145], v[80:81]
	v_pk_add_f32 v[78:79], v[142:143], v[78:79]
	s_waitcnt vmcnt(11)
	v_pk_add_f32 v[66:67], v[66:67], v[82:83]
	v_pk_add_f32 v[72:73], v[136:137], v[72:73]
	v_pk_add_f32 v[70:71], v[134:135], v[70:71]
	v_pk_add_f32 v[68:69], v[68:69], v[84:85]
	s_waitcnt vmcnt(9)
	v_pk_add_f32 v[76:77], v[76:77], v[92:93]
	v_pk_add_f32 v[74:75], v[74:75], v[90:91]
	s_waitcnt vmcnt(8)
	v_pk_add_f32 v[80:81], v[80:81], v[96:97]
	v_pk_add_f32 v[78:79], v[78:79], v[94:95]
	s_waitcnt vmcnt(7)
	v_pk_add_f32 v[66:67], v[66:67], v[98:99]
	v_pk_add_f32 v[72:73], v[72:73], v[88:89]
	v_pk_add_f32 v[70:71], v[70:71], v[86:87]
	v_pk_add_f32 v[68:69], v[68:69], v[100:101]
	s_waitcnt vmcnt(5)
	v_pk_add_f32 v[76:77], v[76:77], v[108:109]
	v_pk_add_f32 v[74:75], v[74:75], v[106:107]
	s_waitcnt vmcnt(4)
	v_pk_add_f32 v[80:81], v[80:81], v[112:113]
	v_pk_add_f32 v[78:79], v[78:79], v[110:111]
	s_waitcnt vmcnt(3)
	v_pk_add_f32 v[144:145], v[66:67], v[114:115]
	v_lshl_add_u64 v[66:67], v[184:185], 0, s[22:23]
	s_lshl_b64 s[22:23], s[70:71], 12
	s_add_i32 s70, s0, 0xffffb800
	v_pk_add_f32 v[72:73], v[72:73], v[104:105]
	v_pk_add_f32 v[70:71], v[70:71], v[102:103]
	v_pk_add_f32 v[142:143], v[68:69], v[116:117]
	s_waitcnt vmcnt(1)
	v_pk_add_f32 v[134:135], v[76:77], v[124:125]
	v_pk_add_f32 v[136:137], v[74:75], v[122:123]
	s_waitcnt vmcnt(0)
	v_pk_add_f32 v[130:131], v[80:81], v[128:129]
	v_pk_add_f32 v[132:133], v[78:79], v[126:127]
	global_load_dwordx4 v[122:125], v[66:67], off
	global_load_dwordx4 v[126:129], v[66:67], off offset:1024
	global_load_dwordx4 v[114:117], v[66:67], off offset:2048
	global_load_dwordx4 v[98:101], v[66:67], off offset:3072
	v_lshl_add_u64 v[66:67], v[184:185], 0, s[22:23]
	s_lshl_b64 s[22:23], s[70:71], 12
	s_add_i32 s70, s0, 0xffffbc00
	v_pk_add_f32 v[138:139], v[72:73], v[120:121]
	v_pk_add_f32 v[140:141], v[70:71], v[118:119]
	global_load_dwordx4 v[110:113], v[66:67], off
	global_load_dwordx4 v[118:121], v[66:67], off offset:1024
	global_load_dwordx4 v[102:105], v[66:67], off offset:2048
	global_load_dwordx4 v[86:89], v[66:67], off offset:3072
	v_lshl_add_u64 v[66:67], v[184:185], 0, s[22:23]
	s_lshl_b64 s[22:23], s[70:71], 12
	global_load_dwordx4 v[94:97], v[66:67], off
	global_load_dwordx4 v[106:109], v[66:67], off offset:1024
	global_load_dwordx4 v[90:93], v[66:67], off offset:2048
	global_load_dwordx4 v[78:81], v[66:67], off offset:3072
	v_lshl_add_u64 v[66:67], v[184:185], 0, s[22:23]
	global_load_dwordx4 v[82:85], v[66:67], off
	global_load_dwordx4 v[74:77], v[66:67], off offset:1024
	global_load_dwordx4 v[70:73], v[66:67], off offset:2048
	global_load_dwordx4 v[66:69], v[66:67], off offset:3072
	s_waitcnt vmcnt(15)
	v_pk_add_f32 v[124:125], v[142:143], v[124:125]
	v_pk_add_f32 v[122:123], v[144:145], v[122:123]
	s_waitcnt vmcnt(14)
	v_pk_add_f32 v[128:129], v[138:139], v[128:129]
	v_pk_add_f32 v[126:127], v[140:141], v[126:127]
	s_waitcnt vmcnt(13)
	v_pk_add_f32 v[116:117], v[134:135], v[116:117]
	v_pk_add_f32 v[114:115], v[136:137], v[114:115]
	s_waitcnt vmcnt(12)
	v_pk_add_f32 v[100:101], v[130:131], v[100:101]
	v_pk_add_f32 v[98:99], v[132:133], v[98:99]
	s_waitcnt vmcnt(11)
	v_pk_add_f32 v[112:113], v[124:125], v[112:113]
	v_pk_add_f32 v[110:111], v[122:123], v[110:111]
	s_waitcnt vmcnt(10)
	v_pk_add_f32 v[120:121], v[128:129], v[120:121]
	v_pk_add_f32 v[118:119], v[126:127], v[118:119]
	s_waitcnt vmcnt(9)
	v_pk_add_f32 v[104:105], v[116:117], v[104:105]
	v_pk_add_f32 v[102:103], v[114:115], v[102:103]
	s_waitcnt vmcnt(8)
	v_pk_add_f32 v[88:89], v[100:101], v[88:89]
	v_pk_add_f32 v[86:87], v[98:99], v[86:87]
	s_waitcnt vmcnt(7)
	v_pk_add_f32 v[96:97], v[112:113], v[96:97]
	v_pk_add_f32 v[94:95], v[110:111], v[94:95]
	s_waitcnt vmcnt(6)
	v_pk_add_f32 v[98:99], v[120:121], v[108:109]
	v_pk_add_f32 v[100:101], v[118:119], v[106:107]
	s_waitcnt vmcnt(5)
	v_pk_add_f32 v[104:105], v[104:105], v[92:93]
	v_pk_add_f32 v[102:103], v[102:103], v[90:91]
	s_waitcnt vmcnt(4)
	v_pk_add_f32 v[80:81], v[88:89], v[80:81]
	v_pk_add_f32 v[78:79], v[86:87], v[78:79]
	s_waitcnt vmcnt(3)
	v_pk_add_f32 v[96:97], v[96:97], v[84:85]
	v_pk_add_f32 v[94:95], v[94:95], v[82:83]
	s_waitcnt vmcnt(2)
	v_pk_add_f32 v[92:93], v[98:99], v[76:77]
	v_pk_add_f32 v[90:91], v[100:101], v[74:75]
	s_waitcnt vmcnt(1)
	v_pk_add_f32 v[88:89], v[104:105], v[72:73]
	v_pk_add_f32 v[86:87], v[102:103], v[70:71]
	s_waitcnt vmcnt(0)
	v_pk_add_f32 v[84:85], v[80:81], v[68:69]
	v_pk_add_f32 v[82:83], v[78:79], v[66:67]
	s_cmp_lt_i32 s0, 0x8000
	s_mov_b64 s[24:25], -1
	s_cbranch_scc0 .LBB0_1249

; __device__ __forceinline__ float bflo(unsigned w) { return __uint_as_float(w << 16); }
; __device__ __forceinline__ float bfhi(unsigned w) { return __uint_as_float(w & 0xffff0000u); }
; #define LOADY(m, y, ns) do { if ((m) >= NLAT) load16part<ns>(WSP(float, WS_PART), (m) - NLAT, lane, y); else load16bf(BY + (size_t)(m) * DM, lane, y); } while (0)
; __device__ __forceinline__ void load16(const float* row, int lane, f32x4 (&v)[4]) {
; #pragma unroll
;     for (int j = 0; j < 4; ++j) v[j] = __builtin_nontemporal_load((const f32x4*)row + lane + 64 * j);
; }
; __device__ __forceinline__ void load16bf(const bf16_t* row, int lane, f32x4 (&v)[4]) {
; #pragma unroll
;     for (int j = 0; j < 4; ++j) { const u32x2 w = __builtin_nontemporal_load((const u32x2*)row + lane + 64 * j); v[j] = (f32x4){bflo(w.x), bfhi(w.x), bflo(w.y), bfhi(w.y)}; }
; }
; __global__ void __launch_bounds__(512, 2) fwd_megakernel(Params p) {
;     ...
;             for (int i = 0; i < 4; ++i) { const int mi = m0 + i * NGW, mc = mi < Mact ? mi : m0; LOADY(mc, yb[i], 16); load16(XS_ROW(mc), lane, xb[i]); }
.LBB0_1254:
	s_lshl_b64 s[0:1], s[22:23], 12
	s_waitcnt lgkmcnt(0)
	s_add_u32 s0, s24, s0
	s_addc_u32 s1, s25, s1
	global_load_dwordx4 v[78:81], v214, s[0:1] nt
	global_load_dwordx4 v[74:77], v214, s[0:1] offset:1024 nt
	global_load_dwordx4 v[70:73], v214, s[0:1] offset:2048 nt
	global_load_dwordx4 v[66:69], v214, s[0:1] offset:3072 nt
	s_add_i32 s22, s12, 0x1800
	s_cmp_lt_i32 s22, s53
	s_cselect_b64 s[24:25], -1, 0
	s_and_b64 s[0:1], s[24:25], exec
	s_cselect_b32 s0, s22, s12
	s_cmpk_gt_i32 s0, 0x7fff
	s_mov_b64 s[26:27], -1
	s_cbranch_scc1 .LBB0_1258
	s_ashr_i32 s1, s0, 31
	s_lshl_b64 s[26:27], s[0:1], 11
	v_lshl_add_u64 v[98:99], v[178:179], 0, s[26:27]
	global_load_dwordx2 v[100:101], v[98:99], off nt
	global_load_dwordx2 v[102:103], v[98:99], off offset:512 nt
	global_load_dwordx2 v[104:105], v[98:99], off offset:1024 nt
	global_load_dwordx2 v[98:99], v[98:99], off offset:1536 nt
	s_waitcnt vmcnt(3)
	v_lshlrev_b32_e32 v126, 16, v100
	v_and_b32_e32 v127, 0xffff0000, v100
	v_lshlrev_b32_e32 v128, 16, v101
	v_and_b32_e32 v129, 0xffff0000, v101
	s_waitcnt vmcnt(2)
	v_lshlrev_b32_e32 v122, 16, v102
	v_and_b32_e32 v123, 0xffff0000, v102
	v_lshlrev_b32_e32 v124, 16, v103
	v_and_b32_e32 v125, 0xffff0000, v103
	s_waitcnt vmcnt(1)
	v_lshlrev_b32_e32 v118, 16, v104
	v_and_b32_e32 v119, 0xffff0000, v104
	v_lshlrev_b32_e32 v120, 16, v105
	v_and_b32_e32 v121, 0xffff0000, v105
	s_waitcnt vmcnt(0)
	v_lshlrev_b32_e32 v114, 16, v98
	v_and_b32_e32 v115, 0xffff0000, v98
	v_lshlrev_b32_e32 v116, 16, v99
	v_and_b32_e32 v117, 0xffff0000, v99
	s_cbranch_execz .LBB0_1259

; template <int NS> __device__ __forceinline__ void load16part(const float* P, int rowrel, int lane, f32x4 (&v)[4]) {
; #pragma unroll
;     for (int j = 0; j < 4; ++j) v[j] = (f32x4){0.f, 0.f, 0.f, 0.f};
; #pragma unroll
;     for (int s0 = 0; s0 < NS; s0 += 4) { f32x4 t[4][4];
; #pragma unroll
;         for (int s = 0; s < 4; ++s) { const f32x4* q = (const f32x4*)(P + ((size_t)(s0 + s) * 1024 + rowrel) * 1024);
; #pragma unroll
;             for (int j = 0; j < 4; ++j) t[s][j] = q[lane + 64 * j]; }
; #pragma unroll
;         for (int s = 0; s < 4; ++s)
; #pragma unroll
;             for (int j = 0; j < 4; ++j) v[j] += t[s][j]; }
; }
.LBB0_1259:
	s_add_i32 s70, s0, 0xffff8000
	s_lshl_b64 s[26:27], s[70:71], 12
	s_add_i32 s70, s0, 0xffff8400
	v_lshl_add_u64 v[110:111], v[184:185], 0, s[26:27]
	s_lshl_b64 s[26:27], s[70:71], 12
	s_add_i32 s70, s0, 0xffff8800
	global_load_dwordx4 v[98:101], v[110:111], off
	global_load_dwordx4 v[102:105], v[110:111], off offset:1024
	global_load_dwordx4 v[106:109], v[110:111], off offset:2048
	global_load_dwordx4 v[110:113], v[110:111], off offset:3072
	v_lshl_add_u64 v[126:127], v[184:185], 0, s[26:27]
	s_lshl_b64 s[26:27], s[70:71], 12
	s_add_i32 s70, s0, 0xffff8c00
	global_load_dwordx4 v[114:117], v[126:127], off
	global_load_dwordx4 v[118:121], v[126:127], off offset:1024
	global_load_dwordx4 v[122:125], v[126:127], off offset:2048
	global_load_dwordx4 v[126:129], v[126:127], off offset:3072
	v_lshl_add_u64 v[142:143], v[184:185], 0, s[26:27]
	s_lshl_b64 s[26:27], s[70:71], 12
	global_load_dwordx4 v[130:133], v[142:143], off
	global_load_dwordx4 v[134:137], v[142:143], off offset:1024
	global_load_dwordx4 v[138:141], v[142:143], off offset:2048
	global_load_dwordx4 v[142:145], v[142:143], off offset:3072
	v_lshl_add_u64 v[158:159], v[184:185], 0, s[26:27]
	global_load_dwordx4 v[146:149], v[158:159], off
	global_load_dwordx4 v[150:153], v[158:159], off offset:1024
	global_load_dwordx4 v[154:157], v[158:159], off offset:2048
	global_load_dwordx4 v[158:161], v[158:159], off offset:3072
	s_add_i32 s70, s0, 0xffff9000
	s_lshl_b64 s[26:27], s[70:71], 12
	s_add_i32 s70, s0, 0xffff9400
	s_waitcnt vmcnt(15)
	v_pk_add_f32 v[100:101], v[100:101], 0 op_sel_hi:[1,0]
	v_pk_add_f32 v[98:99], v[98:99], 0 op_sel_hi:[1,0]
	s_waitcnt vmcnt(14)
	v_pk_add_f32 v[104:105], v[104:105], 0 op_sel_hi:[1,0]
	v_pk_add_f32 v[102:103], v[102:103], 0 op_sel_hi:[1,0]
	s_waitcnt vmcnt(13)
	v_pk_add_f32 v[108:109], v[108:109], 0 op_sel_hi:[1,0]
	v_pk_add_f32 v[106:107], v[106:107], 0 op_sel_hi:[1,0]
	s_waitcnt vmcnt(12)
	v_pk_add_f32 v[112:113], v[112:113], 0 op_sel_hi:[1,0]
	v_pk_add_f32 v[110:111], v[110:111], 0 op_sel_hi:[1,0]
	s_waitcnt vmcnt(11)
	v_pk_add_f32 v[100:101], v[100:101], v[116:117]
	v_pk_add_f32 v[98:99], v[98:99], v[114:115]
	s_waitcnt vmcnt(10)
	v_pk_add_f32 v[104:105], v[104:105], v[120:121]
	v_pk_add_f32 v[102:103], v[102:103], v[118:119]
	s_waitcnt vmcnt(9)
	v_pk_add_f32 v[108:109], v[108:109], v[124:125]
	v_pk_add_f32 v[106:107], v[106:107], v[122:123]
	s_waitcnt vmcnt(8)
	v_pk_add_f32 v[112:113], v[112:113], v[128:129]
	v_pk_add_f32 v[110:111], v[110:111], v[126:127]
	s_waitcnt vmcnt(7)
	v_pk_add_f32 v[100:101], v[100:101], v[132:133]
	v_pk_add_f32 v[98:99], v[98:99], v[130:131]
	s_waitcnt vmcnt(6)
	v_pk_add_f32 v[104:105], v[104:105], v[136:137]
	v_pk_add_f32 v[102:103], v[102:103], v[134:135]
	s_waitcnt vmcnt(5)
	v_pk_add_f32 v[114:115], v[108:109], v[140:141]
	v_pk_add_f32 v[116:117], v[106:107], v[138:139]
	s_waitcnt vmcnt(4)
	v_pk_add_f32 v[118:119], v[112:113], v[144:145]
	v_pk_add_f32 v[120:121], v[110:111], v[142:143]
	v_lshl_add_u64 v[126:127], v[184:185], 0, s[26:27]
	s_lshl_b64 s[26:27], s[70:71], 12
	s_add_i32 s70, s0, 0xffff9800
	s_waitcnt vmcnt(3)
	v_pk_add_f32 v[110:111], v[100:101], v[148:149]
	v_pk_add_f32 v[112:113], v[98:99], v[146:147]
	s_waitcnt vmcnt(2)
	v_pk_add_f32 v[106:107], v[104:105], v[152:153]
	v_pk_add_f32 v[108:109], v[102:103], v[150:151]
	s_waitcnt vmcnt(1)
	v_pk_add_f32 v[98:99], v[114:115], v[156:157]
	v_pk_add_f32 v[100:101], v[116:117], v[154:155]
	s_waitcnt vmcnt(0)
	v_pk_add_f32 v[102:103], v[118:119], v[160:161]
	v_pk_add_f32 v[104:105], v[120:121], v[158:159]
	global_load_dwordx4 v[114:117], v[126:127], off
	global_load_dwordx4 v[118:121], v[126:127], off offset:1024
	global_load_dwordx4 v[122:125], v[126:127], off offset:2048
	global_load_dwordx4 v[126:129], v[126:127], off offset:3072
	v_lshl_add_u64 v[142:143], v[184:185], 0, s[26:27]
	s_lshl_b64 s[26:27], s[70:71], 12
	s_add_i32 s70, s0, 0xffff9c00
	global_load_dwordx4 v[130:133], v[142:143], off
	global_load_dwordx4 v[134:137], v[142:143], off offset:1024
	global_load_dwordx4 v[138:141], v[142:143], off offset:2048
	global_load_dwordx4 v[142:145], v[142:143], off offset:3072
	v_lshl_add_u64 v[158:159], v[184:185], 0, s[26:27]
	s_lshl_b64 s[26:27], s[70:71], 12
	global_load_dwordx4 v[146:149], v[158:159], off
	global_load_dwordx4 v[150:153], v[158:159], off offset:1024
	global_load_dwordx4 v[154:157], v[158:159], off offset:2048
	global_load_dwordx4 v[158:161], v[158:159], off offset:3072
	v_lshl_add_u64 v[174:175], v[184:185], 0, s[26:27]
	global_load_dwordx4 v[162:165], v[174:175], off
	global_load_dwordx4 v[166:169], v[174:175], off offset:1024
	global_load_dwordx4 v[170:173], v[174:175], off offset:2048
	global_load_dwordx4 v[190:193], v[174:175], off offset:3072
	s_add_i32 s70, s0, 0xffffa000
	s_lshl_b64 s[26:27], s[70:71], 12
	s_add_i32 s70, s0, 0xffffa400
	s_waitcnt vmcnt(15)
	v_pk_add_f32 v[110:111], v[110:111], v[116:117]
	v_pk_add_f32 v[112:113], v[112:113], v[114:115]
	s_waitcnt vmcnt(14)
	v_pk_add_f32 v[106:107], v[106:107], v[120:121]
	v_pk_add_f32 v[108:109], v[108:109], v[118:119]
	s_waitcnt vmcnt(13)
	v_pk_add_f32 v[98:99], v[98:99], v[124:125]
	v_pk_add_f32 v[100:101], v[100:101], v[122:123]
	s_waitcnt vmcnt(12)
	v_pk_add_f32 v[102:103], v[102:103], v[128:129]
	v_pk_add_f32 v[104:105], v[104:105], v[126:127]
	s_waitcnt vmcnt(11)
	v_pk_add_f32 v[110:111], v[110:111], v[132:133]
	v_pk_add_f32 v[112:113], v[112:113], v[130:131]
	s_waitcnt vmcnt(10)
	v_pk_add_f32 v[106:107], v[106:107], v[136:137]
	v_pk_add_f32 v[108:109], v[108:109], v[134:135]
	s_waitcnt vmcnt(9)
	v_pk_add_f32 v[98:99], v[98:99], v[140:141]
	v_pk_add_f32 v[100:101], v[100:101], v[138:139]
	s_waitcnt vmcnt(8)
; template <int NS> __device__ __forceinline__ void load16part(const float* P, int rowrel, int lane, f32x4 (&v)[4]) {
; #pragma unroll
;     for (int j = 0; j < 4; ++j) v[j] = (f32x4){0.f, 0.f, 0.f, 0.f};
; #pragma unroll
;     for (int s0 = 0; s0 < NS; s0 += 4) { f32x4 t[4][4];
; #pragma unroll
;         for (int s = 0; s < 4; ++s) { const f32x4* q = (const f32x4*)(P + ((size_t)(s0 + s) * 1024 + rowrel) * 1024);
; #pragma unroll
;             for (int j = 0; j < 4; ++j) t[s][j] = q[lane + 64 * j]; }
; #pragma unroll
;         for (int s = 0; s < 4; ++s)
; #pragma unroll
;             for (int j = 0; j < 4; ++j) v[j] += t[s][j]; }
; }
	v_pk_add_f32 v[102:103], v[102:103], v[144:145]
	v_pk_add_f32 v[104:105], v[104:105], v[142:143]
	s_waitcnt vmcnt(7)
	v_pk_add_f32 v[110:111], v[110:111], v[148:149]
	v_pk_add_f32 v[112:113], v[112:113], v[146:147]
	s_waitcnt vmcnt(6)
	v_pk_add_f32 v[106:107], v[106:107], v[152:153]
	v_pk_add_f32 v[108:109], v[108:109], v[150:151]
	s_waitcnt vmcnt(5)
	v_pk_add_f32 v[98:99], v[98:99], v[156:157]
	v_pk_add_f32 v[100:101], v[100:101], v[154:155]
	s_waitcnt vmcnt(4)
	v_pk_add_f32 v[102:103], v[102:103], v[160:161]
	v_pk_add_f32 v[104:105], v[104:105], v[158:159]
	s_waitcnt vmcnt(3)
	v_pk_add_f32 v[164:165], v[110:111], v[164:165]
	v_lshl_add_u64 v[110:111], v[184:185], 0, s[26:27]
	s_lshl_b64 s[26:27], s[70:71], 12
	s_add_i32 s70, s0, 0xffffa800
	v_pk_add_f32 v[162:163], v[112:113], v[162:163]
	s_waitcnt vmcnt(2)
	v_pk_add_f32 v[168:169], v[106:107], v[168:169]
	v_pk_add_f32 v[166:167], v[108:109], v[166:167]
	s_waitcnt vmcnt(1)
	v_pk_add_f32 v[172:173], v[98:99], v[172:173]
	v_pk_add_f32 v[170:171], v[100:101], v[170:171]
	s_waitcnt vmcnt(0)
	v_pk_add_f32 v[174:175], v[102:103], v[192:193]
	v_pk_add_f32 v[190:191], v[104:105], v[190:191]
	global_load_dwordx4 v[98:101], v[110:111], off
	global_load_dwordx4 v[102:105], v[110:111], off offset:1024
	global_load_dwordx4 v[106:109], v[110:111], off offset:2048
	global_load_dwordx4 v[110:113], v[110:111], off offset:3072
	v_lshl_add_u64 v[126:127], v[184:185], 0, s[26:27]
	s_lshl_b64 s[26:27], s[70:71], 12
	s_add_i32 s70, s0, 0xffffac00
	global_load_dwordx4 v[114:117], v[126:127], off
	global_load_dwordx4 v[118:121], v[126:127], off offset:1024
	global_load_dwordx4 v[122:125], v[126:127], off offset:2048
	global_load_dwordx4 v[126:129], v[126:127], off offset:3072
	v_lshl_add_u64 v[142:143], v[184:185], 0, s[26:27]
	s_lshl_b64 s[26:27], s[70:71], 12
	global_load_dwordx4 v[130:133], v[142:143], off
	global_load_dwordx4 v[134:137], v[142:143], off offset:1024
	global_load_dwordx4 v[138:141], v[142:143], off offset:2048
	global_load_dwordx4 v[142:145], v[142:143], off offset:3072
	v_lshl_add_u64 v[158:159], v[184:185], 0, s[26:27]
	global_load_dwordx4 v[146:149], v[158:159], off
	global_load_dwordx4 v[150:153], v[158:159], off offset:1024
	global_load_dwordx4 v[154:157], v[158:159], off offset:2048
	global_load_dwordx4 v[158:161], v[158:159], off offset:3072
	s_add_i32 s70, s0, 0xffffb000
	s_lshl_b64 s[26:27], s[70:71], 12
	s_add_i32 s70, s0, 0xffffb400
	s_waitcnt vmcnt(15)
	v_pk_add_f32 v[98:99], v[162:163], v[98:99]
	v_pk_add_f32 v[100:101], v[164:165], v[100:101]
	s_waitcnt vmcnt(13)
	v_pk_add_f32 v[108:109], v[172:173], v[108:109]
	v_pk_add_f32 v[106:107], v[170:171], v[106:107]
	s_waitcnt vmcnt(12)
	v_pk_add_f32 v[112:113], v[174:175], v[112:113]
	v_pk_add_f32 v[110:111], v[190:191], v[110:111]
	s_waitcnt vmcnt(11)
	v_pk_add_f32 v[98:99], v[98:99], v[114:115]
	v_pk_add_f32 v[104:105], v[168:169], v[104:105]
	v_pk_add_f32 v[102:103], v[166:167], v[102:103]
	v_pk_add_f32 v[100:101], v[100:101], v[116:117]
	s_waitcnt vmcnt(9)
	v_pk_add_f32 v[108:109], v[108:109], v[124:125]
	v_pk_add_f32 v[106:107], v[106:107], v[122:123]
	s_waitcnt vmcnt(8)
	v_pk_add_f32 v[112:113], v[112:113], v[128:129]
	v_pk_add_f32 v[110:111], v[110:111], v[126:127]
	s_waitcnt vmcnt(7)
	v_pk_add_f32 v[98:99], v[98:99], v[130:131]
	v_pk_add_f32 v[104:105], v[104:105], v[120:121]
	v_pk_add_f32 v[102:103], v[102:103], v[118:119]
	v_pk_add_f32 v[100:101], v[100:101], v[132:133]
	s_waitcnt vmcnt(5)
	v_pk_add_f32 v[108:109], v[108:109], v[140:141]
	v_pk_add_f32 v[106:107], v[106:107], v[138:139]
	s_waitcnt vmcnt(4)
	v_pk_add_f32 v[112:113], v[112:113], v[144:145]
	v_pk_add_f32 v[110:111], v[110:111], v[142:143]
	s_waitcnt vmcnt(3)
; template <int NS> __device__ __forceinline__ void load16part(const float* P, int rowrel, int lane, f32x4 (&v)[4]) {
; #pragma unroll
;     for (int j = 0; j < 4; ++j) v[j] = (f32x4){0.f, 0.f, 0.f, 0.f};
; #pragma unroll
;     for (int s0 = 0; s0 < NS; s0 += 4) { f32x4 t[4][4];
; #pragma unroll
;         for (int s = 0; s < 4; ++s) { const f32x4* q = (const f32x4*)(P + ((size_t)(s0 + s) * 1024 + rowrel) * 1024);
; #pragma unroll
;             for (int j = 0; j < 4; ++j) t[s][j] = q[lane + 64 * j]; }
; #pragma unroll
;         for (int s = 0; s < 4; ++s)
; #pragma unroll
;             for (int j = 0; j < 4; ++j) v[j] += t[s][j]; }
; }
	v_pk_add_f32 v[204:205], v[98:99], v[146:147]
	v_lshl_add_u64 v[98:99], v[184:185], 0, s[26:27]
	s_lshl_b64 s[26:27], s[70:71], 12
	s_add_i32 s70, s0, 0xffffb800
	v_pk_add_f32 v[104:105], v[104:105], v[136:137]
	v_pk_add_f32 v[102:103], v[102:103], v[134:135]
	v_pk_add_f32 v[202:203], v[100:101], v[148:149]
	s_waitcnt vmcnt(1)
	v_pk_add_f32 v[194:195], v[108:109], v[156:157]
	v_pk_add_f32 v[196:197], v[106:107], v[154:155]
	s_waitcnt vmcnt(0)
	v_pk_add_f32 v[190:191], v[112:113], v[160:161]
	v_pk_add_f32 v[192:193], v[110:111], v[158:159]
	global_load_dwordx4 v[154:157], v[98:99], off
	global_load_dwordx4 v[158:161], v[98:99], off offset:1024
	global_load_dwordx4 v[146:149], v[98:99], off offset:2048
	global_load_dwordx4 v[130:133], v[98:99], off offset:3072
	v_lshl_add_u64 v[98:99], v[184:185], 0, s[26:27]
	s_lshl_b64 s[26:27], s[70:71], 12
	s_add_i32 s70, s0, 0xffffbc00
	v_pk_add_f32 v[198:199], v[104:105], v[152:153]
	v_pk_add_f32 v[200:201], v[102:103], v[150:151]
	global_load_dwordx4 v[142:145], v[98:99], off
	global_load_dwordx4 v[150:153], v[98:99], off offset:1024
	global_load_dwordx4 v[134:137], v[98:99], off offset:2048
	global_load_dwordx4 v[118:121], v[98:99], off offset:3072
	v_lshl_add_u64 v[98:99], v[184:185], 0, s[26:27]
	s_lshl_b64 s[26:27], s[70:71], 12
	global_load_dwordx4 v[126:129], v[98:99], off
	global_load_dwordx4 v[138:141], v[98:99], off offset:1024
	global_load_dwordx4 v[122:125], v[98:99], off offset:2048
	global_load_dwordx4 v[110:113], v[98:99], off offset:3072
	v_lshl_add_u64 v[98:99], v[184:185], 0, s[26:27]
	global_load_dwordx4 v[114:117], v[98:99], off
	global_load_dwordx4 v[106:109], v[98:99], off offset:1024
	global_load_dwordx4 v[102:105], v[98:99], off offset:2048
	global_load_dwordx4 v[98:101], v[98:99], off offset:3072
	s_waitcnt vmcnt(15)
	v_pk_add_f32 v[156:157], v[202:203], v[156:157]
	v_pk_add_f32 v[154:155], v[204:205], v[154:155]
	s_waitcnt vmcnt(14)
	v_pk_add_f32 v[160:161], v[198:199], v[160:161]
	v_pk_add_f32 v[158:159], v[200:201], v[158:159]
	s_waitcnt vmcnt(13)
	v_pk_add_f32 v[148:149], v[194:195], v[148:149]
	v_pk_add_f32 v[146:147], v[196:197], v[146:147]
	s_waitcnt vmcnt(12)
	v_pk_add_f32 v[132:133], v[190:191], v[132:133]
	v_pk_add_f32 v[130:131], v[192:193], v[130:131]
	s_waitcnt vmcnt(11)
	v_pk_add_f32 v[144:145], v[156:157], v[144:145]
	v_pk_add_f32 v[142:143], v[154:155], v[142:143]
	s_waitcnt vmcnt(10)
	v_pk_add_f32 v[152:153], v[160:161], v[152:153]
	v_pk_add_f32 v[150:151], v[158:159], v[150:151]
	s_waitcnt vmcnt(9)
	v_pk_add_f32 v[136:137], v[148:149], v[136:137]
	v_pk_add_f32 v[134:135], v[146:147], v[134:135]
	s_waitcnt vmcnt(8)
	v_pk_add_f32 v[120:121], v[132:133], v[120:121]
	v_pk_add_f32 v[118:119], v[130:131], v[118:119]
	s_waitcnt vmcnt(7)
	v_pk_add_f32 v[128:129], v[144:145], v[128:129]
	v_pk_add_f32 v[126:127], v[142:143], v[126:127]
	s_waitcnt vmcnt(6)
	v_pk_add_f32 v[130:131], v[152:153], v[140:141]
	v_pk_add_f32 v[132:133], v[150:151], v[138:139]
	s_waitcnt vmcnt(5)
	v_pk_add_f32 v[136:137], v[136:137], v[124:125]
	v_pk_add_f32 v[134:135], v[134:135], v[122:123]
	s_waitcnt vmcnt(4)
	v_pk_add_f32 v[112:113], v[120:121], v[112:113]
	v_pk_add_f32 v[110:111], v[118:119], v[110:111]
	s_waitcnt vmcnt(3)
	v_pk_add_f32 v[128:129], v[128:129], v[116:117]
	v_pk_add_f32 v[126:127], v[126:127], v[114:115]
	s_waitcnt vmcnt(2)
	v_pk_add_f32 v[124:125], v[130:131], v[108:109]
	v_pk_add_f32 v[122:123], v[132:133], v[106:107]
	s_waitcnt vmcnt(1)
	v_pk_add_f32 v[120:121], v[136:137], v[104:105]
	v_pk_add_f32 v[118:119], v[134:135], v[102:103]
	s_waitcnt vmcnt(0)
	v_pk_add_f32 v[116:117], v[112:113], v[100:101]
	v_pk_add_f32 v[114:115], v[110:111], v[98:99]
	s_cmp_lt_i32 s0, 0x8000
	s_mov_b64 s[28:29], -1
	s_cbranch_scc0 .LBB0_1257
